# GEMM main loops: LDS-DMA loads use scalar tile base plus 32-bit lane offset instead of a VALU 64-bit add (52 sites)
# baseline (speedup 1.0000x reference)
; #define PG8_STAGE(bufoff, gbase, voff) do { _Pragma("unroll") for (int _i = 0; _i < 2; ++_i) \
;         __builtin_amdgcn_global_load_lds((const unsigned*)((const char*)(gbase) + (voff)[_i]), (LAS unsigned*)(lds + (bufoff) + ldsw + _i * 8192), 16, 0, 0); } while (0)
; #define PG8_WAIT_V(n) asm volatile("s_waitcnt vmcnt(" #n ")" ::: "memory")
; #define PG8_BAR __builtin_amdgcn_s_barrier()
; template <class Epi>
; __device__ __forceinline__ void gemm_phase(LAS unsigned char* lds, const Gemm g, const StaticOrder& S, const Epi& E) {
;     const int tid = threadIdx.x, wid = __builtin_amdgcn_readfirstlane(tid >> 6), lane = tid & 63, wr = wid >> 2, wc = wid & 3, fr = lane & 15, fq = lane >> 4;
;     const int K = g.K, nt = K / BK;
;     unsigned voffA[2], voffB[2];
; #pragma unroll
;     for (int i = 0; i < 2; ++i) { int R, C; stage_rc(tid * 16 + i * 8192, R, C); const int Rb = Epi::PERM ? ((R & ~31) + perm32(R & 31)) : R;
;         voffA[i] = (unsigned)(R * K + C) * 2u; voffB[i] = (unsigned)(Rb * K + C) * 2u; }
;     const size_t kstep = (size_t)(BK * 2);
;     const size_t hstep = (size_t)HALF * K * 2;
;     const size_t tstep = 2 * hstep;
;     const unsigned ldsw = (unsigned)wid * 1024u;
;     const int aoff = lds_byte(wr * 64 + fr, fq * 8), boff = lds_byte(wc * 32 + fr, fq * 8);
;     ...
;     Unit cur, nxt; int ui = 0;
;     if (!S.next(0, cur)) return;
;     f32x4 acc[2][2][4][2];
; #pragma unroll
;     for (int a = 0; a < 2; ++a)
; #pragma unroll
;         for (int b = 0; b < 2; ++b)
; #pragma unroll
;             for (int m = 0; m < 4; ++m)
; #pragma unroll
;                 for (int n = 0; n < 2; ++n) acc[a][b][m][n] = (f32x4){0.f, 0.f, 0.f, 0.f};
;     bf16x8 At[4][2], B0[2][2], B1[2][2];
;     const char* cA = (const char*)g.A + (size_t)cur.pm * tstep; const char* cB = (const char*)g.Bt + (size_t)cur.pn * tstep;
;     PG8_STAGE(PG8_SB(0, 0), cB, voffB); PG8_STAGE(PG8_SA(0, 0), cA, voffA); PG8_STAGE(PG8_SB(0, 1), cB + hstep, voffB); PG8_STAGE(PG8_SA(0, 1), cA + hstep, voffA);
;     if (wr == 1) PG8_BAR;
;     PG8_WAIT_V(4); PG8_BAR;
;     PG8_STAGE(PG8_SB(1, 0), cB + kstep, voffB); PG8_STAGE(PG8_SA(1, 0), cA + kstep, voffA); PG8_STAGE(PG8_SB(1, 1), cB + hstep + kstep, voffB);
;     PG8_WAIT_V(6); PG8_BAR;
.LBB0_128:
	s_add_u32 s0, s12, 0x4542000
	s_addc_u32 s1, s13, 0
	s_lshl_b32 s4, s4, 5
	s_and_b32 s11, s4, 0x60
	s_mov_b64 s[4:5], 0x80
	s_add_i32 m0, s17, 0x18000
	v_lshl_add_u64 v[6:7], v[6:7], 0, s[4:5]
	s_ashr_i32 s35, s94, 31
	s_ashr_i32 s50, s96, 31
	s_lshl_b32 s10, s3, 13
	s_lshl_b32 s18, s11, 7
	s_waitcnt vmcnt(4)
	s_barrier
	global_load_lds_dwordx4 v[6:7], off
	v_lshl_add_u64 v[4:5], v[4:5], 0, s[4:5]
	s_add_i32 m0, s17, 0x1a000
	s_add_i32 s51, s17, 0x8000
	s_add_i32 s54, s17, 0xa000
	global_load_lds_dwordx4 v[4:5], off
	v_lshl_add_u64 v[2:3], v[2:3], 0, s[4:5]
	s_mov_b32 m0, s51
	s_add_u32 s8, s24, 0x80080
	global_load_lds_dwordx4 v[2:3], off
	v_lshl_add_u64 v[0:1], v[0:1], 0, s[4:5]
	s_mov_b32 m0, s54
	s_addc_u32 s9, s25, 0
	global_load_lds_dwordx4 v[0:1], off
	s_add_i32 m0, s17, 0x1c000
	s_nop 0
	global_load_lds_dwordx4 v130, s[8:9]
	v_lshl_add_u64 v[0:1], s[8:9], 0, v[134:135]
	s_add_i32 m0, s17, 0x1e000
	s_sext_i32_i16 s72, s2
	global_load_lds_dwordx4 v[0:1], off
	v_lshlrev_b32_e32 v0, 1, v11
	v_lshlrev_b32_e32 v1, 6, v214
	s_movk_i32 s2, 0x3c0
	v_lshlrev_b32_e32 v2, 2, v214
	v_and_or_b32 v1, v1, s2, v0
	v_and_b32_e32 v2, 32, v2
	v_bitop3_b32 v152, s18, v1, v2 bitop3:0xf6
	v_lshlrev_b32_e32 v1, 9, v214
	v_and_b32_e32 v1, 0x70000, v1
	v_lshlrev_b32_e32 v2, 12, v10
	v_or3_b32 v1, v8, v1, v2
	v_lshlrev_b32_e32 v3, 2, v150
	v_add_u32_e32 v136, v1, v9
	v_lshlrev_b32_e32 v1, 5, v12
	v_lshl_or_b32 v0, v150, 6, v0
	v_and_b32_e32 v3, 32, v3
	s_waitcnt vmcnt(6)
	v_and_b32_e32 v1, 0xf0000, v1
	v_bitop3_b32 v0, v0, s10, v3 bitop3:0xde
	v_or3_b32 v1, v8, v1, v2
	s_add_i32 s69, 0, 0x10000
	s_add_i32 s70, 0, 0x14000
	s_mov_b32 s55, s96
	v_lshl_or_b32 v151, s3, 6, v150
	v_or_b32_e32 v153, s11, v11
	v_mov_b32_e32 v137, v131
	v_add_u32_e32 v138, v1, v9
	v_mov_b32_e32 v139, v131
	v_mov_b64_e32 v[140:141], 0x4a4
	v_mov_b64_e32 v[142:143], 0x4a3
	v_add_u32_e32 v154, s69, v152
	v_add_u32_e32 v155, 0, v0
	v_add_u32_e32 v156, s70, v152
	s_movk_i32 s71, 0x4800
	s_barrier

; #define PG8_STAGE(bufoff, gbase, voff) do { _Pragma("unroll") for (int _i = 0; _i < 2; ++_i) \
;         __builtin_amdgcn_global_load_lds((const unsigned*)((const char*)(gbase) + (voff)[_i]), (LAS unsigned*)(lds + (bufoff) + ldsw + _i * 8192), 16, 0, 0); } while (0)
; #define PG8_LDA(dst, b, h) do { _Pragma("unroll") for (int m = 0; m < 4; ++m) _Pragma("unroll") for (int k = 0; k < 2; ++k) dst[m][k] = *(const LAS bf16x8*)(lds + PG8_SA(b, h) + aoff + m * 2048 + k * 1024); } while (0)
; #define PG8_WAIT_V(n) asm volatile("s_waitcnt vmcnt(" #n ")" ::: "memory")
; #define PG8_WAIT_L(n) asm volatile("s_waitcnt lgkmcnt(" #n ")" ::: "memory")
; template <class Epi>
; __device__ __forceinline__ void gemm_phase(LAS unsigned char* lds, const Gemm g, const StaticOrder& S, const Epi& E) {
;     ...
;         for (int t = 0; t < nt; t += 2) {
;             const bool last = (t == nt - 2);
;             const char* a1 = cA + (size_t)(t + 1) * kstep;
;             const char* a2 = last ? nA : cA + (size_t)(t + 2) * kstep; const char* b2 = last ? nB : cB + (size_t)(t + 2) * kstep;
;             const char* a3 = a2 + kstep; const char* b3 = b2 + kstep;
;             PG8_LDB(B0, 0, 0); PG8_SCHED; PG8_LDA(At, 0, 0); PG8_STAGE(PG8_SA(1, 1), a1 + hstep, voffA);
;             PG8_WAIT_L(8); PG8_BAR; PG8_WAIT_L(0); PG8_MMA(0, 0, At, B0); PG8_BAR; PG8_SCHED;
;             PG8_LDB(B1, 0, 1); PG8_STAGE(PG8_SB(0, 0), b2, voffB);
;             PG8_BAR; PG8_WAIT_L(0); PG8_MMA(0, 1, At, B1); PG8_BAR;
;             PG8_LDA(At, 0, 1); PG8_STAGE(PG8_SA(0, 0), a2, voffA);
;             PG8_BAR; PG8_WAIT_L(0); PG8_MMA(1, 0, At, B0); PG8_BAR; PG8_SCHED;
;             PG8_STAGE(PG8_SB(0, 1), b2 + hstep, voffB);
;             PG8_WAIT_V(6); PG8_BAR; PG8_MMA(1, 1, At, B1); PG8_BAR;
;             PG8_LDB(B0, 1, 0); PG8_SCHED; PG8_LDA(At, 1, 0); PG8_STAGE(PG8_SA(0, 1), a2 + hstep, voffA);
;             PG8_WAIT_L(8); PG8_BAR; PG8_WAIT_L(0); PG8_MMA(0, 0, At, B0); PG8_BAR; PG8_SCHED;
;             PG8_LDB(B1, 1, 1); PG8_STAGE(PG8_SB(1, 0), b3, voffB);
;             PG8_BAR; PG8_WAIT_L(0); PG8_MMA(0, 1, At, B1); PG8_BAR;
;             PG8_LDA(At, 1, 1); PG8_STAGE(PG8_SA(1, 0), a3, voffA);
;             PG8_BAR; PG8_WAIT_L(0); PG8_MMA(1, 0, At, B0); PG8_BAR; PG8_SCHED;
;             PG8_STAGE(PG8_SB(1, 1), b3 + hstep, voffB);
;             PG8_WAIT_V(6); PG8_BAR; PG8_MMA(1, 1, At, B1); PG8_BAR;
.LBB0_136:
	ds_read_b128 v[144:147], v154
	ds_read_b128 v[158:161], v154 offset:1024
	ds_read_b128 v[162:165], v154 offset:2048
	ds_read_b128 v[166:169], v154 offset:3072
	s_add_u32 s24, s22, 0xfff80080
	s_addc_u32 s25, s23, -1
	s_cmp_eq_u32 s77, 28
	s_cselect_b32 s27, s11, s25
	s_cselect_b32 s26, s73, s24
	s_cselect_b32 s25, s9, s76
	s_cselect_b32 s24, s74, s75
	s_nop 0
	s_add_i32 m0, s17, 0xc000
	ds_read_b128 v[170:173], v155
	ds_read_b128 v[174:177], v155 offset:1024
	ds_read_b128 v[178:181], v155 offset:2048
	ds_read_b128 v[182:185], v155 offset:3072
	ds_read_b128 v[186:189], v155 offset:4096
	ds_read_b128 v[190:193], v155 offset:5120
	ds_read_b128 v[194:197], v155 offset:6144
	ds_read_b128 v[198:201], v155 offset:7168
	global_load_lds_dwordx4 v136, s[22:23]
	s_nop 0
	s_add_i32 m0, s17, 0xe000
	s_nop 0
	global_load_lds_dwordx4 v138, s[22:23]
	s_waitcnt lgkmcnt(8)
	s_barrier
	s_waitcnt lgkmcnt(0)
	s_waitcnt lgkmcnt(0)
	v_mfma_f32_16x16x32_bf16 v[124:127], v[144:147], v[170:173], v[124:127]
	v_mfma_f32_16x16x32_bf16 v[120:123], v[162:165], v[170:173], v[120:123]
	v_mfma_f32_16x16x32_bf16 v[116:119], v[144:147], v[178:181], v[116:119]
	v_mfma_f32_16x16x32_bf16 v[108:111], v[162:165], v[178:181], v[108:111]
	v_mfma_f32_16x16x32_bf16 v[100:103], v[144:147], v[186:189], v[100:103]
	v_mfma_f32_16x16x32_bf16 v[92:95], v[162:165], v[186:189], v[92:95]
	v_mfma_f32_16x16x32_bf16 v[84:87], v[144:147], v[194:197], v[84:87]
	v_mfma_f32_16x16x32_bf16 v[76:79], v[162:165], v[194:197], v[76:79]
	v_mfma_f32_16x16x32_bf16 v[124:127], v[158:161], v[174:177], v[124:127]
	v_mfma_f32_16x16x32_bf16 v[120:123], v[166:169], v[174:177], v[120:123]
	v_mfma_f32_16x16x32_bf16 v[116:119], v[158:161], v[182:185], v[116:119]
	v_mfma_f32_16x16x32_bf16 v[108:111], v[166:169], v[182:185], v[108:111]
	v_mfma_f32_16x16x32_bf16 v[100:103], v[158:161], v[190:193], v[100:103]
	v_mfma_f32_16x16x32_bf16 v[92:95], v[166:169], v[190:193], v[92:95]
	v_mfma_f32_16x16x32_bf16 v[84:87], v[158:161], v[198:201], v[84:87]
	v_mfma_f32_16x16x32_bf16 v[76:79], v[166:169], v[198:201], v[76:79]
	s_barrier
	s_add_i32 s78, s69, s29
	v_lshl_add_u64 v[220:221], s[24:25], 0, v[130:131]
	s_mov_b32 m0, s78
	ds_read_b128 v[202:205], v156
	ds_read_b128 v[206:209], v156 offset:1024
	ds_read_b128 v[210:213], v156 offset:2048
	ds_read_b128 v[216:219], v156 offset:3072
	global_load_lds_dwordx4 v[220:221], off
	v_lshl_add_u64 v[222:223], s[24:25], 0, v[134:135]
	s_add_i32 m0, s78, 0x2000
	s_nop 0
	global_load_lds_dwordx4 v[222:223], off
	s_barrier
	s_waitcnt lgkmcnt(0)
	s_waitcnt lgkmcnt(0)
	v_mfma_f32_16x16x32_bf16 v[112:115], v[202:205], v[170:173], v[112:115]
	v_mfma_f32_16x16x32_bf16 v[104:107], v[210:213], v[170:173], v[104:107]
	v_mfma_f32_16x16x32_bf16 v[96:99], v[202:205], v[178:181], v[96:99]
	v_mfma_f32_16x16x32_bf16 v[88:91], v[210:213], v[178:181], v[88:91]
	v_mfma_f32_16x16x32_bf16 v[80:83], v[202:205], v[186:189], v[80:83]
	v_mfma_f32_16x16x32_bf16 v[72:75], v[210:213], v[186:189], v[72:75]
	v_mfma_f32_16x16x32_bf16 v[68:71], v[202:205], v[194:197], v[68:71]
	v_mfma_f32_16x16x32_bf16 v[64:67], v[210:213], v[194:197], v[64:67]
	v_mfma_f32_16x16x32_bf16 v[112:115], v[206:209], v[174:177], v[112:115]
	v_mfma_f32_16x16x32_bf16 v[104:107], v[216:219], v[174:177], v[104:107]
	v_mfma_f32_16x16x32_bf16 v[96:99], v[206:209], v[182:185], v[96:99]
	v_mfma_f32_16x16x32_bf16 v[88:91], v[216:219], v[182:185], v[88:91]
	v_mfma_f32_16x16x32_bf16 v[80:83], v[206:209], v[190:193], v[80:83]
	v_mfma_f32_16x16x32_bf16 v[72:75], v[216:219], v[190:193], v[72:75]
	v_mfma_f32_16x16x32_bf16 v[68:71], v[206:209], v[198:201], v[68:71]
	v_mfma_f32_16x16x32_bf16 v[64:67], v[216:219], v[198:201], v[64:67]
	s_mov_b32 m0, s17
	v_lshl_add_u64 v[224:225], s[26:27], 0, v[128:129]
	s_barrier
	ds_read_b128 v[170:173], v155 offset:16384
	ds_read_b128 v[174:177], v155 offset:17408
	ds_read_b128 v[178:181], v155 offset:18432
	ds_read_b128 v[182:185], v155 offset:19456
	ds_read_b128 v[186:189], v155 offset:20480
	ds_read_b128 v[190:193], v155 offset:21504
	ds_read_b128 v[194:197], v155 offset:22528
	ds_read_b128 v[198:201], v155 offset:23552
	global_load_lds_dwordx4 v[224:225], off
	v_lshl_add_u64 v[226:227], s[26:27], 0, v[132:133]
	s_mov_b32 m0, s30
	s_nop 0
	global_load_lds_dwordx4 v[226:227], off
	s_barrier
	s_waitcnt lgkmcnt(0)
	s_waitcnt lgkmcnt(0)
	v_mfma_f32_16x16x32_bf16 v[60:63], v[144:147], v[170:173], v[60:63]
	v_mfma_f32_16x16x32_bf16 v[56:59], v[162:165], v[170:173], v[56:59]
	v_mfma_f32_16x16x32_bf16 v[52:55], v[144:147], v[178:181], v[52:55]
	v_mfma_f32_16x16x32_bf16 v[44:47], v[162:165], v[178:181], v[44:47]
	v_mfma_f32_16x16x32_bf16 v[36:39], v[144:147], v[186:189], v[36:39]
	v_mfma_f32_16x16x32_bf16 v[28:31], v[162:165], v[186:189], v[28:31]
	v_mfma_f32_16x16x32_bf16 v[20:23], v[144:147], v[194:197], v[20:23]
	v_mfma_f32_16x16x32_bf16 v[12:15], v[162:165], v[194:197], v[12:15]
	v_mfma_f32_16x16x32_bf16 v[60:63], v[158:161], v[174:177], v[60:63]
	v_mfma_f32_16x16x32_bf16 v[56:59], v[166:169], v[174:177], v[56:59]
	v_mfma_f32_16x16x32_bf16 v[52:55], v[158:161], v[182:185], v[52:55]
	v_mfma_f32_16x16x32_bf16 v[44:47], v[166:169], v[182:185], v[44:47]
	v_mfma_f32_16x16x32_bf16 v[36:39], v[158:161], v[190:193], v[36:39]
	v_mfma_f32_16x16x32_bf16 v[28:31], v[166:169], v[190:193], v[28:31]
	v_mfma_f32_16x16x32_bf16 v[20:23], v[158:161], v[198:201], v[20:23]
	v_mfma_f32_16x16x32_bf16 v[12:15], v[166:169], v[198:201], v[12:15]
	s_barrier
	s_add_u32 s78, s24, 0x80000
	s_addc_u32 s79, s25, 0
	s_add_i32 s80, s70, s29
	s_nop 0
	s_mov_b32 m0, s80
	s_nop 0
	global_load_lds_dwordx4 v130, s[78:79]
	s_nop 0
	s_add_i32 m0, s80, 0x2000
	s_nop 0
	global_load_lds_dwordx4 v134, s[78:79]
	s_waitcnt vmcnt(6)
	s_barrier
; #define PG8_STAGE(bufoff, gbase, voff) do { _Pragma("unroll") for (int _i = 0; _i < 2; ++_i) \
;         __builtin_amdgcn_global_load_lds((const unsigned*)((const char*)(gbase) + (voff)[_i]), (LAS unsigned*)(lds + (bufoff) + ldsw + _i * 8192), 16, 0, 0); } while (0)
; #define PG8_LDA(dst, b, h) do { _Pragma("unroll") for (int m = 0; m < 4; ++m) _Pragma("unroll") for (int k = 0; k < 2; ++k) dst[m][k] = *(const LAS bf16x8*)(lds + PG8_SA(b, h) + aoff + m * 2048 + k * 1024); } while (0)
; #define PG8_WAIT_V(n) asm volatile("s_waitcnt vmcnt(" #n ")" ::: "memory")
; #define PG8_WAIT_L(n) asm volatile("s_waitcnt lgkmcnt(" #n ")" ::: "memory")
; template <class Epi>
; __device__ __forceinline__ void gemm_phase(LAS unsigned char* lds, const Gemm g, const StaticOrder& S, const Epi& E) {
;     ...
;         for (int t = 0; t < nt; t += 2) {
;             const bool last = (t == nt - 2);
;             const char* a1 = cA + (size_t)(t + 1) * kstep;
;             const char* a2 = last ? nA : cA + (size_t)(t + 2) * kstep; const char* b2 = last ? nB : cB + (size_t)(t + 2) * kstep;
;             const char* a3 = a2 + kstep; const char* b3 = b2 + kstep;
;             PG8_LDB(B0, 0, 0); PG8_SCHED; PG8_LDA(At, 0, 0); PG8_STAGE(PG8_SA(1, 1), a1 + hstep, voffA);
;             PG8_WAIT_L(8); PG8_BAR; PG8_WAIT_L(0); PG8_MMA(0, 0, At, B0); PG8_BAR; PG8_SCHED;
;             PG8_LDB(B1, 0, 1); PG8_STAGE(PG8_SB(0, 0), b2, voffB);
;             PG8_BAR; PG8_WAIT_L(0); PG8_MMA(0, 1, At, B1); PG8_BAR;
;             PG8_LDA(At, 0, 1); PG8_STAGE(PG8_SA(0, 0), a2, voffA);
;             PG8_BAR; PG8_WAIT_L(0); PG8_MMA(1, 0, At, B0); PG8_BAR; PG8_SCHED;
;             PG8_STAGE(PG8_SB(0, 1), b2 + hstep, voffB);
;             PG8_WAIT_V(6); PG8_BAR; PG8_MMA(1, 1, At, B1); PG8_BAR;
;             PG8_LDB(B0, 1, 0); PG8_SCHED; PG8_LDA(At, 1, 0); PG8_STAGE(PG8_SA(0, 1), a2 + hstep, voffA);
;             PG8_WAIT_L(8); PG8_BAR; PG8_WAIT_L(0); PG8_MMA(0, 0, At, B0); PG8_BAR; PG8_SCHED;
;             PG8_LDB(B1, 1, 1); PG8_STAGE(PG8_SB(1, 0), b3, voffB);
;             PG8_BAR; PG8_WAIT_L(0); PG8_MMA(0, 1, At, B1); PG8_BAR;
;             PG8_LDA(At, 1, 1); PG8_STAGE(PG8_SA(1, 0), a3, voffA);
;             PG8_BAR; PG8_WAIT_L(0); PG8_MMA(1, 0, At, B0); PG8_BAR; PG8_SCHED;
;             PG8_STAGE(PG8_SB(1, 1), b3 + hstep, voffB);
;             PG8_WAIT_V(6); PG8_BAR; PG8_MMA(1, 1, At, B1); PG8_BAR;
	v_mfma_f32_16x16x32_bf16 v[48:51], v[202:205], v[170:173], v[48:51]
	v_mfma_f32_16x16x32_bf16 v[40:43], v[210:213], v[170:173], v[40:43]
	v_mfma_f32_16x16x32_bf16 v[32:35], v[202:205], v[178:181], v[32:35]
	v_mfma_f32_16x16x32_bf16 v[24:27], v[210:213], v[178:181], v[24:27]
	v_mfma_f32_16x16x32_bf16 v[16:19], v[202:205], v[186:189], v[16:19]
	v_mfma_f32_16x16x32_bf16 v[8:11], v[210:213], v[186:189], v[8:11]
	v_mfma_f32_16x16x32_bf16 v[4:7], v[202:205], v[194:197], v[4:7]
	v_mfma_f32_16x16x32_bf16 v[0:3], v[210:213], v[194:197], v[0:3]
	v_mfma_f32_16x16x32_bf16 v[48:51], v[206:209], v[174:177], v[48:51]
	v_mfma_f32_16x16x32_bf16 v[40:43], v[216:219], v[174:177], v[40:43]
	v_mfma_f32_16x16x32_bf16 v[32:35], v[206:209], v[182:185], v[32:35]
	v_mfma_f32_16x16x32_bf16 v[24:27], v[216:219], v[182:185], v[24:27]
	v_mfma_f32_16x16x32_bf16 v[16:19], v[206:209], v[190:193], v[16:19]
	v_mfma_f32_16x16x32_bf16 v[8:11], v[216:219], v[190:193], v[8:11]
	v_mfma_f32_16x16x32_bf16 v[4:7], v[206:209], v[198:201], v[4:7]
	v_mfma_f32_16x16x32_bf16 v[0:3], v[216:219], v[198:201], v[0:3]
	s_add_i32 s78, 0, 0x18000
	v_add_u32_e32 v157, s78, v152
	s_barrier
	ds_read_b128 v[144:147], v157
	ds_read_b128 v[158:161], v157 offset:1024
	ds_read_b128 v[162:165], v157 offset:2048
	ds_read_b128 v[166:169], v157 offset:3072
	s_add_u32 s26, s26, 0x80000
	s_addc_u32 s27, s27, 0
	s_mov_b32 m0, s31
	s_nop 0
	ds_read_b128 v[170:173], v155 offset:32768
	ds_read_b128 v[174:177], v155 offset:33792
	ds_read_b128 v[178:181], v155 offset:34816
	ds_read_b128 v[182:185], v155 offset:35840
	ds_read_b128 v[186:189], v155 offset:36864
	ds_read_b128 v[190:193], v155 offset:37888
	ds_read_b128 v[194:197], v155 offset:38912
	ds_read_b128 v[198:201], v155 offset:39936
	global_load_lds_dwordx4 v128, s[26:27]
	s_nop 0
	s_mov_b32 m0, s33
	s_nop 0
	global_load_lds_dwordx4 v132, s[26:27]
	s_waitcnt lgkmcnt(8)
	s_barrier
	s_waitcnt lgkmcnt(0)
	s_waitcnt lgkmcnt(0)
	v_mfma_f32_16x16x32_bf16 v[124:127], v[144:147], v[170:173], v[124:127]
	v_mfma_f32_16x16x32_bf16 v[120:123], v[162:165], v[170:173], v[120:123]
	v_mfma_f32_16x16x32_bf16 v[116:119], v[144:147], v[178:181], v[116:119]
	v_mfma_f32_16x16x32_bf16 v[108:111], v[162:165], v[178:181], v[108:111]
	v_mfma_f32_16x16x32_bf16 v[100:103], v[144:147], v[186:189], v[100:103]
	v_mfma_f32_16x16x32_bf16 v[92:95], v[162:165], v[186:189], v[92:95]
	v_mfma_f32_16x16x32_bf16 v[84:87], v[144:147], v[194:197], v[84:87]
	v_mfma_f32_16x16x32_bf16 v[76:79], v[162:165], v[194:197], v[76:79]
	v_mfma_f32_16x16x32_bf16 v[124:127], v[158:161], v[174:177], v[124:127]
	v_mfma_f32_16x16x32_bf16 v[120:123], v[166:169], v[174:177], v[120:123]
	v_mfma_f32_16x16x32_bf16 v[116:119], v[158:161], v[182:185], v[116:119]
	v_mfma_f32_16x16x32_bf16 v[108:111], v[166:169], v[182:185], v[108:111]
	v_mfma_f32_16x16x32_bf16 v[100:103], v[158:161], v[190:193], v[100:103]
	v_mfma_f32_16x16x32_bf16 v[92:95], v[166:169], v[190:193], v[92:95]
	v_mfma_f32_16x16x32_bf16 v[84:87], v[158:161], v[198:201], v[84:87]
	v_mfma_f32_16x16x32_bf16 v[76:79], v[166:169], v[198:201], v[76:79]
	s_barrier
	s_add_i32 s26, 0, 0x1c000
	s_add_i32 s27, s78, s29
	v_add_u32_e32 v157, s26, v152
	v_lshl_add_u64 v[220:221], v[220:221], 0, s[4:5]
	s_mov_b32 m0, s27
	ds_read_b128 v[202:205], v157
	ds_read_b128 v[206:209], v157 offset:1024
	ds_read_b128 v[210:213], v157 offset:2048
	ds_read_b128 v[216:219], v157 offset:3072
	global_load_lds_dwordx4 v[220:221], off
	v_lshl_add_u64 v[220:221], v[222:223], 0, s[4:5]
	s_add_i32 m0, s27, 0x2000
	s_nop 0
	global_load_lds_dwordx4 v[220:221], off
	s_barrier
	s_waitcnt lgkmcnt(0)
	s_waitcnt lgkmcnt(0)
	v_mfma_f32_16x16x32_bf16 v[112:115], v[202:205], v[170:173], v[112:115]
	v_mfma_f32_16x16x32_bf16 v[104:107], v[210:213], v[170:173], v[104:107]
	v_mfma_f32_16x16x32_bf16 v[96:99], v[202:205], v[178:181], v[96:99]
	v_mfma_f32_16x16x32_bf16 v[88:91], v[210:213], v[178:181], v[88:91]
	v_mfma_f32_16x16x32_bf16 v[80:83], v[202:205], v[186:189], v[80:83]
	v_mfma_f32_16x16x32_bf16 v[72:75], v[210:213], v[186:189], v[72:75]
	v_mfma_f32_16x16x32_bf16 v[68:71], v[202:205], v[194:197], v[68:71]
	v_mfma_f32_16x16x32_bf16 v[64:67], v[210:213], v[194:197], v[64:67]
	v_mfma_f32_16x16x32_bf16 v[112:115], v[206:209], v[174:177], v[112:115]
	v_mfma_f32_16x16x32_bf16 v[104:107], v[216:219], v[174:177], v[104:107]
	v_mfma_f32_16x16x32_bf16 v[96:99], v[206:209], v[182:185], v[96:99]
	v_mfma_f32_16x16x32_bf16 v[88:91], v[216:219], v[182:185], v[88:91]
	v_mfma_f32_16x16x32_bf16 v[80:83], v[206:209], v[190:193], v[80:83]
	v_mfma_f32_16x16x32_bf16 v[72:75], v[216:219], v[190:193], v[72:75]
	v_mfma_f32_16x16x32_bf16 v[68:71], v[206:209], v[198:201], v[68:71]
	v_mfma_f32_16x16x32_bf16 v[64:67], v[216:219], v[198:201], v[64:67]
	s_mov_b32 m0, s51
	v_lshl_add_u64 v[220:221], v[224:225], 0, s[4:5]
	s_barrier
	ds_read_b128 v[170:173], v155 offset:49152
	ds_read_b128 v[174:177], v155 offset:50176
	ds_read_b128 v[178:181], v155 offset:51200
	ds_read_b128 v[182:185], v155 offset:52224
	ds_read_b128 v[186:189], v155 offset:53248
	ds_read_b128 v[190:193], v155 offset:54272
	ds_read_b128 v[194:197], v155 offset:55296
	ds_read_b128 v[198:201], v155 offset:56320
	global_load_lds_dwordx4 v[220:221], off
	v_lshl_add_u64 v[220:221], v[226:227], 0, s[4:5]
	s_mov_b32 m0, s54
	s_nop 0
	global_load_lds_dwordx4 v[220:221], off
	s_barrier
; #define PG8_STAGE(bufoff, gbase, voff) do { _Pragma("unroll") for (int _i = 0; _i < 2; ++_i) \
;         __builtin_amdgcn_global_load_lds((const unsigned*)((const char*)(gbase) + (voff)[_i]), (LAS unsigned*)(lds + (bufoff) + ldsw + _i * 8192), 16, 0, 0); } while (0)
; #define PG8_LDA(dst, b, h) do { _Pragma("unroll") for (int m = 0; m < 4; ++m) _Pragma("unroll") for (int k = 0; k < 2; ++k) dst[m][k] = *(const LAS bf16x8*)(lds + PG8_SA(b, h) + aoff + m * 2048 + k * 1024); } while (0)
; #define PG8_WAIT_V(n) asm volatile("s_waitcnt vmcnt(" #n ")" ::: "memory")
; #define PG8_WAIT_L(n) asm volatile("s_waitcnt lgkmcnt(" #n ")" ::: "memory")
; template <class Epi>
; __device__ __forceinline__ void gemm_phase(LAS unsigned char* lds, const Gemm g, const StaticOrder& S, const Epi& E) {
;     ...
;         for (int t = 0; t < nt; t += 2) {
;             const bool last = (t == nt - 2);
;             const char* a1 = cA + (size_t)(t + 1) * kstep;
;             const char* a2 = last ? nA : cA + (size_t)(t + 2) * kstep; const char* b2 = last ? nB : cB + (size_t)(t + 2) * kstep;
;             const char* a3 = a2 + kstep; const char* b3 = b2 + kstep;
;             PG8_LDB(B0, 0, 0); PG8_SCHED; PG8_LDA(At, 0, 0); PG8_STAGE(PG8_SA(1, 1), a1 + hstep, voffA);
;             PG8_WAIT_L(8); PG8_BAR; PG8_WAIT_L(0); PG8_MMA(0, 0, At, B0); PG8_BAR; PG8_SCHED;
;             PG8_LDB(B1, 0, 1); PG8_STAGE(PG8_SB(0, 0), b2, voffB);
;             PG8_BAR; PG8_WAIT_L(0); PG8_MMA(0, 1, At, B1); PG8_BAR;
;             PG8_LDA(At, 0, 1); PG8_STAGE(PG8_SA(0, 0), a2, voffA);
;             PG8_BAR; PG8_WAIT_L(0); PG8_MMA(1, 0, At, B0); PG8_BAR; PG8_SCHED;
;             PG8_STAGE(PG8_SB(0, 1), b2 + hstep, voffB);
;             PG8_WAIT_V(6); PG8_BAR; PG8_MMA(1, 1, At, B1); PG8_BAR;
;             PG8_LDB(B0, 1, 0); PG8_SCHED; PG8_LDA(At, 1, 0); PG8_STAGE(PG8_SA(0, 1), a2 + hstep, voffA);
;             PG8_WAIT_L(8); PG8_BAR; PG8_WAIT_L(0); PG8_MMA(0, 0, At, B0); PG8_BAR; PG8_SCHED;
;             PG8_LDB(B1, 1, 1); PG8_STAGE(PG8_SB(1, 0), b3, voffB);
;             PG8_BAR; PG8_WAIT_L(0); PG8_MMA(0, 1, At, B1); PG8_BAR;
;             PG8_LDA(At, 1, 1); PG8_STAGE(PG8_SA(1, 0), a3, voffA);
;             PG8_BAR; PG8_WAIT_L(0); PG8_MMA(1, 0, At, B0); PG8_BAR; PG8_SCHED;
;             PG8_STAGE(PG8_SB(1, 1), b3 + hstep, voffB);
;             PG8_WAIT_V(6); PG8_BAR; PG8_MMA(1, 1, At, B1); PG8_BAR;
	s_waitcnt lgkmcnt(0)
	s_waitcnt lgkmcnt(0)
	v_mfma_f32_16x16x32_bf16 v[60:63], v[144:147], v[170:173], v[60:63]
	v_mfma_f32_16x16x32_bf16 v[56:59], v[162:165], v[170:173], v[56:59]
	v_mfma_f32_16x16x32_bf16 v[52:55], v[144:147], v[178:181], v[52:55]
	v_mfma_f32_16x16x32_bf16 v[44:47], v[162:165], v[178:181], v[44:47]
	v_mfma_f32_16x16x32_bf16 v[36:39], v[144:147], v[186:189], v[36:39]
	v_mfma_f32_16x16x32_bf16 v[28:31], v[162:165], v[186:189], v[28:31]
	v_mfma_f32_16x16x32_bf16 v[20:23], v[144:147], v[194:197], v[20:23]
	v_mfma_f32_16x16x32_bf16 v[12:15], v[162:165], v[194:197], v[12:15]
	v_mfma_f32_16x16x32_bf16 v[60:63], v[158:161], v[174:177], v[60:63]
	v_mfma_f32_16x16x32_bf16 v[56:59], v[166:169], v[174:177], v[56:59]
	v_mfma_f32_16x16x32_bf16 v[52:55], v[158:161], v[182:185], v[52:55]
	v_mfma_f32_16x16x32_bf16 v[44:47], v[166:169], v[182:185], v[44:47]
	v_mfma_f32_16x16x32_bf16 v[36:39], v[158:161], v[190:193], v[36:39]
	v_mfma_f32_16x16x32_bf16 v[28:31], v[166:169], v[190:193], v[28:31]
	v_mfma_f32_16x16x32_bf16 v[20:23], v[158:161], v[198:201], v[20:23]
	v_mfma_f32_16x16x32_bf16 v[12:15], v[166:169], v[198:201], v[12:15]
	s_barrier
	s_add_u32 s24, s24, 0x80080
	s_addc_u32 s25, s25, 0
	s_add_i32 s26, s26, s29
	s_nop 0
	s_mov_b32 m0, s26
	s_nop 0
	global_load_lds_dwordx4 v130, s[24:25]
	v_lshl_add_u64 v[144:145], s[24:25], 0, v[134:135]
	s_add_i32 m0, s26, 0x2000
	s_nop 0
	global_load_lds_dwordx4 v[144:145], off
	s_waitcnt vmcnt(6)
	s_barrier
	v_mfma_f32_16x16x32_bf16 v[48:51], v[202:205], v[170:173], v[48:51]
	v_mfma_f32_16x16x32_bf16 v[40:43], v[210:213], v[170:173], v[40:43]
	v_mfma_f32_16x16x32_bf16 v[32:35], v[202:205], v[178:181], v[32:35]
	v_mfma_f32_16x16x32_bf16 v[24:27], v[210:213], v[178:181], v[24:27]
	v_mfma_f32_16x16x32_bf16 v[16:19], v[202:205], v[186:189], v[16:19]
	v_mfma_f32_16x16x32_bf16 v[8:11], v[210:213], v[186:189], v[8:11]
	v_mfma_f32_16x16x32_bf16 v[4:7], v[202:205], v[194:197], v[4:7]
	v_mfma_f32_16x16x32_bf16 v[0:3], v[210:213], v[194:197], v[0:3]
	v_mfma_f32_16x16x32_bf16 v[48:51], v[206:209], v[174:177], v[48:51]
	v_mfma_f32_16x16x32_bf16 v[40:43], v[216:219], v[174:177], v[40:43]
	v_mfma_f32_16x16x32_bf16 v[32:35], v[206:209], v[182:185], v[32:35]
	v_mfma_f32_16x16x32_bf16 v[24:27], v[216:219], v[182:185], v[24:27]
	v_mfma_f32_16x16x32_bf16 v[16:19], v[206:209], v[190:193], v[16:19]
	v_mfma_f32_16x16x32_bf16 v[8:11], v[216:219], v[190:193], v[8:11]
	v_mfma_f32_16x16x32_bf16 v[4:7], v[206:209], v[198:201], v[4:7]
	v_mfma_f32_16x16x32_bf16 v[0:3], v[216:219], v[198:201], v[0:3]
	s_add_i32 s77, s77, 2
	s_add_u32 s22, s22, 0x100
	s_addc_u32 s23, s23, 0
	s_add_u32 s75, s75, 0x100
	s_addc_u32 s76, s76, 0
	s_cmp_gt_u32 s77, 29
	s_barrier
	s_cbranch_scc0 .LBB0_136
; #define PG8_WAIT_V(n) asm volatile("s_waitcnt vmcnt(" #n ")" ::: "memory")
; #define PG8_BAR __builtin_amdgcn_s_barrier()
; __device__ __forceinline__ u32x4 pack8(const f32x4 v0, const f32x4 v1) { u32x4 w; w.x = cvt_pk_bf16(v0[0], v0[1]); w.y = cvt_pk_bf16(v0[2], v0[3]); w.z = cvt_pk_bf16(v1[0], v1[1]); w.w = cvt_pk_bf16(v1[2], v1[3]); return w; }
; template <class Epi>
; __device__ __forceinline__ void gemm_phase(LAS unsigned char* lds, const Gemm g, const StaticOrder& S, const Epi& E) {
;     ...
;         E(acc, cur, wr, wc, fr, fq);
;         if (!has_next) break;
; #pragma unroll
;         for (int a = 0; a < 2; ++a)
; #pragma unroll
;             for (int b = 0; b < 2; ++b)
; #pragma unroll
;                 for (int m = 0; m < 4; ++m)
; #pragma unroll
;                     for (int n = 0; n < 2; ++n) acc[a][b][m][n] = (f32x4){0.f, 0.f, 0.f, 0.f};
;         cur = nxt; cA = nA; cB = nB; ++ui;
;     }
;     PG8_WAIT_V(0);
;     if (wr == 0) PG8_BAR;
;     PG8_BAR;
;     __device__ __forceinline__ void operator()(const AccT& acc, const pg8::Unit& u, int wr, int wc, int fr, int fq) const {
;         const int row0 = u.pm * 256 + wr * 64 + fr, col0 = u.pn * 256 + wc * 32 + 8 * fq;
; #pragma unroll
;         for (int ai = 0; ai < 2; ++ai)
; #pragma unroll
;             for (int m = 0; m < 4; ++m) { bf16_t* rowp = O + (size_t)(row0 + ai * 128 + m * 16) * NPROJ + col0;
; #pragma unroll
;                 for (int bj = 0; bj < 2; ++bj) *(u32x4*)(rowp + bj * 128) = pack8(acc[ai][bj][m][0], acc[ai][bj][m][1]); }
;     }
	v_lshl_or_b32 v146, s72, 8, v153
	v_lshl_add_u32 v157, s16, 8, v151
	v_ashrrev_i32_e32 v147, 31, v146
	v_mov_b64_e32 v[144:145], s[0:1]
	v_mad_i64_i32 v[158:159], s[22:23], v157, s71, v[144:145]
	v_lshlrev_b64 v[146:147], 1, v[146:147]
	v_lshl_add_u64 v[158:159], v[158:159], 0, v[146:147]
	v_cvt_pk_bf16_f32 v124, v124, v125
	v_cvt_pk_bf16_f32 v125, v126, v127
	v_cvt_pk_bf16_f32 v126, v120, v121
	v_cvt_pk_bf16_f32 v127, v122, v123
	global_store_dwordx4 v[158:159], v[124:127], off
	v_cvt_pk_bf16_f32 v112, v112, v113
	v_cvt_pk_bf16_f32 v113, v114, v115
	v_cvt_pk_bf16_f32 v114, v104, v105
	v_or_b32_e32 v104, 16, v157
	v_mad_i64_i32 v[104:105], s[22:23], v104, s71, v[144:145]
	v_cvt_pk_bf16_f32 v115, v106, v107
	global_store_dwordx4 v[158:159], v[112:115], off offset:256
	s_and_b64 vcc, exec, s[2:3]
	s_mov_b32 s72, s8
	v_lshl_add_u64 v[112:113], v[104:105], 0, v[146:147]
	v_cvt_pk_bf16_f32 v104, v116, v117
	v_cvt_pk_bf16_f32 v105, v118, v119
	v_cvt_pk_bf16_f32 v106, v108, v109
	v_cvt_pk_bf16_f32 v107, v110, v111
	global_store_dwordx4 v[112:113], v[104:107], off
	v_cvt_pk_bf16_f32 v96, v96, v97
	v_cvt_pk_bf16_f32 v97, v98, v99
	v_cvt_pk_bf16_f32 v98, v88, v89
	v_or_b32_e32 v88, 32, v157
	v_mad_i64_i32 v[88:89], s[22:23], v88, s71, v[144:145]
	v_cvt_pk_bf16_f32 v99, v90, v91
	global_store_dwordx4 v[112:113], v[96:99], off offset:256
	s_mov_b32 s16, s10
	s_mov_b64 s[24:25], s[20:21]
	v_lshl_add_u64 v[96:97], v[88:89], 0, v[146:147]
	v_cvt_pk_bf16_f32 v88, v100, v101
	v_cvt_pk_bf16_f32 v89, v102, v103
	v_cvt_pk_bf16_f32 v90, v92, v93
	v_cvt_pk_bf16_f32 v91, v94, v95
	global_store_dwordx4 v[96:97], v[88:91], off
	v_cvt_pk_bf16_f32 v80, v80, v81
	v_cvt_pk_bf16_f32 v81, v82, v83
	v_cvt_pk_bf16_f32 v82, v72, v73
	v_or_b32_e32 v72, 48, v157
	v_mad_i64_i32 v[72:73], s[22:23], v72, s71, v[144:145]
	v_cvt_pk_bf16_f32 v83, v74, v75
	global_store_dwordx4 v[96:97], v[80:83], off offset:256
	s_nop 1
	v_lshl_add_u64 v[80:81], v[72:73], 0, v[146:147]
	v_cvt_pk_bf16_f32 v72, v84, v85
	v_cvt_pk_bf16_f32 v73, v86, v87
	v_cvt_pk_bf16_f32 v74, v76, v77
	v_cvt_pk_bf16_f32 v75, v78, v79
	global_store_dwordx4 v[80:81], v[72:75], off
	v_cvt_pk_bf16_f32 v68, v68, v69
	v_cvt_pk_bf16_f32 v69, v70, v71
	v_cvt_pk_bf16_f32 v70, v64, v65
	v_add_u32_e32 v64, 0x80, v157
	v_mad_i64_i32 v[64:65], s[22:23], v64, s71, v[144:145]
	v_lshl_add_u64 v[64:65], v[64:65], 0, v[146:147]
	v_cvt_pk_bf16_f32 v71, v66, v67
	global_store_dwordx4 v[80:81], v[68:71], off offset:256
	v_cvt_pk_bf16_f32 v60, v60, v61
	v_cvt_pk_bf16_f32 v61, v62, v63
	v_cvt_pk_bf16_f32 v62, v56, v57
	v_cvt_pk_bf16_f32 v63, v58, v59
	global_store_dwordx4 v[64:65], v[60:63], off
	v_cvt_pk_bf16_f32 v48, v48, v49
	v_cvt_pk_bf16_f32 v49, v50, v51
	v_cvt_pk_bf16_f32 v50, v40, v41
	v_add_u32_e32 v40, 0x90, v157
	v_mad_i64_i32 v[40:41], s[22:23], v40, s71, v[144:145]
	v_cvt_pk_bf16_f32 v51, v42, v43
	global_store_dwordx4 v[64:65], v[48:51], off offset:256
	s_nop 1
	v_lshl_add_u64 v[48:49], v[40:41], 0, v[146:147]
	v_cvt_pk_bf16_f32 v40, v52, v53
	v_cvt_pk_bf16_f32 v41, v54, v55
	v_cvt_pk_bf16_f32 v42, v44, v45
	v_cvt_pk_bf16_f32 v43, v46, v47
	global_store_dwordx4 v[48:49], v[40:43], off
	v_cvt_pk_bf16_f32 v32, v32, v33
	v_cvt_pk_bf16_f32 v33, v34, v35
	v_cvt_pk_bf16_f32 v34, v24, v25
	v_add_u32_e32 v24, 0xa0, v157
	v_mad_i64_i32 v[24:25], s[22:23], v24, s71, v[144:145]
	v_cvt_pk_bf16_f32 v35, v26, v27
	global_store_dwordx4 v[48:49], v[32:35], off offset:256
	s_nop 1
	v_lshl_add_u64 v[32:33], v[24:25], 0, v[146:147]
	v_cvt_pk_bf16_f32 v24, v36, v37
	v_cvt_pk_bf16_f32 v25, v38, v39
	v_cvt_pk_bf16_f32 v26, v28, v29
	v_cvt_pk_bf16_f32 v27, v30, v31
	global_store_dwordx4 v[32:33], v[24:27], off
	v_cvt_pk_bf16_f32 v16, v16, v17
	v_cvt_pk_bf16_f32 v17, v18, v19
	v_cvt_pk_bf16_f32 v18, v8, v9
	v_add_u32_e32 v8, 0xb0, v157
	v_mad_i64_i32 v[8:9], s[22:23], v8, s71, v[144:145]
	v_cvt_pk_bf16_f32 v19, v10, v11
	global_store_dwordx4 v[32:33], v[16:19], off offset:256
	s_mov_b64 s[22:23], s[18:19]
	s_nop 0
	v_lshl_add_u64 v[16:17], v[8:9], 0, v[146:147]
	v_cvt_pk_bf16_f32 v8, v20, v21
	v_cvt_pk_bf16_f32 v9, v22, v23
	v_cvt_pk_bf16_f32 v10, v12, v13
	v_cvt_pk_bf16_f32 v11, v14, v15
	global_store_dwordx4 v[16:17], v[8:11], off
	v_cvt_pk_bf16_f32 v4, v4, v5
	v_cvt_pk_bf16_f32 v5, v6, v7
	v_cvt_pk_bf16_f32 v6, v0, v1
	v_cvt_pk_bf16_f32 v7, v2, v3
	global_store_dwordx4 v[16:17], v[4:7], off offset:256
	s_cbranch_vccz .LBB0_129
	s_waitcnt vmcnt(0)
	s_cmpk_gt_u32 s28, 0xff
	s_cbranch_scc1 .LBB0_140
	s_barrier

; #define PG8_STAGE(bufoff, gbase, voff) do { _Pragma("unroll") for (int _i = 0; _i < 2; ++_i) \
;         __builtin_amdgcn_global_load_lds((const unsigned*)((const char*)(gbase) + (voff)[_i]), (LAS unsigned*)(lds + (bufoff) + ldsw + _i * 8192), 16, 0, 0); } while (0)
; #define PG8_WAIT_V(n) asm volatile("s_waitcnt vmcnt(" #n ")" ::: "memory")
; #define PG8_BAR __builtin_amdgcn_s_barrier()
; template <class Epi>
; __device__ __forceinline__ void gemm_phase(LAS unsigned char* lds, const Gemm g, const StaticOrder& S, const Epi& E) {
;     const int tid = threadIdx.x, wid = __builtin_amdgcn_readfirstlane(tid >> 6), lane = tid & 63, wr = wid >> 2, wc = wid & 3, fr = lane & 15, fq = lane >> 4;
;     const int K = g.K, nt = K / BK;
;     unsigned voffA[2], voffB[2];
; #pragma unroll
;     for (int i = 0; i < 2; ++i) { int R, C; stage_rc(tid * 16 + i * 8192, R, C); const int Rb = Epi::PERM ? ((R & ~31) + perm32(R & 31)) : R;
;         voffA[i] = (unsigned)(R * K + C) * 2u; voffB[i] = (unsigned)(Rb * K + C) * 2u; }
;     const size_t kstep = (size_t)(BK * 2);
;     const size_t hstep = (size_t)HALF * K * 2;
;     const size_t tstep = 2 * hstep;
;     const unsigned ldsw = (unsigned)wid * 1024u;
;     const int aoff = lds_byte(wr * 64 + fr, fq * 8), boff = lds_byte(wc * 32 + fr, fq * 8);
;     ...
;     Unit cur, nxt; int ui = 0;
;     if (!S.next(0, cur)) return;
;     f32x4 acc[2][2][4][2];
; #pragma unroll
;     for (int a = 0; a < 2; ++a)
; #pragma unroll
;         for (int b = 0; b < 2; ++b)
; #pragma unroll
;             for (int m = 0; m < 4; ++m)
; #pragma unroll
;                 for (int n = 0; n < 2; ++n) acc[a][b][m][n] = (f32x4){0.f, 0.f, 0.f, 0.f};
;     bf16x8 At[4][2], B0[2][2], B1[2][2];
;     const char* cA = (const char*)g.A + (size_t)cur.pm * tstep; const char* cB = (const char*)g.Bt + (size_t)cur.pn * tstep;
;     PG8_STAGE(PG8_SB(0, 0), cB, voffB); PG8_STAGE(PG8_SA(0, 0), cA, voffA); PG8_STAGE(PG8_SB(0, 1), cB + hstep, voffB); PG8_STAGE(PG8_SA(0, 1), cA + hstep, voffA);
;     if (wr == 1) PG8_BAR;
;     PG8_WAIT_V(4); PG8_BAR;
;     PG8_STAGE(PG8_SB(1, 0), cB + kstep, voffB); PG8_STAGE(PG8_SA(1, 0), cA + kstep, voffA); PG8_STAGE(PG8_SB(1, 1), cB + hstep + kstep, voffB);
;     PG8_WAIT_V(6); PG8_BAR;
.LBB0_731:
	s_add_u32 s4, s12, 0x3180000
	s_addc_u32 s5, s13, 0
	s_lshl_b32 s10, s10, 5
	s_and_b32 s19, s10, 0x60
	s_mov_b64 s[10:11], 0x80
	s_add_i32 m0, s31, 0x18000
	v_lshl_add_u64 v[6:7], v[6:7], 0, s[10:11]
	s_ashr_i32 s49, s94, 31
	s_ashr_i32 s50, s96, 31
	s_lshl_b32 s18, s3, 13
	s_lshl_b32 s20, s19, 7
	s_waitcnt vmcnt(4)
	s_barrier
	global_load_lds_dwordx4 v[6:7], off
	v_lshl_add_u64 v[4:5], v[4:5], 0, s[10:11]
	s_add_i32 m0, s31, 0x1a000
	s_add_i32 s51, s31, 0x8000
	s_add_i32 s54, s31, 0xa000
	global_load_lds_dwordx4 v[4:5], off
	v_lshl_add_u64 v[2:3], v[2:3], 0, s[10:11]
	s_mov_b32 m0, s51
	s_add_u32 s16, s40, 0x40080
	global_load_lds_dwordx4 v[2:3], off
	v_lshl_add_u64 v[0:1], v[0:1], 0, s[10:11]
	s_mov_b32 m0, s54
	s_addc_u32 s17, s41, 0
	global_load_lds_dwordx4 v[0:1], off
	s_add_i32 m0, s31, 0x1c000
	s_nop 0
	global_load_lds_dwordx4 v166, s[16:17]
	v_lshl_add_u64 v[0:1], s[16:17], 0, v[170:171]
	s_add_i32 m0, s31, 0x1e000
	s_sext_i32_i8 s58, s2
	global_load_lds_dwordx4 v[0:1], off
	v_lshlrev_b32_e32 v0, 1, v11
	v_lshlrev_b32_e32 v1, 6, v214
	s_movk_i32 s2, 0x3c0
	v_lshlrev_b32_e32 v2, 2, v214
	v_and_or_b32 v1, v1, s2, v0
	v_and_b32_e32 v2, 32, v2
	v_bitop3_b32 v196, s20, v1, v2 bitop3:0xf6
	v_lshlrev_b32_e32 v1, 8, v214
	v_and_b32_e32 v1, 0x38000, v1
	v_lshlrev_b32_e32 v2, 11, v10
	v_or3_b32 v1, v8, v1, v2
	v_lshlrev_b32_e32 v3, 2, v194
	v_add_u32_e32 v172, v1, v9
	v_lshlrev_b32_e32 v1, 4, v12
	v_lshl_or_b32 v0, v194, 6, v0
	v_and_b32_e32 v3, 32, v3
	s_waitcnt vmcnt(6)
	v_and_b32_e32 v1, 0x78000, v1
	v_bitop3_b32 v0, v0, s18, v3 bitop3:0xde
	v_or3_b32 v1, v8, v1, v2
	s_add_i32 s56, 0, 0x10000
	s_add_i32 s57, 0, 0x14000
	s_mov_b32 s55, s96
	v_lshl_or_b32 v195, s3, 6, v194
	v_or_b32_e32 v197, s19, v11
	v_mov_b32_e32 v173, v167
	v_add_u32_e32 v174, v1, v9
	v_mov_b32_e32 v175, v167
	v_mov_b64_e32 v[176:177], 0x84
	v_mov_b64_e32 v[178:179], 0x83
	v_add_u32_e32 v198, s56, v196
	v_add_u32_e32 v199, 0, v0
	v_add_u32_e32 v200, s57, v196
	s_mov_b64 s[16:17], 0x48000
	s_mov_b64 s[18:19], 0x50000
	s_mov_b64 s[20:21], 0x58000
	s_barrier

; #define PG8_STAGE(bufoff, gbase, voff) do { _Pragma("unroll") for (int _i = 0; _i < 2; ++_i) \
;         __builtin_amdgcn_global_load_lds((const unsigned*)((const char*)(gbase) + (voff)[_i]), (LAS unsigned*)(lds + (bufoff) + ldsw + _i * 8192), 16, 0, 0); } while (0)
; #define PG8_LDA(dst, b, h) do { _Pragma("unroll") for (int m = 0; m < 4; ++m) _Pragma("unroll") for (int k = 0; k < 2; ++k) dst[m][k] = *(const LAS bf16x8*)(lds + PG8_SA(b, h) + aoff + m * 2048 + k * 1024); } while (0)
; #define PG8_WAIT_V(n) asm volatile("s_waitcnt vmcnt(" #n ")" ::: "memory")
; #define PG8_WAIT_L(n) asm volatile("s_waitcnt lgkmcnt(" #n ")" ::: "memory")
; template <class Epi>
; __device__ __forceinline__ void gemm_phase(LAS unsigned char* lds, const Gemm g, const StaticOrder& S, const Epi& E) {
;     ...
;         for (int t = 0; t < nt; t += 2) {
;             const bool last = (t == nt - 2);
;             const char* a1 = cA + (size_t)(t + 1) * kstep;
;             const char* a2 = last ? nA : cA + (size_t)(t + 2) * kstep; const char* b2 = last ? nB : cB + (size_t)(t + 2) * kstep;
;             const char* a3 = a2 + kstep; const char* b3 = b2 + kstep;
;             PG8_LDB(B0, 0, 0); PG8_SCHED; PG8_LDA(At, 0, 0); PG8_STAGE(PG8_SA(1, 1), a1 + hstep, voffA);
;             PG8_WAIT_L(8); PG8_BAR; PG8_WAIT_L(0); PG8_MMA(0, 0, At, B0); PG8_BAR; PG8_SCHED;
;             PG8_LDB(B1, 0, 1); PG8_STAGE(PG8_SB(0, 0), b2, voffB);
;             PG8_BAR; PG8_WAIT_L(0); PG8_MMA(0, 1, At, B1); PG8_BAR;
;             PG8_LDA(At, 0, 1); PG8_STAGE(PG8_SA(0, 0), a2, voffA);
;             PG8_BAR; PG8_WAIT_L(0); PG8_MMA(1, 0, At, B0); PG8_BAR; PG8_SCHED;
;             PG8_STAGE(PG8_SB(0, 1), b2 + hstep, voffB);
;             PG8_WAIT_V(6); PG8_BAR; PG8_MMA(1, 1, At, B1); PG8_BAR;
;             PG8_LDB(B0, 1, 0); PG8_SCHED; PG8_LDA(At, 1, 0); PG8_STAGE(PG8_SA(0, 1), a2 + hstep, voffA);
;             PG8_WAIT_L(8); PG8_BAR; PG8_WAIT_L(0); PG8_MMA(0, 0, At, B0); PG8_BAR; PG8_SCHED;
;             PG8_LDB(B1, 1, 1); PG8_STAGE(PG8_SB(1, 0), b3, voffB);
;             PG8_BAR; PG8_WAIT_L(0); PG8_MMA(0, 1, At, B1); PG8_BAR;
;             PG8_LDA(At, 1, 1); PG8_STAGE(PG8_SA(1, 0), a3, voffA);
;             PG8_BAR; PG8_WAIT_L(0); PG8_MMA(1, 0, At, B0); PG8_BAR; PG8_SCHED;
;             PG8_STAGE(PG8_SB(1, 1), b3 + hstep, voffB);
;             PG8_WAIT_V(6); PG8_BAR; PG8_MMA(1, 1, At, B1); PG8_BAR;
.LBB0_739:
	ds_read_b128 v[64:67], v198
	ds_read_b128 v[68:71], v198 offset:1024
	ds_read_b128 v[80:83], v198 offset:2048
	ds_read_b128 v[84:87], v198 offset:3072
	s_add_u32 s40, s34, 0xfffc0080
	s_addc_u32 s41, s35, -1
	s_cmp_eq_u32 s63, 12
	s_cselect_b32 s43, s25, s41
	s_cselect_b32 s42, s59, s40
	s_cselect_b32 s41, s23, s62
	s_cselect_b32 s40, s60, s61
	s_nop 0
	s_add_i32 m0, s31, 0xc000
	ds_read_b128 v[144:147], v199
	ds_read_b128 v[148:151], v199 offset:1024
	ds_read_b128 v[152:155], v199 offset:2048
	ds_read_b128 v[156:159], v199 offset:3072
	ds_read_b128 v[160:163], v199 offset:4096
	ds_read_b128 v[180:183], v199 offset:5120
	ds_read_b128 v[184:187], v199 offset:6144
	ds_read_b128 v[188:191], v199 offset:7168
	global_load_lds_dwordx4 v172, s[34:35]
	s_nop 0
	s_add_i32 m0, s31, 0xe000
	s_nop 0
	global_load_lds_dwordx4 v174, s[34:35]
	s_waitcnt lgkmcnt(8)
	s_barrier
	s_waitcnt lgkmcnt(0)
	s_waitcnt lgkmcnt(0)
	v_mfma_f32_16x16x32_bf16 v[140:143], v[64:67], v[144:147], v[140:143]
	v_mfma_f32_16x16x32_bf16 v[136:139], v[80:83], v[144:147], v[136:139]
	v_mfma_f32_16x16x32_bf16 v[124:127], v[64:67], v[152:155], v[124:127]
	v_mfma_f32_16x16x32_bf16 v[120:123], v[80:83], v[152:155], v[120:123]
	v_mfma_f32_16x16x32_bf16 v[108:111], v[64:67], v[160:163], v[108:111]
	v_mfma_f32_16x16x32_bf16 v[104:107], v[80:83], v[160:163], v[104:107]
	v_mfma_f32_16x16x32_bf16 v[92:95], v[64:67], v[184:187], v[92:95]
	v_mfma_f32_16x16x32_bf16 v[88:91], v[80:83], v[184:187], v[88:91]
	v_mfma_f32_16x16x32_bf16 v[140:143], v[68:71], v[148:151], v[140:143]
	v_mfma_f32_16x16x32_bf16 v[136:139], v[84:87], v[148:151], v[136:139]
	v_mfma_f32_16x16x32_bf16 v[124:127], v[68:71], v[156:159], v[124:127]
	v_mfma_f32_16x16x32_bf16 v[120:123], v[84:87], v[156:159], v[120:123]
	v_mfma_f32_16x16x32_bf16 v[108:111], v[68:71], v[180:183], v[108:111]
	v_mfma_f32_16x16x32_bf16 v[104:107], v[84:87], v[180:183], v[104:107]
	v_mfma_f32_16x16x32_bf16 v[92:95], v[68:71], v[188:191], v[92:95]
	v_mfma_f32_16x16x32_bf16 v[88:91], v[84:87], v[188:191], v[88:91]
	s_barrier
	s_add_i32 s64, s56, s44
	v_lshl_add_u64 v[220:221], s[40:41], 0, v[166:167]
	s_mov_b32 m0, s64
	ds_read_b128 v[202:205], v200
	ds_read_b128 v[206:209], v200 offset:1024
	ds_read_b128 v[210:213], v200 offset:2048
	ds_read_b128 v[216:219], v200 offset:3072
	global_load_lds_dwordx4 v[220:221], off
	v_lshl_add_u64 v[222:223], s[40:41], 0, v[170:171]
	s_add_i32 m0, s64, 0x2000
	s_nop 0
	global_load_lds_dwordx4 v[222:223], off
	s_barrier
	s_waitcnt lgkmcnt(0)
	s_waitcnt lgkmcnt(0)
	v_mfma_f32_16x16x32_bf16 v[132:135], v[202:205], v[144:147], v[132:135]
	v_mfma_f32_16x16x32_bf16 v[128:131], v[210:213], v[144:147], v[128:131]
	v_mfma_f32_16x16x32_bf16 v[116:119], v[202:205], v[152:155], v[116:119]
	v_mfma_f32_16x16x32_bf16 v[112:115], v[210:213], v[152:155], v[112:115]
	v_mfma_f32_16x16x32_bf16 v[100:103], v[202:205], v[160:163], v[100:103]
	v_mfma_f32_16x16x32_bf16 v[96:99], v[210:213], v[160:163], v[96:99]
	v_mfma_f32_16x16x32_bf16 v[76:79], v[202:205], v[184:187], v[76:79]
	v_mfma_f32_16x16x32_bf16 v[72:75], v[210:213], v[184:187], v[72:75]
	v_mfma_f32_16x16x32_bf16 v[132:135], v[206:209], v[148:151], v[132:135]
	v_mfma_f32_16x16x32_bf16 v[128:131], v[216:219], v[148:151], v[128:131]
	v_mfma_f32_16x16x32_bf16 v[116:119], v[206:209], v[156:159], v[116:119]
	v_mfma_f32_16x16x32_bf16 v[112:115], v[216:219], v[156:159], v[112:115]
	v_mfma_f32_16x16x32_bf16 v[100:103], v[206:209], v[180:183], v[100:103]
	v_mfma_f32_16x16x32_bf16 v[96:99], v[216:219], v[180:183], v[96:99]
	v_mfma_f32_16x16x32_bf16 v[76:79], v[206:209], v[188:191], v[76:79]
	v_mfma_f32_16x16x32_bf16 v[72:75], v[216:219], v[188:191], v[72:75]
	s_mov_b32 m0, s31
	v_lshl_add_u64 v[224:225], s[42:43], 0, v[164:165]
	s_barrier
	ds_read_b128 v[144:147], v199 offset:16384
	ds_read_b128 v[148:151], v199 offset:17408
	ds_read_b128 v[152:155], v199 offset:18432
	ds_read_b128 v[156:159], v199 offset:19456
	ds_read_b128 v[160:163], v199 offset:20480
	ds_read_b128 v[180:183], v199 offset:21504
	ds_read_b128 v[184:187], v199 offset:22528
	ds_read_b128 v[188:191], v199 offset:23552
	global_load_lds_dwordx4 v[224:225], off
	v_lshl_add_u64 v[226:227], s[42:43], 0, v[168:169]
	s_mov_b32 m0, s45
	s_nop 0
	global_load_lds_dwordx4 v[226:227], off
	s_barrier
	s_waitcnt lgkmcnt(0)
	s_waitcnt lgkmcnt(0)
	v_mfma_f32_16x16x32_bf16 v[60:63], v[64:67], v[144:147], v[60:63]
	v_mfma_f32_16x16x32_bf16 v[56:59], v[80:83], v[144:147], v[56:59]
	v_mfma_f32_16x16x32_bf16 v[44:47], v[64:67], v[152:155], v[44:47]
	v_mfma_f32_16x16x32_bf16 v[40:43], v[80:83], v[152:155], v[40:43]
	v_mfma_f32_16x16x32_bf16 v[28:31], v[64:67], v[160:163], v[28:31]
	v_mfma_f32_16x16x32_bf16 v[24:27], v[80:83], v[160:163], v[24:27]
	v_mfma_f32_16x16x32_bf16 v[12:15], v[64:67], v[184:187], v[12:15]
	v_mfma_f32_16x16x32_bf16 v[8:11], v[80:83], v[184:187], v[8:11]
	v_mfma_f32_16x16x32_bf16 v[60:63], v[68:71], v[148:151], v[60:63]
	v_mfma_f32_16x16x32_bf16 v[56:59], v[84:87], v[148:151], v[56:59]
	v_mfma_f32_16x16x32_bf16 v[44:47], v[68:71], v[156:159], v[44:47]
	v_mfma_f32_16x16x32_bf16 v[40:43], v[84:87], v[156:159], v[40:43]
	v_mfma_f32_16x16x32_bf16 v[28:31], v[68:71], v[180:183], v[28:31]
	v_mfma_f32_16x16x32_bf16 v[24:27], v[84:87], v[180:183], v[24:27]
	v_mfma_f32_16x16x32_bf16 v[12:15], v[68:71], v[188:191], v[12:15]
	v_mfma_f32_16x16x32_bf16 v[8:11], v[84:87], v[188:191], v[8:11]
	s_barrier
	s_add_u32 s64, s40, 0x40000
	s_addc_u32 s65, s41, 0
	s_add_i32 s66, s57, s44
	s_nop 0
	s_mov_b32 m0, s66
	s_nop 0
	global_load_lds_dwordx4 v166, s[64:65]
	s_nop 0
	s_add_i32 m0, s66, 0x2000
	s_nop 0
	global_load_lds_dwordx4 v170, s[64:65]
	s_waitcnt vmcnt(6)
	s_barrier
; #define PG8_STAGE(bufoff, gbase, voff) do { _Pragma("unroll") for (int _i = 0; _i < 2; ++_i) \
;         __builtin_amdgcn_global_load_lds((const unsigned*)((const char*)(gbase) + (voff)[_i]), (LAS unsigned*)(lds + (bufoff) + ldsw + _i * 8192), 16, 0, 0); } while (0)
; #define PG8_LDA(dst, b, h) do { _Pragma("unroll") for (int m = 0; m < 4; ++m) _Pragma("unroll") for (int k = 0; k < 2; ++k) dst[m][k] = *(const LAS bf16x8*)(lds + PG8_SA(b, h) + aoff + m * 2048 + k * 1024); } while (0)
; #define PG8_WAIT_V(n) asm volatile("s_waitcnt vmcnt(" #n ")" ::: "memory")
; #define PG8_WAIT_L(n) asm volatile("s_waitcnt lgkmcnt(" #n ")" ::: "memory")
; template <class Epi>
; __device__ __forceinline__ void gemm_phase(LAS unsigned char* lds, const Gemm g, const StaticOrder& S, const Epi& E) {
;     ...
;         for (int t = 0; t < nt; t += 2) {
;             const bool last = (t == nt - 2);
;             const char* a1 = cA + (size_t)(t + 1) * kstep;
;             const char* a2 = last ? nA : cA + (size_t)(t + 2) * kstep; const char* b2 = last ? nB : cB + (size_t)(t + 2) * kstep;
;             const char* a3 = a2 + kstep; const char* b3 = b2 + kstep;
;             PG8_LDB(B0, 0, 0); PG8_SCHED; PG8_LDA(At, 0, 0); PG8_STAGE(PG8_SA(1, 1), a1 + hstep, voffA);
;             PG8_WAIT_L(8); PG8_BAR; PG8_WAIT_L(0); PG8_MMA(0, 0, At, B0); PG8_BAR; PG8_SCHED;
;             PG8_LDB(B1, 0, 1); PG8_STAGE(PG8_SB(0, 0), b2, voffB);
;             PG8_BAR; PG8_WAIT_L(0); PG8_MMA(0, 1, At, B1); PG8_BAR;
;             PG8_LDA(At, 0, 1); PG8_STAGE(PG8_SA(0, 0), a2, voffA);
;             PG8_BAR; PG8_WAIT_L(0); PG8_MMA(1, 0, At, B0); PG8_BAR; PG8_SCHED;
;             PG8_STAGE(PG8_SB(0, 1), b2 + hstep, voffB);
;             PG8_WAIT_V(6); PG8_BAR; PG8_MMA(1, 1, At, B1); PG8_BAR;
;             PG8_LDB(B0, 1, 0); PG8_SCHED; PG8_LDA(At, 1, 0); PG8_STAGE(PG8_SA(0, 1), a2 + hstep, voffA);
;             PG8_WAIT_L(8); PG8_BAR; PG8_WAIT_L(0); PG8_MMA(0, 0, At, B0); PG8_BAR; PG8_SCHED;
;             PG8_LDB(B1, 1, 1); PG8_STAGE(PG8_SB(1, 0), b3, voffB);
;             PG8_BAR; PG8_WAIT_L(0); PG8_MMA(0, 1, At, B1); PG8_BAR;
;             PG8_LDA(At, 1, 1); PG8_STAGE(PG8_SA(1, 0), a3, voffA);
;             PG8_BAR; PG8_WAIT_L(0); PG8_MMA(1, 0, At, B0); PG8_BAR; PG8_SCHED;
;             PG8_STAGE(PG8_SB(1, 1), b3 + hstep, voffB);
;             PG8_WAIT_V(6); PG8_BAR; PG8_MMA(1, 1, At, B1); PG8_BAR;
	v_mfma_f32_16x16x32_bf16 v[52:55], v[202:205], v[144:147], v[52:55]
	v_mfma_f32_16x16x32_bf16 v[48:51], v[210:213], v[144:147], v[48:51]
	v_mfma_f32_16x16x32_bf16 v[36:39], v[202:205], v[152:155], v[36:39]
	v_mfma_f32_16x16x32_bf16 v[32:35], v[210:213], v[152:155], v[32:35]
	v_mfma_f32_16x16x32_bf16 v[20:23], v[202:205], v[160:163], v[20:23]
	v_mfma_f32_16x16x32_bf16 v[16:19], v[210:213], v[160:163], v[16:19]
	v_mfma_f32_16x16x32_bf16 v[4:7], v[202:205], v[184:187], v[4:7]
	v_mfma_f32_16x16x32_bf16 v[0:3], v[210:213], v[184:187], v[0:3]
	v_mfma_f32_16x16x32_bf16 v[52:55], v[206:209], v[148:151], v[52:55]
	v_mfma_f32_16x16x32_bf16 v[48:51], v[216:219], v[148:151], v[48:51]
	v_mfma_f32_16x16x32_bf16 v[36:39], v[206:209], v[156:159], v[36:39]
	v_mfma_f32_16x16x32_bf16 v[32:35], v[216:219], v[156:159], v[32:35]
	v_mfma_f32_16x16x32_bf16 v[20:23], v[206:209], v[180:183], v[20:23]
	v_mfma_f32_16x16x32_bf16 v[16:19], v[216:219], v[180:183], v[16:19]
	v_mfma_f32_16x16x32_bf16 v[4:7], v[206:209], v[188:191], v[4:7]
	v_mfma_f32_16x16x32_bf16 v[0:3], v[216:219], v[188:191], v[0:3]
	s_add_i32 s64, 0, 0x18000
	v_add_u32_e32 v84, s64, v196
	s_barrier
	ds_read_b128 v[64:67], v84
	ds_read_b128 v[68:71], v84 offset:1024
	ds_read_b128 v[80:83], v84 offset:2048
	ds_read_b128 v[84:87], v84 offset:3072
	s_add_u32 s42, s42, 0x40000
	s_addc_u32 s43, s43, 0
	s_mov_b32 m0, s46
	s_nop 0
	ds_read_b128 v[144:147], v199 offset:32768
	ds_read_b128 v[148:151], v199 offset:33792
	ds_read_b128 v[152:155], v199 offset:34816
	ds_read_b128 v[156:159], v199 offset:35840
	ds_read_b128 v[160:163], v199 offset:36864
	ds_read_b128 v[180:183], v199 offset:37888
	ds_read_b128 v[184:187], v199 offset:38912
	ds_read_b128 v[188:191], v199 offset:39936
	global_load_lds_dwordx4 v164, s[42:43]
	s_nop 0
	s_mov_b32 m0, s47
	s_nop 0
	global_load_lds_dwordx4 v168, s[42:43]
	s_waitcnt lgkmcnt(8)
	s_barrier
	s_waitcnt lgkmcnt(0)
	s_waitcnt lgkmcnt(0)
	v_mfma_f32_16x16x32_bf16 v[140:143], v[64:67], v[144:147], v[140:143]
	v_mfma_f32_16x16x32_bf16 v[136:139], v[80:83], v[144:147], v[136:139]
	v_mfma_f32_16x16x32_bf16 v[124:127], v[64:67], v[152:155], v[124:127]
	v_mfma_f32_16x16x32_bf16 v[120:123], v[80:83], v[152:155], v[120:123]
	v_mfma_f32_16x16x32_bf16 v[108:111], v[64:67], v[160:163], v[108:111]
	v_mfma_f32_16x16x32_bf16 v[104:107], v[80:83], v[160:163], v[104:107]
	v_mfma_f32_16x16x32_bf16 v[92:95], v[64:67], v[184:187], v[92:95]
	v_mfma_f32_16x16x32_bf16 v[88:91], v[80:83], v[184:187], v[88:91]
	v_mfma_f32_16x16x32_bf16 v[140:143], v[68:71], v[148:151], v[140:143]
	v_mfma_f32_16x16x32_bf16 v[136:139], v[84:87], v[148:151], v[136:139]
	v_mfma_f32_16x16x32_bf16 v[124:127], v[68:71], v[156:159], v[124:127]
	v_mfma_f32_16x16x32_bf16 v[120:123], v[84:87], v[156:159], v[120:123]
	v_mfma_f32_16x16x32_bf16 v[108:111], v[68:71], v[180:183], v[108:111]
	v_mfma_f32_16x16x32_bf16 v[104:107], v[84:87], v[180:183], v[104:107]
	v_mfma_f32_16x16x32_bf16 v[92:95], v[68:71], v[188:191], v[92:95]
	v_mfma_f32_16x16x32_bf16 v[88:91], v[84:87], v[188:191], v[88:91]
	s_barrier
	s_add_i32 s42, 0, 0x1c000
	s_add_i32 s43, s64, s44
	v_add_u32_e32 v201, s42, v196
	v_lshl_add_u64 v[220:221], v[220:221], 0, s[10:11]
	s_mov_b32 m0, s43
	ds_read_b128 v[202:205], v201
	ds_read_b128 v[206:209], v201 offset:1024
	ds_read_b128 v[210:213], v201 offset:2048
	ds_read_b128 v[216:219], v201 offset:3072
	global_load_lds_dwordx4 v[220:221], off
	v_lshl_add_u64 v[220:221], v[222:223], 0, s[10:11]
	s_add_i32 m0, s43, 0x2000
	s_nop 0
	global_load_lds_dwordx4 v[220:221], off
	s_barrier
	s_waitcnt lgkmcnt(0)
	s_waitcnt lgkmcnt(0)
	v_mfma_f32_16x16x32_bf16 v[132:135], v[202:205], v[144:147], v[132:135]
	v_mfma_f32_16x16x32_bf16 v[128:131], v[210:213], v[144:147], v[128:131]
	v_mfma_f32_16x16x32_bf16 v[116:119], v[202:205], v[152:155], v[116:119]
	v_mfma_f32_16x16x32_bf16 v[112:115], v[210:213], v[152:155], v[112:115]
	v_mfma_f32_16x16x32_bf16 v[100:103], v[202:205], v[160:163], v[100:103]
	v_mfma_f32_16x16x32_bf16 v[96:99], v[210:213], v[160:163], v[96:99]
	v_mfma_f32_16x16x32_bf16 v[76:79], v[202:205], v[184:187], v[76:79]
	v_mfma_f32_16x16x32_bf16 v[72:75], v[210:213], v[184:187], v[72:75]
	v_mfma_f32_16x16x32_bf16 v[132:135], v[206:209], v[148:151], v[132:135]
	v_mfma_f32_16x16x32_bf16 v[128:131], v[216:219], v[148:151], v[128:131]
	v_mfma_f32_16x16x32_bf16 v[116:119], v[206:209], v[156:159], v[116:119]
	v_mfma_f32_16x16x32_bf16 v[112:115], v[216:219], v[156:159], v[112:115]
	v_mfma_f32_16x16x32_bf16 v[100:103], v[206:209], v[180:183], v[100:103]
	v_mfma_f32_16x16x32_bf16 v[96:99], v[216:219], v[180:183], v[96:99]
	v_mfma_f32_16x16x32_bf16 v[76:79], v[206:209], v[188:191], v[76:79]
	v_mfma_f32_16x16x32_bf16 v[72:75], v[216:219], v[188:191], v[72:75]
	s_mov_b32 m0, s51
	v_lshl_add_u64 v[220:221], v[224:225], 0, s[10:11]
	s_barrier
	ds_read_b128 v[144:147], v199 offset:49152
	ds_read_b128 v[148:151], v199 offset:50176
	ds_read_b128 v[152:155], v199 offset:51200
	ds_read_b128 v[156:159], v199 offset:52224
	ds_read_b128 v[160:163], v199 offset:53248
	ds_read_b128 v[180:183], v199 offset:54272
	ds_read_b128 v[184:187], v199 offset:55296
	ds_read_b128 v[188:191], v199 offset:56320
	global_load_lds_dwordx4 v[220:221], off
	v_lshl_add_u64 v[220:221], v[226:227], 0, s[10:11]
	s_mov_b32 m0, s54
	s_nop 0
	global_load_lds_dwordx4 v[220:221], off
	s_barrier
; #define PG8_WAIT_V(n) asm volatile("s_waitcnt vmcnt(" #n ")" ::: "memory")
; template <class Epi>
; __device__ __forceinline__ void gemm_phase(LAS unsigned char* lds, const Gemm g, const StaticOrder& S, const Epi& E) {
;     ...
;         for (int t = 0; t < nt; t += 2) {
;             const bool last = (t == nt - 2);
;             const char* a1 = cA + (size_t)(t + 1) * kstep;
;             const char* a2 = last ? nA : cA + (size_t)(t + 2) * kstep; const char* b2 = last ? nB : cB + (size_t)(t + 2) * kstep;
;             const char* a3 = a2 + kstep; const char* b3 = b2 + kstep;
;             PG8_LDB(B0, 0, 0); PG8_SCHED; PG8_LDA(At, 0, 0); PG8_STAGE(PG8_SA(1, 1), a1 + hstep, voffA);
;             PG8_WAIT_L(8); PG8_BAR; PG8_WAIT_L(0); PG8_MMA(0, 0, At, B0); PG8_BAR; PG8_SCHED;
;             PG8_LDB(B1, 0, 1); PG8_STAGE(PG8_SB(0, 0), b2, voffB);
;             PG8_BAR; PG8_WAIT_L(0); PG8_MMA(0, 1, At, B1); PG8_BAR;
;             PG8_LDA(At, 0, 1); PG8_STAGE(PG8_SA(0, 0), a2, voffA);
;             PG8_BAR; PG8_WAIT_L(0); PG8_MMA(1, 0, At, B0); PG8_BAR; PG8_SCHED;
;             PG8_STAGE(PG8_SB(0, 1), b2 + hstep, voffB);
;             PG8_WAIT_V(6); PG8_BAR; PG8_MMA(1, 1, At, B1); PG8_BAR;
;             PG8_LDB(B0, 1, 0); PG8_SCHED; PG8_LDA(At, 1, 0); PG8_STAGE(PG8_SA(0, 1), a2 + hstep, voffA);
;             PG8_WAIT_L(8); PG8_BAR; PG8_WAIT_L(0); PG8_MMA(0, 0, At, B0); PG8_BAR; PG8_SCHED;
;             PG8_LDB(B1, 1, 1); PG8_STAGE(PG8_SB(1, 0), b3, voffB);
;             PG8_BAR; PG8_WAIT_L(0); PG8_MMA(0, 1, At, B1); PG8_BAR;
;             PG8_LDA(At, 1, 1); PG8_STAGE(PG8_SA(1, 0), a3, voffA);
;             PG8_BAR; PG8_WAIT_L(0); PG8_MMA(1, 0, At, B0); PG8_BAR; PG8_SCHED;
;             PG8_STAGE(PG8_SB(1, 1), b3 + hstep, voffB);
;             PG8_WAIT_V(6); PG8_BAR; PG8_MMA(1, 1, At, B1); PG8_BAR;
;     __device__ __forceinline__ void operator()(const AccT& acc, const pg8::Unit& u, int wr, int wc, int fr, int fq) const {
;         const int row0 = u.pm * 256 + wr * 64 + fr, col0 = u.pn * 256 + wc * 32 + 8 * fq;
;         f32x4 bv[2][2];
; #pragma unroll
;         for (int bj = 0; bj < 2; ++bj)
; #pragma unroll
;             for (int n = 0; n < 2; ++n) bv[bj][n] = *(const f32x4*)(bias + col0 + bj * 128 + 4 * n);
; #pragma unroll
;         for (int ai = 0; ai < 2; ++ai) { u32x4 gw[4][2];
; #pragma unroll
;             for (int m = 0; m < 4; ++m)
; #pragma unroll
	s_waitcnt lgkmcnt(0)
	s_waitcnt lgkmcnt(0)
	v_mfma_f32_16x16x32_bf16 v[60:63], v[64:67], v[144:147], v[60:63]
	v_mfma_f32_16x16x32_bf16 v[56:59], v[80:83], v[144:147], v[56:59]
	v_mfma_f32_16x16x32_bf16 v[44:47], v[64:67], v[152:155], v[44:47]
	v_mfma_f32_16x16x32_bf16 v[40:43], v[80:83], v[152:155], v[40:43]
	v_mfma_f32_16x16x32_bf16 v[28:31], v[64:67], v[160:163], v[28:31]
	v_mfma_f32_16x16x32_bf16 v[24:27], v[80:83], v[160:163], v[24:27]
	v_mfma_f32_16x16x32_bf16 v[12:15], v[64:67], v[184:187], v[12:15]
	v_mfma_f32_16x16x32_bf16 v[8:11], v[80:83], v[184:187], v[8:11]
	v_mfma_f32_16x16x32_bf16 v[60:63], v[68:71], v[148:151], v[60:63]
	v_mfma_f32_16x16x32_bf16 v[56:59], v[84:87], v[148:151], v[56:59]
	v_mfma_f32_16x16x32_bf16 v[44:47], v[68:71], v[156:159], v[44:47]
	v_mfma_f32_16x16x32_bf16 v[40:43], v[84:87], v[156:159], v[40:43]
	v_mfma_f32_16x16x32_bf16 v[28:31], v[68:71], v[180:183], v[28:31]
	v_mfma_f32_16x16x32_bf16 v[24:27], v[84:87], v[180:183], v[24:27]
	v_mfma_f32_16x16x32_bf16 v[12:15], v[68:71], v[188:191], v[12:15]
	v_mfma_f32_16x16x32_bf16 v[8:11], v[84:87], v[188:191], v[8:11]
	s_barrier
	s_add_u32 s40, s40, 0x40080
	s_addc_u32 s41, s41, 0
	s_add_i32 s42, s42, s44
	s_nop 0
	s_mov_b32 m0, s42
	s_nop 0
	global_load_lds_dwordx4 v166, s[40:41]
	v_lshl_add_u64 v[64:65], s[40:41], 0, v[170:171]
	s_add_i32 m0, s42, 0x2000
	s_nop 0
	global_load_lds_dwordx4 v[64:65], off
	s_waitcnt vmcnt(6)
	s_barrier
	v_mfma_f32_16x16x32_bf16 v[52:55], v[202:205], v[144:147], v[52:55]
	v_mfma_f32_16x16x32_bf16 v[48:51], v[210:213], v[144:147], v[48:51]
	v_mfma_f32_16x16x32_bf16 v[36:39], v[202:205], v[152:155], v[36:39]
	v_mfma_f32_16x16x32_bf16 v[32:35], v[210:213], v[152:155], v[32:35]
	v_mfma_f32_16x16x32_bf16 v[20:23], v[202:205], v[160:163], v[20:23]
	v_mfma_f32_16x16x32_bf16 v[16:19], v[210:213], v[160:163], v[16:19]
	v_mfma_f32_16x16x32_bf16 v[4:7], v[202:205], v[184:187], v[4:7]
	v_mfma_f32_16x16x32_bf16 v[0:3], v[210:213], v[184:187], v[0:3]
	v_mfma_f32_16x16x32_bf16 v[52:55], v[206:209], v[148:151], v[52:55]
	v_mfma_f32_16x16x32_bf16 v[48:51], v[216:219], v[148:151], v[48:51]
	v_mfma_f32_16x16x32_bf16 v[36:39], v[206:209], v[156:159], v[36:39]
	v_mfma_f32_16x16x32_bf16 v[32:35], v[216:219], v[156:159], v[32:35]
	v_mfma_f32_16x16x32_bf16 v[20:23], v[206:209], v[180:183], v[20:23]
	v_mfma_f32_16x16x32_bf16 v[16:19], v[216:219], v[180:183], v[16:19]
	v_mfma_f32_16x16x32_bf16 v[4:7], v[206:209], v[188:191], v[4:7]
	v_mfma_f32_16x16x32_bf16 v[0:3], v[216:219], v[188:191], v[0:3]
	s_add_i32 s63, s63, 2
	s_add_u32 s34, s34, 0x100
	s_addc_u32 s35, s35, 0
	s_add_u32 s61, s61, 0x100
	s_addc_u32 s62, s62, 0
	s_cmp_gt_u32 s63, 13
	s_barrier
	s_cbranch_scc0 .LBB0_739
	v_lshl_or_b32 v64, s58, 8, v197
	v_ashrrev_i32_e32 v65, 31, v64
	v_readlane_b32 s60, v245, 18
	v_lshl_add_u32 v144, s30, 8, v195
	v_readlane_b32 s66, v245, 24
	v_readlane_b32 s67, v245, 25
	v_ashrrev_i32_e32 v145, 31, v144
	v_lshlrev_b64 v[180:181], 1, v[64:65]
	v_lshl_add_u64 v[66:67], v[64:65], 2, s[66:67]
	v_lshlrev_b64 v[184:185], 11, v[144:145]
	v_lshl_add_u64 v[182:183], s[6:7], 0, v[180:181]
	global_load_dwordx4 v[84:87], v[66:67], off
	global_load_dwordx4 v[80:83], v[66:67], off offset:16
	global_load_dwordx4 v[68:71], v[66:67], off offset:512
	v_lshl_add_u64 v[64:65], v[182:183], 0, v[184:185]
	global_load_dwordx4 v[202:205], v[64:65], off
	global_load_dwordx4 v[206:209], v[64:65], off offset:256
	s_nop 0
	global_load_dwordx4 v[64:67], v[66:67], off offset:528
	v_or_b32_e32 v146, 16, v144
	v_or_b32_e32 v148, 32, v144
	v_or_b32_e32 v144, 48, v144
	v_ashrrev_i32_e32 v147, 31, v146
	v_ashrrev_i32_e32 v149, 31, v148
	v_ashrrev_i32_e32 v145, 31, v144
	v_lshlrev_b64 v[190:191], 11, v[146:147]
	v_lshlrev_b64 v[188:189], 11, v[148:149]
	v_lshlrev_b64 v[186:187], 11, v[144:145]
	v_lshl_add_u64 v[144:145], s[4:5], 0, v[184:185]
	v_lshl_add_u64 v[146:147], v[182:183], 0, v[190:191]
	v_lshl_add_u64 v[148:149], v[182:183], 0, v[188:189]
	v_lshl_add_u64 v[216:217], v[182:183], 0, v[186:187]
	v_lshl_add_u64 v[218:219], v[144:145], 0, v[180:181]
	global_load_dwordx4 v[210:213], v[146:147], off
	global_load_dwordx4 v[160:163], v[146:147], off offset:256
	global_load_dwordx4 v[156:159], v[148:149], off
	global_load_dwordx4 v[152:155], v[148:149], off offset:256
	s_nop 0
	global_load_dwordx4 v[148:151], v[216:217], off
	global_load_dwordx4 v[144:147], v[216:217], off offset:256
	s_and_b64 vcc, exec, s[2:3]
	s_mov_b32 s58, s22
	s_mov_b32 s30, s24
	s_mov_b64 s[40:41], s[28:29]
	s_mov_b64 s[34:35], s[26:27]
	v_readlane_b32 s61, v245, 19
	v_readlane_b32 s62, v245, 20
	v_readlane_b32 s63, v245, 21
	v_readlane_b32 s64, v245, 22
	v_readlane_b32 s65, v245, 23
	v_readlane_b32 s68, v245, 26
	v_readlane_b32 s69, v245, 27
	v_readlane_b32 s70, v245, 28
	v_readlane_b32 s71, v245, 29
	v_readlane_b32 s72, v245, 30
	v_readlane_b32 s73, v245, 31
	v_readlane_b32 s74, v245, 32
	v_readlane_b32 s75, v245, 33
	s_waitcnt vmcnt(0)
; __device__ __forceinline__ u32x4 pack8(const f32x4 v0, const f32x4 v1) { u32x4 w; w.x = cvt_pk_bf16(v0[0], v0[1]); w.y = cvt_pk_bf16(v0[2], v0[3]); w.z = cvt_pk_bf16(v1[0], v1[1]); w.w = cvt_pk_bf16(v1[2], v1[3]); return w; }
; __device__ __forceinline__ void unpack8(const u32x4 w, f32x4& v0, f32x4& v1) { v0 = (f32x4){bflo(w.x), bfhi(w.x), bflo(w.y), bfhi(w.y)}; v1 = (f32x4){bflo(w.z), bfhi(w.z), bflo(w.w), bfhi(w.w)}; }
; __device__ __forceinline__ f32x4 sig4(const f32x4 v) { return (f32x4){sigmoidf_(v[0]), sigmoidf_(v[1]), sigmoidf_(v[2]), sigmoidf_(v[3])}; }
;     __device__ __forceinline__ void operator()(const AccT& acc, const pg8::Unit& u, int wr, int wc, int fr, int fq) const {
;     ...
;         for (int ai = 0; ai < 2; ++ai) { u32x4 gw[4][2];
; #pragma unroll
;             for (int m = 0; m < 4; ++m)
; #pragma unroll
;                 for (int bj = 0; bj < 2; ++bj) gw[m][bj] = *(const u32x4*)(G + (size_t)(row0 + ai * 128 + m * 16) * 1024 + col0 + bj * 128);
; #pragma unroll
;             for (int m = 0; m < 4; ++m)
; #pragma unroll
;                 for (int bj = 0; bj < 2; ++bj) { f32x4 g0, g1; unpack8(gw[m][bj], g0, g1);
;                     *(u32x4*)(O + (size_t)(row0 + ai * 128 + m * 16) * 1024 + col0 + bj * 128) = pack8(g0 * sig4(acc[ai][bj][m][0] + bv[bj][0]), g1 * sig4(acc[ai][bj][m][1] + bv[bj][1])); } }
	v_pk_add_f32 v[140:141], v[140:141], v[84:85]
	v_pk_add_f32 v[142:143], v[142:143], v[86:87]
	v_mul_f32_e32 v201, 0xbfb8aa3b, v140
	v_mul_f32_e32 v216, 0xbfb8aa3b, v141
	v_pk_add_f32 v[138:139], v[138:139], v[82:83]
	v_pk_add_f32 v[136:137], v[136:137], v[80:81]
	v_mul_f32_e32 v217, 0xbfb8aa3b, v142
	v_mul_f32_e32 v220, 0xbfb8aa3b, v143
	v_exp_f32_e32 v201, v201
	v_exp_f32_e32 v216, v216
	v_pk_add_f32 v[132:133], v[132:133], v[68:69]
	v_mul_f32_e32 v221, 0xbfb8aa3b, v136
	v_mul_f32_e32 v222, 0xbfb8aa3b, v137
	v_mul_f32_e32 v223, 0xbfb8aa3b, v138
	v_mul_f32_e32 v224, 0xbfb8aa3b, v139
	v_exp_f32_e32 v217, v217
	v_exp_f32_e32 v220, v220
	v_pk_add_f32 v[134:135], v[134:135], v[70:71]
	v_pk_add_f32 v[128:129], v[128:129], v[64:65]
	v_pk_add_f32 v[130:131], v[130:131], v[66:67]
	v_mul_f32_e32 v132, 0xbfb8aa3b, v132
	v_exp_f32_e32 v221, v221
	v_exp_f32_e32 v222, v222
	v_exp_f32_e32 v223, v223
	v_exp_f32_e32 v224, v224
	v_mul_f32_e32 v133, 0xbfb8aa3b, v133
	v_mul_f32_e32 v134, 0xbfb8aa3b, v134
	v_mul_f32_e32 v135, 0xbfb8aa3b, v135
	v_mul_f32_e32 v128, 0xbfb8aa3b, v128
	v_mul_f32_e32 v129, 0xbfb8aa3b, v129
	v_mul_f32_e32 v130, 0xbfb8aa3b, v130
	v_mul_f32_e32 v131, 0xbfb8aa3b, v131
	v_exp_f32_e32 v132, v132
	v_exp_f32_e32 v133, v133
	v_exp_f32_e32 v134, v134
	v_exp_f32_e32 v135, v135
	v_exp_f32_e32 v128, v128
	v_exp_f32_e32 v129, v129
	v_exp_f32_e32 v130, v130
	v_exp_f32_e32 v131, v131
	v_pk_add_f32 v[124:125], v[124:125], v[84:85]
	v_lshlrev_b32_e32 v136, 16, v202
	v_and_b32_e32 v137, 0xffff0000, v202
	v_lshlrev_b32_e32 v138, 16, v203
	v_and_b32_e32 v139, 0xffff0000, v203
	v_lshlrev_b32_e32 v140, 16, v204
	v_and_b32_e32 v141, 0xffff0000, v204
	v_lshlrev_b32_e32 v142, 16, v205
	v_and_b32_e32 v143, 0xffff0000, v205
	v_lshlrev_b32_e32 v202, 16, v206
	v_and_b32_e32 v203, 0xffff0000, v206
	v_lshlrev_b32_e32 v204, 16, v207
	v_and_b32_e32 v205, 0xffff0000, v207
	v_lshlrev_b32_e32 v206, 16, v208
	v_and_b32_e32 v207, 0xffff0000, v208
	v_add_f32_e32 v201, 1.0, v201
	v_add_f32_e32 v208, 1.0, v216
	v_mul_f32_e32 v124, 0xbfb8aa3b, v124
	v_mul_f32_e32 v125, 0xbfb8aa3b, v125
	v_pk_add_f32 v[120:121], v[120:121], v[80:81]
	v_pk_add_f32 v[122:123], v[122:123], v[82:83]
	v_add_f32_e32 v225, 1.0, v217
	v_add_f32_e32 v226, 1.0, v220
	v_rcp_f32_e32 v216, v201
	v_rcp_f32_e32 v217, v208
	v_exp_f32_e32 v124, v124
	v_pk_add_f32 v[126:127], v[126:127], v[86:87]
	v_exp_f32_e32 v125, v125
	v_mul_f32_e32 v120, 0xbfb8aa3b, v120
	v_mul_f32_e32 v121, 0xbfb8aa3b, v121
	v_mul_f32_e32 v122, 0xbfb8aa3b, v122
	v_mul_f32_e32 v123, 0xbfb8aa3b, v123
	v_add_f32_e32 v227, 1.0, v221
	v_add_f32_e32 v228, 1.0, v222
	v_add_f32_e32 v223, 1.0, v223
	v_add_f32_e32 v229, 1.0, v224
	v_rcp_f32_e32 v220, v225
	v_rcp_f32_e32 v221, v226
	v_mul_f32_e32 v126, 0xbfb8aa3b, v126
	v_mul_f32_e32 v127, 0xbfb8aa3b, v127
	v_exp_f32_e32 v120, v120
	v_exp_f32_e32 v121, v121
	v_exp_f32_e32 v122, v122
	v_exp_f32_e32 v123, v123
	v_rcp_f32_e32 v222, v227
	v_rcp_f32_e32 v224, v223
	v_rcp_f32_e32 v225, v229
	v_rcp_f32_e32 v223, v228
	v_add_f32_e32 v132, 1.0, v132
	v_add_f32_e32 v133, 1.0, v133
	v_add_f32_e32 v134, 1.0, v134
	v_add_f32_e32 v135, 1.0, v135
	v_add_f32_e32 v128, 1.0, v128
	v_add_f32_e32 v129, 1.0, v129
	v_add_f32_e32 v130, 1.0, v130
	v_add_f32_e32 v131, 1.0, v131
	v_exp_f32_e32 v126, v126
	v_exp_f32_e32 v127, v127
	v_pk_add_f32 v[116:117], v[116:117], v[68:69]
	v_pk_add_f32 v[118:119], v[118:119], v[70:71]
	v_pk_add_f32 v[112:113], v[112:113], v[64:65]
	v_pk_add_f32 v[114:115], v[114:115], v[66:67]
	v_rcp_f32_e32 v132, v132
	v_rcp_f32_e32 v133, v133
	v_rcp_f32_e32 v134, v134
	v_rcp_f32_e32 v135, v135
	v_rcp_f32_e32 v128, v128
	v_rcp_f32_e32 v130, v130
	v_rcp_f32_e32 v131, v131
	v_rcp_f32_e32 v129, v129
	v_mul_f32_e32 v116, 0xbfb8aa3b, v116
	v_mul_f32_e32 v117, 0xbfb8aa3b, v117
	v_mul_f32_e32 v118, 0xbfb8aa3b, v118
	v_mul_f32_e32 v119, 0xbfb8aa3b, v119
	v_mul_f32_e32 v112, 0xbfb8aa3b, v112
	v_mul_f32_e32 v113, 0xbfb8aa3b, v113
	v_mul_f32_e32 v114, 0xbfb8aa3b, v114
	v_mul_f32_e32 v115, 0xbfb8aa3b, v115
	v_pk_mul_f32 v[136:137], v[216:217], v[136:137]
	v_add_f32_e32 v124, 1.0, v124
	v_add_f32_e32 v125, 1.0, v125
	v_exp_f32_e32 v116, v116
	v_exp_f32_e32 v117, v117
	v_exp_f32_e32 v118, v118
	v_exp_f32_e32 v119, v119
	v_exp_f32_e32 v112, v112
	v_exp_f32_e32 v113, v113
	v_exp_f32_e32 v114, v114
	v_exp_f32_e32 v115, v115
	v_pk_add_f32 v[108:109], v[108:109], v[84:85]
	v_pk_mul_f32 v[138:139], v[220:221], v[138:139]
	v_cvt_pk_bf16_f32 v136, v136, v137
	v_rcp_f32_e32 v124, v124
	v_cvt_pk_bf16_f32 v137, v138, v139
	v_rcp_f32_e32 v125, v125
	v_add_f32_e32 v120, 1.0, v120
	v_add_f32_e32 v121, 1.0, v121
	v_add_f32_e32 v122, 1.0, v122
	v_add_f32_e32 v123, 1.0, v123
	v_mul_f32_e32 v108, 0xbfb8aa3b, v108
	v_mul_f32_e32 v109, 0xbfb8aa3b, v109
	v_pk_add_f32 v[104:105], v[104:105], v[80:81]
	v_pk_add_f32 v[106:107], v[106:107], v[82:83]
	v_pk_mul_f32 v[142:143], v[224:225], v[142:143]
	v_pk_mul_f32 v[140:141], v[222:223], v[140:141]
	v_add_f32_e32 v126, 1.0, v126
	v_cvt_pk_bf16_f32 v138, v140, v141
	v_cvt_pk_bf16_f32 v139, v142, v143
	global_store_dwordx4 v[218:219], v[136:139], off
	v_add_f32_e32 v127, 1.0, v127
	v_rcp_f32_e32 v120, v120
	v_lshlrev_b32_e32 v136, 16, v209
	v_and_b32_e32 v137, 0xffff0000, v209
	v_rcp_f32_e32 v122, v122
	v_rcp_f32_e32 v123, v123
	v_rcp_f32_e32 v121, v121
	v_exp_f32_e32 v108, v108
	v_pk_add_f32 v[110:111], v[110:111], v[86:87]
	v_exp_f32_e32 v109, v109
	v_mul_f32_e32 v104, 0xbfb8aa3b, v104
	v_mul_f32_e32 v105, 0xbfb8aa3b, v105
	v_mul_f32_e32 v106, 0xbfb8aa3b, v106
	v_mul_f32_e32 v107, 0xbfb8aa3b, v107
	v_pk_mul_f32 v[134:135], v[134:135], v[204:205]
	v_pk_mul_f32 v[132:133], v[132:133], v[202:203]
; __device__ __forceinline__ u32x4 pack8(const f32x4 v0, const f32x4 v1) { u32x4 w; w.x = cvt_pk_bf16(v0[0], v0[1]); w.y = cvt_pk_bf16(v0[2], v0[3]); w.z = cvt_pk_bf16(v1[0], v1[1]); w.w = cvt_pk_bf16(v1[2], v1[3]); return w; }
; __device__ __forceinline__ void unpack8(const u32x4 w, f32x4& v0, f32x4& v1) { v0 = (f32x4){bflo(w.x), bfhi(w.x), bflo(w.y), bfhi(w.y)}; v1 = (f32x4){bflo(w.z), bfhi(w.z), bflo(w.w), bfhi(w.w)}; }
; __device__ __forceinline__ f32x4 sig4(const f32x4 v) { return (f32x4){sigmoidf_(v[0]), sigmoidf_(v[1]), sigmoidf_(v[2]), sigmoidf_(v[3])}; }
;     __device__ __forceinline__ void operator()(const AccT& acc, const pg8::Unit& u, int wr, int wc, int fr, int fq) const {
;     ...
;         for (int ai = 0; ai < 2; ++ai) { u32x4 gw[4][2];
; #pragma unroll
;             for (int m = 0; m < 4; ++m)
; #pragma unroll
;                 for (int bj = 0; bj < 2; ++bj) gw[m][bj] = *(const u32x4*)(G + (size_t)(row0 + ai * 128 + m * 16) * 1024 + col0 + bj * 128);
; #pragma unroll
;             for (int m = 0; m < 4; ++m)
; #pragma unroll
;                 for (int bj = 0; bj < 2; ++bj) { f32x4 g0, g1; unpack8(gw[m][bj], g0, g1);
;                     *(u32x4*)(O + (size_t)(row0 + ai * 128 + m * 16) * 1024 + col0 + bj * 128) = pack8(g0 * sig4(acc[ai][bj][m][0] + bv[bj][0]), g1 * sig4(acc[ai][bj][m][1] + bv[bj][1])); } }
	v_pk_mul_f32 v[136:137], v[130:131], v[136:137]
	v_pk_mul_f32 v[130:131], v[128:129], v[206:207]
	v_cvt_pk_bf16_f32 v128, v132, v133
	v_cvt_pk_bf16_f32 v129, v134, v135
	v_rcp_f32_e32 v126, v126
	v_rcp_f32_e32 v127, v127
	v_mul_f32_e32 v110, 0xbfb8aa3b, v110
	v_mul_f32_e32 v111, 0xbfb8aa3b, v111
	v_exp_f32_e32 v104, v104
	v_exp_f32_e32 v105, v105
	v_exp_f32_e32 v106, v106
	v_exp_f32_e32 v107, v107
	v_cvt_pk_bf16_f32 v130, v130, v131
	v_cvt_pk_bf16_f32 v131, v136, v137
	global_store_dwordx4 v[218:219], v[128:131], off offset:256
	v_add_f32_e32 v116, 1.0, v116
	v_add_f32_e32 v117, 1.0, v117
	v_lshlrev_b32_e32 v128, 16, v210
	v_and_b32_e32 v129, 0xffff0000, v210
	v_add_f32_e32 v118, 1.0, v118
	v_add_f32_e32 v119, 1.0, v119
	v_add_f32_e32 v112, 1.0, v112
	v_add_f32_e32 v113, 1.0, v113
	v_add_f32_e32 v114, 1.0, v114
	v_add_f32_e32 v115, 1.0, v115
	v_exp_f32_e32 v110, v110
	v_exp_f32_e32 v111, v111
	v_pk_add_f32 v[100:101], v[100:101], v[68:69]
	v_pk_add_f32 v[102:103], v[102:103], v[70:71]
	v_pk_add_f32 v[96:97], v[96:97], v[64:65]
	v_pk_add_f32 v[98:99], v[98:99], v[66:67]
	v_lshlrev_b32_e32 v132, 16, v212
	v_and_b32_e32 v133, 0xffff0000, v212
	v_lshlrev_b32_e32 v134, 16, v213
	v_and_b32_e32 v135, 0xffff0000, v213
	v_pk_mul_f32 v[124:125], v[124:125], v[128:129]
	v_rcp_f32_e32 v116, v116
	v_rcp_f32_e32 v117, v117
	v_rcp_f32_e32 v118, v118
	v_rcp_f32_e32 v119, v119
	v_rcp_f32_e32 v112, v112
	v_rcp_f32_e32 v114, v114
	v_rcp_f32_e32 v115, v115
	v_rcp_f32_e32 v113, v113
	v_mul_f32_e32 v100, 0xbfb8aa3b, v100
	v_mul_f32_e32 v101, 0xbfb8aa3b, v101
	v_mul_f32_e32 v102, 0xbfb8aa3b, v102
	v_mul_f32_e32 v103, 0xbfb8aa3b, v103
	v_mul_f32_e32 v96, 0xbfb8aa3b, v96
	v_mul_f32_e32 v97, 0xbfb8aa3b, v97
	v_mul_f32_e32 v98, 0xbfb8aa3b, v98
	v_mul_f32_e32 v99, 0xbfb8aa3b, v99
	v_lshlrev_b32_e32 v130, 16, v211
	v_and_b32_e32 v131, 0xffff0000, v211
	v_pk_mul_f32 v[128:129], v[122:123], v[134:135]
	v_pk_mul_f32 v[122:123], v[120:121], v[132:133]
	v_cvt_pk_bf16_f32 v120, v124, v125
	v_lshl_add_u64 v[124:125], s[4:5], 0, v[190:191]
	v_add_f32_e32 v108, 1.0, v108
	v_add_f32_e32 v109, 1.0, v109
	v_exp_f32_e32 v100, v100
	v_exp_f32_e32 v101, v101
	v_exp_f32_e32 v102, v102
	v_exp_f32_e32 v103, v103
	v_exp_f32_e32 v96, v96
	v_exp_f32_e32 v97, v97
	v_exp_f32_e32 v98, v98
	v_exp_f32_e32 v99, v99
	v_pk_add_f32 v[92:93], v[92:93], v[84:85]
	v_pk_mul_f32 v[126:127], v[126:127], v[130:131]
	v_lshl_add_u64 v[124:125], v[124:125], 0, v[180:181]
	v_cvt_pk_bf16_f32 v121, v126, v127
	v_cvt_pk_bf16_f32 v122, v122, v123
	v_cvt_pk_bf16_f32 v123, v128, v129
	v_rcp_f32_e32 v108, v108
	v_rcp_f32_e32 v109, v109
	v_add_f32_e32 v104, 1.0, v104
	v_add_f32_e32 v105, 1.0, v105
	v_add_f32_e32 v106, 1.0, v106
	v_add_f32_e32 v107, 1.0, v107
	v_mul_f32_e32 v92, 0xbfb8aa3b, v92
	v_mul_f32_e32 v93, 0xbfb8aa3b, v93
	v_pk_add_f32 v[88:89], v[88:89], v[80:81]
	v_pk_add_f32 v[90:91], v[90:91], v[82:83]
	global_store_dwordx4 v[124:125], v[120:123], off
	v_lshlrev_b32_e32 v126, 16, v162
	v_and_b32_e32 v127, 0xffff0000, v162
	v_lshlrev_b32_e32 v120, 16, v160
	v_and_b32_e32 v121, 0xffff0000, v160
	v_lshlrev_b32_e32 v122, 16, v161
	v_and_b32_e32 v123, 0xffff0000, v161
	v_lshlrev_b32_e32 v128, 16, v163
	v_and_b32_e32 v129, 0xffff0000, v163
	v_add_f32_e32 v110, 1.0, v110
	v_add_f32_e32 v111, 1.0, v111
	v_rcp_f32_e32 v104, v104
	v_rcp_f32_e32 v106, v106
	v_rcp_f32_e32 v107, v107
	v_rcp_f32_e32 v105, v105
	v_exp_f32_e32 v92, v92
	v_pk_add_f32 v[94:95], v[94:95], v[86:87]
	v_exp_f32_e32 v93, v93
	v_mul_f32_e32 v88, 0xbfb8aa3b, v88
	v_mul_f32_e32 v89, 0xbfb8aa3b, v89
	v_mul_f32_e32 v90, 0xbfb8aa3b, v90
	v_mul_f32_e32 v91, 0xbfb8aa3b, v91
	v_pk_mul_f32 v[118:119], v[118:119], v[122:123]
	v_pk_mul_f32 v[116:117], v[116:117], v[120:121]
	v_pk_mul_f32 v[120:121], v[114:115], v[128:129]
	v_pk_mul_f32 v[114:115], v[112:113], v[126:127]
	v_cvt_pk_bf16_f32 v112, v116, v117
	v_cvt_pk_bf16_f32 v113, v118, v119
	v_rcp_f32_e32 v110, v110
	v_rcp_f32_e32 v111, v111
	v_mul_f32_e32 v94, 0xbfb8aa3b, v94
	v_mul_f32_e32 v95, 0xbfb8aa3b, v95
	v_exp_f32_e32 v88, v88
	v_exp_f32_e32 v89, v89
	v_exp_f32_e32 v90, v90
	v_exp_f32_e32 v91, v91
	v_cvt_pk_bf16_f32 v114, v114, v115
	v_cvt_pk_bf16_f32 v115, v120, v121
	global_store_dwordx4 v[124:125], v[112:115], off offset:256
	v_add_f32_e32 v100, 1.0, v100
	v_add_f32_e32 v101, 1.0, v101
	v_lshlrev_b32_e32 v112, 16, v156
	v_and_b32_e32 v113, 0xffff0000, v156
	v_add_f32_e32 v102, 1.0, v102
	v_add_f32_e32 v103, 1.0, v103
	v_add_f32_e32 v96, 1.0, v96
	v_add_f32_e32 v97, 1.0, v97
	v_add_f32_e32 v98, 1.0, v98
	v_add_f32_e32 v99, 1.0, v99
	v_exp_f32_e32 v94, v94
	v_exp_f32_e32 v95, v95
	v_pk_add_f32 v[76:77], v[76:77], v[68:69]
	v_lshlrev_b32_e32 v116, 16, v158
	v_and_b32_e32 v117, 0xffff0000, v158
	v_lshlrev_b32_e32 v118, 16, v159
	v_and_b32_e32 v119, 0xffff0000, v159
	v_pk_mul_f32 v[108:109], v[108:109], v[112:113]
	v_rcp_f32_e32 v100, v100
	v_rcp_f32_e32 v101, v101
	v_rcp_f32_e32 v102, v102
	v_rcp_f32_e32 v103, v103
	v_rcp_f32_e32 v96, v96
	v_rcp_f32_e32 v98, v98
	v_rcp_f32_e32 v99, v99
	v_rcp_f32_e32 v97, v97
	v_mul_f32_e32 v76, 0xbfb8aa3b, v76
	v_mul_f32_e32 v77, 0xbfb8aa3b, v77
	v_pk_add_f32 v[72:73], v[72:73], v[64:65]
	v_pk_add_f32 v[74:75], v[74:75], v[66:67]
	v_lshlrev_b32_e32 v114, 16, v157
	v_and_b32_e32 v115, 0xffff0000, v157
	v_pk_mul_f32 v[112:113], v[106:107], v[118:119]
	v_pk_mul_f32 v[106:107], v[104:105], v[116:117]
	v_cvt_pk_bf16_f32 v104, v108, v109
	v_lshl_add_u64 v[108:109], s[4:5], 0, v[188:189]
	v_add_f32_e32 v92, 1.0, v92
	v_add_f32_e32 v93, 1.0, v93
	v_exp_f32_e32 v76, v76
	v_pk_add_f32 v[78:79], v[78:79], v[70:71]
	v_exp_f32_e32 v77, v77
	v_mul_f32_e32 v72, 0xbfb8aa3b, v72
; __device__ __forceinline__ u32x4 pack8(const f32x4 v0, const f32x4 v1) { u32x4 w; w.x = cvt_pk_bf16(v0[0], v0[1]); w.y = cvt_pk_bf16(v0[2], v0[3]); w.z = cvt_pk_bf16(v1[0], v1[1]); w.w = cvt_pk_bf16(v1[2], v1[3]); return w; }
; __device__ __forceinline__ void unpack8(const u32x4 w, f32x4& v0, f32x4& v1) { v0 = (f32x4){bflo(w.x), bfhi(w.x), bflo(w.y), bfhi(w.y)}; v1 = (f32x4){bflo(w.z), bfhi(w.z), bflo(w.w), bfhi(w.w)}; }
; __device__ __forceinline__ f32x4 sig4(const f32x4 v) { return (f32x4){sigmoidf_(v[0]), sigmoidf_(v[1]), sigmoidf_(v[2]), sigmoidf_(v[3])}; }
;     __device__ __forceinline__ void operator()(const AccT& acc, const pg8::Unit& u, int wr, int wc, int fr, int fq) const {
;     ...
;         for (int ai = 0; ai < 2; ++ai) { u32x4 gw[4][2];
; #pragma unroll
;             for (int m = 0; m < 4; ++m)
; #pragma unroll
;                 for (int bj = 0; bj < 2; ++bj) gw[m][bj] = *(const u32x4*)(G + (size_t)(row0 + ai * 128 + m * 16) * 1024 + col0 + bj * 128);
; #pragma unroll
;             for (int m = 0; m < 4; ++m)
; #pragma unroll
;                 for (int bj = 0; bj < 2; ++bj) { f32x4 g0, g1; unpack8(gw[m][bj], g0, g1);
;                     *(u32x4*)(O + (size_t)(row0 + ai * 128 + m * 16) * 1024 + col0 + bj * 128) = pack8(g0 * sig4(acc[ai][bj][m][0] + bv[bj][0]), g1 * sig4(acc[ai][bj][m][1] + bv[bj][1])); } }
	v_mul_f32_e32 v73, 0xbfb8aa3b, v73
	v_mul_f32_e32 v74, 0xbfb8aa3b, v74
	v_mul_f32_e32 v75, 0xbfb8aa3b, v75
	v_pk_mul_f32 v[110:111], v[110:111], v[114:115]
	v_lshl_add_u64 v[108:109], v[108:109], 0, v[180:181]
	v_cvt_pk_bf16_f32 v105, v110, v111
	v_cvt_pk_bf16_f32 v106, v106, v107
	v_cvt_pk_bf16_f32 v107, v112, v113
	v_rcp_f32_e32 v92, v92
	v_rcp_f32_e32 v93, v93
	v_add_f32_e32 v88, 1.0, v88
	v_add_f32_e32 v89, 1.0, v89
	v_add_f32_e32 v90, 1.0, v90
	v_add_f32_e32 v91, 1.0, v91
	v_mul_f32_e32 v78, 0xbfb8aa3b, v78
	v_mul_f32_e32 v79, 0xbfb8aa3b, v79
	v_exp_f32_e32 v72, v72
	v_exp_f32_e32 v73, v73
	v_exp_f32_e32 v74, v74
	v_exp_f32_e32 v75, v75
	global_store_dwordx4 v[108:109], v[104:107], off
	v_lshlrev_b32_e32 v110, 16, v154
	v_and_b32_e32 v111, 0xffff0000, v154
	v_lshlrev_b32_e32 v104, 16, v152
	v_and_b32_e32 v105, 0xffff0000, v152
	v_lshlrev_b32_e32 v106, 16, v153
	v_and_b32_e32 v107, 0xffff0000, v153
	v_lshlrev_b32_e32 v112, 16, v155
	v_and_b32_e32 v113, 0xffff0000, v155
	v_add_f32_e32 v94, 1.0, v94
	v_add_f32_e32 v95, 1.0, v95
	v_rcp_f32_e32 v88, v88
	v_rcp_f32_e32 v90, v90
	v_rcp_f32_e32 v91, v91
	v_rcp_f32_e32 v89, v89
	v_exp_f32_e32 v78, v78
	v_exp_f32_e32 v79, v79
	v_pk_mul_f32 v[102:103], v[102:103], v[106:107]
	v_pk_mul_f32 v[100:101], v[100:101], v[104:105]
	v_pk_mul_f32 v[104:105], v[98:99], v[112:113]
	v_pk_mul_f32 v[98:99], v[96:97], v[110:111]
	v_cvt_pk_bf16_f32 v96, v100, v101
	v_cvt_pk_bf16_f32 v97, v102, v103
	v_rcp_f32_e32 v94, v94
	v_rcp_f32_e32 v95, v95
	v_cvt_pk_bf16_f32 v98, v98, v99
	v_cvt_pk_bf16_f32 v99, v104, v105
	global_store_dwordx4 v[108:109], v[96:99], off offset:256
	v_add_f32_e32 v76, 1.0, v76
	v_add_f32_e32 v77, 1.0, v77
	v_lshlrev_b32_e32 v96, 16, v148
	v_and_b32_e32 v97, 0xffff0000, v148
	v_lshlrev_b32_e32 v100, 16, v150
	v_and_b32_e32 v101, 0xffff0000, v150
	v_lshlrev_b32_e32 v102, 16, v151
	v_and_b32_e32 v103, 0xffff0000, v151
	v_pk_mul_f32 v[92:93], v[92:93], v[96:97]
	v_rcp_f32_e32 v76, v76
	v_rcp_f32_e32 v77, v77
	v_add_f32_e32 v72, 1.0, v72
	v_add_f32_e32 v73, 1.0, v73
	v_add_f32_e32 v74, 1.0, v74
	v_add_f32_e32 v75, 1.0, v75
	v_lshlrev_b32_e32 v98, 16, v149
	v_and_b32_e32 v99, 0xffff0000, v149
	v_pk_mul_f32 v[96:97], v[90:91], v[102:103]
	v_pk_mul_f32 v[90:91], v[88:89], v[100:101]
	v_cvt_pk_bf16_f32 v88, v92, v93
	v_lshl_add_u64 v[92:93], s[4:5], 0, v[186:187]
	v_add_f32_e32 v78, 1.0, v78
	v_add_f32_e32 v79, 1.0, v79
	v_rcp_f32_e32 v72, v72
	v_rcp_f32_e32 v74, v74
	v_rcp_f32_e32 v75, v75
	v_rcp_f32_e32 v73, v73
	v_pk_mul_f32 v[94:95], v[94:95], v[98:99]
	v_lshl_add_u64 v[92:93], v[92:93], 0, v[180:181]
	v_cvt_pk_bf16_f32 v89, v94, v95
	v_rcp_f32_e32 v78, v78
	v_rcp_f32_e32 v79, v79
	v_cvt_pk_bf16_f32 v90, v90, v91
	v_cvt_pk_bf16_f32 v91, v96, v97
	global_store_dwordx4 v[92:93], v[88:91], off
	v_lshlrev_b32_e32 v94, 16, v146
	v_and_b32_e32 v95, 0xffff0000, v146
	v_lshlrev_b32_e32 v88, 16, v144
	v_and_b32_e32 v89, 0xffff0000, v144
	v_lshlrev_b32_e32 v96, 16, v147
	v_and_b32_e32 v97, 0xffff0000, v147
	v_pk_mul_f32 v[76:77], v[76:77], v[88:89]
	v_lshl_add_u64 v[118:119], v[184:185], 0, s[0:1]
	v_lshlrev_b32_e32 v90, 16, v145
	v_and_b32_e32 v91, 0xffff0000, v145
	v_pk_mul_f32 v[88:89], v[74:75], v[96:97]
	v_pk_mul_f32 v[74:75], v[72:73], v[94:95]
	v_cvt_pk_bf16_f32 v72, v76, v77
	v_lshl_add_u64 v[76:77], v[182:183], 0, v[118:119]
	v_pk_mul_f32 v[78:79], v[78:79], v[90:91]
	v_lshl_add_u64 v[104:105], v[184:185], 0, s[16:17]
	v_cvt_pk_bf16_f32 v73, v78, v79
	v_cvt_pk_bf16_f32 v74, v74, v75
	v_cvt_pk_bf16_f32 v75, v88, v89
	global_load_dwordx4 v[106:109], v[76:77], off
	global_load_dwordx4 v[110:113], v[76:77], off offset:256
	v_lshl_add_u64 v[102:103], v[184:185], 0, s[18:19]
	global_store_dwordx4 v[92:93], v[72:75], off offset:256
	v_lshl_add_u64 v[100:101], v[184:185], 0, s[20:21]
	v_pk_add_f32 v[60:61], v[60:61], v[84:85]
	v_lshl_add_u64 v[72:73], v[182:183], 0, v[104:105]
	global_load_dwordx4 v[114:117], v[72:73], off
	global_load_dwordx4 v[96:99], v[72:73], off offset:256
	v_lshl_add_u64 v[72:73], v[182:183], 0, v[102:103]
	global_load_dwordx4 v[92:95], v[72:73], off
	global_load_dwordx4 v[88:91], v[72:73], off offset:256
	v_lshl_add_u64 v[72:73], v[182:183], 0, v[100:101]
	global_load_dwordx4 v[76:79], v[72:73], off
	s_nop 0
	global_load_dwordx4 v[72:75], v[72:73], off offset:256
	v_mul_f32_e32 v60, 0xbfb8aa3b, v60
	v_pk_add_f32 v[62:63], v[62:63], v[86:87]
	v_mul_f32_e32 v61, 0xbfb8aa3b, v61
	v_pk_add_f32 v[56:57], v[56:57], v[80:81]
	v_pk_add_f32 v[58:59], v[58:59], v[82:83]
	v_exp_f32_e32 v60, v60
	v_exp_f32_e32 v61, v61
	v_mul_f32_e32 v62, 0xbfb8aa3b, v62
	v_mul_f32_e32 v63, 0xbfb8aa3b, v63
	v_mul_f32_e32 v56, 0xbfb8aa3b, v56
	v_mul_f32_e32 v57, 0xbfb8aa3b, v57
	v_mul_f32_e32 v58, 0xbfb8aa3b, v58
	v_mul_f32_e32 v59, 0xbfb8aa3b, v59
	v_exp_f32_e32 v62, v62
	v_exp_f32_e32 v63, v63
	v_exp_f32_e32 v56, v56
	v_exp_f32_e32 v57, v57
	v_exp_f32_e32 v58, v58
	v_exp_f32_e32 v59, v59
	v_pk_add_f32 v[52:53], v[52:53], v[68:69]
	v_pk_add_f32 v[54:55], v[54:55], v[70:71]
	v_pk_add_f32 v[48:49], v[48:49], v[64:65]
	v_pk_add_f32 v[50:51], v[50:51], v[66:67]
	v_mul_f32_e32 v52, 0xbfb8aa3b, v52
	v_mul_f32_e32 v53, 0xbfb8aa3b, v53
	v_mul_f32_e32 v54, 0xbfb8aa3b, v54
	v_mul_f32_e32 v55, 0xbfb8aa3b, v55
	v_mul_f32_e32 v48, 0xbfb8aa3b, v48
	v_mul_f32_e32 v49, 0xbfb8aa3b, v49
	v_mul_f32_e32 v50, 0xbfb8aa3b, v50
	v_mul_f32_e32 v51, 0xbfb8aa3b, v51
	v_add_f32_e32 v60, 1.0, v60
	v_add_f32_e32 v61, 1.0, v61
	v_exp_f32_e32 v52, v52
	v_exp_f32_e32 v53, v53
	v_exp_f32_e32 v54, v54
	v_exp_f32_e32 v55, v55
	v_exp_f32_e32 v48, v48
	v_exp_f32_e32 v49, v49
	v_exp_f32_e32 v50, v50
	v_exp_f32_e32 v51, v51
	v_pk_add_f32 v[44:45], v[44:45], v[84:85]
	v_rcp_f32_e32 v60, v60
	v_rcp_f32_e32 v61, v61
	v_add_f32_e32 v62, 1.0, v62
	v_add_f32_e32 v63, 1.0, v63
	v_add_f32_e32 v56, 1.0, v56
	v_add_f32_e32 v57, 1.0, v57
	v_add_f32_e32 v58, 1.0, v58
	v_add_f32_e32 v59, 1.0, v59
	v_mul_f32_e32 v44, 0xbfb8aa3b, v44
	v_mul_f32_e32 v45, 0xbfb8aa3b, v45
	v_pk_add_f32 v[40:41], v[40:41], v[80:81]
	v_pk_add_f32 v[42:43], v[42:43], v[82:83]
	v_rcp_f32_e32 v62, v62
	v_rcp_f32_e32 v63, v63
	v_rcp_f32_e32 v56, v56
	v_rcp_f32_e32 v58, v58
	v_rcp_f32_e32 v59, v59
	v_rcp_f32_e32 v57, v57
	v_exp_f32_e32 v44, v44
	v_pk_add_f32 v[46:47], v[46:47], v[86:87]
	v_exp_f32_e32 v45, v45
	v_mul_f32_e32 v40, 0xbfb8aa3b, v40
	v_mul_f32_e32 v41, 0xbfb8aa3b, v41
	v_mul_f32_e32 v42, 0xbfb8aa3b, v42
	v_mul_f32_e32 v43, 0xbfb8aa3b, v43
	v_mul_f32_e32 v46, 0xbfb8aa3b, v46
	v_mul_f32_e32 v47, 0xbfb8aa3b, v47
	v_exp_f32_e32 v40, v40
	v_exp_f32_e32 v41, v41
	v_exp_f32_e32 v42, v42
	v_exp_f32_e32 v43, v43
	s_waitcnt vmcnt(0)
; __device__ __forceinline__ u32x4 pack8(const f32x4 v0, const f32x4 v1) { u32x4 w; w.x = cvt_pk_bf16(v0[0], v0[1]); w.y = cvt_pk_bf16(v0[2], v0[3]); w.z = cvt_pk_bf16(v1[0], v1[1]); w.w = cvt_pk_bf16(v1[2], v1[3]); return w; }
; __device__ __forceinline__ void unpack8(const u32x4 w, f32x4& v0, f32x4& v1) { v0 = (f32x4){bflo(w.x), bfhi(w.x), bflo(w.y), bfhi(w.y)}; v1 = (f32x4){bflo(w.z), bfhi(w.z), bflo(w.w), bfhi(w.w)}; }
; __device__ __forceinline__ f32x4 sig4(const f32x4 v) { return (f32x4){sigmoidf_(v[0]), sigmoidf_(v[1]), sigmoidf_(v[2]), sigmoidf_(v[3])}; }
;     __device__ __forceinline__ void operator()(const AccT& acc, const pg8::Unit& u, int wr, int wc, int fr, int fq) const {
;     ...
;         for (int ai = 0; ai < 2; ++ai) { u32x4 gw[4][2];
; #pragma unroll
;             for (int m = 0; m < 4; ++m)
; #pragma unroll
;                 for (int bj = 0; bj < 2; ++bj) gw[m][bj] = *(const u32x4*)(G + (size_t)(row0 + ai * 128 + m * 16) * 1024 + col0 + bj * 128);
; #pragma unroll
;             for (int m = 0; m < 4; ++m)
; #pragma unroll
;                 for (int bj = 0; bj < 2; ++bj) { f32x4 g0, g1; unpack8(gw[m][bj], g0, g1);
;                     *(u32x4*)(O + (size_t)(row0 + ai * 128 + m * 16) * 1024 + col0 + bj * 128) = pack8(g0 * sig4(acc[ai][bj][m][0] + bv[bj][0]), g1 * sig4(acc[ai][bj][m][1] + bv[bj][1])); } }
	v_lshlrev_b32_e32 v120, 16, v106
	v_and_b32_e32 v121, 0xffff0000, v106
	v_add_f32_e32 v52, 1.0, v52
	v_add_f32_e32 v53, 1.0, v53
	v_add_f32_e32 v54, 1.0, v54
	v_add_f32_e32 v55, 1.0, v55
	v_add_f32_e32 v48, 1.0, v48
	v_add_f32_e32 v49, 1.0, v49
	v_add_f32_e32 v50, 1.0, v50
	v_add_f32_e32 v51, 1.0, v51
	v_exp_f32_e32 v46, v46
	v_exp_f32_e32 v47, v47
	v_pk_add_f32 v[36:37], v[36:37], v[68:69]
	v_pk_add_f32 v[38:39], v[38:39], v[70:71]
	v_pk_add_f32 v[32:33], v[32:33], v[64:65]
	v_pk_add_f32 v[34:35], v[34:35], v[66:67]
	v_lshlrev_b32_e32 v106, 16, v107
	v_and_b32_e32 v107, 0xffff0000, v107
	v_lshlrev_b32_e32 v122, 16, v108
	v_and_b32_e32 v123, 0xffff0000, v108
	v_lshlrev_b32_e32 v108, 16, v109
	v_and_b32_e32 v109, 0xffff0000, v109
	v_pk_mul_f32 v[60:61], v[60:61], v[120:121]
	v_rcp_f32_e32 v52, v52
	v_rcp_f32_e32 v53, v53
	v_rcp_f32_e32 v54, v54
	v_rcp_f32_e32 v55, v55
	v_rcp_f32_e32 v48, v48
	v_rcp_f32_e32 v50, v50
	v_rcp_f32_e32 v51, v51
	v_rcp_f32_e32 v49, v49
	v_mul_f32_e32 v36, 0xbfb8aa3b, v36
	v_mul_f32_e32 v37, 0xbfb8aa3b, v37
	v_mul_f32_e32 v38, 0xbfb8aa3b, v38
	v_mul_f32_e32 v39, 0xbfb8aa3b, v39
	v_mul_f32_e32 v32, 0xbfb8aa3b, v32
	v_mul_f32_e32 v33, 0xbfb8aa3b, v33
	v_mul_f32_e32 v34, 0xbfb8aa3b, v34
	v_mul_f32_e32 v35, 0xbfb8aa3b, v35
	v_pk_mul_f32 v[62:63], v[62:63], v[106:107]
	v_pk_mul_f32 v[106:107], v[58:59], v[108:109]
	v_pk_mul_f32 v[58:59], v[56:57], v[122:123]
	v_cvt_pk_bf16_f32 v56, v60, v61
	v_lshl_add_u64 v[60:61], s[4:5], 0, v[118:119]
	v_add_f32_e32 v44, 1.0, v44
	v_add_f32_e32 v45, 1.0, v45
	v_exp_f32_e32 v36, v36
	v_exp_f32_e32 v37, v37
	v_exp_f32_e32 v38, v38
	v_exp_f32_e32 v39, v39
	v_exp_f32_e32 v32, v32
	v_exp_f32_e32 v33, v33
	v_exp_f32_e32 v34, v34
	v_exp_f32_e32 v35, v35
	v_pk_add_f32 v[28:29], v[28:29], v[84:85]
	v_cvt_pk_bf16_f32 v57, v62, v63
	v_cvt_pk_bf16_f32 v58, v58, v59
	v_cvt_pk_bf16_f32 v59, v106, v107
	v_lshl_add_u64 v[60:61], v[60:61], 0, v[180:181]
	v_rcp_f32_e32 v44, v44
	v_rcp_f32_e32 v45, v45
	v_add_f32_e32 v40, 1.0, v40
	v_add_f32_e32 v41, 1.0, v41
	v_add_f32_e32 v42, 1.0, v42
	v_add_f32_e32 v43, 1.0, v43
	v_mul_f32_e32 v28, 0xbfb8aa3b, v28
	v_mul_f32_e32 v29, 0xbfb8aa3b, v29
	v_pk_add_f32 v[24:25], v[24:25], v[80:81]
	v_pk_add_f32 v[26:27], v[26:27], v[82:83]
	global_store_dwordx4 v[60:61], v[56:59], off
	v_lshlrev_b32_e32 v62, 16, v112
	v_and_b32_e32 v63, 0xffff0000, v112
	v_lshlrev_b32_e32 v56, 16, v110
	v_and_b32_e32 v57, 0xffff0000, v110
	v_lshlrev_b32_e32 v58, 16, v111
	v_and_b32_e32 v59, 0xffff0000, v111
	v_lshlrev_b32_e32 v106, 16, v113
	v_and_b32_e32 v107, 0xffff0000, v113
	v_add_f32_e32 v46, 1.0, v46
	v_add_f32_e32 v47, 1.0, v47
	v_rcp_f32_e32 v40, v40
	v_rcp_f32_e32 v42, v42
	v_rcp_f32_e32 v43, v43
	v_rcp_f32_e32 v41, v41
	v_exp_f32_e32 v28, v28
	v_pk_add_f32 v[30:31], v[30:31], v[86:87]
	v_exp_f32_e32 v29, v29
	v_mul_f32_e32 v24, 0xbfb8aa3b, v24
	v_mul_f32_e32 v25, 0xbfb8aa3b, v25
	v_mul_f32_e32 v26, 0xbfb8aa3b, v26
	v_mul_f32_e32 v27, 0xbfb8aa3b, v27
	v_pk_mul_f32 v[54:55], v[54:55], v[58:59]
	v_pk_mul_f32 v[52:53], v[52:53], v[56:57]
	v_pk_mul_f32 v[56:57], v[50:51], v[106:107]
	v_pk_mul_f32 v[50:51], v[48:49], v[62:63]
	v_cvt_pk_bf16_f32 v48, v52, v53
	v_cvt_pk_bf16_f32 v49, v54, v55
	v_rcp_f32_e32 v46, v46
	v_rcp_f32_e32 v47, v47
	v_mul_f32_e32 v30, 0xbfb8aa3b, v30
	v_mul_f32_e32 v31, 0xbfb8aa3b, v31
	v_exp_f32_e32 v24, v24
	v_exp_f32_e32 v25, v25
	v_exp_f32_e32 v26, v26
	v_exp_f32_e32 v27, v27
	v_cvt_pk_bf16_f32 v50, v50, v51
	v_cvt_pk_bf16_f32 v51, v56, v57
	global_store_dwordx4 v[60:61], v[48:51], off offset:256
	v_add_f32_e32 v36, 1.0, v36
	v_add_f32_e32 v37, 1.0, v37
	v_lshlrev_b32_e32 v48, 16, v114
	v_and_b32_e32 v49, 0xffff0000, v114
	v_add_f32_e32 v38, 1.0, v38
	v_add_f32_e32 v39, 1.0, v39
	v_add_f32_e32 v32, 1.0, v32
	v_add_f32_e32 v33, 1.0, v33
	v_add_f32_e32 v34, 1.0, v34
	v_add_f32_e32 v35, 1.0, v35
	v_exp_f32_e32 v30, v30
	v_exp_f32_e32 v31, v31
	v_pk_add_f32 v[20:21], v[20:21], v[68:69]
	v_pk_add_f32 v[22:23], v[22:23], v[70:71]
	v_pk_add_f32 v[16:17], v[16:17], v[64:65]
	v_pk_add_f32 v[18:19], v[18:19], v[66:67]
	v_lshlrev_b32_e32 v52, 16, v116
	v_and_b32_e32 v53, 0xffff0000, v116
	v_lshlrev_b32_e32 v54, 16, v117
	v_and_b32_e32 v55, 0xffff0000, v117
	v_pk_mul_f32 v[44:45], v[44:45], v[48:49]
	v_rcp_f32_e32 v36, v36
	v_rcp_f32_e32 v37, v37
	v_rcp_f32_e32 v38, v38
	v_rcp_f32_e32 v39, v39
	v_rcp_f32_e32 v32, v32
	v_rcp_f32_e32 v34, v34
	v_rcp_f32_e32 v35, v35
	v_rcp_f32_e32 v33, v33
	v_mul_f32_e32 v20, 0xbfb8aa3b, v20
	v_mul_f32_e32 v21, 0xbfb8aa3b, v21
	v_mul_f32_e32 v22, 0xbfb8aa3b, v22
	v_mul_f32_e32 v23, 0xbfb8aa3b, v23
	v_mul_f32_e32 v16, 0xbfb8aa3b, v16
	v_mul_f32_e32 v17, 0xbfb8aa3b, v17
	v_mul_f32_e32 v18, 0xbfb8aa3b, v18
	v_mul_f32_e32 v19, 0xbfb8aa3b, v19
	v_lshlrev_b32_e32 v50, 16, v115
	v_and_b32_e32 v51, 0xffff0000, v115
	v_pk_mul_f32 v[48:49], v[42:43], v[54:55]
	v_pk_mul_f32 v[42:43], v[40:41], v[52:53]
	v_cvt_pk_bf16_f32 v40, v44, v45
	v_lshl_add_u64 v[44:45], s[4:5], 0, v[104:105]
	v_add_f32_e32 v28, 1.0, v28
	v_add_f32_e32 v29, 1.0, v29
	v_exp_f32_e32 v20, v20
	v_exp_f32_e32 v21, v21
	v_exp_f32_e32 v22, v22
	v_exp_f32_e32 v23, v23
	v_exp_f32_e32 v16, v16
	v_exp_f32_e32 v17, v17
	v_exp_f32_e32 v18, v18
	v_exp_f32_e32 v19, v19
	v_pk_add_f32 v[12:13], v[12:13], v[84:85]
	v_pk_mul_f32 v[46:47], v[46:47], v[50:51]
	v_lshl_add_u64 v[44:45], v[44:45], 0, v[180:181]
	v_cvt_pk_bf16_f32 v41, v46, v47
	v_cvt_pk_bf16_f32 v42, v42, v43
	v_cvt_pk_bf16_f32 v43, v48, v49
	v_rcp_f32_e32 v28, v28
	v_rcp_f32_e32 v29, v29
	v_add_f32_e32 v24, 1.0, v24
	v_add_f32_e32 v25, 1.0, v25
	v_add_f32_e32 v26, 1.0, v26
	v_add_f32_e32 v27, 1.0, v27
	v_mul_f32_e32 v12, 0xbfb8aa3b, v12
; #define PG8_WAIT_V(n) asm volatile("s_waitcnt vmcnt(" #n ")" ::: "memory")
; #define PG8_BAR __builtin_amdgcn_s_barrier()
; __device__ __forceinline__ u32x4 pack8(const f32x4 v0, const f32x4 v1) { u32x4 w; w.x = cvt_pk_bf16(v0[0], v0[1]); w.y = cvt_pk_bf16(v0[2], v0[3]); w.z = cvt_pk_bf16(v1[0], v1[1]); w.w = cvt_pk_bf16(v1[2], v1[3]); return w; }
; __device__ __forceinline__ void unpack8(const u32x4 w, f32x4& v0, f32x4& v1) { v0 = (f32x4){bflo(w.x), bfhi(w.x), bflo(w.y), bfhi(w.y)}; v1 = (f32x4){bflo(w.z), bfhi(w.z), bflo(w.w), bfhi(w.w)}; }
; __device__ __forceinline__ f32x4 sig4(const f32x4 v) { return (f32x4){sigmoidf_(v[0]), sigmoidf_(v[1]), sigmoidf_(v[2]), sigmoidf_(v[3])}; }
; template <class Epi>
; __device__ __forceinline__ void gemm_phase(LAS unsigned char* lds, const Gemm g, const StaticOrder& S, const Epi& E) {
;     ...
;         E(acc, cur, wr, wc, fr, fq);
;         if (!has_next) break;
; #pragma unroll
;         for (int a = 0; a < 2; ++a)
; #pragma unroll
;             for (int b = 0; b < 2; ++b)
; #pragma unroll
;                 for (int m = 0; m < 4; ++m)
; #pragma unroll
;                     for (int n = 0; n < 2; ++n) acc[a][b][m][n] = (f32x4){0.f, 0.f, 0.f, 0.f};
;         cur = nxt; cA = nA; cB = nB; ++ui;
;     }
;     PG8_WAIT_V(0);
;     if (wr == 0) PG8_BAR;
;     PG8_BAR;
;     __device__ __forceinline__ void operator()(const AccT& acc, const pg8::Unit& u, int wr, int wc, int fr, int fq) const {
;     ...
;         for (int ai = 0; ai < 2; ++ai) { u32x4 gw[4][2];
; #pragma unroll
;             for (int m = 0; m < 4; ++m)
; #pragma unroll
;                 for (int bj = 0; bj < 2; ++bj) gw[m][bj] = *(const u32x4*)(G + (size_t)(row0 + ai * 128 + m * 16) * 1024 + col0 + bj * 128);
; #pragma unroll
;             for (int m = 0; m < 4; ++m)
; #pragma unroll
;                 for (int bj = 0; bj < 2; ++bj) { f32x4 g0, g1; unpack8(gw[m][bj], g0, g1);
;                     *(u32x4*)(O + (size_t)(row0 + ai * 128 + m * 16) * 1024 + col0 + bj * 128) = pack8(g0 * sig4(acc[ai][bj][m][0] + bv[bj][0]), g1 * sig4(acc[ai][bj][m][1] + bv[bj][1])); } }
	v_mul_f32_e32 v13, 0xbfb8aa3b, v13
	v_pk_add_f32 v[8:9], v[8:9], v[80:81]
	v_pk_add_f32 v[10:11], v[10:11], v[82:83]
	global_store_dwordx4 v[44:45], v[40:43], off
	v_lshlrev_b32_e32 v46, 16, v98
	v_and_b32_e32 v47, 0xffff0000, v98
	v_lshlrev_b32_e32 v40, 16, v96
	v_and_b32_e32 v41, 0xffff0000, v96
	v_lshlrev_b32_e32 v42, 16, v97
	v_and_b32_e32 v43, 0xffff0000, v97
	v_lshlrev_b32_e32 v48, 16, v99
	v_and_b32_e32 v49, 0xffff0000, v99
	v_add_f32_e32 v30, 1.0, v30
	v_add_f32_e32 v31, 1.0, v31
	v_rcp_f32_e32 v24, v24
	v_rcp_f32_e32 v26, v26
	v_rcp_f32_e32 v27, v27
	v_rcp_f32_e32 v25, v25
	v_exp_f32_e32 v12, v12
	v_pk_add_f32 v[14:15], v[14:15], v[86:87]
	v_exp_f32_e32 v13, v13
	v_mul_f32_e32 v8, 0xbfb8aa3b, v8
	v_mul_f32_e32 v9, 0xbfb8aa3b, v9
	v_mul_f32_e32 v10, 0xbfb8aa3b, v10
	v_mul_f32_e32 v11, 0xbfb8aa3b, v11
	v_pk_mul_f32 v[38:39], v[38:39], v[42:43]
	v_pk_mul_f32 v[36:37], v[36:37], v[40:41]
	v_pk_mul_f32 v[40:41], v[34:35], v[48:49]
	v_pk_mul_f32 v[34:35], v[32:33], v[46:47]
	v_cvt_pk_bf16_f32 v32, v36, v37
	v_cvt_pk_bf16_f32 v33, v38, v39
	v_rcp_f32_e32 v30, v30
	v_rcp_f32_e32 v31, v31
	v_mul_f32_e32 v14, 0xbfb8aa3b, v14
	v_mul_f32_e32 v15, 0xbfb8aa3b, v15
	v_exp_f32_e32 v8, v8
	v_exp_f32_e32 v9, v9
	v_exp_f32_e32 v10, v10
	v_exp_f32_e32 v11, v11
	v_cvt_pk_bf16_f32 v34, v34, v35
	v_cvt_pk_bf16_f32 v35, v40, v41
	global_store_dwordx4 v[44:45], v[32:35], off offset:256
	v_add_f32_e32 v20, 1.0, v20
	v_add_f32_e32 v21, 1.0, v21
	v_lshlrev_b32_e32 v32, 16, v92
	v_and_b32_e32 v33, 0xffff0000, v92
	v_add_f32_e32 v22, 1.0, v22
	v_add_f32_e32 v23, 1.0, v23
	v_add_f32_e32 v16, 1.0, v16
	v_add_f32_e32 v17, 1.0, v17
	v_add_f32_e32 v18, 1.0, v18
	v_add_f32_e32 v19, 1.0, v19
	v_exp_f32_e32 v14, v14
	v_exp_f32_e32 v15, v15
	v_pk_add_f32 v[4:5], v[4:5], v[68:69]
	v_pk_add_f32 v[0:1], v[0:1], v[64:65]
	v_pk_add_f32 v[2:3], v[2:3], v[66:67]
	v_lshlrev_b32_e32 v36, 16, v94
	v_and_b32_e32 v37, 0xffff0000, v94
	v_lshlrev_b32_e32 v38, 16, v95
	v_and_b32_e32 v39, 0xffff0000, v95
	v_pk_mul_f32 v[28:29], v[28:29], v[32:33]
	v_rcp_f32_e32 v20, v20
	v_rcp_f32_e32 v21, v21
	v_rcp_f32_e32 v22, v22
	v_rcp_f32_e32 v23, v23
	v_rcp_f32_e32 v16, v16
	v_rcp_f32_e32 v18, v18
	v_rcp_f32_e32 v19, v19
	v_rcp_f32_e32 v17, v17
	v_mul_f32_e32 v4, 0xbfb8aa3b, v4
	v_pk_add_f32 v[6:7], v[6:7], v[70:71]
	v_mul_f32_e32 v5, 0xbfb8aa3b, v5
	v_mul_f32_e32 v0, 0xbfb8aa3b, v0
	v_mul_f32_e32 v1, 0xbfb8aa3b, v1
	v_mul_f32_e32 v2, 0xbfb8aa3b, v2
	v_mul_f32_e32 v3, 0xbfb8aa3b, v3
	v_lshlrev_b32_e32 v34, 16, v93
	v_and_b32_e32 v35, 0xffff0000, v93
	v_pk_mul_f32 v[32:33], v[26:27], v[38:39]
	v_pk_mul_f32 v[26:27], v[24:25], v[36:37]
	v_cvt_pk_bf16_f32 v24, v28, v29
	v_lshl_add_u64 v[28:29], s[4:5], 0, v[102:103]
	v_add_f32_e32 v12, 1.0, v12
	v_add_f32_e32 v13, 1.0, v13
	v_exp_f32_e32 v4, v4
	v_exp_f32_e32 v5, v5
	v_mul_f32_e32 v6, 0xbfb8aa3b, v6
	v_mul_f32_e32 v7, 0xbfb8aa3b, v7
	v_exp_f32_e32 v0, v0
	v_exp_f32_e32 v1, v1
	v_exp_f32_e32 v2, v2
	v_exp_f32_e32 v3, v3
	v_pk_mul_f32 v[30:31], v[30:31], v[34:35]
	v_lshl_add_u64 v[28:29], v[28:29], 0, v[180:181]
	v_cvt_pk_bf16_f32 v25, v30, v31
	v_cvt_pk_bf16_f32 v26, v26, v27
	v_cvt_pk_bf16_f32 v27, v32, v33
	v_rcp_f32_e32 v12, v12
	v_rcp_f32_e32 v13, v13
	v_add_f32_e32 v8, 1.0, v8
	v_add_f32_e32 v9, 1.0, v9
	v_add_f32_e32 v10, 1.0, v10
	v_add_f32_e32 v11, 1.0, v11
	v_exp_f32_e32 v6, v6
	v_exp_f32_e32 v7, v7
	global_store_dwordx4 v[28:29], v[24:27], off
	v_lshlrev_b32_e32 v30, 16, v90
	v_and_b32_e32 v31, 0xffff0000, v90
	v_lshlrev_b32_e32 v24, 16, v88
	v_and_b32_e32 v25, 0xffff0000, v88
	v_lshlrev_b32_e32 v26, 16, v89
	v_and_b32_e32 v27, 0xffff0000, v89
	v_lshlrev_b32_e32 v32, 16, v91
	v_and_b32_e32 v33, 0xffff0000, v91
	v_add_f32_e32 v14, 1.0, v14
	v_add_f32_e32 v15, 1.0, v15
	v_rcp_f32_e32 v8, v8
	v_rcp_f32_e32 v10, v10
	v_rcp_f32_e32 v11, v11
	v_rcp_f32_e32 v9, v9
	v_pk_mul_f32 v[22:23], v[22:23], v[26:27]
	v_pk_mul_f32 v[20:21], v[20:21], v[24:25]
	v_pk_mul_f32 v[24:25], v[18:19], v[32:33]
	v_pk_mul_f32 v[18:19], v[16:17], v[30:31]
	v_cvt_pk_bf16_f32 v16, v20, v21
	v_cvt_pk_bf16_f32 v17, v22, v23
	v_rcp_f32_e32 v14, v14
	v_rcp_f32_e32 v15, v15
	v_cvt_pk_bf16_f32 v18, v18, v19
	v_cvt_pk_bf16_f32 v19, v24, v25
	global_store_dwordx4 v[28:29], v[16:19], off offset:256
	v_add_f32_e32 v4, 1.0, v4
	v_add_f32_e32 v5, 1.0, v5
	v_lshlrev_b32_e32 v16, 16, v76
	v_and_b32_e32 v17, 0xffff0000, v76
	v_add_f32_e32 v0, 1.0, v0
	v_add_f32_e32 v1, 1.0, v1
	v_add_f32_e32 v2, 1.0, v2
	v_add_f32_e32 v3, 1.0, v3
	v_lshlrev_b32_e32 v20, 16, v78
	v_and_b32_e32 v21, 0xffff0000, v78
	v_lshlrev_b32_e32 v22, 16, v79
	v_and_b32_e32 v23, 0xffff0000, v79
	v_pk_mul_f32 v[12:13], v[12:13], v[16:17]
	v_rcp_f32_e32 v4, v4
	v_rcp_f32_e32 v5, v5
	v_add_f32_e32 v6, 1.0, v6
	v_add_f32_e32 v7, 1.0, v7
	v_rcp_f32_e32 v0, v0
	v_rcp_f32_e32 v2, v2
	v_rcp_f32_e32 v3, v3
	v_rcp_f32_e32 v1, v1
	v_lshlrev_b32_e32 v18, 16, v77
	v_and_b32_e32 v19, 0xffff0000, v77
	v_pk_mul_f32 v[16:17], v[10:11], v[22:23]
	v_pk_mul_f32 v[10:11], v[8:9], v[20:21]
	v_cvt_pk_bf16_f32 v8, v12, v13
	v_lshl_add_u64 v[12:13], s[4:5], 0, v[100:101]
	v_rcp_f32_e32 v6, v6
	v_rcp_f32_e32 v7, v7
	v_pk_mul_f32 v[14:15], v[14:15], v[18:19]
	v_lshl_add_u64 v[12:13], v[12:13], 0, v[180:181]
	v_cvt_pk_bf16_f32 v9, v14, v15
	v_cvt_pk_bf16_f32 v10, v10, v11
	v_cvt_pk_bf16_f32 v11, v16, v17
	global_store_dwordx4 v[12:13], v[8:11], off
	v_lshlrev_b32_e32 v14, 16, v74
	v_and_b32_e32 v15, 0xffff0000, v74
	v_lshlrev_b32_e32 v8, 16, v72
	v_and_b32_e32 v9, 0xffff0000, v72
	v_lshlrev_b32_e32 v16, 16, v75
	v_and_b32_e32 v17, 0xffff0000, v75
	v_lshlrev_b32_e32 v10, 16, v73
	v_and_b32_e32 v11, 0xffff0000, v73
	v_pk_mul_f32 v[4:5], v[4:5], v[8:9]
	v_pk_mul_f32 v[8:9], v[2:3], v[16:17]
	v_pk_mul_f32 v[2:3], v[0:1], v[14:15]
	v_pk_mul_f32 v[6:7], v[6:7], v[10:11]
	v_cvt_pk_bf16_f32 v0, v4, v5
	s_nop 0
	v_cvt_pk_bf16_f32 v1, v6, v7
	v_cvt_pk_bf16_f32 v2, v2, v3
	v_cvt_pk_bf16_f32 v3, v8, v9
	global_store_dwordx4 v[12:13], v[0:3], off offset:256
	s_cbranch_vccz .LBB0_732
	s_waitcnt vmcnt(0)
	s_cmpk_gt_u32 s33, 0xff
	s_cbranch_scc1 .LBB0_743
	s_barrier

; #define LAS __attribute__((address_space(3)))
; #define PG8_WAIT_V(n) asm volatile("s_waitcnt vmcnt(" #n ")" ::: "memory")
; template <class Epi>
; __device__ __forceinline__ void gemm_phase(LAS unsigned char* lds, const Gemm g, const StaticOrder& S, const Epi& E) {
;     const int tid = threadIdx.x, wid = __builtin_amdgcn_readfirstlane(tid >> 6), lane = tid & 63, wr = wid >> 2, wc = wid & 3, fr = lane & 15, fq = lane >> 4;
;     const int K = g.K, nt = K / BK;
;     unsigned voffA[2], voffB[2];
; #pragma unroll
;     for (int i = 0; i < 2; ++i) { int R, C; stage_rc(tid * 16 + i * 8192, R, C); const int Rb = Epi::PERM ? ((R & ~31) + perm32(R & 31)) : R;
;         voffA[i] = (unsigned)(R * K + C) * 2u; voffB[i] = (unsigned)(Rb * K + C) * 2u; }
;     const size_t kstep = (size_t)(BK * 2);
;     const size_t hstep = (size_t)HALF * K * 2;
;     const size_t tstep = 2 * hstep;
;     const unsigned ldsw = (unsigned)wid * 1024u;
;     const int aoff = lds_byte(wr * 64 + fr, fq * 8), boff = lds_byte(wc * 32 + fr, fq * 8);
;     ...
;     Unit cur, nxt; int ui = 0;
;     if (!S.next(0, cur)) return;
;     f32x4 acc[2][2][4][2];
; #pragma unroll
;     for (int a = 0; a < 2; ++a)
; #pragma unroll
;         for (int b = 0; b < 2; ++b)
; #pragma unroll
;             for (int m = 0; m < 4; ++m)
; #pragma unroll
;                 for (int n = 0; n < 2; ++n) acc[a][b][m][n] = (f32x4){0.f, 0.f, 0.f, 0.f};
;     bf16x8 At[4][2], B0[2][2], B1[2][2];
;     const char* cA = (const char*)g.A + (size_t)cur.pm * tstep; const char* cB = (const char*)g.Bt + (size_t)cur.pn * tstep;
;     PG8_STAGE(PG8_SB(0, 0), cB, voffB); PG8_STAGE(PG8_SA(0, 0), cA, voffA); PG8_STAGE(PG8_SB(0, 1), cB + hstep, voffB); PG8_STAGE(PG8_SA(0, 1), cA + hstep, voffA);
;     if (wr == 1) PG8_BAR;
;     PG8_WAIT_V(4); PG8_BAR;
;     PG8_STAGE(PG8_SB(1, 0), cB + kstep, voffB); PG8_STAGE(PG8_SA(1, 0), cA + kstep, voffA); PG8_STAGE(PG8_SB(1, 1), cB + hstep + kstep, voffB);
;     PG8_WAIT_V(6); PG8_BAR;
; __global__ void __launch_bounds__(512, 2) fwd(Params P) {
;     ...
;     if (IN(6)) for (int rep_ = 0; rep_ < NREP(6); ++rep_) { pg8::StaticOrder S; S.init(ROW_S, D, gridDim.x, blockIdx.x);
;         { pg8::Gemm g{(const bf16_t*)(ws + O_YA), (const bf16_t*)(ws + O_WAT), ROW_S, D, 1024}; EpiUpA E{(const bf16_t*)(ws + O_PROJ), (bf16_t*)(ws + O_TMP)}; pg8::gemm_phase<EpiUpA>((LAS unsigned char*)shm, g, S, E); }
.Lp6_gemm:
	v_lshrrev_b32_e32 v2, 5, v214
	v_lshrrev_b32_e32 v4, 1, v214
	s_add_u32 s0, s12, 0x4542000
	v_and_b32_e32 v2, 4, v2
	v_bfe_u32 v3, v214, 2, 2
	v_and_b32_e32 v180, 24, v4
	s_addc_u32 s1, s13, 0
	v_lshlrev_b32_e32 v0, 4, v214
	v_and_b32_e32 v1, 32, v214
	v_bfe_u32 v170, v214, 2, 4
	v_or3_b32 v2, v2, v3, v180
	v_lshrrev_b32_e32 v3, 3, v214
	s_movk_i32 s2, 0x70
	s_add_u32 s4, s12, 0x13e42000
	v_bitop3_b32 v168, v0, v1, 48 bitop3:0x6c
	v_and_b32_e32 v169, 64, v214
	v_and_or_b32 v4, v3, s2, v170
	s_movk_i32 s2, 0x60
	v_add_u32_e32 v171, 0x2000, v0
	s_addc_u32 s5, s13, 0
	v_or_b32_e32 v1, v168, v169
	v_and_or_b32 v3, v3, s2, v2
	v_lshrrev_b32_e32 v0, 7, v171
	s_movk_i32 s2, 0xf0
	s_ashr_i32 s33, s94, 31
	v_lshl_or_b32 v174, v3, 11, v1
	v_and_or_b32 v3, v0, s2, v170
	s_movk_i32 s2, 0xe0
	s_cmpk_lt_i32 s94, 0x100
	v_and_or_b32 v0, v0, s2, v2
	s_cselect_b64 s[6:7], -1, 0
	s_lshr_b32 s2, s33, 24
	s_add_i32 s2, s94, s2
	s_and_b32 s2, s2, 0xff00
	s_sub_i32 s2, s94, s2
	s_sext_i32_i16 s3, s2
	s_bfe_u32 s3, s3, 0x3001c
	s_add_i32 s3, s2, s3
	s_sext_i32_i16 s8, s3
	s_and_b32 s3, s3, 0xfff8
	s_sub_i32 s47, s2, s3
	s_ashr_i32 s40, s96, 31
	s_lshr_b32 s45, s8, 3
	s_sext_i32_i16 s2, s47
	v_lshl_or_b32 v172, v4, 11, v1
	v_lshl_or_b32 v176, v3, 11, v1
	v_lshl_or_b32 v178, v0, 11, v1
	v_lshlrev_b32_e32 v0, 6, v214
	v_lshlrev_b32_e32 v1, 2, v214
	s_cmp_lt_i32 s2, 0
	v_lshlrev_b32_e32 v181, 1, v180
	v_and_b32_e32 v0, 0x3c0, v0
	v_and_b32_e32 v1, 32, v1
	s_cselect_b64 s[8:9], -1, 0
	s_lshl_b32 s46, s47, 5
	v_mov_b32_e32 v175, 0
	v_and_b32_e32 v202, 15, v214
	v_bitop3_b32 v182, v181, v1, v0 bitop3:0x36
	s_cmpk_gt_i32 s94, 0xff
	v_mov_b32_e32 v179, v175
	v_mov_b32_e32 v173, v175
	v_mov_b32_e32 v177, v175
	s_mul_i32 s47, s47, 33
	v_readfirstlane_b32 s41, v214
	s_cbranch_scc1 .LBB0_919
	s_add_u32 s42, s12, 0x3180000
	s_addc_u32 s43, s13, 0
	s_add_u32 s44, s12, 0xdbc2000
	s_addc_u32 s48, s13, 0
	s_lshr_b32 s10, s41, 6
	s_lshr_b32 s3, s41, 8
	s_lshl_b32 s49, s10, 10
	s_and_b64 s[16:17], s[8:9], exec
	s_cselect_b32 s2, s47, s46
	s_add_i32 s2, s2, s45
	s_sext_i32_i16 s11, s2
	s_bfe_u32 s11, s11, 0x60019
	s_add_i32 s11, s2, s11
	s_sext_i32_i16 s16, s11
	s_and_b32 s11, s11, 0xffc0
	s_sub_i32 s11, s2, s11
	s_bfe_i32 s2, s11, 0x80000
	s_bfe_u32 s2, s2, 0x3000c
	s_add_i32 s17, s11, s2
	s_bfe_i32 s2, s17, 0x80000
	s_and_b32 s17, s17, 0xf8
	s_ashr_i32 s16, s16, 6
	s_sub_i32 s11, s11, s17
	s_lshl_b32 s16, s16, 3
	s_sext_i32_i16 s2, s2
	s_sext_i32_i8 s11, s11
	s_lshr_b32 s2, s2, 3
	s_add_i32 s26, s16, s11
	s_ashr_i32 s27, s26, 31
	s_bfe_i64 s[18:19], s[2:3], 0x100000
	s_lshl_b64 s[16:17], s[26:27], 19
	s_lshl_b64 s[18:19], s[18:19], 19
	s_add_u32 s30, s44, s18
	s_addc_u32 s31, s48, s19
	s_add_i32 s27, s49, 0
	s_add_i32 m0, s27, 0x10000
	v_lshl_add_u64 v[0:1], s[30:31], 0, v[174:175]
	global_load_lds_dwordx4 v[0:1], off
	s_add_i32 m0, s27, 0x12000
	s_add_u32 s28, s42, s16
	v_lshl_add_u64 v[2:3], s[30:31], 0, v[178:179]
	s_addc_u32 s29, s43, s17
	s_add_i32 s50, s27, 0x2000
	global_load_lds_dwordx4 v[2:3], off
	v_lshl_add_u64 v[6:7], s[28:29], 0, v[172:173]
	s_mov_b32 m0, s27
	s_add_u32 s16, s30, 0x40000
	global_load_lds_dwordx4 v[6:7], off
	v_lshl_add_u64 v[4:5], s[28:29], 0, v[176:177]
	s_mov_b32 m0, s50
	s_addc_u32 s17, s31, 0
	global_load_lds_dwordx4 v[4:5], off
	s_add_i32 m0, s27, 0x14000
	s_nop 0
	global_load_lds_dwordx4 v174, s[16:17]
	s_add_i32 m0, s27, 0x16000
	v_lshl_add_u64 v[8:9], s[16:17], 0, v[178:179]
	s_add_u32 s16, s28, 0x40000
	s_addc_u32 s17, s29, 0
	s_add_i32 s51, s27, 0x4000
	global_load_lds_dwordx4 v[8:9], off
	s_nop 0
	s_mov_b32 m0, s51
	s_add_i32 s54, s27, 0x6000
	global_load_lds_dwordx4 v172, s[16:17]
	v_lshl_add_u64 v[8:9], s[16:17], 0, v[176:177]
	s_mov_b32 m0, s54
	s_cmp_lg_u32 s3, 1
	global_load_lds_dwordx4 v[8:9], off
	s_cbranch_scc1 .LBB0_906
	s_barrier
.LBB0_906:
	s_lshl_b32 s10, s10, 5
	s_and_b32 s19, s10, 0x60
	s_mov_b64 s[10:11], 0x80
	s_add_i32 m0, s27, 0x18000
	v_lshl_add_u64 v[0:1], v[0:1], 0, s[10:11]
	s_lshl_b32 s18, s3, 13
	s_waitcnt vmcnt(4)
	s_barrier
	global_load_lds_dwordx4 v[0:1], off
	v_lshl_add_u64 v[0:1], v[2:3], 0, s[10:11]
	s_add_i32 m0, s27, 0x1a000
	s_add_i32 s55, s27, 0x8000
	s_add_i32 s56, s27, 0xa000
	global_load_lds_dwordx4 v[0:1], off
	v_lshl_add_u64 v[0:1], v[6:7], 0, s[10:11]
	s_mov_b32 m0, s55
	s_add_u32 s16, s30, 0x40080
	global_load_lds_dwordx4 v[0:1], off
	v_lshl_add_u64 v[0:1], v[4:5], 0, s[10:11]
	s_mov_b32 m0, s56
	s_addc_u32 s17, s31, 0
	global_load_lds_dwordx4 v[0:1], off
	s_add_i32 m0, s27, 0x1c000
	s_nop 0
	global_load_lds_dwordx4 v174, s[16:17]
	v_lshl_add_u64 v[0:1], s[16:17], 0, v[178:179]
	s_add_i32 m0, s27, 0x1e000
	v_lshlrev_b32_e32 v2, 11, v170
	global_load_lds_dwordx4 v[0:1], off
	v_lshlrev_b32_e32 v1, 2, v202
	v_lshl_or_b32 v0, v202, 6, v181
	v_and_b32_e32 v1, 32, v1
	v_bitop3_b32 v0, v0, s18, v1 bitop3:0xde
	v_lshlrev_b32_e32 v1, 8, v214
	v_and_b32_e32 v1, 0x38000, v1
	v_or3_b32 v1, v168, v1, v2
	v_add_u32_e32 v148, v1, v169
	v_lshlrev_b32_e32 v1, 4, v171
	s_waitcnt vmcnt(6)
	v_and_b32_e32 v1, 0x78000, v1
	v_lshl_or_b32 v184, s19, 7, v182
	v_mov_b32_e32 v149, 0
	v_or3_b32 v1, v168, v1, v2
	s_add_i32 s58, 0, 0x10000
	s_add_i32 s59, 0, 0x14000
	s_sext_i32_i8 s62, s2
	v_lshl_or_b32 v183, s3, 6, v202
	s_mov_b32 s57, 0
	v_or_b32_e32 v185, s19, v180
	v_add_u32_e32 v150, v1, v169
	v_mov_b32_e32 v151, v149
	v_mov_b64_e32 v[152:153], 0x100
	v_mov_b64_e32 v[154:155], 0xff
	v_add_u32_e32 v186, s58, v184
	v_add_u32_e32 v187, 0, v0
	v_add_u32_e32 v188, s59, v184
	s_movk_i32 s60, 0x2000
	s_movk_i32 s61, 0x4800
	s_mov_b64 s[16:17], 0x2800
	s_barrier

; #define PG8_STAGE(bufoff, gbase, voff) do { _Pragma("unroll") for (int _i = 0; _i < 2; ++_i) \
;         __builtin_amdgcn_global_load_lds((const unsigned*)((const char*)(gbase) + (voff)[_i]), (LAS unsigned*)(lds + (bufoff) + ldsw + _i * 8192), 16, 0, 0); } while (0)
; #define PG8_LDA(dst, b, h) do { _Pragma("unroll") for (int m = 0; m < 4; ++m) _Pragma("unroll") for (int k = 0; k < 2; ++k) dst[m][k] = *(const LAS bf16x8*)(lds + PG8_SA(b, h) + aoff + m * 2048 + k * 1024); } while (0)
; #define PG8_WAIT_V(n) asm volatile("s_waitcnt vmcnt(" #n ")" ::: "memory")
; #define PG8_WAIT_L(n) asm volatile("s_waitcnt lgkmcnt(" #n ")" ::: "memory")
; template <class Epi>
; __device__ __forceinline__ void gemm_phase(LAS unsigned char* lds, const Gemm g, const StaticOrder& S, const Epi& E) {
;     ...
;         for (int t = 0; t < nt; t += 2) {
;             const bool last = (t == nt - 2);
;             const char* a1 = cA + (size_t)(t + 1) * kstep;
;             const char* a2 = last ? nA : cA + (size_t)(t + 2) * kstep; const char* b2 = last ? nB : cB + (size_t)(t + 2) * kstep;
;             const char* a3 = a2 + kstep; const char* b3 = b2 + kstep;
;             PG8_LDB(B0, 0, 0); PG8_SCHED; PG8_LDA(At, 0, 0); PG8_STAGE(PG8_SA(1, 1), a1 + hstep, voffA);
;             PG8_WAIT_L(8); PG8_BAR; PG8_WAIT_L(0); PG8_MMA(0, 0, At, B0); PG8_BAR; PG8_SCHED;
;             PG8_LDB(B1, 0, 1); PG8_STAGE(PG8_SB(0, 0), b2, voffB);
;             PG8_BAR; PG8_WAIT_L(0); PG8_MMA(0, 1, At, B1); PG8_BAR;
;             PG8_LDA(At, 0, 1); PG8_STAGE(PG8_SA(0, 0), a2, voffA);
;             PG8_BAR; PG8_WAIT_L(0); PG8_MMA(1, 0, At, B0); PG8_BAR; PG8_SCHED;
;             PG8_STAGE(PG8_SB(0, 1), b2 + hstep, voffB);
;             PG8_WAIT_V(6); PG8_BAR; PG8_MMA(1, 1, At, B1); PG8_BAR;
;             PG8_LDB(B0, 1, 0); PG8_SCHED; PG8_LDA(At, 1, 0); PG8_STAGE(PG8_SA(0, 1), a2 + hstep, voffA);
;             PG8_WAIT_L(8); PG8_BAR; PG8_WAIT_L(0); PG8_MMA(0, 0, At, B0); PG8_BAR; PG8_SCHED;
;             PG8_LDB(B1, 1, 1); PG8_STAGE(PG8_SB(1, 0), b3, voffB);
;             PG8_BAR; PG8_WAIT_L(0); PG8_MMA(0, 1, At, B1); PG8_BAR;
;             PG8_LDA(At, 1, 1); PG8_STAGE(PG8_SA(1, 0), a3, voffA);
;             PG8_BAR; PG8_WAIT_L(0); PG8_MMA(1, 0, At, B0); PG8_BAR; PG8_SCHED;
;             PG8_STAGE(PG8_SB(1, 1), b3 + hstep, voffB);
;             PG8_WAIT_V(6); PG8_BAR; PG8_MMA(1, 1, At, B1); PG8_BAR;
.LBB0_914:
	ds_read_b128 v[128:131], v186
	ds_read_b128 v[132:135], v186 offset:1024
	ds_read_b128 v[136:139], v186 offset:2048
	ds_read_b128 v[140:143], v186 offset:3072
	s_add_u32 s30, s28, 0xfffc0080
	s_addc_u32 s31, s29, -1
	s_cmp_eq_u32 s67, 12
	s_cselect_b32 s35, s19, s31
	s_cselect_b32 s34, s63, s30
	s_cselect_b32 s31, s21, s66
	s_cselect_b32 s30, s64, s65
	s_nop 0
	s_add_i32 m0, s27, 0xc000
	ds_read_b128 v[144:147], v187
	ds_read_b128 v[156:159], v187 offset:1024
	ds_read_b128 v[160:163], v187 offset:2048
	ds_read_b128 v[164:167], v187 offset:3072
	ds_read_b128 v[190:193], v187 offset:4096
	ds_read_b128 v[194:197], v187 offset:5120
	ds_read_b128 v[198:201], v187 offset:6144
	ds_read_b128 v[204:207], v187 offset:7168
	global_load_lds_dwordx4 v148, s[28:29]
	s_nop 0
	s_add_i32 m0, s27, 0xe000
	s_nop 0
	global_load_lds_dwordx4 v150, s[28:29]
	s_waitcnt lgkmcnt(8)
	s_barrier
	s_waitcnt lgkmcnt(0)
	s_waitcnt lgkmcnt(0)
	v_mfma_f32_16x16x32_bf16 v[124:127], v[128:131], v[144:147], v[124:127]
	v_mfma_f32_16x16x32_bf16 v[120:123], v[136:139], v[144:147], v[120:123]
	v_mfma_f32_16x16x32_bf16 v[108:111], v[128:131], v[160:163], v[108:111]
	v_mfma_f32_16x16x32_bf16 v[104:107], v[136:139], v[160:163], v[104:107]
	v_mfma_f32_16x16x32_bf16 v[92:95], v[128:131], v[190:193], v[92:95]
	v_mfma_f32_16x16x32_bf16 v[88:91], v[136:139], v[190:193], v[88:91]
	v_mfma_f32_16x16x32_bf16 v[76:79], v[128:131], v[198:201], v[76:79]
	v_mfma_f32_16x16x32_bf16 v[72:75], v[136:139], v[198:201], v[72:75]
	v_mfma_f32_16x16x32_bf16 v[124:127], v[132:135], v[156:159], v[124:127]
	v_mfma_f32_16x16x32_bf16 v[120:123], v[140:143], v[156:159], v[120:123]
	v_mfma_f32_16x16x32_bf16 v[108:111], v[132:135], v[164:167], v[108:111]
	v_mfma_f32_16x16x32_bf16 v[104:107], v[140:143], v[164:167], v[104:107]
	v_mfma_f32_16x16x32_bf16 v[92:95], v[132:135], v[194:197], v[92:95]
	v_mfma_f32_16x16x32_bf16 v[88:91], v[140:143], v[194:197], v[88:91]
	v_mfma_f32_16x16x32_bf16 v[76:79], v[132:135], v[204:207], v[76:79]
	v_mfma_f32_16x16x32_bf16 v[72:75], v[140:143], v[204:207], v[72:75]
	s_barrier
	s_add_i32 s69, s58, s49
	v_lshl_add_u64 v[212:213], s[30:31], 0, v[174:175]
	s_mov_b32 m0, s69
	ds_read_b128 v[208:211], v188
	ds_read_b128 v[216:219], v188 offset:1024
	ds_read_b128 v[220:223], v188 offset:2048
	ds_read_b128 v[224:227], v188 offset:3072
	global_load_lds_dwordx4 v[212:213], off
	v_lshl_add_u64 v[228:229], s[30:31], 0, v[178:179]
	s_add_i32 m0, s69, 0x2000
	s_nop 0
	global_load_lds_dwordx4 v[228:229], off
	s_barrier
	s_waitcnt lgkmcnt(0)
	s_waitcnt lgkmcnt(0)
	v_mfma_f32_16x16x32_bf16 v[116:119], v[208:211], v[144:147], v[116:119]
	v_mfma_f32_16x16x32_bf16 v[112:115], v[220:223], v[144:147], v[112:115]
	v_mfma_f32_16x16x32_bf16 v[100:103], v[208:211], v[160:163], v[100:103]
	v_mfma_f32_16x16x32_bf16 v[96:99], v[220:223], v[160:163], v[96:99]
	v_mfma_f32_16x16x32_bf16 v[84:87], v[208:211], v[190:193], v[84:87]
	v_mfma_f32_16x16x32_bf16 v[80:83], v[220:223], v[190:193], v[80:83]
	v_mfma_f32_16x16x32_bf16 v[68:71], v[208:211], v[198:201], v[68:71]
	v_mfma_f32_16x16x32_bf16 v[64:67], v[220:223], v[198:201], v[64:67]
	v_mfma_f32_16x16x32_bf16 v[116:119], v[216:219], v[156:159], v[116:119]
	v_mfma_f32_16x16x32_bf16 v[112:115], v[224:227], v[156:159], v[112:115]
	v_mfma_f32_16x16x32_bf16 v[100:103], v[216:219], v[164:167], v[100:103]
	v_mfma_f32_16x16x32_bf16 v[96:99], v[224:227], v[164:167], v[96:99]
	v_mfma_f32_16x16x32_bf16 v[84:87], v[216:219], v[194:197], v[84:87]
	v_mfma_f32_16x16x32_bf16 v[80:83], v[224:227], v[194:197], v[80:83]
	v_mfma_f32_16x16x32_bf16 v[68:71], v[216:219], v[204:207], v[68:71]
	v_mfma_f32_16x16x32_bf16 v[64:67], v[224:227], v[204:207], v[64:67]
	s_mov_b32 m0, s27
	v_lshl_add_u64 v[230:231], s[34:35], 0, v[172:173]
	s_barrier
	ds_read_b128 v[144:147], v187 offset:16384
	ds_read_b128 v[156:159], v187 offset:17408
	ds_read_b128 v[160:163], v187 offset:18432
	ds_read_b128 v[164:167], v187 offset:19456
	ds_read_b128 v[190:193], v187 offset:20480
	ds_read_b128 v[194:197], v187 offset:21504
	ds_read_b128 v[198:201], v187 offset:22528
	ds_read_b128 v[204:207], v187 offset:23552
	global_load_lds_dwordx4 v[230:231], off
	v_lshl_add_u64 v[232:233], s[34:35], 0, v[176:177]
	s_mov_b32 m0, s50
	s_nop 0
	global_load_lds_dwordx4 v[232:233], off
	s_barrier
	s_waitcnt lgkmcnt(0)
	s_waitcnt lgkmcnt(0)
	v_mfma_f32_16x16x32_bf16 v[60:63], v[128:131], v[144:147], v[60:63]
	v_mfma_f32_16x16x32_bf16 v[56:59], v[136:139], v[144:147], v[56:59]
	v_mfma_f32_16x16x32_bf16 v[44:47], v[128:131], v[160:163], v[44:47]
	v_mfma_f32_16x16x32_bf16 v[40:43], v[136:139], v[160:163], v[40:43]
	v_mfma_f32_16x16x32_bf16 v[28:31], v[128:131], v[190:193], v[28:31]
	v_mfma_f32_16x16x32_bf16 v[24:27], v[136:139], v[190:193], v[24:27]
	v_mfma_f32_16x16x32_bf16 v[12:15], v[128:131], v[198:201], v[12:15]
	v_mfma_f32_16x16x32_bf16 v[8:11], v[136:139], v[198:201], v[8:11]
	v_mfma_f32_16x16x32_bf16 v[60:63], v[132:135], v[156:159], v[60:63]
	v_mfma_f32_16x16x32_bf16 v[56:59], v[140:143], v[156:159], v[56:59]
	v_mfma_f32_16x16x32_bf16 v[44:47], v[132:135], v[164:167], v[44:47]
	v_mfma_f32_16x16x32_bf16 v[40:43], v[140:143], v[164:167], v[40:43]
	v_mfma_f32_16x16x32_bf16 v[28:31], v[132:135], v[194:197], v[28:31]
	v_mfma_f32_16x16x32_bf16 v[24:27], v[140:143], v[194:197], v[24:27]
	v_mfma_f32_16x16x32_bf16 v[12:15], v[132:135], v[204:207], v[12:15]
	v_mfma_f32_16x16x32_bf16 v[8:11], v[140:143], v[204:207], v[8:11]
	s_barrier
	s_add_u32 s70, s30, 0x40000
	s_addc_u32 s71, s31, 0
	s_add_i32 s69, s59, s49
	s_nop 0
	s_mov_b32 m0, s69
	s_nop 0
	global_load_lds_dwordx4 v174, s[70:71]
	s_nop 0
	s_add_i32 m0, s69, 0x2000
	s_nop 0
	global_load_lds_dwordx4 v178, s[70:71]
	s_waitcnt vmcnt(6)
	s_barrier
; #define PG8_STAGE(bufoff, gbase, voff) do { _Pragma("unroll") for (int _i = 0; _i < 2; ++_i) \
;         __builtin_amdgcn_global_load_lds((const unsigned*)((const char*)(gbase) + (voff)[_i]), (LAS unsigned*)(lds + (bufoff) + ldsw + _i * 8192), 16, 0, 0); } while (0)
; #define PG8_LDA(dst, b, h) do { _Pragma("unroll") for (int m = 0; m < 4; ++m) _Pragma("unroll") for (int k = 0; k < 2; ++k) dst[m][k] = *(const LAS bf16x8*)(lds + PG8_SA(b, h) + aoff + m * 2048 + k * 1024); } while (0)
; #define PG8_WAIT_V(n) asm volatile("s_waitcnt vmcnt(" #n ")" ::: "memory")
; #define PG8_WAIT_L(n) asm volatile("s_waitcnt lgkmcnt(" #n ")" ::: "memory")
; template <class Epi>
; __device__ __forceinline__ void gemm_phase(LAS unsigned char* lds, const Gemm g, const StaticOrder& S, const Epi& E) {
;     ...
;         for (int t = 0; t < nt; t += 2) {
;             const bool last = (t == nt - 2);
;             const char* a1 = cA + (size_t)(t + 1) * kstep;
;             const char* a2 = last ? nA : cA + (size_t)(t + 2) * kstep; const char* b2 = last ? nB : cB + (size_t)(t + 2) * kstep;
;             const char* a3 = a2 + kstep; const char* b3 = b2 + kstep;
;             PG8_LDB(B0, 0, 0); PG8_SCHED; PG8_LDA(At, 0, 0); PG8_STAGE(PG8_SA(1, 1), a1 + hstep, voffA);
;             PG8_WAIT_L(8); PG8_BAR; PG8_WAIT_L(0); PG8_MMA(0, 0, At, B0); PG8_BAR; PG8_SCHED;
;             PG8_LDB(B1, 0, 1); PG8_STAGE(PG8_SB(0, 0), b2, voffB);
;             PG8_BAR; PG8_WAIT_L(0); PG8_MMA(0, 1, At, B1); PG8_BAR;
;             PG8_LDA(At, 0, 1); PG8_STAGE(PG8_SA(0, 0), a2, voffA);
;             PG8_BAR; PG8_WAIT_L(0); PG8_MMA(1, 0, At, B0); PG8_BAR; PG8_SCHED;
;             PG8_STAGE(PG8_SB(0, 1), b2 + hstep, voffB);
;             PG8_WAIT_V(6); PG8_BAR; PG8_MMA(1, 1, At, B1); PG8_BAR;
;             PG8_LDB(B0, 1, 0); PG8_SCHED; PG8_LDA(At, 1, 0); PG8_STAGE(PG8_SA(0, 1), a2 + hstep, voffA);
;             PG8_WAIT_L(8); PG8_BAR; PG8_WAIT_L(0); PG8_MMA(0, 0, At, B0); PG8_BAR; PG8_SCHED;
;             PG8_LDB(B1, 1, 1); PG8_STAGE(PG8_SB(1, 0), b3, voffB);
;             PG8_BAR; PG8_WAIT_L(0); PG8_MMA(0, 1, At, B1); PG8_BAR;
;             PG8_LDA(At, 1, 1); PG8_STAGE(PG8_SA(1, 0), a3, voffA);
;             PG8_BAR; PG8_WAIT_L(0); PG8_MMA(1, 0, At, B0); PG8_BAR; PG8_SCHED;
;             PG8_STAGE(PG8_SB(1, 1), b3 + hstep, voffB);
;             PG8_WAIT_V(6); PG8_BAR; PG8_MMA(1, 1, At, B1); PG8_BAR;
	v_mfma_f32_16x16x32_bf16 v[52:55], v[208:211], v[144:147], v[52:55]
	v_mfma_f32_16x16x32_bf16 v[48:51], v[220:223], v[144:147], v[48:51]
	v_mfma_f32_16x16x32_bf16 v[36:39], v[208:211], v[160:163], v[36:39]
	v_mfma_f32_16x16x32_bf16 v[32:35], v[220:223], v[160:163], v[32:35]
	v_mfma_f32_16x16x32_bf16 v[20:23], v[208:211], v[190:193], v[20:23]
	v_mfma_f32_16x16x32_bf16 v[16:19], v[220:223], v[190:193], v[16:19]
	v_mfma_f32_16x16x32_bf16 v[4:7], v[208:211], v[198:201], v[4:7]
	v_mfma_f32_16x16x32_bf16 v[0:3], v[220:223], v[198:201], v[0:3]
	v_mfma_f32_16x16x32_bf16 v[52:55], v[216:219], v[156:159], v[52:55]
	v_mfma_f32_16x16x32_bf16 v[48:51], v[224:227], v[156:159], v[48:51]
	v_mfma_f32_16x16x32_bf16 v[36:39], v[216:219], v[164:167], v[36:39]
	v_mfma_f32_16x16x32_bf16 v[32:35], v[224:227], v[164:167], v[32:35]
	v_mfma_f32_16x16x32_bf16 v[20:23], v[216:219], v[194:197], v[20:23]
	v_mfma_f32_16x16x32_bf16 v[16:19], v[224:227], v[194:197], v[16:19]
	v_mfma_f32_16x16x32_bf16 v[4:7], v[216:219], v[204:207], v[4:7]
	v_mfma_f32_16x16x32_bf16 v[0:3], v[224:227], v[204:207], v[0:3]
	s_add_i32 s69, 0, 0x18000
	v_add_u32_e32 v140, s69, v184
	s_barrier
	ds_read_b128 v[128:131], v140
	ds_read_b128 v[132:135], v140 offset:1024
	ds_read_b128 v[136:139], v140 offset:2048
	ds_read_b128 v[140:143], v140 offset:3072
	s_add_u32 s34, s34, 0x40000
	s_addc_u32 s35, s35, 0
	s_mov_b32 m0, s51
	s_nop 0
	ds_read_b128 v[144:147], v187 offset:32768
	ds_read_b128 v[156:159], v187 offset:33792
	ds_read_b128 v[160:163], v187 offset:34816
	ds_read_b128 v[164:167], v187 offset:35840
	ds_read_b128 v[190:193], v187 offset:36864
	ds_read_b128 v[194:197], v187 offset:37888
	ds_read_b128 v[198:201], v187 offset:38912
	ds_read_b128 v[204:207], v187 offset:39936
	global_load_lds_dwordx4 v172, s[34:35]
	s_nop 0
	s_mov_b32 m0, s54
	s_nop 0
	global_load_lds_dwordx4 v176, s[34:35]
	s_waitcnt lgkmcnt(8)
	s_barrier
	s_waitcnt lgkmcnt(0)
	s_waitcnt lgkmcnt(0)
	v_mfma_f32_16x16x32_bf16 v[124:127], v[128:131], v[144:147], v[124:127]
	v_mfma_f32_16x16x32_bf16 v[120:123], v[136:139], v[144:147], v[120:123]
	v_mfma_f32_16x16x32_bf16 v[108:111], v[128:131], v[160:163], v[108:111]
	v_mfma_f32_16x16x32_bf16 v[104:107], v[136:139], v[160:163], v[104:107]
	v_mfma_f32_16x16x32_bf16 v[92:95], v[128:131], v[190:193], v[92:95]
	v_mfma_f32_16x16x32_bf16 v[88:91], v[136:139], v[190:193], v[88:91]
	v_mfma_f32_16x16x32_bf16 v[76:79], v[128:131], v[198:201], v[76:79]
	v_mfma_f32_16x16x32_bf16 v[72:75], v[136:139], v[198:201], v[72:75]
	v_mfma_f32_16x16x32_bf16 v[124:127], v[132:135], v[156:159], v[124:127]
	v_mfma_f32_16x16x32_bf16 v[120:123], v[140:143], v[156:159], v[120:123]
	v_mfma_f32_16x16x32_bf16 v[108:111], v[132:135], v[164:167], v[108:111]
	v_mfma_f32_16x16x32_bf16 v[104:107], v[140:143], v[164:167], v[104:107]
	v_mfma_f32_16x16x32_bf16 v[92:95], v[132:135], v[194:197], v[92:95]
	v_mfma_f32_16x16x32_bf16 v[88:91], v[140:143], v[194:197], v[88:91]
	v_mfma_f32_16x16x32_bf16 v[76:79], v[132:135], v[204:207], v[76:79]
	v_mfma_f32_16x16x32_bf16 v[72:75], v[140:143], v[204:207], v[72:75]
	s_barrier
	s_add_i32 s34, 0, 0x1c000
	s_add_i32 s35, s69, s49
	v_add_u32_e32 v189, s34, v184
	v_lshl_add_u64 v[212:213], v[212:213], 0, s[10:11]
	s_mov_b32 m0, s35
	ds_read_b128 v[208:211], v189
	ds_read_b128 v[216:219], v189 offset:1024
	ds_read_b128 v[220:223], v189 offset:2048
	ds_read_b128 v[224:227], v189 offset:3072
	global_load_lds_dwordx4 v[212:213], off
	v_lshl_add_u64 v[212:213], v[228:229], 0, s[10:11]
	s_add_i32 m0, s35, 0x2000
	s_nop 0
	global_load_lds_dwordx4 v[212:213], off
	s_barrier
	s_waitcnt lgkmcnt(0)
	s_waitcnt lgkmcnt(0)
	v_mfma_f32_16x16x32_bf16 v[116:119], v[208:211], v[144:147], v[116:119]
	v_mfma_f32_16x16x32_bf16 v[112:115], v[220:223], v[144:147], v[112:115]
	v_mfma_f32_16x16x32_bf16 v[100:103], v[208:211], v[160:163], v[100:103]
	v_mfma_f32_16x16x32_bf16 v[96:99], v[220:223], v[160:163], v[96:99]
	v_mfma_f32_16x16x32_bf16 v[84:87], v[208:211], v[190:193], v[84:87]
	v_mfma_f32_16x16x32_bf16 v[80:83], v[220:223], v[190:193], v[80:83]
	v_mfma_f32_16x16x32_bf16 v[68:71], v[208:211], v[198:201], v[68:71]
	v_mfma_f32_16x16x32_bf16 v[64:67], v[220:223], v[198:201], v[64:67]
	v_mfma_f32_16x16x32_bf16 v[116:119], v[216:219], v[156:159], v[116:119]
	v_mfma_f32_16x16x32_bf16 v[112:115], v[224:227], v[156:159], v[112:115]
	v_mfma_f32_16x16x32_bf16 v[100:103], v[216:219], v[164:167], v[100:103]
	v_mfma_f32_16x16x32_bf16 v[96:99], v[224:227], v[164:167], v[96:99]
	v_mfma_f32_16x16x32_bf16 v[84:87], v[216:219], v[194:197], v[84:87]
	v_mfma_f32_16x16x32_bf16 v[80:83], v[224:227], v[194:197], v[80:83]
	v_mfma_f32_16x16x32_bf16 v[68:71], v[216:219], v[204:207], v[68:71]
	v_mfma_f32_16x16x32_bf16 v[64:67], v[224:227], v[204:207], v[64:67]
	s_mov_b32 m0, s55
	v_lshl_add_u64 v[212:213], v[230:231], 0, s[10:11]
	s_barrier
	ds_read_b128 v[144:147], v187 offset:49152
	ds_read_b128 v[156:159], v187 offset:50176
	ds_read_b128 v[160:163], v187 offset:51200
	ds_read_b128 v[164:167], v187 offset:52224
	ds_read_b128 v[190:193], v187 offset:53248
	ds_read_b128 v[194:197], v187 offset:54272
	ds_read_b128 v[198:201], v187 offset:55296
	ds_read_b128 v[204:207], v187 offset:56320
	global_load_lds_dwordx4 v[212:213], off
	v_lshl_add_u64 v[212:213], v[232:233], 0, s[10:11]
	s_mov_b32 m0, s56
	s_nop 0
	global_load_lds_dwordx4 v[212:213], off
	s_barrier
; #define PG8_LDA(dst, b, h) do { _Pragma("unroll") for (int m = 0; m < 4; ++m) _Pragma("unroll") for (int k = 0; k < 2; ++k) dst[m][k] = *(const LAS bf16x8*)(lds + PG8_SA(b, h) + aoff + m * 2048 + k * 1024); } while (0)
; template <class Epi>
; __device__ __forceinline__ void gemm_phase(LAS unsigned char* lds, const Gemm g, const StaticOrder& S, const Epi& E) {
;     ...
;         for (int t = 0; t < nt; t += 2) {
;             const bool last = (t == nt - 2);
;             const char* a1 = cA + (size_t)(t + 1) * kstep;
;             const char* a2 = last ? nA : cA + (size_t)(t + 2) * kstep; const char* b2 = last ? nB : cB + (size_t)(t + 2) * kstep;
;             const char* a3 = a2 + kstep; const char* b3 = b2 + kstep;
;             PG8_LDB(B0, 0, 0); PG8_SCHED; PG8_LDA(At, 0, 0); PG8_STAGE(PG8_SA(1, 1), a1 + hstep, voffA);
;             PG8_WAIT_L(8); PG8_BAR; PG8_WAIT_L(0); PG8_MMA(0, 0, At, B0); PG8_BAR; PG8_SCHED;
;             PG8_LDB(B1, 0, 1); PG8_STAGE(PG8_SB(0, 0), b2, voffB);
;             PG8_BAR; PG8_WAIT_L(0); PG8_MMA(0, 1, At, B1); PG8_BAR;
;             PG8_LDA(At, 0, 1); PG8_STAGE(PG8_SA(0, 0), a2, voffA);
;             PG8_BAR; PG8_WAIT_L(0); PG8_MMA(1, 0, At, B0); PG8_BAR; PG8_SCHED;
;             PG8_STAGE(PG8_SB(0, 1), b2 + hstep, voffB);
;             PG8_WAIT_V(6); PG8_BAR; PG8_MMA(1, 1, At, B1); PG8_BAR;
;             PG8_LDB(B0, 1, 0); PG8_SCHED; PG8_LDA(At, 1, 0); PG8_STAGE(PG8_SA(0, 1), a2 + hstep, voffA);
;             PG8_WAIT_L(8); PG8_BAR; PG8_WAIT_L(0); PG8_MMA(0, 0, At, B0); PG8_BAR; PG8_SCHED;
;             PG8_LDB(B1, 1, 1); PG8_STAGE(PG8_SB(1, 0), b3, voffB);
;             PG8_BAR; PG8_WAIT_L(0); PG8_MMA(0, 1, At, B1); PG8_BAR;
;             PG8_LDA(At, 1, 1); PG8_STAGE(PG8_SA(1, 0), a3, voffA);
;             PG8_BAR; PG8_WAIT_L(0); PG8_MMA(1, 0, At, B0); PG8_BAR; PG8_SCHED;
;             PG8_STAGE(PG8_SB(1, 1), b3 + hstep, voffB);
;             PG8_WAIT_V(6); PG8_BAR; PG8_MMA(1, 1, At, B1); PG8_BAR;
;     __device__ __forceinline__ void operator()(const AccT& acc, const pg8::Unit& u, int wr, int wc, int fr, int fq) const {
;     ...
;         for (int ai = 0; ai < 2; ++ai) { u32x4 gw[4][2];
; #pragma unroll
;             for (int m = 0; m < 4; ++m)
; #pragma unroll
;                 for (int bj = 0; bj < 2; ++bj) gw[m][bj] = *(const u32x4*)(PROJ + (size_t)(row0 + ai * 128 + m * 16) * NPROJ + C_GA + col0 + bj * 128);
	s_waitcnt lgkmcnt(0)
	s_waitcnt lgkmcnt(0)
	v_mfma_f32_16x16x32_bf16 v[60:63], v[128:131], v[144:147], v[60:63]
	v_mfma_f32_16x16x32_bf16 v[56:59], v[136:139], v[144:147], v[56:59]
	v_mfma_f32_16x16x32_bf16 v[44:47], v[128:131], v[160:163], v[44:47]
	v_mfma_f32_16x16x32_bf16 v[40:43], v[136:139], v[160:163], v[40:43]
	v_mfma_f32_16x16x32_bf16 v[28:31], v[128:131], v[190:193], v[28:31]
	v_mfma_f32_16x16x32_bf16 v[24:27], v[136:139], v[190:193], v[24:27]
	v_mfma_f32_16x16x32_bf16 v[12:15], v[128:131], v[198:201], v[12:15]
	v_mfma_f32_16x16x32_bf16 v[8:11], v[136:139], v[198:201], v[8:11]
	v_mfma_f32_16x16x32_bf16 v[60:63], v[132:135], v[156:159], v[60:63]
	v_mfma_f32_16x16x32_bf16 v[56:59], v[140:143], v[156:159], v[56:59]
	v_mfma_f32_16x16x32_bf16 v[44:47], v[132:135], v[164:167], v[44:47]
	v_mfma_f32_16x16x32_bf16 v[40:43], v[140:143], v[164:167], v[40:43]
	v_mfma_f32_16x16x32_bf16 v[28:31], v[132:135], v[194:197], v[28:31]
	v_mfma_f32_16x16x32_bf16 v[24:27], v[140:143], v[194:197], v[24:27]
	v_mfma_f32_16x16x32_bf16 v[12:15], v[132:135], v[204:207], v[12:15]
	v_mfma_f32_16x16x32_bf16 v[8:11], v[140:143], v[204:207], v[8:11]
	s_barrier
	s_add_u32 s30, s30, 0x40080
	s_addc_u32 s31, s31, 0
	s_add_i32 s34, s34, s49
	s_nop 0
	s_mov_b32 m0, s34
	s_nop 0
	global_load_lds_dwordx4 v174, s[30:31]
	v_lshl_add_u64 v[128:129], s[30:31], 0, v[178:179]
	s_add_i32 m0, s34, 0x2000
	s_nop 0
	global_load_lds_dwordx4 v[128:129], off
	s_waitcnt vmcnt(6)
	s_barrier
	v_mfma_f32_16x16x32_bf16 v[52:55], v[208:211], v[144:147], v[52:55]
	v_mfma_f32_16x16x32_bf16 v[48:51], v[220:223], v[144:147], v[48:51]
	v_mfma_f32_16x16x32_bf16 v[36:39], v[208:211], v[160:163], v[36:39]
	v_mfma_f32_16x16x32_bf16 v[32:35], v[220:223], v[160:163], v[32:35]
	v_mfma_f32_16x16x32_bf16 v[20:23], v[208:211], v[190:193], v[20:23]
	v_mfma_f32_16x16x32_bf16 v[16:19], v[220:223], v[190:193], v[16:19]
	v_mfma_f32_16x16x32_bf16 v[4:7], v[208:211], v[198:201], v[4:7]
	v_mfma_f32_16x16x32_bf16 v[0:3], v[220:223], v[198:201], v[0:3]
	v_mfma_f32_16x16x32_bf16 v[52:55], v[216:219], v[156:159], v[52:55]
	v_mfma_f32_16x16x32_bf16 v[48:51], v[224:227], v[156:159], v[48:51]
	v_mfma_f32_16x16x32_bf16 v[36:39], v[216:219], v[164:167], v[36:39]
	v_mfma_f32_16x16x32_bf16 v[32:35], v[224:227], v[164:167], v[32:35]
	v_mfma_f32_16x16x32_bf16 v[20:23], v[216:219], v[194:197], v[20:23]
	v_mfma_f32_16x16x32_bf16 v[16:19], v[224:227], v[194:197], v[16:19]
	v_mfma_f32_16x16x32_bf16 v[4:7], v[216:219], v[204:207], v[4:7]
	v_mfma_f32_16x16x32_bf16 v[0:3], v[224:227], v[204:207], v[0:3]
	s_add_i32 s67, s67, 2
	s_add_u32 s28, s28, 0x100
	s_addc_u32 s29, s29, 0
	s_add_u32 s65, s65, 0x100
	s_addc_u32 s66, s66, 0
	s_cmp_gt_u32 s67, 13
	s_barrier
	s_cbranch_scc0 .LBB0_914
	v_lshl_or_b32 v128, s62, 8, v185
	v_lshl_add_u32 v158, s26, 8, v183
	v_ashrrev_i32_e32 v129, 31, v128
	v_mov_b64_e32 v[160:161], s[0:1]
	v_mad_i64_i32 v[130:131], s[28:29], v158, s61, v[160:161]
	v_lshlrev_b64 v[156:157], 1, v[128:129]
	v_lshl_add_u64 v[128:129], v[130:131], 0, v[156:157]
	v_add_co_u32_e32 v130, vcc, 0x2000, v128
	v_or_b32_e32 v166, 16, v158
	s_nop 0
	v_addc_co_u32_e32 v131, vcc, 0, v129, vcc
	global_load_dwordx4 v[190:193], v[130:131], off offset:2048
	v_lshl_add_u64 v[128:129], v[128:129], 0, s[16:17]
	global_load_dwordx4 v[194:197], v[128:129], off offset:256
	v_or_b32_e32 v164, 32, v158
	v_or_b32_e32 v162, 48, v158
	v_mad_i64_i32 v[130:131], s[28:29], v166, s61, v[160:161]
	v_mad_i64_i32 v[132:133], s[28:29], v164, s61, v[160:161]
	v_mad_i64_i32 v[134:135], s[28:29], v162, s61, v[160:161]
	v_lshl_add_u64 v[128:129], v[130:131], 0, v[156:157]
	v_lshl_add_u64 v[130:131], v[132:133], 0, v[156:157]
	v_lshl_add_u64 v[132:133], v[134:135], 0, v[156:157]
	v_lshl_add_u64 v[134:135], v[128:129], 0, s[16:17]
	v_add_co_u32_e32 v128, vcc, 0x2000, v128
	v_lshl_add_u64 v[136:137], v[130:131], 0, s[16:17]
	s_nop 0
	v_addc_co_u32_e32 v129, vcc, 0, v129, vcc
	global_load_dwordx4 v[198:201], v[128:129], off offset:2048
	global_load_dwordx4 v[144:147], v[134:135], off offset:256
	v_add_co_u32_e32 v130, vcc, 0x2000, v130
	v_ashrrev_i32_e32 v159, 31, v158
	s_nop 0
	v_addc_co_u32_e32 v131, vcc, 0, v131, vcc
	global_load_dwordx4 v[140:143], v[130:131], off offset:2048
	s_nop 0
	global_load_dwordx4 v[136:139], v[136:137], off offset:256
	v_add_co_u32_e32 v128, vcc, 0x2000, v132
	v_lshlrev_b64 v[204:205], 12, v[158:159]
	v_lshl_add_u64 v[206:207], v[132:133], 0, s[16:17]
	v_addc_co_u32_e32 v129, vcc, 0, v133, vcc
	global_load_dwordx4 v[132:135], v[128:129], off offset:2048
	s_nop 0
	global_load_dwordx4 v[128:131], v[206:207], off offset:256
	v_ashrrev_i32_e32 v167, 31, v166
	v_ashrrev_i32_e32 v165, 31, v164
	v_ashrrev_i32_e32 v163, 31, v162
	s_mov_b32 s62, s20
	s_mov_b32 s26, s18
	s_mov_b64 s[30:31], s[24:25]
	s_waitcnt vmcnt(0)
; __device__ __forceinline__ u32x4 pack8(const f32x4 v0, const f32x4 v1) { u32x4 w; w.x = cvt_pk_bf16(v0[0], v0[1]); w.y = cvt_pk_bf16(v0[2], v0[3]); w.z = cvt_pk_bf16(v1[0], v1[1]); w.w = cvt_pk_bf16(v1[2], v1[3]); return w; }
; __device__ __forceinline__ void unpack8(const u32x4 w, f32x4& v0, f32x4& v1) { v0 = (f32x4){bflo(w.x), bfhi(w.x), bflo(w.y), bfhi(w.y)}; v1 = (f32x4){bflo(w.z), bfhi(w.z), bflo(w.w), bfhi(w.w)}; }
; __device__ __forceinline__ f32x4 sig4(const f32x4 v) { return (f32x4){sigmoidf_(v[0]), sigmoidf_(v[1]), sigmoidf_(v[2]), sigmoidf_(v[3])}; }
;     __device__ __forceinline__ void operator()(const AccT& acc, const pg8::Unit& u, int wr, int wc, int fr, int fq) const {
;         const int row0 = u.pm * 256 + wr * 64 + fr, col0 = u.pn * 256 + wc * 32 + 8 * fq;
; #pragma unroll
;         for (int ai = 0; ai < 2; ++ai) { u32x4 gw[4][2];
; #pragma unroll
;             for (int m = 0; m < 4; ++m)
; #pragma unroll
;                 for (int bj = 0; bj < 2; ++bj) gw[m][bj] = *(const u32x4*)(PROJ + (size_t)(row0 + ai * 128 + m * 16) * NPROJ + C_GA + col0 + bj * 128);
; #pragma unroll
;             for (int m = 0; m < 4; ++m)
; #pragma unroll
;                 for (int bj = 0; bj < 2; ++bj) { f32x4 g0, g1; unpack8(gw[m][bj], g0, g1);
;                     *(u32x4*)(T + (size_t)(row0 + ai * 128 + m * 16) * D + col0 + bj * 128) = pack8(sig4(g0) * acc[ai][bj][m][0], sig4(g1) * acc[ai][bj][m][1]); } }
;     }
	v_lshlrev_b32_e32 v159, 16, v190
	v_and_b32_e32 v189, 0xffff0000, v190
	v_lshlrev_b32_e32 v190, 16, v191
	v_and_b32_e32 v191, 0xffff0000, v191
	v_lshlrev_b32_e32 v203, 16, v192
	v_and_b32_e32 v192, 0xffff0000, v192
	v_lshlrev_b32_e32 v206, 16, v193
	v_and_b32_e32 v193, 0xffff0000, v193
	v_mul_f32_e32 v159, 0xbfb8aa3b, v159
	v_mul_f32_e32 v189, 0xbfb8aa3b, v189
	v_mul_f32_e32 v190, 0xbfb8aa3b, v190
	v_mul_f32_e32 v191, 0xbfb8aa3b, v191
	v_mul_f32_e32 v203, 0xbfb8aa3b, v203
	v_mul_f32_e32 v192, 0xbfb8aa3b, v192
	v_mul_f32_e32 v206, 0xbfb8aa3b, v206
	v_mul_f32_e32 v193, 0xbfb8aa3b, v193
	v_exp_f32_e32 v159, v159
	v_exp_f32_e32 v189, v189
	v_exp_f32_e32 v190, v190
	v_exp_f32_e32 v191, v191
	v_exp_f32_e32 v203, v203
	v_exp_f32_e32 v192, v192
	v_exp_f32_e32 v206, v206
	v_exp_f32_e32 v193, v193
	v_add_f32_e32 v159, 1.0, v159
	v_add_f32_e32 v189, 1.0, v189
	v_add_f32_e32 v207, 1.0, v190
	v_add_f32_e32 v208, 1.0, v191
	v_add_f32_e32 v203, 1.0, v203
	v_add_f32_e32 v210, 1.0, v192
	v_add_f32_e32 v209, 1.0, v206
	v_add_f32_e32 v211, 1.0, v193
	v_rcp_f32_e32 v190, v159
	v_rcp_f32_e32 v191, v189
	v_rcp_f32_e32 v192, v207
	v_rcp_f32_e32 v193, v208
	v_rcp_f32_e32 v206, v203
	v_rcp_f32_e32 v208, v209
	v_rcp_f32_e32 v209, v211
	v_rcp_f32_e32 v207, v210
	v_pk_mul_f32 v[124:125], v[124:125], v[190:191]
	v_pk_mul_f32 v[126:127], v[126:127], v[192:193]
	v_pk_mul_f32 v[190:191], v[122:123], v[208:209]
	v_pk_mul_f32 v[122:123], v[120:121], v[206:207]
	v_cvt_pk_bf16_f32 v120, v124, v125
	v_lshl_add_u64 v[124:125], s[4:5], 0, v[204:205]
	v_cvt_pk_bf16_f32 v121, v126, v127
	v_lshl_add_u64 v[124:125], v[124:125], 0, v[156:157]
	v_lshlrev_b32_e32 v159, 16, v197
	v_cvt_pk_bf16_f32 v122, v122, v123
	v_cvt_pk_bf16_f32 v123, v190, v191
	global_store_dwordx4 v[124:125], v[120:123], off
	v_lshlrev_b32_e32 v126, 16, v196
	v_and_b32_e32 v127, 0xffff0000, v196
	v_lshlrev_b32_e32 v120, 16, v194
	v_and_b32_e32 v121, 0xffff0000, v194
	v_and_b32_e32 v189, 0xffff0000, v197
	v_mul_f32_e32 v159, 0xbfb8aa3b, v159
	v_lshlrev_b32_e32 v122, 16, v195
	v_and_b32_e32 v123, 0xffff0000, v195
	v_mul_f32_e32 v120, 0xbfb8aa3b, v120
	v_mul_f32_e32 v121, 0xbfb8aa3b, v121
	v_mul_f32_e32 v126, 0xbfb8aa3b, v126
	v_mul_f32_e32 v127, 0xbfb8aa3b, v127
	v_exp_f32_e32 v159, v159
	v_mul_f32_e32 v189, 0xbfb8aa3b, v189
	v_exp_f32_e32 v120, v120
	v_exp_f32_e32 v121, v121
	v_mul_f32_e32 v122, 0xbfb8aa3b, v122
	v_mul_f32_e32 v123, 0xbfb8aa3b, v123
	v_exp_f32_e32 v126, v126
	v_exp_f32_e32 v127, v127
	v_exp_f32_e32 v189, v189
	v_exp_f32_e32 v122, v122
	v_exp_f32_e32 v123, v123
	v_add_f32_e32 v159, 1.0, v159
	v_add_f32_e32 v120, 1.0, v120
	v_add_f32_e32 v121, 1.0, v121
	v_add_f32_e32 v126, 1.0, v126
	v_add_f32_e32 v127, 1.0, v127
	v_rcp_f32_e32 v190, v159
	v_add_f32_e32 v159, 1.0, v189
	v_rcp_f32_e32 v120, v120
	v_rcp_f32_e32 v121, v121
	v_add_f32_e32 v122, 1.0, v122
	v_add_f32_e32 v123, 1.0, v123
	v_rcp_f32_e32 v126, v126
	v_rcp_f32_e32 v191, v159
	v_rcp_f32_e32 v127, v127
	v_rcp_f32_e32 v122, v122
	v_rcp_f32_e32 v123, v123
	v_pk_mul_f32 v[116:117], v[116:117], v[120:121]
	v_pk_mul_f32 v[120:121], v[114:115], v[190:191]
	v_pk_mul_f32 v[114:115], v[112:113], v[126:127]
	v_pk_mul_f32 v[118:119], v[118:119], v[122:123]
	v_cvt_pk_bf16_f32 v112, v116, v117
	v_lshlrev_b32_e32 v116, 16, v199
	v_cvt_pk_bf16_f32 v113, v118, v119
	v_cvt_pk_bf16_f32 v114, v114, v115
	v_cvt_pk_bf16_f32 v115, v120, v121
	global_store_dwordx4 v[124:125], v[112:115], off offset:256
	v_lshlrev_b32_e32 v118, 16, v200
	v_and_b32_e32 v119, 0xffff0000, v200
	v_lshlrev_b32_e32 v114, 16, v198
	v_and_b32_e32 v115, 0xffff0000, v198
	v_mul_f32_e32 v114, 0xbfb8aa3b, v114
	v_lshlrev_b32_e32 v120, 16, v201
	v_and_b32_e32 v121, 0xffff0000, v201
	v_mul_f32_e32 v115, 0xbfb8aa3b, v115
	v_and_b32_e32 v117, 0xffff0000, v199
	v_exp_f32_e32 v114, v114
	v_exp_f32_e32 v115, v115
	v_mul_f32_e32 v118, 0xbfb8aa3b, v118
	v_mul_f32_e32 v119, 0xbfb8aa3b, v119
	v_mul_f32_e32 v120, 0xbfb8aa3b, v120
	v_mul_f32_e32 v121, 0xbfb8aa3b, v121
	v_mul_f32_e32 v116, 0xbfb8aa3b, v116
	v_mul_f32_e32 v117, 0xbfb8aa3b, v117
	v_exp_f32_e32 v118, v118
	v_exp_f32_e32 v119, v119
	v_exp_f32_e32 v120, v120
	v_exp_f32_e32 v121, v121
	v_exp_f32_e32 v116, v116
	v_exp_f32_e32 v117, v117
	v_add_f32_e32 v114, 1.0, v114
	v_add_f32_e32 v115, 1.0, v115
	v_rcp_f32_e32 v114, v114
	v_rcp_f32_e32 v115, v115
	v_add_f32_e32 v118, 1.0, v118
	v_add_f32_e32 v119, 1.0, v119
	v_add_f32_e32 v120, 1.0, v120
	v_add_f32_e32 v121, 1.0, v121
	v_add_f32_e32 v116, 1.0, v116
	v_add_f32_e32 v117, 1.0, v117
	v_rcp_f32_e32 v118, v118
	v_rcp_f32_e32 v120, v120
	v_rcp_f32_e32 v121, v121
	v_rcp_f32_e32 v119, v119
	v_rcp_f32_e32 v116, v116
	v_rcp_f32_e32 v117, v117
	v_lshlrev_b64 v[112:113], 12, v[166:167]
	v_pk_mul_f32 v[108:109], v[108:109], v[114:115]
	v_pk_mul_f32 v[114:115], v[106:107], v[120:121]
	v_pk_mul_f32 v[106:107], v[104:105], v[118:119]
	v_cvt_pk_bf16_f32 v104, v108, v109
	v_lshl_add_u64 v[108:109], s[4:5], 0, v[112:113]
	v_pk_mul_f32 v[110:111], v[110:111], v[116:117]
	v_lshl_add_u64 v[108:109], v[108:109], 0, v[156:157]
	v_cvt_pk_bf16_f32 v105, v110, v111
	v_cvt_pk_bf16_f32 v106, v106, v107
	v_cvt_pk_bf16_f32 v107, v114, v115
	global_store_dwordx4 v[108:109], v[104:107], off
	v_lshlrev_b32_e32 v110, 16, v146
	v_and_b32_e32 v111, 0xffff0000, v146
	v_lshlrev_b32_e32 v104, 16, v144
	v_and_b32_e32 v105, 0xffff0000, v144
	v_lshlrev_b32_e32 v112, 16, v147
	v_and_b32_e32 v113, 0xffff0000, v147
	v_lshlrev_b32_e32 v106, 16, v145
	v_and_b32_e32 v107, 0xffff0000, v145
	v_mul_f32_e32 v104, 0xbfb8aa3b, v104
	v_mul_f32_e32 v105, 0xbfb8aa3b, v105
	v_mul_f32_e32 v110, 0xbfb8aa3b, v110
	v_mul_f32_e32 v111, 0xbfb8aa3b, v111
; __device__ __forceinline__ u32x4 pack8(const f32x4 v0, const f32x4 v1) { u32x4 w; w.x = cvt_pk_bf16(v0[0], v0[1]); w.y = cvt_pk_bf16(v0[2], v0[3]); w.z = cvt_pk_bf16(v1[0], v1[1]); w.w = cvt_pk_bf16(v1[2], v1[3]); return w; }
; __device__ __forceinline__ void unpack8(const u32x4 w, f32x4& v0, f32x4& v1) { v0 = (f32x4){bflo(w.x), bfhi(w.x), bflo(w.y), bfhi(w.y)}; v1 = (f32x4){bflo(w.z), bfhi(w.z), bflo(w.w), bfhi(w.w)}; }
; __device__ __forceinline__ f32x4 sig4(const f32x4 v) { return (f32x4){sigmoidf_(v[0]), sigmoidf_(v[1]), sigmoidf_(v[2]), sigmoidf_(v[3])}; }
;     __device__ __forceinline__ void operator()(const AccT& acc, const pg8::Unit& u, int wr, int wc, int fr, int fq) const {
;         const int row0 = u.pm * 256 + wr * 64 + fr, col0 = u.pn * 256 + wc * 32 + 8 * fq;
; #pragma unroll
;         for (int ai = 0; ai < 2; ++ai) { u32x4 gw[4][2];
; #pragma unroll
;             for (int m = 0; m < 4; ++m)
; #pragma unroll
;                 for (int bj = 0; bj < 2; ++bj) gw[m][bj] = *(const u32x4*)(PROJ + (size_t)(row0 + ai * 128 + m * 16) * NPROJ + C_GA + col0 + bj * 128);
; #pragma unroll
;             for (int m = 0; m < 4; ++m)
; #pragma unroll
;                 for (int bj = 0; bj < 2; ++bj) { f32x4 g0, g1; unpack8(gw[m][bj], g0, g1);
;                     *(u32x4*)(T + (size_t)(row0 + ai * 128 + m * 16) * D + col0 + bj * 128) = pack8(sig4(g0) * acc[ai][bj][m][0], sig4(g1) * acc[ai][bj][m][1]); } }
;     }
	v_mul_f32_e32 v112, 0xbfb8aa3b, v112
	v_mul_f32_e32 v113, 0xbfb8aa3b, v113
	v_exp_f32_e32 v104, v104
	v_exp_f32_e32 v105, v105
	v_mul_f32_e32 v106, 0xbfb8aa3b, v106
	v_mul_f32_e32 v107, 0xbfb8aa3b, v107
	v_exp_f32_e32 v110, v110
	v_exp_f32_e32 v111, v111
	v_exp_f32_e32 v112, v112
	v_exp_f32_e32 v113, v113
	v_exp_f32_e32 v106, v106
	v_exp_f32_e32 v107, v107
	v_add_f32_e32 v104, 1.0, v104
	v_add_f32_e32 v105, 1.0, v105
	v_add_f32_e32 v110, 1.0, v110
	v_add_f32_e32 v111, 1.0, v111
	v_add_f32_e32 v112, 1.0, v112
	v_add_f32_e32 v113, 1.0, v113
	v_rcp_f32_e32 v104, v104
	v_rcp_f32_e32 v105, v105
	v_add_f32_e32 v106, 1.0, v106
	v_add_f32_e32 v107, 1.0, v107
	v_rcp_f32_e32 v110, v110
	v_rcp_f32_e32 v112, v112
	v_rcp_f32_e32 v113, v113
	v_rcp_f32_e32 v111, v111
	v_rcp_f32_e32 v106, v106
	v_rcp_f32_e32 v107, v107
	v_pk_mul_f32 v[100:101], v[100:101], v[104:105]
	v_pk_mul_f32 v[104:105], v[98:99], v[112:113]
	v_pk_mul_f32 v[98:99], v[96:97], v[110:111]
	v_pk_mul_f32 v[102:103], v[102:103], v[106:107]
	v_cvt_pk_bf16_f32 v96, v100, v101
	v_lshlrev_b32_e32 v100, 16, v141
	v_cvt_pk_bf16_f32 v97, v102, v103
	v_cvt_pk_bf16_f32 v98, v98, v99
	v_cvt_pk_bf16_f32 v99, v104, v105
	global_store_dwordx4 v[108:109], v[96:99], off offset:256
	v_lshlrev_b32_e32 v102, 16, v142
	v_and_b32_e32 v103, 0xffff0000, v142
	v_lshlrev_b32_e32 v98, 16, v140
	v_and_b32_e32 v99, 0xffff0000, v140
	v_mul_f32_e32 v98, 0xbfb8aa3b, v98
	v_lshlrev_b32_e32 v104, 16, v143
	v_and_b32_e32 v105, 0xffff0000, v143
	v_mul_f32_e32 v99, 0xbfb8aa3b, v99
	v_and_b32_e32 v101, 0xffff0000, v141
	v_exp_f32_e32 v98, v98
	v_exp_f32_e32 v99, v99
	v_mul_f32_e32 v102, 0xbfb8aa3b, v102
	v_mul_f32_e32 v103, 0xbfb8aa3b, v103
	v_mul_f32_e32 v104, 0xbfb8aa3b, v104
	v_mul_f32_e32 v105, 0xbfb8aa3b, v105
	v_mul_f32_e32 v100, 0xbfb8aa3b, v100
	v_mul_f32_e32 v101, 0xbfb8aa3b, v101
	v_exp_f32_e32 v102, v102
	v_exp_f32_e32 v103, v103
	v_exp_f32_e32 v104, v104
	v_exp_f32_e32 v105, v105
	v_exp_f32_e32 v100, v100
	v_exp_f32_e32 v101, v101
	v_add_f32_e32 v98, 1.0, v98
	v_add_f32_e32 v99, 1.0, v99
	v_rcp_f32_e32 v98, v98
	v_rcp_f32_e32 v99, v99
	v_add_f32_e32 v102, 1.0, v102
	v_add_f32_e32 v103, 1.0, v103
	v_add_f32_e32 v104, 1.0, v104
	v_add_f32_e32 v105, 1.0, v105
	v_add_f32_e32 v100, 1.0, v100
	v_add_f32_e32 v101, 1.0, v101
	v_rcp_f32_e32 v102, v102
	v_rcp_f32_e32 v104, v104
	v_rcp_f32_e32 v105, v105
	v_rcp_f32_e32 v103, v103
	v_rcp_f32_e32 v100, v100
	v_rcp_f32_e32 v101, v101
	v_lshlrev_b64 v[96:97], 12, v[164:165]
	v_pk_mul_f32 v[92:93], v[92:93], v[98:99]
	v_pk_mul_f32 v[98:99], v[90:91], v[104:105]
	v_pk_mul_f32 v[90:91], v[88:89], v[102:103]
	v_cvt_pk_bf16_f32 v88, v92, v93
	v_lshl_add_u64 v[92:93], s[4:5], 0, v[96:97]
	v_pk_mul_f32 v[94:95], v[94:95], v[100:101]
	v_lshl_add_u64 v[92:93], v[92:93], 0, v[156:157]
	v_cvt_pk_bf16_f32 v89, v94, v95
	v_cvt_pk_bf16_f32 v90, v90, v91
	v_cvt_pk_bf16_f32 v91, v98, v99
	global_store_dwordx4 v[92:93], v[88:91], off
	v_lshlrev_b32_e32 v94, 16, v138
	v_and_b32_e32 v95, 0xffff0000, v138
	v_lshlrev_b32_e32 v88, 16, v136
	v_and_b32_e32 v89, 0xffff0000, v136
	v_lshlrev_b32_e32 v96, 16, v139
	v_and_b32_e32 v97, 0xffff0000, v139
	v_lshlrev_b32_e32 v90, 16, v137
	v_and_b32_e32 v91, 0xffff0000, v137
	v_mul_f32_e32 v88, 0xbfb8aa3b, v88
	v_mul_f32_e32 v89, 0xbfb8aa3b, v89
	v_mul_f32_e32 v94, 0xbfb8aa3b, v94
	v_mul_f32_e32 v95, 0xbfb8aa3b, v95
	v_mul_f32_e32 v96, 0xbfb8aa3b, v96
	v_mul_f32_e32 v97, 0xbfb8aa3b, v97
	v_exp_f32_e32 v88, v88
	v_exp_f32_e32 v89, v89
	v_mul_f32_e32 v90, 0xbfb8aa3b, v90
	v_mul_f32_e32 v91, 0xbfb8aa3b, v91
	v_exp_f32_e32 v94, v94
	v_exp_f32_e32 v95, v95
	v_exp_f32_e32 v96, v96
	v_exp_f32_e32 v97, v97
	v_exp_f32_e32 v90, v90
	v_exp_f32_e32 v91, v91
	v_add_f32_e32 v88, 1.0, v88
	v_add_f32_e32 v89, 1.0, v89
	v_add_f32_e32 v94, 1.0, v94
	v_add_f32_e32 v95, 1.0, v95
	v_add_f32_e32 v96, 1.0, v96
	v_add_f32_e32 v97, 1.0, v97
	v_rcp_f32_e32 v88, v88
	v_rcp_f32_e32 v89, v89
	v_add_f32_e32 v90, 1.0, v90
	v_add_f32_e32 v91, 1.0, v91
	v_rcp_f32_e32 v94, v94
	v_rcp_f32_e32 v96, v96
	v_rcp_f32_e32 v97, v97
	v_rcp_f32_e32 v95, v95
	v_rcp_f32_e32 v90, v90
	v_rcp_f32_e32 v91, v91
	v_pk_mul_f32 v[84:85], v[84:85], v[88:89]
	v_pk_mul_f32 v[88:89], v[82:83], v[96:97]
	v_pk_mul_f32 v[82:83], v[80:81], v[94:95]
	v_pk_mul_f32 v[86:87], v[86:87], v[90:91]
	v_cvt_pk_bf16_f32 v80, v84, v85
	v_lshlrev_b32_e32 v84, 16, v133
	v_cvt_pk_bf16_f32 v81, v86, v87
	v_cvt_pk_bf16_f32 v82, v82, v83
	v_cvt_pk_bf16_f32 v83, v88, v89
	global_store_dwordx4 v[92:93], v[80:83], off offset:256
	v_lshlrev_b32_e32 v86, 16, v134
	v_and_b32_e32 v87, 0xffff0000, v134
	v_lshlrev_b32_e32 v82, 16, v132
	v_and_b32_e32 v83, 0xffff0000, v132
	v_mul_f32_e32 v82, 0xbfb8aa3b, v82
	v_lshlrev_b32_e32 v88, 16, v135
	v_and_b32_e32 v89, 0xffff0000, v135
	v_mul_f32_e32 v83, 0xbfb8aa3b, v83
	v_and_b32_e32 v85, 0xffff0000, v133
	v_exp_f32_e32 v82, v82
	v_exp_f32_e32 v83, v83
	v_mul_f32_e32 v86, 0xbfb8aa3b, v86
	v_mul_f32_e32 v87, 0xbfb8aa3b, v87
	v_mul_f32_e32 v88, 0xbfb8aa3b, v88
	v_mul_f32_e32 v89, 0xbfb8aa3b, v89
	v_mul_f32_e32 v84, 0xbfb8aa3b, v84
	v_mul_f32_e32 v85, 0xbfb8aa3b, v85
	v_exp_f32_e32 v86, v86
	v_exp_f32_e32 v87, v87
	v_exp_f32_e32 v88, v88
	v_exp_f32_e32 v89, v89
	v_exp_f32_e32 v84, v84
	v_exp_f32_e32 v85, v85
	v_add_f32_e32 v82, 1.0, v82
	v_add_f32_e32 v83, 1.0, v83
	v_rcp_f32_e32 v82, v82
	v_rcp_f32_e32 v83, v83
	v_add_f32_e32 v86, 1.0, v86
	v_add_f32_e32 v87, 1.0, v87
	v_add_f32_e32 v88, 1.0, v88
	v_add_f32_e32 v89, 1.0, v89
	v_add_f32_e32 v84, 1.0, v84
	v_add_f32_e32 v85, 1.0, v85
	v_rcp_f32_e32 v86, v86
	v_rcp_f32_e32 v88, v88
	v_rcp_f32_e32 v89, v89
	v_rcp_f32_e32 v87, v87
	v_rcp_f32_e32 v84, v84
; __device__ __forceinline__ u32x4 pack8(const f32x4 v0, const f32x4 v1) { u32x4 w; w.x = cvt_pk_bf16(v0[0], v0[1]); w.y = cvt_pk_bf16(v0[2], v0[3]); w.z = cvt_pk_bf16(v1[0], v1[1]); w.w = cvt_pk_bf16(v1[2], v1[3]); return w; }
; __device__ __forceinline__ void unpack8(const u32x4 w, f32x4& v0, f32x4& v1) { v0 = (f32x4){bflo(w.x), bfhi(w.x), bflo(w.y), bfhi(w.y)}; v1 = (f32x4){bflo(w.z), bfhi(w.z), bflo(w.w), bfhi(w.w)}; }
; __device__ __forceinline__ f32x4 sig4(const f32x4 v) { return (f32x4){sigmoidf_(v[0]), sigmoidf_(v[1]), sigmoidf_(v[2]), sigmoidf_(v[3])}; }
;     __device__ __forceinline__ void operator()(const AccT& acc, const pg8::Unit& u, int wr, int wc, int fr, int fq) const {
;         const int row0 = u.pm * 256 + wr * 64 + fr, col0 = u.pn * 256 + wc * 32 + 8 * fq;
; #pragma unroll
;         for (int ai = 0; ai < 2; ++ai) { u32x4 gw[4][2];
; #pragma unroll
;             for (int m = 0; m < 4; ++m)
; #pragma unroll
;                 for (int bj = 0; bj < 2; ++bj) gw[m][bj] = *(const u32x4*)(PROJ + (size_t)(row0 + ai * 128 + m * 16) * NPROJ + C_GA + col0 + bj * 128);
; #pragma unroll
;             for (int m = 0; m < 4; ++m)
; #pragma unroll
;                 for (int bj = 0; bj < 2; ++bj) { f32x4 g0, g1; unpack8(gw[m][bj], g0, g1);
;                     *(u32x4*)(T + (size_t)(row0 + ai * 128 + m * 16) * D + col0 + bj * 128) = pack8(sig4(g0) * acc[ai][bj][m][0], sig4(g1) * acc[ai][bj][m][1]); } }
;     }
	v_rcp_f32_e32 v85, v85
	v_lshlrev_b64 v[80:81], 12, v[162:163]
	v_pk_mul_f32 v[76:77], v[76:77], v[82:83]
	v_pk_mul_f32 v[82:83], v[74:75], v[88:89]
	v_pk_mul_f32 v[74:75], v[72:73], v[86:87]
	v_cvt_pk_bf16_f32 v72, v76, v77
	v_lshl_add_u64 v[76:77], s[4:5], 0, v[80:81]
	v_pk_mul_f32 v[78:79], v[78:79], v[84:85]
	v_lshl_add_u64 v[76:77], v[76:77], 0, v[156:157]
	v_cvt_pk_bf16_f32 v73, v78, v79
	v_cvt_pk_bf16_f32 v74, v74, v75
	v_cvt_pk_bf16_f32 v75, v82, v83
	global_store_dwordx4 v[76:77], v[72:75], off
	v_lshlrev_b32_e32 v78, 16, v130
	v_and_b32_e32 v79, 0xffff0000, v130
	v_lshlrev_b32_e32 v72, 16, v128
	v_and_b32_e32 v73, 0xffff0000, v128
	v_mul_f32_e32 v72, 0xbfb8aa3b, v72
	v_lshlrev_b32_e32 v80, 16, v131
	v_and_b32_e32 v81, 0xffff0000, v131
	v_mul_f32_e32 v73, 0xbfb8aa3b, v73
	v_lshlrev_b32_e32 v74, 16, v129
	v_and_b32_e32 v75, 0xffff0000, v129
	v_exp_f32_e32 v72, v72
	v_exp_f32_e32 v73, v73
	v_mul_f32_e32 v78, 0xbfb8aa3b, v78
	v_mul_f32_e32 v79, 0xbfb8aa3b, v79
	v_mul_f32_e32 v80, 0xbfb8aa3b, v80
	v_mul_f32_e32 v81, 0xbfb8aa3b, v81
	v_mul_f32_e32 v74, 0xbfb8aa3b, v74
	v_mul_f32_e32 v75, 0xbfb8aa3b, v75
	v_exp_f32_e32 v78, v78
	v_exp_f32_e32 v79, v79
	v_exp_f32_e32 v80, v80
	v_exp_f32_e32 v81, v81
	v_exp_f32_e32 v74, v74
	v_exp_f32_e32 v75, v75
	v_add_f32_e32 v72, 1.0, v72
	v_add_f32_e32 v73, 1.0, v73
	v_rcp_f32_e32 v72, v72
	v_rcp_f32_e32 v73, v73
	v_add_f32_e32 v78, 1.0, v78
	v_add_f32_e32 v79, 1.0, v79
	v_add_f32_e32 v80, 1.0, v80
	v_add_f32_e32 v81, 1.0, v81
	v_add_f32_e32 v74, 1.0, v74
	v_add_f32_e32 v75, 1.0, v75
	v_rcp_f32_e32 v78, v78
	v_rcp_f32_e32 v80, v80
	v_rcp_f32_e32 v81, v81
	v_rcp_f32_e32 v79, v79
	v_rcp_f32_e32 v74, v74
	v_rcp_f32_e32 v75, v75
	v_pk_mul_f32 v[68:69], v[68:69], v[72:73]
	v_add_u32_e32 v100, 0x80, v158
	v_pk_mul_f32 v[72:73], v[66:67], v[80:81]
	v_pk_mul_f32 v[66:67], v[64:65], v[78:79]
	v_cvt_pk_bf16_f32 v64, v68, v69
	v_mad_i64_i32 v[68:69], s[28:29], v100, s61, v[160:161]
	v_pk_mul_f32 v[70:71], v[70:71], v[74:75]
	v_lshl_add_u64 v[68:69], v[68:69], 0, v[156:157]
	v_cvt_pk_bf16_f32 v65, v70, v71
	v_add_co_u32_e32 v70, vcc, s60, v68
	v_cvt_pk_bf16_f32 v66, v66, v67
	v_cvt_pk_bf16_f32 v67, v72, v73
	global_store_dwordx4 v[76:77], v[64:67], off offset:256
	s_nop 0
	v_addc_co_u32_e32 v71, vcc, 0, v69, vcc
	global_load_dwordx4 v[88:91], v[70:71], off offset:2048
	v_lshl_add_u64 v[64:65], v[68:69], 0, s[16:17]
	global_load_dwordx4 v[92:95], v[64:65], off offset:256
	v_add_u32_e32 v102, 0x90, v158
	v_mad_i64_i32 v[64:65], s[28:29], v102, s61, v[160:161]
	v_lshl_add_u64 v[64:65], v[64:65], 0, v[156:157]
	v_lshl_add_u64 v[66:67], v[64:65], 0, s[16:17]
	v_add_co_u32_e32 v64, vcc, s60, v64
	v_add_u32_e32 v86, 0xa0, v158
	s_nop 0
	v_addc_co_u32_e32 v65, vcc, 0, v65, vcc
	global_load_dwordx4 v[96:99], v[64:65], off offset:2048
	global_load_dwordx4 v[80:83], v[66:67], off offset:256
	v_mad_i64_i32 v[64:65], s[28:29], v86, s61, v[160:161]
	v_lshl_add_u64 v[64:65], v[64:65], 0, v[156:157]
	v_lshl_add_u64 v[66:67], v[64:65], 0, s[16:17]
	v_add_co_u32_e32 v64, vcc, s60, v64
	v_add_u32_e32 v84, 0xb0, v158
	s_nop 0
	v_addc_co_u32_e32 v65, vcc, 0, v65, vcc
	global_load_dwordx4 v[76:79], v[64:65], off offset:2048
	global_load_dwordx4 v[72:75], v[66:67], off offset:256
	v_mad_i64_i32 v[64:65], s[28:29], v84, s61, v[160:161]
	v_lshl_add_u64 v[64:65], v[64:65], 0, v[156:157]
	v_lshl_add_u64 v[66:67], v[64:65], 0, s[16:17]
	v_add_co_u32_e32 v64, vcc, s60, v64
	v_ashrrev_i32_e32 v101, 31, v100
	s_nop 0
	v_addc_co_u32_e32 v65, vcc, 0, v65, vcc
	global_load_dwordx4 v[68:71], v[64:65], off offset:2048
	s_nop 0
	global_load_dwordx4 v[64:67], v[66:67], off offset:256
	v_lshlrev_b64 v[100:101], 12, v[100:101]
	v_ashrrev_i32_e32 v103, 31, v102
	v_ashrrev_i32_e32 v87, 31, v86
	v_ashrrev_i32_e32 v85, 31, v84
	s_and_b64 vcc, exec, s[2:3]
	s_mov_b64 s[28:29], s[22:23]
	s_waitcnt vmcnt(0)
	v_lshlrev_b32_e32 v104, 16, v88
	v_and_b32_e32 v88, 0xffff0000, v88
	v_lshlrev_b32_e32 v105, 16, v89
	v_and_b32_e32 v106, 0xffff0000, v89
	v_mul_f32_e32 v89, 0xbfb8aa3b, v104
	v_mul_f32_e32 v88, 0xbfb8aa3b, v88
	v_lshlrev_b32_e32 v107, 16, v90
	v_exp_f32_e32 v89, v89
	v_and_b32_e32 v108, 0xffff0000, v90
	v_exp_f32_e32 v90, v88
	v_mul_f32_e32 v88, 0xbfb8aa3b, v105
	v_lshlrev_b32_e32 v109, 16, v91
	v_and_b32_e32 v110, 0xffff0000, v91
	v_exp_f32_e32 v91, v88
	v_add_f32_e32 v89, 1.0, v89
	v_rcp_f32_e32 v88, v89
	v_add_f32_e32 v89, 1.0, v90
	v_add_f32_e32 v90, 1.0, v91
	v_mul_f32_e32 v91, 0xbfb8aa3b, v106
	v_mul_f32_e32 v104, 0xbfb8aa3b, v107
	v_mul_f32_e32 v105, 0xbfb8aa3b, v108
	v_mul_f32_e32 v106, 0xbfb8aa3b, v109
	v_mul_f32_e32 v107, 0xbfb8aa3b, v110
	v_exp_f32_e32 v104, v104
	v_exp_f32_e32 v105, v105
	v_exp_f32_e32 v106, v106
	v_exp_f32_e32 v107, v107
	v_exp_f32_e32 v91, v91
	v_rcp_f32_e32 v89, v89
	v_add_f32_e32 v104, 1.0, v104
	v_add_f32_e32 v105, 1.0, v105
	v_add_f32_e32 v106, 1.0, v106
	v_add_f32_e32 v107, 1.0, v107
	v_add_f32_e32 v91, 1.0, v91
	v_rcp_f32_e32 v104, v104
	v_rcp_f32_e32 v106, v106
	v_rcp_f32_e32 v107, v107
	v_rcp_f32_e32 v105, v105
	v_rcp_f32_e32 v90, v90
	v_rcp_f32_e32 v91, v91
	v_pk_mul_f32 v[60:61], v[60:61], v[88:89]
	v_pk_mul_f32 v[88:89], v[58:59], v[106:107]
	v_pk_mul_f32 v[58:59], v[56:57], v[104:105]
	v_cvt_pk_bf16_f32 v56, v60, v61
	v_lshl_add_u64 v[60:61], s[4:5], 0, v[100:101]
	v_pk_mul_f32 v[62:63], v[62:63], v[90:91]
	v_lshl_add_u64 v[60:61], v[60:61], 0, v[156:157]
	v_cvt_pk_bf16_f32 v57, v62, v63
	v_cvt_pk_bf16_f32 v58, v58, v59
	v_cvt_pk_bf16_f32 v59, v88, v89
	global_store_dwordx4 v[60:61], v[56:59], off
	v_lshlrev_b32_e32 v62, 16, v94
	v_and_b32_e32 v63, 0xffff0000, v94
	v_lshlrev_b32_e32 v56, 16, v92
; __device__ __forceinline__ u32x4 pack8(const f32x4 v0, const f32x4 v1) { u32x4 w; w.x = cvt_pk_bf16(v0[0], v0[1]); w.y = cvt_pk_bf16(v0[2], v0[3]); w.z = cvt_pk_bf16(v1[0], v1[1]); w.w = cvt_pk_bf16(v1[2], v1[3]); return w; }
; __device__ __forceinline__ void unpack8(const u32x4 w, f32x4& v0, f32x4& v1) { v0 = (f32x4){bflo(w.x), bfhi(w.x), bflo(w.y), bfhi(w.y)}; v1 = (f32x4){bflo(w.z), bfhi(w.z), bflo(w.w), bfhi(w.w)}; }
; __device__ __forceinline__ f32x4 sig4(const f32x4 v) { return (f32x4){sigmoidf_(v[0]), sigmoidf_(v[1]), sigmoidf_(v[2]), sigmoidf_(v[3])}; }
;     __device__ __forceinline__ void operator()(const AccT& acc, const pg8::Unit& u, int wr, int wc, int fr, int fq) const {
;         const int row0 = u.pm * 256 + wr * 64 + fr, col0 = u.pn * 256 + wc * 32 + 8 * fq;
; #pragma unroll
;         for (int ai = 0; ai < 2; ++ai) { u32x4 gw[4][2];
; #pragma unroll
;             for (int m = 0; m < 4; ++m)
; #pragma unroll
;                 for (int bj = 0; bj < 2; ++bj) gw[m][bj] = *(const u32x4*)(PROJ + (size_t)(row0 + ai * 128 + m * 16) * NPROJ + C_GA + col0 + bj * 128);
; #pragma unroll
;             for (int m = 0; m < 4; ++m)
; #pragma unroll
;                 for (int bj = 0; bj < 2; ++bj) { f32x4 g0, g1; unpack8(gw[m][bj], g0, g1);
;                     *(u32x4*)(T + (size_t)(row0 + ai * 128 + m * 16) * D + col0 + bj * 128) = pack8(sig4(g0) * acc[ai][bj][m][0], sig4(g1) * acc[ai][bj][m][1]); } }
;     }
	v_and_b32_e32 v57, 0xffff0000, v92
	v_lshlrev_b32_e32 v88, 16, v95
	v_and_b32_e32 v89, 0xffff0000, v95
	v_lshlrev_b32_e32 v58, 16, v93
	v_and_b32_e32 v59, 0xffff0000, v93
	v_mul_f32_e32 v56, 0xbfb8aa3b, v56
	v_mul_f32_e32 v57, 0xbfb8aa3b, v57
	v_mul_f32_e32 v62, 0xbfb8aa3b, v62
	v_mul_f32_e32 v63, 0xbfb8aa3b, v63
	v_mul_f32_e32 v88, 0xbfb8aa3b, v88
	v_mul_f32_e32 v89, 0xbfb8aa3b, v89
	v_exp_f32_e32 v56, v56
	v_exp_f32_e32 v57, v57
	v_mul_f32_e32 v58, 0xbfb8aa3b, v58
	v_mul_f32_e32 v59, 0xbfb8aa3b, v59
	v_exp_f32_e32 v62, v62
	v_exp_f32_e32 v63, v63
	v_exp_f32_e32 v88, v88
	v_exp_f32_e32 v89, v89
	v_exp_f32_e32 v58, v58
	v_exp_f32_e32 v59, v59
	v_add_f32_e32 v56, 1.0, v56
	v_add_f32_e32 v57, 1.0, v57
	v_add_f32_e32 v62, 1.0, v62
	v_add_f32_e32 v63, 1.0, v63
	v_add_f32_e32 v88, 1.0, v88
	v_add_f32_e32 v89, 1.0, v89
	v_rcp_f32_e32 v56, v56
	v_rcp_f32_e32 v57, v57
	v_add_f32_e32 v58, 1.0, v58
	v_add_f32_e32 v59, 1.0, v59
	v_rcp_f32_e32 v62, v62
	v_rcp_f32_e32 v88, v88
	v_rcp_f32_e32 v89, v89
	v_rcp_f32_e32 v63, v63
	v_rcp_f32_e32 v58, v58
	v_rcp_f32_e32 v59, v59
	v_pk_mul_f32 v[52:53], v[52:53], v[56:57]
	v_pk_mul_f32 v[56:57], v[50:51], v[88:89]
	v_pk_mul_f32 v[50:51], v[48:49], v[62:63]
	v_pk_mul_f32 v[54:55], v[54:55], v[58:59]
	v_cvt_pk_bf16_f32 v48, v52, v53
	v_lshlrev_b32_e32 v52, 16, v97
	v_cvt_pk_bf16_f32 v49, v54, v55
	v_cvt_pk_bf16_f32 v50, v50, v51
	v_cvt_pk_bf16_f32 v51, v56, v57
	global_store_dwordx4 v[60:61], v[48:51], off offset:256
	v_lshlrev_b32_e32 v54, 16, v98
	v_and_b32_e32 v55, 0xffff0000, v98
	v_lshlrev_b32_e32 v50, 16, v96
	v_and_b32_e32 v51, 0xffff0000, v96
	v_mul_f32_e32 v50, 0xbfb8aa3b, v50
	v_lshlrev_b32_e32 v56, 16, v99
	v_and_b32_e32 v57, 0xffff0000, v99
	v_mul_f32_e32 v51, 0xbfb8aa3b, v51
	v_and_b32_e32 v53, 0xffff0000, v97
	v_exp_f32_e32 v50, v50
	v_exp_f32_e32 v51, v51
	v_mul_f32_e32 v54, 0xbfb8aa3b, v54
	v_mul_f32_e32 v55, 0xbfb8aa3b, v55
	v_mul_f32_e32 v56, 0xbfb8aa3b, v56
	v_mul_f32_e32 v57, 0xbfb8aa3b, v57
	v_mul_f32_e32 v52, 0xbfb8aa3b, v52
	v_mul_f32_e32 v53, 0xbfb8aa3b, v53
	v_exp_f32_e32 v54, v54
	v_exp_f32_e32 v55, v55
	v_exp_f32_e32 v56, v56
	v_exp_f32_e32 v57, v57
	v_exp_f32_e32 v52, v52
	v_exp_f32_e32 v53, v53
	v_add_f32_e32 v50, 1.0, v50
	v_add_f32_e32 v51, 1.0, v51
	v_rcp_f32_e32 v50, v50
	v_rcp_f32_e32 v51, v51
	v_add_f32_e32 v54, 1.0, v54
	v_add_f32_e32 v55, 1.0, v55
	v_add_f32_e32 v56, 1.0, v56
	v_add_f32_e32 v57, 1.0, v57
	v_add_f32_e32 v52, 1.0, v52
	v_add_f32_e32 v53, 1.0, v53
	v_rcp_f32_e32 v54, v54
	v_rcp_f32_e32 v56, v56
	v_rcp_f32_e32 v57, v57
	v_rcp_f32_e32 v55, v55
	v_rcp_f32_e32 v52, v52
	v_rcp_f32_e32 v53, v53
	v_lshlrev_b64 v[48:49], 12, v[102:103]
	v_pk_mul_f32 v[44:45], v[44:45], v[50:51]
	v_pk_mul_f32 v[50:51], v[42:43], v[56:57]
	v_pk_mul_f32 v[42:43], v[40:41], v[54:55]
	v_cvt_pk_bf16_f32 v40, v44, v45
	v_lshl_add_u64 v[44:45], s[4:5], 0, v[48:49]
	v_pk_mul_f32 v[46:47], v[46:47], v[52:53]
	v_lshl_add_u64 v[44:45], v[44:45], 0, v[156:157]
	v_cvt_pk_bf16_f32 v41, v46, v47
	v_cvt_pk_bf16_f32 v42, v42, v43
	v_cvt_pk_bf16_f32 v43, v50, v51
	global_store_dwordx4 v[44:45], v[40:43], off
	v_lshlrev_b32_e32 v46, 16, v82
	v_and_b32_e32 v47, 0xffff0000, v82
	v_lshlrev_b32_e32 v40, 16, v80
	v_and_b32_e32 v41, 0xffff0000, v80
	v_lshlrev_b32_e32 v48, 16, v83
	v_and_b32_e32 v49, 0xffff0000, v83
	v_lshlrev_b32_e32 v42, 16, v81
	v_and_b32_e32 v43, 0xffff0000, v81
	v_mul_f32_e32 v40, 0xbfb8aa3b, v40
	v_mul_f32_e32 v41, 0xbfb8aa3b, v41
	v_mul_f32_e32 v46, 0xbfb8aa3b, v46
	v_mul_f32_e32 v47, 0xbfb8aa3b, v47
	v_mul_f32_e32 v48, 0xbfb8aa3b, v48
	v_mul_f32_e32 v49, 0xbfb8aa3b, v49
	v_exp_f32_e32 v40, v40
	v_exp_f32_e32 v41, v41
	v_mul_f32_e32 v42, 0xbfb8aa3b, v42
	v_mul_f32_e32 v43, 0xbfb8aa3b, v43
	v_exp_f32_e32 v46, v46
	v_exp_f32_e32 v47, v47
	v_exp_f32_e32 v48, v48
	v_exp_f32_e32 v49, v49
	v_exp_f32_e32 v42, v42
	v_exp_f32_e32 v43, v43
	v_add_f32_e32 v40, 1.0, v40
	v_add_f32_e32 v41, 1.0, v41
	v_add_f32_e32 v46, 1.0, v46
	v_add_f32_e32 v47, 1.0, v47
	v_add_f32_e32 v48, 1.0, v48
	v_add_f32_e32 v49, 1.0, v49
	v_rcp_f32_e32 v40, v40
	v_rcp_f32_e32 v41, v41
	v_add_f32_e32 v42, 1.0, v42
	v_add_f32_e32 v43, 1.0, v43
	v_rcp_f32_e32 v46, v46
	v_rcp_f32_e32 v48, v48
	v_rcp_f32_e32 v49, v49
	v_rcp_f32_e32 v47, v47
	v_rcp_f32_e32 v42, v42
	v_rcp_f32_e32 v43, v43
	v_pk_mul_f32 v[36:37], v[36:37], v[40:41]
	v_pk_mul_f32 v[40:41], v[34:35], v[48:49]
	v_pk_mul_f32 v[34:35], v[32:33], v[46:47]
	v_pk_mul_f32 v[38:39], v[38:39], v[42:43]
	v_cvt_pk_bf16_f32 v32, v36, v37
	v_lshlrev_b32_e32 v36, 16, v77
	v_cvt_pk_bf16_f32 v33, v38, v39
	v_cvt_pk_bf16_f32 v34, v34, v35
	v_cvt_pk_bf16_f32 v35, v40, v41
	global_store_dwordx4 v[44:45], v[32:35], off offset:256
	v_lshlrev_b32_e32 v38, 16, v78
	v_and_b32_e32 v39, 0xffff0000, v78
	v_lshlrev_b32_e32 v34, 16, v76
	v_and_b32_e32 v35, 0xffff0000, v76
	v_mul_f32_e32 v34, 0xbfb8aa3b, v34
	v_lshlrev_b32_e32 v40, 16, v79
	v_and_b32_e32 v41, 0xffff0000, v79
	v_mul_f32_e32 v35, 0xbfb8aa3b, v35
	v_and_b32_e32 v37, 0xffff0000, v77
	v_exp_f32_e32 v34, v34
	v_exp_f32_e32 v35, v35
	v_mul_f32_e32 v38, 0xbfb8aa3b, v38
	v_mul_f32_e32 v39, 0xbfb8aa3b, v39
	v_mul_f32_e32 v40, 0xbfb8aa3b, v40
	v_mul_f32_e32 v41, 0xbfb8aa3b, v41
	v_mul_f32_e32 v36, 0xbfb8aa3b, v36
	v_mul_f32_e32 v37, 0xbfb8aa3b, v37
	v_exp_f32_e32 v38, v38
	v_exp_f32_e32 v39, v39
	v_exp_f32_e32 v40, v40
	v_exp_f32_e32 v41, v41
	v_exp_f32_e32 v36, v36
	v_exp_f32_e32 v37, v37
	v_add_f32_e32 v34, 1.0, v34
	v_add_f32_e32 v35, 1.0, v35
	v_rcp_f32_e32 v34, v34
	v_rcp_f32_e32 v35, v35
	v_add_f32_e32 v38, 1.0, v38
	v_add_f32_e32 v39, 1.0, v39
; #define PG8_WAIT_V(n) asm volatile("s_waitcnt vmcnt(" #n ")" ::: "memory")
; #define PG8_BAR __builtin_amdgcn_s_barrier()
; __device__ __forceinline__ u32x4 pack8(const f32x4 v0, const f32x4 v1) { u32x4 w; w.x = cvt_pk_bf16(v0[0], v0[1]); w.y = cvt_pk_bf16(v0[2], v0[3]); w.z = cvt_pk_bf16(v1[0], v1[1]); w.w = cvt_pk_bf16(v1[2], v1[3]); return w; }
; __device__ __forceinline__ void unpack8(const u32x4 w, f32x4& v0, f32x4& v1) { v0 = (f32x4){bflo(w.x), bfhi(w.x), bflo(w.y), bfhi(w.y)}; v1 = (f32x4){bflo(w.z), bfhi(w.z), bflo(w.w), bfhi(w.w)}; }
; __device__ __forceinline__ f32x4 sig4(const f32x4 v) { return (f32x4){sigmoidf_(v[0]), sigmoidf_(v[1]), sigmoidf_(v[2]), sigmoidf_(v[3])}; }
; template <class Epi>
; __device__ __forceinline__ void gemm_phase(LAS unsigned char* lds, const Gemm g, const StaticOrder& S, const Epi& E) {
;     ...
;         E(acc, cur, wr, wc, fr, fq);
;         if (!has_next) break;
; #pragma unroll
;         for (int a = 0; a < 2; ++a)
; #pragma unroll
;             for (int b = 0; b < 2; ++b)
; #pragma unroll
;                 for (int m = 0; m < 4; ++m)
; #pragma unroll
;                     for (int n = 0; n < 2; ++n) acc[a][b][m][n] = (f32x4){0.f, 0.f, 0.f, 0.f};
;         cur = nxt; cA = nA; cB = nB; ++ui;
;     }
;     PG8_WAIT_V(0);
;     if (wr == 0) PG8_BAR;
;     PG8_BAR;
;     __device__ __forceinline__ void operator()(const AccT& acc, const pg8::Unit& u, int wr, int wc, int fr, int fq) const {
;         const int row0 = u.pm * 256 + wr * 64 + fr, col0 = u.pn * 256 + wc * 32 + 8 * fq;
; #pragma unroll
;         for (int ai = 0; ai < 2; ++ai) { u32x4 gw[4][2];
; #pragma unroll
;             for (int m = 0; m < 4; ++m)
; #pragma unroll
;                 for (int bj = 0; bj < 2; ++bj) gw[m][bj] = *(const u32x4*)(PROJ + (size_t)(row0 + ai * 128 + m * 16) * NPROJ + C_GA + col0 + bj * 128);
; #pragma unroll
;             for (int m = 0; m < 4; ++m)
; #pragma unroll
;                 for (int bj = 0; bj < 2; ++bj) { f32x4 g0, g1; unpack8(gw[m][bj], g0, g1);
;                     *(u32x4*)(T + (size_t)(row0 + ai * 128 + m * 16) * D + col0 + bj * 128) = pack8(sig4(g0) * acc[ai][bj][m][0], sig4(g1) * acc[ai][bj][m][1]); } }
;     }
	v_add_f32_e32 v40, 1.0, v40
	v_add_f32_e32 v41, 1.0, v41
	v_add_f32_e32 v36, 1.0, v36
	v_add_f32_e32 v37, 1.0, v37
	v_rcp_f32_e32 v38, v38
	v_rcp_f32_e32 v40, v40
	v_rcp_f32_e32 v41, v41
	v_rcp_f32_e32 v39, v39
	v_rcp_f32_e32 v36, v36
	v_rcp_f32_e32 v37, v37
	v_lshlrev_b64 v[32:33], 12, v[86:87]
	v_pk_mul_f32 v[28:29], v[28:29], v[34:35]
	v_pk_mul_f32 v[34:35], v[26:27], v[40:41]
	v_pk_mul_f32 v[26:27], v[24:25], v[38:39]
	v_cvt_pk_bf16_f32 v24, v28, v29
	v_lshl_add_u64 v[28:29], s[4:5], 0, v[32:33]
	v_pk_mul_f32 v[30:31], v[30:31], v[36:37]
	v_lshl_add_u64 v[28:29], v[28:29], 0, v[156:157]
	v_cvt_pk_bf16_f32 v25, v30, v31
	v_cvt_pk_bf16_f32 v26, v26, v27
	v_cvt_pk_bf16_f32 v27, v34, v35
	global_store_dwordx4 v[28:29], v[24:27], off
	v_lshlrev_b32_e32 v30, 16, v74
	v_and_b32_e32 v31, 0xffff0000, v74
	v_lshlrev_b32_e32 v24, 16, v72
	v_and_b32_e32 v25, 0xffff0000, v72
	v_lshlrev_b32_e32 v32, 16, v75
	v_and_b32_e32 v33, 0xffff0000, v75
	v_lshlrev_b32_e32 v26, 16, v73
	v_and_b32_e32 v27, 0xffff0000, v73
	v_mul_f32_e32 v24, 0xbfb8aa3b, v24
	v_mul_f32_e32 v25, 0xbfb8aa3b, v25
	v_mul_f32_e32 v30, 0xbfb8aa3b, v30
	v_mul_f32_e32 v31, 0xbfb8aa3b, v31
	v_mul_f32_e32 v32, 0xbfb8aa3b, v32
	v_mul_f32_e32 v33, 0xbfb8aa3b, v33
	v_exp_f32_e32 v24, v24
	v_exp_f32_e32 v25, v25
	v_mul_f32_e32 v26, 0xbfb8aa3b, v26
	v_mul_f32_e32 v27, 0xbfb8aa3b, v27
	v_exp_f32_e32 v30, v30
	v_exp_f32_e32 v31, v31
	v_exp_f32_e32 v32, v32
	v_exp_f32_e32 v33, v33
	v_exp_f32_e32 v26, v26
	v_exp_f32_e32 v27, v27
	v_add_f32_e32 v24, 1.0, v24
	v_add_f32_e32 v25, 1.0, v25
	v_add_f32_e32 v30, 1.0, v30
	v_add_f32_e32 v31, 1.0, v31
	v_add_f32_e32 v32, 1.0, v32
	v_add_f32_e32 v33, 1.0, v33
	v_rcp_f32_e32 v24, v24
	v_rcp_f32_e32 v25, v25
	v_add_f32_e32 v26, 1.0, v26
	v_add_f32_e32 v27, 1.0, v27
	v_rcp_f32_e32 v30, v30
	v_rcp_f32_e32 v32, v32
	v_rcp_f32_e32 v33, v33
	v_rcp_f32_e32 v31, v31
	v_rcp_f32_e32 v26, v26
	v_rcp_f32_e32 v27, v27
	v_pk_mul_f32 v[20:21], v[20:21], v[24:25]
	v_pk_mul_f32 v[24:25], v[18:19], v[32:33]
	v_pk_mul_f32 v[18:19], v[16:17], v[30:31]
	v_pk_mul_f32 v[22:23], v[22:23], v[26:27]
	v_cvt_pk_bf16_f32 v16, v20, v21
	v_lshlrev_b32_e32 v20, 16, v69
	v_cvt_pk_bf16_f32 v17, v22, v23
	v_cvt_pk_bf16_f32 v18, v18, v19
	v_cvt_pk_bf16_f32 v19, v24, v25
	global_store_dwordx4 v[28:29], v[16:19], off offset:256
	v_lshlrev_b32_e32 v22, 16, v70
	v_and_b32_e32 v23, 0xffff0000, v70
	v_lshlrev_b32_e32 v18, 16, v68
	v_and_b32_e32 v19, 0xffff0000, v68
	v_mul_f32_e32 v18, 0xbfb8aa3b, v18
	v_lshlrev_b32_e32 v24, 16, v71
	v_and_b32_e32 v25, 0xffff0000, v71
	v_mul_f32_e32 v19, 0xbfb8aa3b, v19
	v_and_b32_e32 v21, 0xffff0000, v69
	v_exp_f32_e32 v18, v18
	v_exp_f32_e32 v19, v19
	v_mul_f32_e32 v22, 0xbfb8aa3b, v22
	v_mul_f32_e32 v23, 0xbfb8aa3b, v23
	v_mul_f32_e32 v24, 0xbfb8aa3b, v24
	v_mul_f32_e32 v25, 0xbfb8aa3b, v25
	v_mul_f32_e32 v20, 0xbfb8aa3b, v20
	v_mul_f32_e32 v21, 0xbfb8aa3b, v21
	v_exp_f32_e32 v22, v22
	v_exp_f32_e32 v23, v23
	v_exp_f32_e32 v24, v24
	v_exp_f32_e32 v25, v25
	v_exp_f32_e32 v20, v20
	v_exp_f32_e32 v21, v21
	v_add_f32_e32 v18, 1.0, v18
	v_add_f32_e32 v19, 1.0, v19
	v_rcp_f32_e32 v18, v18
	v_rcp_f32_e32 v19, v19
	v_add_f32_e32 v22, 1.0, v22
	v_add_f32_e32 v23, 1.0, v23
	v_add_f32_e32 v24, 1.0, v24
	v_add_f32_e32 v25, 1.0, v25
	v_add_f32_e32 v20, 1.0, v20
	v_add_f32_e32 v21, 1.0, v21
	v_rcp_f32_e32 v22, v22
	v_rcp_f32_e32 v24, v24
	v_rcp_f32_e32 v25, v25
	v_rcp_f32_e32 v23, v23
	v_rcp_f32_e32 v20, v20
	v_rcp_f32_e32 v21, v21
	v_lshlrev_b64 v[16:17], 12, v[84:85]
	v_pk_mul_f32 v[12:13], v[12:13], v[18:19]
	v_pk_mul_f32 v[18:19], v[10:11], v[24:25]
	v_pk_mul_f32 v[10:11], v[8:9], v[22:23]
	v_cvt_pk_bf16_f32 v8, v12, v13
	v_lshl_add_u64 v[12:13], s[4:5], 0, v[16:17]
	v_pk_mul_f32 v[14:15], v[14:15], v[20:21]
	v_lshl_add_u64 v[12:13], v[12:13], 0, v[156:157]
	v_cvt_pk_bf16_f32 v9, v14, v15
	v_cvt_pk_bf16_f32 v10, v10, v11
	v_cvt_pk_bf16_f32 v11, v18, v19
	global_store_dwordx4 v[12:13], v[8:11], off
	v_lshlrev_b32_e32 v14, 16, v66
	v_and_b32_e32 v15, 0xffff0000, v66
	v_lshlrev_b32_e32 v8, 16, v64
	v_and_b32_e32 v9, 0xffff0000, v64
	v_lshlrev_b32_e32 v16, 16, v67
	v_and_b32_e32 v17, 0xffff0000, v67
	v_lshlrev_b32_e32 v10, 16, v65
	v_and_b32_e32 v11, 0xffff0000, v65
	v_mul_f32_e32 v8, 0xbfb8aa3b, v8
	v_mul_f32_e32 v9, 0xbfb8aa3b, v9
	v_mul_f32_e32 v14, 0xbfb8aa3b, v14
	v_mul_f32_e32 v15, 0xbfb8aa3b, v15
	v_mul_f32_e32 v16, 0xbfb8aa3b, v16
	v_mul_f32_e32 v17, 0xbfb8aa3b, v17
	v_exp_f32_e32 v8, v8
	v_exp_f32_e32 v9, v9
	v_mul_f32_e32 v10, 0xbfb8aa3b, v10
	v_mul_f32_e32 v11, 0xbfb8aa3b, v11
	v_exp_f32_e32 v14, v14
	v_exp_f32_e32 v15, v15
	v_exp_f32_e32 v16, v16
	v_exp_f32_e32 v17, v17
	v_exp_f32_e32 v10, v10
	v_exp_f32_e32 v11, v11
	v_add_f32_e32 v8, 1.0, v8
	v_add_f32_e32 v9, 1.0, v9
	v_add_f32_e32 v14, 1.0, v14
	v_add_f32_e32 v15, 1.0, v15
	v_add_f32_e32 v16, 1.0, v16
	v_add_f32_e32 v17, 1.0, v17
	v_rcp_f32_e32 v8, v8
	v_rcp_f32_e32 v9, v9
	v_add_f32_e32 v10, 1.0, v10
	v_add_f32_e32 v11, 1.0, v11
	v_rcp_f32_e32 v14, v14
	v_rcp_f32_e32 v16, v16
	v_rcp_f32_e32 v17, v17
	v_rcp_f32_e32 v15, v15
	v_rcp_f32_e32 v10, v10
	v_rcp_f32_e32 v11, v11
	v_pk_mul_f32 v[4:5], v[4:5], v[8:9]
	v_pk_mul_f32 v[8:9], v[2:3], v[16:17]
	v_pk_mul_f32 v[2:3], v[0:1], v[14:15]
	v_pk_mul_f32 v[6:7], v[6:7], v[10:11]
	v_cvt_pk_bf16_f32 v0, v4, v5
	s_nop 0
	v_cvt_pk_bf16_f32 v1, v6, v7
	v_cvt_pk_bf16_f32 v2, v2, v3
	v_cvt_pk_bf16_f32 v3, v8, v9
	global_store_dwordx4 v[12:13], v[0:3], off offset:256
	s_cbranch_vccz .LBB0_907
	s_waitcnt vmcnt(0)
	s_cmpk_gt_u32 s41, 0xff
	s_cbranch_scc1 .LBB0_918
	s_barrier

; #define PG8_STAGE(bufoff, gbase, voff) do { _Pragma("unroll") for (int _i = 0; _i < 2; ++_i) \
;         __builtin_amdgcn_global_load_lds((const unsigned*)((const char*)(gbase) + (voff)[_i]), (LAS unsigned*)(lds + (bufoff) + ldsw + _i * 8192), 16, 0, 0); } while (0)
; #define PG8_LDA(dst, b, h) do { _Pragma("unroll") for (int m = 0; m < 4; ++m) _Pragma("unroll") for (int k = 0; k < 2; ++k) dst[m][k] = *(const LAS bf16x8*)(lds + PG8_SA(b, h) + aoff + m * 2048 + k * 1024); } while (0)
; #define PG8_LDB(dst, b, h) do { _Pragma("unroll") for (int n = 0; n < 2; ++n) _Pragma("unroll") for (int k = 0; k < 2; ++k) dst[n][k] = *(const LAS bf16x8*)(lds + PG8_SB(b, h) + boff + n * 2048 + k * 1024); } while (0)
; #define PG8_MMA(ai, bj, At, Bt) do { __builtin_amdgcn_s_setprio(1); _Pragma("unroll") for (int m = 0; m < 4; ++m) _Pragma("unroll") for (int n = 0; n < 2; ++n) _Pragma("unroll") for (int k = 0; k < 2; ++k) \
;         acc[ai][bj][m][n] = __builtin_amdgcn_mfma_f32_16x16x32_bf16(Bt[n][k], At[m][k], acc[ai][bj][m][n], 0, 0, 0); __builtin_amdgcn_s_setprio(0); } while (0)
; #define PG8_WAIT_V(n) asm volatile("s_waitcnt vmcnt(" #n ")" ::: "memory")
; #define PG8_WAIT_L(n) asm volatile("s_waitcnt lgkmcnt(" #n ")" ::: "memory")
; #define PG8_BAR __builtin_amdgcn_s_barrier()
; #define PG8_SCHED __builtin_amdgcn_sched_barrier(0)
; template <class Epi>
; __device__ __forceinline__ void gemm_phase(LAS unsigned char* lds, const Gemm g, const StaticOrder& S, const Epi& E) {
;     ...
;             PG8_LDB(B0, 0, 0); PG8_SCHED; PG8_LDA(At, 0, 0); PG8_STAGE(PG8_SA(1, 1), a1 + hstep, voffA);
;             PG8_WAIT_L(8); PG8_BAR; PG8_WAIT_L(0); PG8_MMA(0, 0, At, B0); PG8_BAR; PG8_SCHED;
;             PG8_LDB(B1, 0, 1); PG8_STAGE(PG8_SB(0, 0), b2, voffB);
;             PG8_BAR; PG8_WAIT_L(0); PG8_MMA(0, 1, At, B1); PG8_BAR;
;             PG8_LDA(At, 0, 1); PG8_STAGE(PG8_SA(0, 0), a2, voffA);
;             PG8_BAR; PG8_WAIT_L(0); PG8_MMA(1, 0, At, B0); PG8_BAR; PG8_SCHED;
;             PG8_STAGE(PG8_SB(0, 1), b2 + hstep, voffB);
;             PG8_WAIT_V(6); PG8_BAR; PG8_MMA(1, 1, At, B1); PG8_BAR;
.LBB0_930:
	ds_read_b128 v[128:131], v207
	ds_read_b128 v[132:135], v207 offset:1024
	ds_read_b128 v[136:139], v207 offset:2048
	ds_read_b128 v[140:143], v207 offset:3072
	s_add_u32 s28, s26, 0xfffc0080
	s_addc_u32 s29, s27, -1
	s_cmp_eq_u32 s62, 12
	s_cselect_b32 s31, s17, s29
	s_cselect_b32 s30, s58, s28
	s_cselect_b32 s29, s19, s61
	s_cselect_b32 s28, s59, s60
	s_nop 0
	s_add_i32 m0, s25, 0xc000
	ds_read_b128 v[144:147], v208
	ds_read_b128 v[148:151], v208 offset:1024
	ds_read_b128 v[152:155], v208 offset:2048
	ds_read_b128 v[156:159], v208 offset:3072
	ds_read_b128 v[160:163], v208 offset:4096
	ds_read_b128 v[164:167], v208 offset:5120
	ds_read_b128 v[168:171], v208 offset:6144
	ds_read_b128 v[188:191], v208 offset:7168
	global_load_lds_dwordx4 v180, s[26:27]
	s_nop 0
	s_add_i32 m0, s25, 0xe000
	s_nop 0
	global_load_lds_dwordx4 v182, s[26:27]
	s_waitcnt lgkmcnt(8)
	s_barrier
	s_waitcnt lgkmcnt(0)
	s_waitcnt lgkmcnt(0)
	v_mfma_f32_16x16x32_bf16 v[124:127], v[128:131], v[144:147], v[124:127]
	v_mfma_f32_16x16x32_bf16 v[120:123], v[136:139], v[144:147], v[120:123]
	v_mfma_f32_16x16x32_bf16 v[108:111], v[128:131], v[152:155], v[108:111]
	v_mfma_f32_16x16x32_bf16 v[104:107], v[136:139], v[152:155], v[104:107]
	v_mfma_f32_16x16x32_bf16 v[92:95], v[128:131], v[160:163], v[92:95]
	v_mfma_f32_16x16x32_bf16 v[88:91], v[136:139], v[160:163], v[88:91]
	v_mfma_f32_16x16x32_bf16 v[76:79], v[128:131], v[168:171], v[76:79]
	v_mfma_f32_16x16x32_bf16 v[72:75], v[136:139], v[168:171], v[72:75]
	v_mfma_f32_16x16x32_bf16 v[124:127], v[132:135], v[148:151], v[124:127]
	v_mfma_f32_16x16x32_bf16 v[120:123], v[140:143], v[148:151], v[120:123]
	v_mfma_f32_16x16x32_bf16 v[108:111], v[132:135], v[156:159], v[108:111]
	v_mfma_f32_16x16x32_bf16 v[104:107], v[140:143], v[156:159], v[104:107]
	v_mfma_f32_16x16x32_bf16 v[92:95], v[132:135], v[164:167], v[92:95]
	v_mfma_f32_16x16x32_bf16 v[88:91], v[140:143], v[164:167], v[88:91]
	v_mfma_f32_16x16x32_bf16 v[76:79], v[132:135], v[188:191], v[76:79]
	v_mfma_f32_16x16x32_bf16 v[72:75], v[140:143], v[188:191], v[72:75]
	s_barrier
	s_add_i32 s63, s51, s35
	v_lshl_add_u64 v[200:201], s[28:29], 0, v[174:175]
	s_mov_b32 m0, s63
	ds_read_b128 v[192:195], v209
	ds_read_b128 v[196:199], v209 offset:1024
	ds_read_b128 v[210:213], v209 offset:2048
	ds_read_b128 v[216:219], v209 offset:3072
	global_load_lds_dwordx4 v[200:201], off
	v_lshl_add_u64 v[220:221], s[28:29], 0, v[178:179]
	s_add_i32 m0, s63, 0x2000
	s_nop 0
	global_load_lds_dwordx4 v[220:221], off
	s_barrier
	s_waitcnt lgkmcnt(0)
	s_waitcnt lgkmcnt(0)
	v_mfma_f32_16x16x32_bf16 v[116:119], v[192:195], v[144:147], v[116:119]
	v_mfma_f32_16x16x32_bf16 v[112:115], v[210:213], v[144:147], v[112:115]
	v_mfma_f32_16x16x32_bf16 v[100:103], v[192:195], v[152:155], v[100:103]
	v_mfma_f32_16x16x32_bf16 v[96:99], v[210:213], v[152:155], v[96:99]
	v_mfma_f32_16x16x32_bf16 v[84:87], v[192:195], v[160:163], v[84:87]
	v_mfma_f32_16x16x32_bf16 v[80:83], v[210:213], v[160:163], v[80:83]
	v_mfma_f32_16x16x32_bf16 v[68:71], v[192:195], v[168:171], v[68:71]
	v_mfma_f32_16x16x32_bf16 v[64:67], v[210:213], v[168:171], v[64:67]
	v_mfma_f32_16x16x32_bf16 v[116:119], v[196:199], v[148:151], v[116:119]
	v_mfma_f32_16x16x32_bf16 v[112:115], v[216:219], v[148:151], v[112:115]
	v_mfma_f32_16x16x32_bf16 v[100:103], v[196:199], v[156:159], v[100:103]
	v_mfma_f32_16x16x32_bf16 v[96:99], v[216:219], v[156:159], v[96:99]
	v_mfma_f32_16x16x32_bf16 v[84:87], v[196:199], v[164:167], v[84:87]
	v_mfma_f32_16x16x32_bf16 v[80:83], v[216:219], v[164:167], v[80:83]
	v_mfma_f32_16x16x32_bf16 v[68:71], v[196:199], v[188:191], v[68:71]
	v_mfma_f32_16x16x32_bf16 v[64:67], v[216:219], v[188:191], v[64:67]
	s_mov_b32 m0, s25
	v_lshl_add_u64 v[222:223], s[30:31], 0, v[172:173]
	s_barrier
	ds_read_b128 v[144:147], v208 offset:16384
	ds_read_b128 v[148:151], v208 offset:17408
	ds_read_b128 v[152:155], v208 offset:18432
	ds_read_b128 v[156:159], v208 offset:19456
	ds_read_b128 v[160:163], v208 offset:20480
	ds_read_b128 v[164:167], v208 offset:21504
	ds_read_b128 v[168:171], v208 offset:22528
	ds_read_b128 v[188:191], v208 offset:23552
	global_load_lds_dwordx4 v[222:223], off
	v_lshl_add_u64 v[224:225], s[30:31], 0, v[176:177]
	s_mov_b32 m0, s45
	s_nop 0
	global_load_lds_dwordx4 v[224:225], off
	s_barrier
	s_waitcnt lgkmcnt(0)
	s_waitcnt lgkmcnt(0)
	v_mfma_f32_16x16x32_bf16 v[60:63], v[128:131], v[144:147], v[60:63]
	v_mfma_f32_16x16x32_bf16 v[56:59], v[136:139], v[144:147], v[56:59]
	v_mfma_f32_16x16x32_bf16 v[44:47], v[128:131], v[152:155], v[44:47]
	v_mfma_f32_16x16x32_bf16 v[40:43], v[136:139], v[152:155], v[40:43]
	v_mfma_f32_16x16x32_bf16 v[28:31], v[128:131], v[160:163], v[28:31]
	v_mfma_f32_16x16x32_bf16 v[24:27], v[136:139], v[160:163], v[24:27]
	v_mfma_f32_16x16x32_bf16 v[12:15], v[128:131], v[168:171], v[12:15]
	v_mfma_f32_16x16x32_bf16 v[8:11], v[136:139], v[168:171], v[8:11]
	v_mfma_f32_16x16x32_bf16 v[60:63], v[132:135], v[148:151], v[60:63]
	v_mfma_f32_16x16x32_bf16 v[56:59], v[140:143], v[148:151], v[56:59]
	v_mfma_f32_16x16x32_bf16 v[44:47], v[132:135], v[156:159], v[44:47]
	v_mfma_f32_16x16x32_bf16 v[40:43], v[140:143], v[156:159], v[40:43]
	v_mfma_f32_16x16x32_bf16 v[28:31], v[132:135], v[164:167], v[28:31]
	v_mfma_f32_16x16x32_bf16 v[24:27], v[140:143], v[164:167], v[24:27]
	v_mfma_f32_16x16x32_bf16 v[12:15], v[132:135], v[188:191], v[12:15]
	v_mfma_f32_16x16x32_bf16 v[8:11], v[140:143], v[188:191], v[8:11]
	s_barrier
	s_add_u32 s64, s28, 0x40000
	s_addc_u32 s65, s29, 0
	s_add_i32 s63, s54, s35
	v_lshl_add_u64 v[128:129], s[64:65], 0, v[174:175]
	s_mov_b32 m0, s63
	s_nop 0
	global_load_lds_dwordx4 v[128:129], off
	v_lshl_add_u64 v[128:129], s[64:65], 0, v[178:179]
	s_add_i32 m0, s63, 0x2000
	s_nop 0
	global_load_lds_dwordx4 v[128:129], off
	s_waitcnt vmcnt(6)
	s_barrier
; #define PG8_STAGE(bufoff, gbase, voff) do { _Pragma("unroll") for (int _i = 0; _i < 2; ++_i) \
;         __builtin_amdgcn_global_load_lds((const unsigned*)((const char*)(gbase) + (voff)[_i]), (LAS unsigned*)(lds + (bufoff) + ldsw + _i * 8192), 16, 0, 0); } while (0)
; #define PG8_LDA(dst, b, h) do { _Pragma("unroll") for (int m = 0; m < 4; ++m) _Pragma("unroll") for (int k = 0; k < 2; ++k) dst[m][k] = *(const LAS bf16x8*)(lds + PG8_SA(b, h) + aoff + m * 2048 + k * 1024); } while (0)
; #define PG8_LDB(dst, b, h) do { _Pragma("unroll") for (int n = 0; n < 2; ++n) _Pragma("unroll") for (int k = 0; k < 2; ++k) dst[n][k] = *(const LAS bf16x8*)(lds + PG8_SB(b, h) + boff + n * 2048 + k * 1024); } while (0)
; #define PG8_MMA(ai, bj, At, Bt) do { __builtin_amdgcn_s_setprio(1); _Pragma("unroll") for (int m = 0; m < 4; ++m) _Pragma("unroll") for (int n = 0; n < 2; ++n) _Pragma("unroll") for (int k = 0; k < 2; ++k) \
;         acc[ai][bj][m][n] = __builtin_amdgcn_mfma_f32_16x16x32_bf16(Bt[n][k], At[m][k], acc[ai][bj][m][n], 0, 0, 0); __builtin_amdgcn_s_setprio(0); } while (0)
; #define PG8_WAIT_V(n) asm volatile("s_waitcnt vmcnt(" #n ")" ::: "memory")
; #define PG8_WAIT_L(n) asm volatile("s_waitcnt lgkmcnt(" #n ")" ::: "memory")
; #define PG8_BAR __builtin_amdgcn_s_barrier()
; #define PG8_SCHED __builtin_amdgcn_sched_barrier(0)
; template <class Epi>
; __device__ __forceinline__ void gemm_phase(LAS unsigned char* lds, const Gemm g, const StaticOrder& S, const Epi& E) {
;     ...
;             PG8_WAIT_V(6); PG8_BAR; PG8_MMA(1, 1, At, B1); PG8_BAR;
;             PG8_LDB(B0, 1, 0); PG8_SCHED; PG8_LDA(At, 1, 0); PG8_STAGE(PG8_SA(0, 1), a2 + hstep, voffA);
;             PG8_WAIT_L(8); PG8_BAR; PG8_WAIT_L(0); PG8_MMA(0, 0, At, B0); PG8_BAR; PG8_SCHED;
;             PG8_LDB(B1, 1, 1); PG8_STAGE(PG8_SB(1, 0), b3, voffB);
;             PG8_BAR; PG8_WAIT_L(0); PG8_MMA(0, 1, At, B1); PG8_BAR;
;             PG8_LDA(At, 1, 1); PG8_STAGE(PG8_SA(1, 0), a3, voffA);
;             PG8_BAR; PG8_WAIT_L(0); PG8_MMA(1, 0, At, B0); PG8_BAR; PG8_SCHED;
	v_mfma_f32_16x16x32_bf16 v[52:55], v[192:195], v[144:147], v[52:55]
	v_mfma_f32_16x16x32_bf16 v[48:51], v[210:213], v[144:147], v[48:51]
	v_mfma_f32_16x16x32_bf16 v[36:39], v[192:195], v[152:155], v[36:39]
	v_mfma_f32_16x16x32_bf16 v[32:35], v[210:213], v[152:155], v[32:35]
	v_mfma_f32_16x16x32_bf16 v[20:23], v[192:195], v[160:163], v[20:23]
	v_mfma_f32_16x16x32_bf16 v[16:19], v[210:213], v[160:163], v[16:19]
	v_mfma_f32_16x16x32_bf16 v[4:7], v[192:195], v[168:171], v[4:7]
	v_mfma_f32_16x16x32_bf16 v[0:3], v[210:213], v[168:171], v[0:3]
	v_mfma_f32_16x16x32_bf16 v[52:55], v[196:199], v[148:151], v[52:55]
	v_mfma_f32_16x16x32_bf16 v[48:51], v[216:219], v[148:151], v[48:51]
	v_mfma_f32_16x16x32_bf16 v[36:39], v[196:199], v[156:159], v[36:39]
	v_mfma_f32_16x16x32_bf16 v[32:35], v[216:219], v[156:159], v[32:35]
	v_mfma_f32_16x16x32_bf16 v[20:23], v[196:199], v[164:167], v[20:23]
	v_mfma_f32_16x16x32_bf16 v[16:19], v[216:219], v[164:167], v[16:19]
	v_mfma_f32_16x16x32_bf16 v[4:7], v[196:199], v[188:191], v[4:7]
	v_mfma_f32_16x16x32_bf16 v[0:3], v[216:219], v[188:191], v[0:3]
	s_add_i32 s63, 0, 0x18000
	v_add_u32_e32 v140, s63, v205
	s_barrier
	ds_read_b128 v[128:131], v140
	ds_read_b128 v[132:135], v140 offset:1024
	ds_read_b128 v[136:139], v140 offset:2048
	ds_read_b128 v[140:143], v140 offset:3072
	s_add_u32 s30, s30, 0x40000
	s_addc_u32 s31, s31, 0
	s_mov_b32 m0, s46
	v_lshl_add_u64 v[192:193], s[30:31], 0, v[172:173]
	ds_read_b128 v[144:147], v208 offset:32768
	ds_read_b128 v[148:151], v208 offset:33792
	ds_read_b128 v[152:155], v208 offset:34816
	ds_read_b128 v[156:159], v208 offset:35840
	ds_read_b128 v[160:163], v208 offset:36864
	ds_read_b128 v[164:167], v208 offset:37888
	ds_read_b128 v[168:171], v208 offset:38912
	ds_read_b128 v[188:191], v208 offset:39936
	global_load_lds_dwordx4 v[192:193], off
	v_lshl_add_u64 v[192:193], s[30:31], 0, v[176:177]
	s_mov_b32 m0, s47
	s_nop 0
	global_load_lds_dwordx4 v[192:193], off
	s_waitcnt lgkmcnt(8)
	s_barrier
	s_waitcnt lgkmcnt(0)
	s_waitcnt lgkmcnt(0)
	v_mfma_f32_16x16x32_bf16 v[124:127], v[128:131], v[144:147], v[124:127]
	v_mfma_f32_16x16x32_bf16 v[120:123], v[136:139], v[144:147], v[120:123]
	v_mfma_f32_16x16x32_bf16 v[108:111], v[128:131], v[152:155], v[108:111]
	v_mfma_f32_16x16x32_bf16 v[104:107], v[136:139], v[152:155], v[104:107]
	v_mfma_f32_16x16x32_bf16 v[92:95], v[128:131], v[160:163], v[92:95]
	v_mfma_f32_16x16x32_bf16 v[88:91], v[136:139], v[160:163], v[88:91]
	v_mfma_f32_16x16x32_bf16 v[76:79], v[128:131], v[168:171], v[76:79]
	v_mfma_f32_16x16x32_bf16 v[72:75], v[136:139], v[168:171], v[72:75]
	v_mfma_f32_16x16x32_bf16 v[124:127], v[132:135], v[148:151], v[124:127]
	v_mfma_f32_16x16x32_bf16 v[120:123], v[140:143], v[148:151], v[120:123]
	v_mfma_f32_16x16x32_bf16 v[108:111], v[132:135], v[156:159], v[108:111]
	v_mfma_f32_16x16x32_bf16 v[104:107], v[140:143], v[156:159], v[104:107]
	v_mfma_f32_16x16x32_bf16 v[92:95], v[132:135], v[164:167], v[92:95]
	v_mfma_f32_16x16x32_bf16 v[88:91], v[140:143], v[164:167], v[88:91]
	v_mfma_f32_16x16x32_bf16 v[76:79], v[132:135], v[188:191], v[76:79]
	v_mfma_f32_16x16x32_bf16 v[72:75], v[140:143], v[188:191], v[72:75]
	s_barrier
	s_add_i32 s30, 0, 0x1c000
	s_add_i32 s31, s63, s35
	v_add_u32_e32 v216, s30, v205
	v_lshl_add_u64 v[200:201], v[200:201], 0, s[8:9]
	s_mov_b32 m0, s31
	ds_read_b128 v[192:195], v216
	ds_read_b128 v[196:199], v216 offset:1024
	ds_read_b128 v[210:213], v216 offset:2048
	ds_read_b128 v[216:219], v216 offset:3072
	global_load_lds_dwordx4 v[200:201], off
	v_lshl_add_u64 v[200:201], v[220:221], 0, s[8:9]
	s_add_i32 m0, s31, 0x2000
	s_nop 0
	global_load_lds_dwordx4 v[200:201], off
	s_barrier
	s_waitcnt lgkmcnt(0)
	s_waitcnt lgkmcnt(0)
	v_mfma_f32_16x16x32_bf16 v[116:119], v[192:195], v[144:147], v[116:119]
	v_mfma_f32_16x16x32_bf16 v[112:115], v[210:213], v[144:147], v[112:115]
	v_mfma_f32_16x16x32_bf16 v[100:103], v[192:195], v[152:155], v[100:103]
	v_mfma_f32_16x16x32_bf16 v[96:99], v[210:213], v[152:155], v[96:99]
	v_mfma_f32_16x16x32_bf16 v[84:87], v[192:195], v[160:163], v[84:87]
	v_mfma_f32_16x16x32_bf16 v[80:83], v[210:213], v[160:163], v[80:83]
	v_mfma_f32_16x16x32_bf16 v[68:71], v[192:195], v[168:171], v[68:71]
	v_mfma_f32_16x16x32_bf16 v[64:67], v[210:213], v[168:171], v[64:67]
	v_mfma_f32_16x16x32_bf16 v[116:119], v[196:199], v[148:151], v[116:119]
	v_mfma_f32_16x16x32_bf16 v[112:115], v[216:219], v[148:151], v[112:115]
	v_mfma_f32_16x16x32_bf16 v[100:103], v[196:199], v[156:159], v[100:103]
	v_mfma_f32_16x16x32_bf16 v[96:99], v[216:219], v[156:159], v[96:99]
	v_mfma_f32_16x16x32_bf16 v[84:87], v[196:199], v[164:167], v[84:87]
	v_mfma_f32_16x16x32_bf16 v[80:83], v[216:219], v[164:167], v[80:83]
	v_mfma_f32_16x16x32_bf16 v[68:71], v[196:199], v[188:191], v[68:71]
	v_mfma_f32_16x16x32_bf16 v[64:67], v[216:219], v[188:191], v[64:67]
	s_mov_b32 m0, s49
	v_lshl_add_u64 v[200:201], v[222:223], 0, s[8:9]
	s_barrier
	ds_read_b128 v[144:147], v208 offset:49152
	ds_read_b128 v[148:151], v208 offset:50176
	ds_read_b128 v[152:155], v208 offset:51200
	ds_read_b128 v[156:159], v208 offset:52224
	ds_read_b128 v[160:163], v208 offset:53248
	ds_read_b128 v[164:167], v208 offset:54272
	ds_read_b128 v[168:171], v208 offset:55296
	ds_read_b128 v[188:191], v208 offset:56320
	global_load_lds_dwordx4 v[200:201], off
	v_lshl_add_u64 v[200:201], v[224:225], 0, s[8:9]
	s_mov_b32 m0, s50
	s_nop 0
	global_load_lds_dwordx4 v[200:201], off
	s_barrier
; #define PG8_STAGE(bufoff, gbase, voff) do { _Pragma("unroll") for (int _i = 0; _i < 2; ++_i) \
;         __builtin_amdgcn_global_load_lds((const unsigned*)((const char*)(gbase) + (voff)[_i]), (LAS unsigned*)(lds + (bufoff) + ldsw + _i * 8192), 16, 0, 0); } while (0)
; #define PG8_MMA(ai, bj, At, Bt) do { __builtin_amdgcn_s_setprio(1); _Pragma("unroll") for (int m = 0; m < 4; ++m) _Pragma("unroll") for (int n = 0; n < 2; ++n) _Pragma("unroll") for (int k = 0; k < 2; ++k) \
;         acc[ai][bj][m][n] = __builtin_amdgcn_mfma_f32_16x16x32_bf16(Bt[n][k], At[m][k], acc[ai][bj][m][n], 0, 0, 0); __builtin_amdgcn_s_setprio(0); } while (0)
; #define PG8_WAIT_V(n) asm volatile("s_waitcnt vmcnt(" #n ")" ::: "memory")
; #define PG8_WAIT_L(n) asm volatile("s_waitcnt lgkmcnt(" #n ")" ::: "memory")
; #define PG8_BAR __builtin_amdgcn_s_barrier()
; #define PG8_SCHED __builtin_amdgcn_sched_barrier(0)
; template <class Epi>
; __device__ __forceinline__ void gemm_phase(LAS unsigned char* lds, const Gemm g, const StaticOrder& S, const Epi& E) {
;     ...
;             PG8_BAR; PG8_WAIT_L(0); PG8_MMA(1, 0, At, B0); PG8_BAR; PG8_SCHED;
;             PG8_STAGE(PG8_SB(1, 1), b3 + hstep, voffB);
;             PG8_WAIT_V(6); PG8_BAR; PG8_MMA(1, 1, At, B1); PG8_BAR;
;         }
;     __device__ __forceinline__ void operator()(const AccT& acc, const pg8::Unit& u, int wr, int wc, int fr, int fq) const {
;         const int row0 = u.pm * 256 + wr * 64 + fr, col0 = u.pn * 256 + wc * 32 + 8 * fq;
; #pragma unroll
;         for (int ai = 0; ai < 2; ++ai) { u32x4 gw[4][2], tw[4][2];
; #pragma unroll
;             for (int m = 0; m < 4; ++m)
; #pragma unroll
;                 for (int bj = 0; bj < 2; ++bj) { const int r = row0 + ai * 128 + m * 16; gw[m][bj] = *(const u32x4*)(PROJ + (size_t)r * NPROJ + C_GB + col0 + bj * 128); tw[m][bj] = *(const u32x4*)(T + (size_t)r * D + col0 + bj * 128); }
	s_waitcnt lgkmcnt(0)
	s_waitcnt lgkmcnt(0)
	v_mfma_f32_16x16x32_bf16 v[60:63], v[128:131], v[144:147], v[60:63]
	v_mfma_f32_16x16x32_bf16 v[56:59], v[136:139], v[144:147], v[56:59]
	v_mfma_f32_16x16x32_bf16 v[44:47], v[128:131], v[152:155], v[44:47]
	v_mfma_f32_16x16x32_bf16 v[40:43], v[136:139], v[152:155], v[40:43]
	v_mfma_f32_16x16x32_bf16 v[28:31], v[128:131], v[160:163], v[28:31]
	v_mfma_f32_16x16x32_bf16 v[24:27], v[136:139], v[160:163], v[24:27]
	v_mfma_f32_16x16x32_bf16 v[12:15], v[128:131], v[168:171], v[12:15]
	v_mfma_f32_16x16x32_bf16 v[8:11], v[136:139], v[168:171], v[8:11]
	v_mfma_f32_16x16x32_bf16 v[60:63], v[132:135], v[148:151], v[60:63]
	v_mfma_f32_16x16x32_bf16 v[56:59], v[140:143], v[148:151], v[56:59]
	v_mfma_f32_16x16x32_bf16 v[44:47], v[132:135], v[156:159], v[44:47]
	v_mfma_f32_16x16x32_bf16 v[40:43], v[140:143], v[156:159], v[40:43]
	v_mfma_f32_16x16x32_bf16 v[28:31], v[132:135], v[164:167], v[28:31]
	v_mfma_f32_16x16x32_bf16 v[24:27], v[140:143], v[164:167], v[24:27]
	v_mfma_f32_16x16x32_bf16 v[12:15], v[132:135], v[188:191], v[12:15]
	v_mfma_f32_16x16x32_bf16 v[8:11], v[140:143], v[188:191], v[8:11]
	s_barrier
	s_add_u32 s28, s28, 0x40080
	s_addc_u32 s29, s29, 0
	s_add_i32 s30, s30, s35
	v_lshl_add_u64 v[128:129], s[28:29], 0, v[174:175]
	s_mov_b32 m0, s30
	s_nop 0
	global_load_lds_dwordx4 v[128:129], off
	v_lshl_add_u64 v[128:129], s[28:29], 0, v[178:179]
	s_add_i32 m0, s30, 0x2000
	s_nop 0
	global_load_lds_dwordx4 v[128:129], off
	s_waitcnt vmcnt(6)
	s_barrier
	v_mfma_f32_16x16x32_bf16 v[52:55], v[192:195], v[144:147], v[52:55]
	v_mfma_f32_16x16x32_bf16 v[48:51], v[210:213], v[144:147], v[48:51]
	v_mfma_f32_16x16x32_bf16 v[36:39], v[192:195], v[152:155], v[36:39]
	v_mfma_f32_16x16x32_bf16 v[32:35], v[210:213], v[152:155], v[32:35]
	v_mfma_f32_16x16x32_bf16 v[20:23], v[192:195], v[160:163], v[20:23]
	v_mfma_f32_16x16x32_bf16 v[16:19], v[210:213], v[160:163], v[16:19]
	v_mfma_f32_16x16x32_bf16 v[4:7], v[192:195], v[168:171], v[4:7]
	v_mfma_f32_16x16x32_bf16 v[0:3], v[210:213], v[168:171], v[0:3]
	v_mfma_f32_16x16x32_bf16 v[52:55], v[196:199], v[148:151], v[52:55]
	v_mfma_f32_16x16x32_bf16 v[48:51], v[216:219], v[148:151], v[48:51]
	v_mfma_f32_16x16x32_bf16 v[36:39], v[196:199], v[156:159], v[36:39]
	v_mfma_f32_16x16x32_bf16 v[32:35], v[216:219], v[156:159], v[32:35]
	v_mfma_f32_16x16x32_bf16 v[20:23], v[196:199], v[164:167], v[20:23]
	v_mfma_f32_16x16x32_bf16 v[16:19], v[216:219], v[164:167], v[16:19]
	v_mfma_f32_16x16x32_bf16 v[4:7], v[196:199], v[188:191], v[4:7]
	v_mfma_f32_16x16x32_bf16 v[0:3], v[216:219], v[188:191], v[0:3]
	s_add_i32 s62, s62, 2
	s_add_u32 s26, s26, 0x100
	s_addc_u32 s27, s27, 0
	s_add_u32 s60, s60, 0x100
	s_addc_u32 s61, s61, 0
	s_cmp_gt_u32 s62, 13
	s_barrier
	s_cbranch_scc0 .LBB0_930
	v_lshl_or_b32 v128, s57, 8, v206
	v_lshl_add_u32 v192, s24, 8, v204
	v_ashrrev_i32_e32 v129, 31, v128
	v_mov_b64_e32 v[194:195], s[0:1]
	v_lshlrev_b64 v[188:189], 1, v[128:129]
	v_mad_i64_i32 v[128:129], s[26:27], v192, s55, v[194:195]
	v_lshl_add_u64 v[128:129], v[128:129], 0, v[188:189]
	v_add_co_u32_e32 v130, vcc, 0x3000, v128
	v_ashrrev_i32_e32 v193, 31, v192
	s_nop 0
	v_addc_co_u32_e32 v131, vcc, 0, v129, vcc
	global_load_dwordx4 v[216:219], v[130:131], off offset:2048
	v_lshl_add_u64 v[190:191], s[4:5], 0, v[188:189]
	v_lshlrev_b64 v[232:233], 12, v[192:193]
	v_lshl_add_u64 v[132:133], v[190:191], 0, v[232:233]
	global_load_dwordx4 v[210:213], v[132:133], off
	v_lshl_add_u64 v[128:129], v[128:129], 0, s[10:11]
	global_load_dwordx4 v[220:223], v[128:129], off offset:256
	v_or_b32_e32 v130, 16, v192
	v_or_b32_e32 v134, 32, v192
	v_or_b32_e32 v136, 48, v192
	v_ashrrev_i32_e32 v131, 31, v130
	v_mad_i64_i32 v[138:139], s[26:27], v130, s55, v[194:195]
	v_mad_i64_i32 v[140:141], s[26:27], v134, s55, v[194:195]
	v_ashrrev_i32_e32 v135, 31, v134
	v_ashrrev_i32_e32 v137, 31, v136
	v_mad_i64_i32 v[142:143], s[26:27], v136, s55, v[194:195]
	v_lshl_add_u64 v[148:149], v[138:139], 0, v[188:189]
	v_lshlrev_b64 v[200:201], 12, v[130:131]
	v_lshl_add_u64 v[140:141], v[140:141], 0, v[188:189]
	v_lshlrev_b64 v[198:199], 12, v[134:135]
	v_lshl_add_u64 v[134:135], v[142:143], 0, v[188:189]
	v_lshlrev_b64 v[196:197], 12, v[136:137]
	v_lshl_add_u64 v[130:131], v[148:149], 0, s[10:11]
	v_lshl_add_u64 v[142:143], v[190:191], 0, v[200:201]
	v_lshl_add_u64 v[136:137], v[140:141], 0, s[10:11]
	v_lshl_add_u64 v[150:151], v[190:191], 0, v[198:199]
	v_lshl_add_u64 v[156:157], v[134:135], 0, s[10:11]
	v_lshl_add_u64 v[234:235], v[190:191], 0, v[196:197]
	global_load_dwordx4 v[168:171], v[142:143], off
	global_load_dwordx4 v[160:163], v[130:131], off offset:256
	global_load_dwordx4 v[152:155], v[150:151], off
	global_load_dwordx4 v[144:147], v[136:137], off offset:256
	s_nop 0
	global_load_dwordx4 v[136:139], v[234:235], off
	global_load_dwordx4 v[128:131], v[156:157], off offset:256
	global_load_dwordx4 v[224:227], v[132:133], off offset:256
	v_add_co_u32_e32 v148, vcc, s56, v148
	s_mov_b32 s57, s18
	s_nop 0
	v_addc_co_u32_e32 v149, vcc, 0, v149, vcc
	global_load_dwordx4 v[228:231], v[148:149], off offset:2048
	global_load_dwordx4 v[164:167], v[142:143], off offset:256
	v_add_co_u32_e32 v132, vcc, s56, v140
	s_mov_b32 s24, s16
	s_nop 0
	v_addc_co_u32_e32 v133, vcc, 0, v141, vcc
	global_load_dwordx4 v[156:159], v[132:133], off offset:2048
	s_nop 0
	global_load_dwordx4 v[148:151], v[150:151], off offset:256
	v_add_co_u32_e32 v134, vcc, s56, v134
	s_mov_b64 s[28:29], s[22:23]
	s_nop 0
	v_addc_co_u32_e32 v135, vcc, 0, v135, vcc
	global_load_dwordx4 v[140:143], v[134:135], off offset:2048
	s_nop 0
	global_load_dwordx4 v[132:135], v[234:235], off offset:256
	s_waitcnt vmcnt(0)
; __device__ __forceinline__ u32x4 pack8(const f32x4 v0, const f32x4 v1) { u32x4 w; w.x = cvt_pk_bf16(v0[0], v0[1]); w.y = cvt_pk_bf16(v0[2], v0[3]); w.z = cvt_pk_bf16(v1[0], v1[1]); w.w = cvt_pk_bf16(v1[2], v1[3]); return w; }
; __device__ __forceinline__ void unpack8(const u32x4 w, f32x4& v0, f32x4& v1) { v0 = (f32x4){bflo(w.x), bfhi(w.x), bflo(w.y), bfhi(w.y)}; v1 = (f32x4){bflo(w.z), bfhi(w.z), bflo(w.w), bfhi(w.w)}; }
; __device__ __forceinline__ f32x4 sig4(const f32x4 v) { return (f32x4){sigmoidf_(v[0]), sigmoidf_(v[1]), sigmoidf_(v[2]), sigmoidf_(v[3])}; }
;     __device__ __forceinline__ void operator()(const AccT& acc, const pg8::Unit& u, int wr, int wc, int fr, int fq) const {
;         const int row0 = u.pm * 256 + wr * 64 + fr, col0 = u.pn * 256 + wc * 32 + 8 * fq;
; #pragma unroll
;         for (int ai = 0; ai < 2; ++ai) { u32x4 gw[4][2], tw[4][2];
; #pragma unroll
;             for (int m = 0; m < 4; ++m)
; #pragma unroll
;                 for (int bj = 0; bj < 2; ++bj) { const int r = row0 + ai * 128 + m * 16; gw[m][bj] = *(const u32x4*)(PROJ + (size_t)r * NPROJ + C_GB + col0 + bj * 128); tw[m][bj] = *(const u32x4*)(T + (size_t)r * D + col0 + bj * 128); }
; #pragma unroll
;             for (int m = 0; m < 4; ++m)
; #pragma unroll
;                 for (int bj = 0; bj < 2; ++bj) { f32x4 g0, g1, t0, t1; unpack8(gw[m][bj], g0, g1); unpack8(tw[m][bj], t0, t1);
;                     *(u32x4*)(O + (size_t)(row0 + ai * 128 + m * 16) * D + col0 + bj * 128) = pack8(t0 + sig4(g0) * acc[ai][bj][m][0], t1 + sig4(g1) * acc[ai][bj][m][1]); } }
;     }
	v_lshlrev_b32_e32 v193, 16, v216
	v_and_b32_e32 v216, 0xffff0000, v216
	v_mul_f32_e32 v193, 0xbfb8aa3b, v193
	v_lshlrev_b32_e32 v238, 16, v217
	v_exp_f32_e32 v193, v193
	v_mul_f32_e32 v216, 0xbfb8aa3b, v216
	v_and_b32_e32 v239, 0xffff0000, v217
	v_exp_f32_e32 v217, v216
	v_mul_f32_e32 v216, 0xbfb8aa3b, v238
	v_lshlrev_b32_e32 v240, 16, v218
	v_and_b32_e32 v241, 0xffff0000, v218
	v_exp_f32_e32 v218, v216
	v_add_f32_e32 v193, 1.0, v193
	v_rcp_f32_e32 v216, v193
	v_add_f32_e32 v193, 1.0, v217
	v_rcp_f32_e32 v217, v193
	v_add_f32_e32 v193, 1.0, v218
	v_mul_f32_e32 v218, 0xbfb8aa3b, v239
	v_lshlrev_b32_e32 v242, 16, v219
	v_and_b32_e32 v243, 0xffff0000, v219
	v_exp_f32_e32 v219, v218
	v_mul_f32_e32 v218, 0xbfb8aa3b, v240
	v_exp_f32_e32 v238, v218
	v_rcp_f32_e32 v218, v193
	v_add_f32_e32 v193, 1.0, v219
	v_rcp_f32_e32 v219, v193
	v_add_f32_e32 v193, 1.0, v238
	v_mul_f32_e32 v239, 0xbfb8aa3b, v242
	v_rcp_f32_e32 v238, v193
	v_mul_f32_e32 v193, 0xbfb8aa3b, v241
	v_exp_f32_e32 v239, v239
	v_mul_f32_e32 v240, 0xbfb8aa3b, v243
	v_exp_f32_e32 v193, v193
	v_exp_f32_e32 v241, v240
	v_add_f32_e32 v239, 1.0, v239
	v_rcp_f32_e32 v240, v239
	v_add_f32_e32 v193, 1.0, v193
	v_add_f32_e32 v239, 1.0, v241
	v_rcp_f32_e32 v241, v239
	v_rcp_f32_e32 v239, v193
	v_lshlrev_b32_e32 v234, 16, v210
	v_and_b32_e32 v235, 0xffff0000, v210
	v_lshlrev_b32_e32 v210, 16, v211
	v_and_b32_e32 v211, 0xffff0000, v211
	v_lshlrev_b32_e32 v236, 16, v212
	v_and_b32_e32 v237, 0xffff0000, v212
	v_lshlrev_b32_e32 v212, 16, v213
	v_and_b32_e32 v213, 0xffff0000, v213
	v_pk_fma_f32 v[126:127], v[126:127], v[218:219], v[210:211]
	v_pk_fma_f32 v[124:125], v[124:125], v[216:217], v[234:235]
	v_pk_fma_f32 v[210:211], v[122:123], v[240:241], v[212:213]
	v_pk_fma_f32 v[122:123], v[120:121], v[238:239], v[236:237]
	v_cvt_pk_bf16_f32 v120, v124, v125
	v_cvt_pk_bf16_f32 v121, v126, v127
	v_lshlrev_b32_e32 v127, 16, v220
	v_and_b32_e32 v193, 0xffff0000, v220
	v_lshlrev_b32_e32 v212, 16, v221
	v_mul_f32_e32 v127, 0xbfb8aa3b, v127
	v_mul_f32_e32 v193, 0xbfb8aa3b, v193
	v_exp_f32_e32 v213, v127
	v_exp_f32_e32 v193, v193
	v_mul_f32_e32 v212, 0xbfb8aa3b, v212
	v_exp_f32_e32 v218, v212
	v_and_b32_e32 v216, 0xffff0000, v221
	v_lshlrev_b32_e32 v217, 16, v222
	v_add_f32_e32 v213, 1.0, v213
	v_add_f32_e32 v193, 1.0, v193
	v_mul_f32_e32 v216, 0xbfb8aa3b, v216
	v_rcp_f32_e32 v212, v213
	v_rcp_f32_e32 v213, v193
	v_add_f32_e32 v193, 1.0, v218
	v_exp_f32_e32 v218, v216
	v_mul_f32_e32 v216, 0xbfb8aa3b, v217
	v_and_b32_e32 v219, 0xffff0000, v222
	v_exp_f32_e32 v222, v216
	v_rcp_f32_e32 v216, v193
	v_add_f32_e32 v193, 1.0, v218
	v_lshlrev_b32_e32 v220, 16, v223
	v_rcp_f32_e32 v217, v193
	v_add_f32_e32 v193, 1.0, v222
	v_and_b32_e32 v221, 0xffff0000, v223
	v_rcp_f32_e32 v218, v193
	v_mul_f32_e32 v193, 0xbfb8aa3b, v219
	v_mul_f32_e32 v219, 0xbfb8aa3b, v220
	v_exp_f32_e32 v219, v219
	v_mul_f32_e32 v220, 0xbfb8aa3b, v221
	v_exp_f32_e32 v193, v193
	v_exp_f32_e32 v221, v220
	v_add_f32_e32 v219, 1.0, v219
	v_rcp_f32_e32 v220, v219
	v_add_f32_e32 v193, 1.0, v193
	v_add_f32_e32 v219, 1.0, v221
	v_rcp_f32_e32 v221, v219
	v_rcp_f32_e32 v219, v193
	v_lshl_add_u64 v[124:125], s[6:7], 0, v[232:233]
	v_lshl_add_u64 v[124:125], v[124:125], 0, v[188:189]
	v_cvt_pk_bf16_f32 v122, v122, v123
	v_cvt_pk_bf16_f32 v123, v210, v211
	global_store_dwordx4 v[124:125], v[120:123], off
	v_lshlrev_b32_e32 v126, 16, v226
	v_and_b32_e32 v127, 0xffff0000, v226
	v_lshlrev_b32_e32 v120, 16, v224
	v_and_b32_e32 v121, 0xffff0000, v224
	v_lshlrev_b32_e32 v210, 16, v227
	v_and_b32_e32 v211, 0xffff0000, v227
	v_lshlrev_b32_e32 v122, 16, v225
	v_and_b32_e32 v123, 0xffff0000, v225
	v_pk_fma_f32 v[116:117], v[116:117], v[212:213], v[120:121]
	v_pk_fma_f32 v[120:121], v[114:115], v[220:221], v[210:211]
	v_pk_fma_f32 v[114:115], v[112:113], v[218:219], v[126:127]
	v_pk_fma_f32 v[118:119], v[118:119], v[216:217], v[122:123]
	v_cvt_pk_bf16_f32 v112, v116, v117
	v_lshlrev_b32_e32 v117, 16, v228
	v_cvt_pk_bf16_f32 v113, v118, v119
	v_cvt_pk_bf16_f32 v114, v114, v115
	v_cvt_pk_bf16_f32 v115, v120, v121
	v_and_b32_e32 v120, 0xffff0000, v228
	v_lshlrev_b32_e32 v121, 16, v229
	v_mul_f32_e32 v117, 0xbfb8aa3b, v117
	v_mul_f32_e32 v120, 0xbfb8aa3b, v120
	global_store_dwordx4 v[124:125], v[112:115], off offset:256
	v_exp_f32_e32 v124, v117
	v_and_b32_e32 v122, 0xffff0000, v229
	v_lshlrev_b32_e32 v112, 16, v168
	v_and_b32_e32 v113, 0xffff0000, v168
	v_exp_f32_e32 v168, v120
	v_mul_f32_e32 v120, 0xbfb8aa3b, v121
	v_lshlrev_b32_e32 v114, 16, v169
	v_and_b32_e32 v115, 0xffff0000, v169
	v_exp_f32_e32 v169, v120
	v_lshlrev_b32_e32 v123, 16, v230
	v_and_b32_e32 v125, 0xffff0000, v230
	v_lshlrev_b32_e32 v126, 16, v231
	v_and_b32_e32 v127, 0xffff0000, v231
	v_mul_f32_e32 v122, 0xbfb8aa3b, v122
	v_add_f32_e32 v124, 1.0, v124
	v_add_f32_e32 v121, 1.0, v168
	v_exp_f32_e32 v168, v122
	v_mul_f32_e32 v122, 0xbfb8aa3b, v123
	v_mul_f32_e32 v125, 0xbfb8aa3b, v125
	v_mul_f32_e32 v126, 0xbfb8aa3b, v126
	v_mul_f32_e32 v127, 0xbfb8aa3b, v127
	v_rcp_f32_e32 v120, v124
	v_add_f32_e32 v124, 1.0, v169
	v_exp_f32_e32 v169, v122
	v_exp_f32_e32 v125, v125
	v_exp_f32_e32 v126, v126
	v_exp_f32_e32 v127, v127
	v_add_f32_e32 v123, 1.0, v168
	v_rcp_f32_e32 v122, v124
	v_rcp_f32_e32 v123, v123
	v_add_f32_e32 v124, 1.0, v169
	v_add_f32_e32 v125, 1.0, v125
	v_add_f32_e32 v126, 1.0, v126
	v_add_f32_e32 v127, 1.0, v127
	v_rcp_f32_e32 v121, v121
	v_rcp_f32_e32 v124, v124
	v_rcp_f32_e32 v126, v126
	v_rcp_f32_e32 v127, v127
	v_rcp_f32_e32 v125, v125
	v_lshlrev_b32_e32 v116, 16, v170
	v_and_b32_e32 v117, 0xffff0000, v170
	v_lshlrev_b32_e32 v118, 16, v171
	v_and_b32_e32 v119, 0xffff0000, v171
; __device__ __forceinline__ u32x4 pack8(const f32x4 v0, const f32x4 v1) { u32x4 w; w.x = cvt_pk_bf16(v0[0], v0[1]); w.y = cvt_pk_bf16(v0[2], v0[3]); w.z = cvt_pk_bf16(v1[0], v1[1]); w.w = cvt_pk_bf16(v1[2], v1[3]); return w; }
; __device__ __forceinline__ void unpack8(const u32x4 w, f32x4& v0, f32x4& v1) { v0 = (f32x4){bflo(w.x), bfhi(w.x), bflo(w.y), bfhi(w.y)}; v1 = (f32x4){bflo(w.z), bfhi(w.z), bflo(w.w), bfhi(w.w)}; }
; __device__ __forceinline__ f32x4 sig4(const f32x4 v) { return (f32x4){sigmoidf_(v[0]), sigmoidf_(v[1]), sigmoidf_(v[2]), sigmoidf_(v[3])}; }
;     __device__ __forceinline__ void operator()(const AccT& acc, const pg8::Unit& u, int wr, int wc, int fr, int fq) const {
;         const int row0 = u.pm * 256 + wr * 64 + fr, col0 = u.pn * 256 + wc * 32 + 8 * fq;
; #pragma unroll
;         for (int ai = 0; ai < 2; ++ai) { u32x4 gw[4][2], tw[4][2];
; #pragma unroll
;             for (int m = 0; m < 4; ++m)
; #pragma unroll
;                 for (int bj = 0; bj < 2; ++bj) { const int r = row0 + ai * 128 + m * 16; gw[m][bj] = *(const u32x4*)(PROJ + (size_t)r * NPROJ + C_GB + col0 + bj * 128); tw[m][bj] = *(const u32x4*)(T + (size_t)r * D + col0 + bj * 128); }
; #pragma unroll
;             for (int m = 0; m < 4; ++m)
; #pragma unroll
;                 for (int bj = 0; bj < 2; ++bj) { f32x4 g0, g1, t0, t1; unpack8(gw[m][bj], g0, g1); unpack8(tw[m][bj], t0, t1);
;                     *(u32x4*)(O + (size_t)(row0 + ai * 128 + m * 16) * D + col0 + bj * 128) = pack8(t0 + sig4(g0) * acc[ai][bj][m][0], t1 + sig4(g1) * acc[ai][bj][m][1]); } }
;     }
	v_pk_fma_f32 v[110:111], v[110:111], v[122:123], v[114:115]
	v_pk_fma_f32 v[108:109], v[108:109], v[120:121], v[112:113]
	v_pk_fma_f32 v[112:113], v[106:107], v[126:127], v[118:119]
	v_pk_fma_f32 v[106:107], v[104:105], v[124:125], v[116:117]
	v_cvt_pk_bf16_f32 v104, v108, v109
	v_cvt_pk_bf16_f32 v105, v110, v111
	v_lshlrev_b32_e32 v111, 16, v160
	v_and_b32_e32 v114, 0xffff0000, v160
	v_lshlrev_b32_e32 v115, 16, v161
	v_mul_f32_e32 v111, 0xbfb8aa3b, v111
	v_mul_f32_e32 v114, 0xbfb8aa3b, v114
	v_exp_f32_e32 v118, v111
	v_exp_f32_e32 v122, v114
	v_mul_f32_e32 v114, 0xbfb8aa3b, v115
	v_exp_f32_e32 v123, v114
	v_and_b32_e32 v116, 0xffff0000, v161
	v_lshlrev_b32_e32 v117, 16, v162
	v_and_b32_e32 v119, 0xffff0000, v162
	v_lshlrev_b32_e32 v120, 16, v163
	v_and_b32_e32 v121, 0xffff0000, v163
	v_mul_f32_e32 v116, 0xbfb8aa3b, v116
	v_add_f32_e32 v118, 1.0, v118
	v_add_f32_e32 v115, 1.0, v122
	v_exp_f32_e32 v122, v116
	v_mul_f32_e32 v116, 0xbfb8aa3b, v117
	v_mul_f32_e32 v119, 0xbfb8aa3b, v119
	v_mul_f32_e32 v120, 0xbfb8aa3b, v120
	v_mul_f32_e32 v121, 0xbfb8aa3b, v121
	v_rcp_f32_e32 v114, v118
	v_add_f32_e32 v118, 1.0, v123
	v_exp_f32_e32 v123, v116
	v_exp_f32_e32 v119, v119
	v_exp_f32_e32 v120, v120
	v_exp_f32_e32 v121, v121
	v_rcp_f32_e32 v116, v118
	v_add_f32_e32 v118, 1.0, v123
	v_add_f32_e32 v119, 1.0, v119
	v_add_f32_e32 v120, 1.0, v120
	v_add_f32_e32 v121, 1.0, v121
	v_rcp_f32_e32 v115, v115
	v_add_f32_e32 v117, 1.0, v122
	v_rcp_f32_e32 v118, v118
	v_rcp_f32_e32 v120, v120
	v_rcp_f32_e32 v121, v121
	v_rcp_f32_e32 v119, v119
	v_lshl_add_u64 v[108:109], s[6:7], 0, v[200:201]
	v_rcp_f32_e32 v117, v117
	v_lshl_add_u64 v[108:109], v[108:109], 0, v[188:189]
	v_cvt_pk_bf16_f32 v106, v106, v107
	v_cvt_pk_bf16_f32 v107, v112, v113
	global_store_dwordx4 v[108:109], v[104:107], off
	v_lshlrev_b32_e32 v110, 16, v166
	v_and_b32_e32 v111, 0xffff0000, v166
	v_lshlrev_b32_e32 v104, 16, v164
	v_and_b32_e32 v105, 0xffff0000, v164
	v_lshlrev_b32_e32 v112, 16, v167
	v_and_b32_e32 v113, 0xffff0000, v167
	v_lshlrev_b32_e32 v106, 16, v165
	v_and_b32_e32 v107, 0xffff0000, v165
	v_pk_fma_f32 v[100:101], v[100:101], v[114:115], v[104:105]
	v_pk_fma_f32 v[104:105], v[98:99], v[120:121], v[112:113]
	v_pk_fma_f32 v[98:99], v[96:97], v[118:119], v[110:111]
	v_pk_fma_f32 v[102:103], v[102:103], v[116:117], v[106:107]
	v_cvt_pk_bf16_f32 v96, v100, v101
	v_lshlrev_b32_e32 v101, 16, v156
	v_cvt_pk_bf16_f32 v97, v102, v103
	v_cvt_pk_bf16_f32 v98, v98, v99
	v_cvt_pk_bf16_f32 v99, v104, v105
	v_and_b32_e32 v104, 0xffff0000, v156
	v_lshlrev_b32_e32 v105, 16, v157
	v_mul_f32_e32 v101, 0xbfb8aa3b, v101
	v_mul_f32_e32 v104, 0xbfb8aa3b, v104
	global_store_dwordx4 v[108:109], v[96:99], off offset:256
	v_exp_f32_e32 v108, v101
	v_exp_f32_e32 v112, v104
	v_mul_f32_e32 v104, 0xbfb8aa3b, v105
	v_exp_f32_e32 v113, v104
	v_and_b32_e32 v106, 0xffff0000, v157
	v_lshlrev_b32_e32 v107, 16, v158
	v_and_b32_e32 v109, 0xffff0000, v158
	v_lshlrev_b32_e32 v110, 16, v159
	v_and_b32_e32 v111, 0xffff0000, v159
	v_mul_f32_e32 v106, 0xbfb8aa3b, v106
	v_add_f32_e32 v108, 1.0, v108
	v_add_f32_e32 v105, 1.0, v112
	v_exp_f32_e32 v112, v106
	v_mul_f32_e32 v106, 0xbfb8aa3b, v107
	v_mul_f32_e32 v109, 0xbfb8aa3b, v109
	v_mul_f32_e32 v110, 0xbfb8aa3b, v110
	v_mul_f32_e32 v111, 0xbfb8aa3b, v111
	v_rcp_f32_e32 v104, v108
	v_add_f32_e32 v108, 1.0, v113
	v_exp_f32_e32 v113, v106
	v_exp_f32_e32 v109, v109
	v_exp_f32_e32 v110, v110
	v_exp_f32_e32 v111, v111
	v_add_f32_e32 v107, 1.0, v112
	v_rcp_f32_e32 v106, v108
	v_rcp_f32_e32 v107, v107
	v_add_f32_e32 v108, 1.0, v113
	v_add_f32_e32 v109, 1.0, v109
	v_add_f32_e32 v110, 1.0, v110
	v_add_f32_e32 v111, 1.0, v111
	v_rcp_f32_e32 v105, v105
	v_rcp_f32_e32 v108, v108
	v_rcp_f32_e32 v110, v110
	v_rcp_f32_e32 v111, v111
	v_rcp_f32_e32 v109, v109
	v_lshlrev_b32_e32 v98, 16, v153
	v_and_b32_e32 v99, 0xffff0000, v153
	v_lshlrev_b32_e32 v96, 16, v152
	v_and_b32_e32 v97, 0xffff0000, v152
	v_lshlrev_b32_e32 v100, 16, v154
	v_and_b32_e32 v101, 0xffff0000, v154
	v_lshlrev_b32_e32 v102, 16, v155
	v_and_b32_e32 v103, 0xffff0000, v155
	v_pk_fma_f32 v[94:95], v[94:95], v[106:107], v[98:99]
	v_pk_fma_f32 v[92:93], v[92:93], v[104:105], v[96:97]
	v_pk_fma_f32 v[96:97], v[90:91], v[110:111], v[102:103]
	v_pk_fma_f32 v[90:91], v[88:89], v[108:109], v[100:101]
	v_cvt_pk_bf16_f32 v88, v92, v93
	v_cvt_pk_bf16_f32 v89, v94, v95
	v_lshlrev_b32_e32 v95, 16, v144
	v_and_b32_e32 v98, 0xffff0000, v144
	v_lshlrev_b32_e32 v99, 16, v145
	v_mul_f32_e32 v95, 0xbfb8aa3b, v95
	v_mul_f32_e32 v98, 0xbfb8aa3b, v98
	v_exp_f32_e32 v102, v95
	v_exp_f32_e32 v106, v98
	v_mul_f32_e32 v98, 0xbfb8aa3b, v99
	v_exp_f32_e32 v107, v98
	v_and_b32_e32 v100, 0xffff0000, v145
	v_lshlrev_b32_e32 v101, 16, v146
	v_and_b32_e32 v103, 0xffff0000, v146
	v_lshlrev_b32_e32 v104, 16, v147
	v_and_b32_e32 v105, 0xffff0000, v147
	v_mul_f32_e32 v100, 0xbfb8aa3b, v100
	v_add_f32_e32 v102, 1.0, v102
	v_add_f32_e32 v99, 1.0, v106
	v_exp_f32_e32 v106, v100
	v_mul_f32_e32 v100, 0xbfb8aa3b, v101
	v_mul_f32_e32 v103, 0xbfb8aa3b, v103
	v_mul_f32_e32 v104, 0xbfb8aa3b, v104
	v_mul_f32_e32 v105, 0xbfb8aa3b, v105
	v_rcp_f32_e32 v98, v102
	v_add_f32_e32 v102, 1.0, v107
	v_exp_f32_e32 v107, v100
	v_exp_f32_e32 v103, v103
	v_exp_f32_e32 v104, v104
	v_exp_f32_e32 v105, v105
	v_rcp_f32_e32 v100, v102
	v_add_f32_e32 v102, 1.0, v107
	v_add_f32_e32 v103, 1.0, v103
	v_add_f32_e32 v104, 1.0, v104
	v_add_f32_e32 v105, 1.0, v105
	v_rcp_f32_e32 v99, v99
	v_add_f32_e32 v101, 1.0, v106
	v_rcp_f32_e32 v102, v102
	v_rcp_f32_e32 v104, v104
	v_rcp_f32_e32 v105, v105
	v_rcp_f32_e32 v103, v103
	v_lshl_add_u64 v[92:93], s[6:7], 0, v[198:199]
	v_rcp_f32_e32 v101, v101
; __device__ __forceinline__ u32x4 pack8(const f32x4 v0, const f32x4 v1) { u32x4 w; w.x = cvt_pk_bf16(v0[0], v0[1]); w.y = cvt_pk_bf16(v0[2], v0[3]); w.z = cvt_pk_bf16(v1[0], v1[1]); w.w = cvt_pk_bf16(v1[2], v1[3]); return w; }
; __device__ __forceinline__ void unpack8(const u32x4 w, f32x4& v0, f32x4& v1) { v0 = (f32x4){bflo(w.x), bfhi(w.x), bflo(w.y), bfhi(w.y)}; v1 = (f32x4){bflo(w.z), bfhi(w.z), bflo(w.w), bfhi(w.w)}; }
; __device__ __forceinline__ f32x4 sig4(const f32x4 v) { return (f32x4){sigmoidf_(v[0]), sigmoidf_(v[1]), sigmoidf_(v[2]), sigmoidf_(v[3])}; }
;     __device__ __forceinline__ void operator()(const AccT& acc, const pg8::Unit& u, int wr, int wc, int fr, int fq) const {
;         const int row0 = u.pm * 256 + wr * 64 + fr, col0 = u.pn * 256 + wc * 32 + 8 * fq;
; #pragma unroll
;         for (int ai = 0; ai < 2; ++ai) { u32x4 gw[4][2], tw[4][2];
; #pragma unroll
;             for (int m = 0; m < 4; ++m)
; #pragma unroll
;                 for (int bj = 0; bj < 2; ++bj) { const int r = row0 + ai * 128 + m * 16; gw[m][bj] = *(const u32x4*)(PROJ + (size_t)r * NPROJ + C_GB + col0 + bj * 128); tw[m][bj] = *(const u32x4*)(T + (size_t)r * D + col0 + bj * 128); }
; #pragma unroll
;             for (int m = 0; m < 4; ++m)
; #pragma unroll
;                 for (int bj = 0; bj < 2; ++bj) { f32x4 g0, g1, t0, t1; unpack8(gw[m][bj], g0, g1); unpack8(tw[m][bj], t0, t1);
;                     *(u32x4*)(O + (size_t)(row0 + ai * 128 + m * 16) * D + col0 + bj * 128) = pack8(t0 + sig4(g0) * acc[ai][bj][m][0], t1 + sig4(g1) * acc[ai][bj][m][1]); } }
;     }
	v_lshl_add_u64 v[92:93], v[92:93], 0, v[188:189]
	v_cvt_pk_bf16_f32 v90, v90, v91
	v_cvt_pk_bf16_f32 v91, v96, v97
	global_store_dwordx4 v[92:93], v[88:91], off
	v_lshlrev_b32_e32 v94, 16, v150
	v_and_b32_e32 v95, 0xffff0000, v150
	v_lshlrev_b32_e32 v88, 16, v148
	v_and_b32_e32 v89, 0xffff0000, v148
	v_lshlrev_b32_e32 v96, 16, v151
	v_and_b32_e32 v97, 0xffff0000, v151
	v_lshlrev_b32_e32 v90, 16, v149
	v_and_b32_e32 v91, 0xffff0000, v149
	v_pk_fma_f32 v[84:85], v[84:85], v[98:99], v[88:89]
	v_pk_fma_f32 v[88:89], v[82:83], v[104:105], v[96:97]
	v_pk_fma_f32 v[82:83], v[80:81], v[102:103], v[94:95]
	v_pk_fma_f32 v[86:87], v[86:87], v[100:101], v[90:91]
	v_cvt_pk_bf16_f32 v80, v84, v85
	v_lshlrev_b32_e32 v85, 16, v140
	v_cvt_pk_bf16_f32 v81, v86, v87
	v_cvt_pk_bf16_f32 v82, v82, v83
	v_cvt_pk_bf16_f32 v83, v88, v89
	v_and_b32_e32 v88, 0xffff0000, v140
	v_lshlrev_b32_e32 v89, 16, v141
	v_mul_f32_e32 v85, 0xbfb8aa3b, v85
	v_mul_f32_e32 v88, 0xbfb8aa3b, v88
	global_store_dwordx4 v[92:93], v[80:83], off offset:256
	v_exp_f32_e32 v92, v85
	v_exp_f32_e32 v96, v88
	v_mul_f32_e32 v88, 0xbfb8aa3b, v89
	v_exp_f32_e32 v97, v88
	v_and_b32_e32 v90, 0xffff0000, v141
	v_lshlrev_b32_e32 v91, 16, v142
	v_and_b32_e32 v93, 0xffff0000, v142
	v_lshlrev_b32_e32 v94, 16, v143
	v_and_b32_e32 v95, 0xffff0000, v143
	v_mul_f32_e32 v90, 0xbfb8aa3b, v90
	v_add_f32_e32 v92, 1.0, v92
	v_add_f32_e32 v89, 1.0, v96
	v_exp_f32_e32 v96, v90
	v_mul_f32_e32 v90, 0xbfb8aa3b, v91
	v_mul_f32_e32 v93, 0xbfb8aa3b, v93
	v_mul_f32_e32 v94, 0xbfb8aa3b, v94
	v_mul_f32_e32 v95, 0xbfb8aa3b, v95
	v_rcp_f32_e32 v88, v92
	v_add_f32_e32 v92, 1.0, v97
	v_exp_f32_e32 v97, v90
	v_exp_f32_e32 v93, v93
	v_exp_f32_e32 v94, v94
	v_exp_f32_e32 v95, v95
	v_add_f32_e32 v91, 1.0, v96
	v_rcp_f32_e32 v90, v92
	v_rcp_f32_e32 v91, v91
	v_add_f32_e32 v92, 1.0, v97
	v_add_f32_e32 v93, 1.0, v93
	v_add_f32_e32 v94, 1.0, v94
	v_add_f32_e32 v95, 1.0, v95
	v_rcp_f32_e32 v89, v89
	v_rcp_f32_e32 v92, v92
	v_rcp_f32_e32 v94, v94
	v_rcp_f32_e32 v95, v95
	v_rcp_f32_e32 v93, v93
	v_lshlrev_b32_e32 v82, 16, v137
	v_and_b32_e32 v83, 0xffff0000, v137
	v_lshlrev_b32_e32 v80, 16, v136
	v_and_b32_e32 v81, 0xffff0000, v136
	v_lshlrev_b32_e32 v84, 16, v138
	v_and_b32_e32 v85, 0xffff0000, v138
	v_lshlrev_b32_e32 v86, 16, v139
	v_and_b32_e32 v87, 0xffff0000, v139
	v_pk_fma_f32 v[78:79], v[78:79], v[90:91], v[82:83]
	v_pk_fma_f32 v[76:77], v[76:77], v[88:89], v[80:81]
	v_pk_fma_f32 v[80:81], v[74:75], v[94:95], v[86:87]
	v_pk_fma_f32 v[74:75], v[72:73], v[92:93], v[84:85]
	v_cvt_pk_bf16_f32 v72, v76, v77
	v_cvt_pk_bf16_f32 v73, v78, v79
	v_lshlrev_b32_e32 v79, 16, v128
	v_and_b32_e32 v82, 0xffff0000, v128
	v_lshlrev_b32_e32 v83, 16, v129
	v_mul_f32_e32 v79, 0xbfb8aa3b, v79
	v_mul_f32_e32 v82, 0xbfb8aa3b, v82
	v_exp_f32_e32 v86, v79
	v_exp_f32_e32 v90, v82
	v_mul_f32_e32 v82, 0xbfb8aa3b, v83
	v_exp_f32_e32 v91, v82
	v_and_b32_e32 v84, 0xffff0000, v129
	v_lshlrev_b32_e32 v85, 16, v130
	v_and_b32_e32 v87, 0xffff0000, v130
	v_lshlrev_b32_e32 v88, 16, v131
	v_and_b32_e32 v89, 0xffff0000, v131
	v_mul_f32_e32 v84, 0xbfb8aa3b, v84
	v_add_f32_e32 v86, 1.0, v86
	v_add_f32_e32 v83, 1.0, v90
	v_exp_f32_e32 v90, v84
	v_mul_f32_e32 v84, 0xbfb8aa3b, v85
	v_mul_f32_e32 v87, 0xbfb8aa3b, v87
	v_mul_f32_e32 v88, 0xbfb8aa3b, v88
	v_mul_f32_e32 v89, 0xbfb8aa3b, v89
	v_rcp_f32_e32 v82, v86
	v_add_f32_e32 v86, 1.0, v91
	v_exp_f32_e32 v91, v84
	v_exp_f32_e32 v87, v87
	v_exp_f32_e32 v88, v88
	v_exp_f32_e32 v89, v89
	v_rcp_f32_e32 v83, v83
	v_rcp_f32_e32 v84, v86
	v_add_f32_e32 v85, 1.0, v90
	v_add_f32_e32 v86, 1.0, v91
	v_add_f32_e32 v87, 1.0, v87
	v_add_f32_e32 v88, 1.0, v88
	v_add_f32_e32 v89, 1.0, v89
	v_lshl_add_u64 v[76:77], s[6:7], 0, v[196:197]
	v_rcp_f32_e32 v85, v85
	v_rcp_f32_e32 v86, v86
	v_rcp_f32_e32 v88, v88
	v_rcp_f32_e32 v89, v89
	v_rcp_f32_e32 v87, v87
	v_lshl_add_u64 v[76:77], v[76:77], 0, v[188:189]
	v_cvt_pk_bf16_f32 v74, v74, v75
	v_cvt_pk_bf16_f32 v75, v80, v81
	global_store_dwordx4 v[76:77], v[72:75], off
	v_lshlrev_b32_e32 v78, 16, v134
	v_and_b32_e32 v79, 0xffff0000, v134
	v_lshlrev_b32_e32 v72, 16, v132
	v_and_b32_e32 v73, 0xffff0000, v132
	v_lshlrev_b32_e32 v74, 16, v133
	v_and_b32_e32 v75, 0xffff0000, v133
	v_lshlrev_b32_e32 v80, 16, v135
	v_and_b32_e32 v81, 0xffff0000, v135
	v_pk_fma_f32 v[68:69], v[68:69], v[82:83], v[72:73]
	v_pk_fma_f32 v[70:71], v[70:71], v[84:85], v[74:75]
	v_pk_fma_f32 v[72:73], v[66:67], v[88:89], v[80:81]
	v_pk_fma_f32 v[66:67], v[64:65], v[86:87], v[78:79]
	v_cvt_pk_bf16_f32 v64, v68, v69
	v_add_u32_e32 v68, 0x80, v192
	v_cvt_pk_bf16_f32 v65, v70, v71
	v_mad_i64_i32 v[70:71], s[26:27], v68, s55, v[194:195]
	v_lshl_add_u64 v[70:71], v[70:71], 0, v[188:189]
	v_cvt_pk_bf16_f32 v66, v66, v67
	v_cvt_pk_bf16_f32 v67, v72, v73
	v_add_co_u32_e32 v72, vcc, s56, v70
	v_ashrrev_i32_e32 v69, 31, v68
	s_nop 0
	v_addc_co_u32_e32 v73, vcc, 0, v71, vcc
	global_load_dwordx4 v[118:121], v[72:73], off offset:2048
	v_lshlrev_b64 v[134:135], 12, v[68:69]
	v_lshl_add_u64 v[68:69], v[190:191], 0, v[134:135]
	global_load_dwordx4 v[122:125], v[68:69], off
	s_waitcnt vmcnt(0)
; __device__ __forceinline__ u32x4 pack8(const f32x4 v0, const f32x4 v1) { u32x4 w; w.x = cvt_pk_bf16(v0[0], v0[1]); w.y = cvt_pk_bf16(v0[2], v0[3]); w.z = cvt_pk_bf16(v1[0], v1[1]); w.w = cvt_pk_bf16(v1[2], v1[3]); return w; }
; __device__ __forceinline__ void unpack8(const u32x4 w, f32x4& v0, f32x4& v1) { v0 = (f32x4){bflo(w.x), bfhi(w.x), bflo(w.y), bfhi(w.y)}; v1 = (f32x4){bflo(w.z), bfhi(w.z), bflo(w.w), bfhi(w.w)}; }
; __device__ __forceinline__ f32x4 sig4(const f32x4 v) { return (f32x4){sigmoidf_(v[0]), sigmoidf_(v[1]), sigmoidf_(v[2]), sigmoidf_(v[3])}; }
;     __device__ __forceinline__ void operator()(const AccT& acc, const pg8::Unit& u, int wr, int wc, int fr, int fq) const {
;         const int row0 = u.pm * 256 + wr * 64 + fr, col0 = u.pn * 256 + wc * 32 + 8 * fq;
; #pragma unroll
;         for (int ai = 0; ai < 2; ++ai) { u32x4 gw[4][2], tw[4][2];
; #pragma unroll
;             for (int m = 0; m < 4; ++m)
; #pragma unroll
;                 for (int bj = 0; bj < 2; ++bj) { const int r = row0 + ai * 128 + m * 16; gw[m][bj] = *(const u32x4*)(PROJ + (size_t)r * NPROJ + C_GB + col0 + bj * 128); tw[m][bj] = *(const u32x4*)(T + (size_t)r * D + col0 + bj * 128); }
; #pragma unroll
;             for (int m = 0; m < 4; ++m)
; #pragma unroll
;                 for (int bj = 0; bj < 2; ++bj) { f32x4 g0, g1, t0, t1; unpack8(gw[m][bj], g0, g1); unpack8(tw[m][bj], t0, t1);
;                     *(u32x4*)(O + (size_t)(row0 + ai * 128 + m * 16) * D + col0 + bj * 128) = pack8(t0 + sig4(g0) * acc[ai][bj][m][0], t1 + sig4(g1) * acc[ai][bj][m][1]); } }
;     }
	v_lshlrev_b32_e32 v138, 16, v119
	global_store_dwordx4 v[76:77], v[64:67], off offset:256
	v_and_b32_e32 v139, 0xffff0000, v119
	v_lshlrev_b32_e32 v136, 16, v118
	v_lshl_add_u64 v[64:65], v[70:71], 0, s[10:11]
	global_load_dwordx4 v[126:129], v[64:65], off offset:256
	global_load_dwordx4 v[130:133], v[68:69], off offset:256
	v_add_u32_e32 v64, 0x90, v192
	v_ashrrev_i32_e32 v65, 31, v64
	v_mad_i64_i32 v[66:67], s[26:27], v64, s55, v[194:195]
	v_lshl_add_u64 v[66:67], v[66:67], 0, v[188:189]
	v_lshlrev_b64 v[116:117], 12, v[64:65]
	v_lshl_add_u64 v[68:69], v[66:67], 0, s[10:11]
	v_lshl_add_u64 v[64:65], v[190:191], 0, v[116:117]
	v_add_co_u32_e32 v66, vcc, s56, v66
	v_and_b32_e32 v137, 0xffff0000, v118
	s_nop 0
	v_addc_co_u32_e32 v67, vcc, 0, v67, vcc
	global_load_dwordx4 v[104:107], v[64:65], off
	global_load_dwordx4 v[100:103], v[68:69], off offset:256
	global_load_dwordx4 v[108:111], v[66:67], off offset:2048
	global_load_dwordx4 v[96:99], v[64:65], off offset:256
	v_add_u32_e32 v64, 0xa0, v192
	v_ashrrev_i32_e32 v65, 31, v64
	v_mad_i64_i32 v[66:67], s[26:27], v64, s55, v[194:195]
	v_lshl_add_u64 v[66:67], v[66:67], 0, v[188:189]
	v_lshlrev_b64 v[114:115], 12, v[64:65]
	v_lshl_add_u64 v[68:69], v[66:67], 0, s[10:11]
	v_lshl_add_u64 v[64:65], v[190:191], 0, v[114:115]
	v_add_co_u32_e32 v66, vcc, s56, v66
	v_lshlrev_b32_e32 v140, 16, v120
	s_nop 0
	v_addc_co_u32_e32 v67, vcc, 0, v67, vcc
	global_load_dwordx4 v[88:91], v[64:65], off
	global_load_dwordx4 v[84:87], v[68:69], off offset:256
	global_load_dwordx4 v[92:95], v[66:67], off offset:2048
	global_load_dwordx4 v[80:83], v[64:65], off offset:256
	v_and_b32_e32 v141, 0xffff0000, v120
	v_lshlrev_b32_e32 v142, 16, v121
	v_and_b32_e32 v143, 0xffff0000, v121
	v_mul_f32_e32 v138, 0xbfb8aa3b, v138
	v_mul_f32_e32 v139, 0xbfb8aa3b, v139
	v_lshlrev_b32_e32 v120, 16, v123
	v_and_b32_e32 v121, 0xffff0000, v123
	v_mul_f32_e32 v123, 0xbfb8aa3b, v136
	v_mul_f32_e32 v137, 0xbfb8aa3b, v137
	v_exp_f32_e32 v138, v138
	v_exp_f32_e32 v139, v139
	v_mul_f32_e32 v140, 0xbfb8aa3b, v140
	v_mul_f32_e32 v141, 0xbfb8aa3b, v141
	v_mul_f32_e32 v142, 0xbfb8aa3b, v142
	v_mul_f32_e32 v143, 0xbfb8aa3b, v143
	v_exp_f32_e32 v136, v123
	v_exp_f32_e32 v137, v137
	v_exp_f32_e32 v140, v140
	v_exp_f32_e32 v141, v141
	v_exp_f32_e32 v142, v142
	v_exp_f32_e32 v143, v143
	v_add_f32_e32 v138, 1.0, v138
	v_add_f32_e32 v139, 1.0, v139
	v_add_u32_e32 v64, 0xb0, v192
	v_add_f32_e32 v136, 1.0, v136
	v_add_f32_e32 v137, 1.0, v137
	v_rcp_f32_e32 v138, v138
	v_rcp_f32_e32 v139, v139
	v_add_f32_e32 v140, 1.0, v140
	v_add_f32_e32 v141, 1.0, v141
	v_add_f32_e32 v142, 1.0, v142
	v_add_f32_e32 v143, 1.0, v143
	v_mad_i64_i32 v[66:67], s[26:27], v64, s55, v[194:195]
	v_rcp_f32_e32 v136, v136
	v_rcp_f32_e32 v137, v137
	v_rcp_f32_e32 v140, v140
	v_rcp_f32_e32 v142, v142
	v_rcp_f32_e32 v143, v143
	v_rcp_f32_e32 v141, v141
	v_ashrrev_i32_e32 v65, 31, v64
	v_lshl_add_u64 v[66:67], v[66:67], 0, v[188:189]
	v_lshl_add_u64 v[68:69], v[66:67], 0, s[10:11]
	v_lshlrev_b64 v[112:113], 12, v[64:65]
	v_add_co_u32_e32 v66, vcc, s56, v66
	v_lshl_add_u64 v[64:65], v[190:191], 0, v[112:113]
	s_nop 0
	v_addc_co_u32_e32 v67, vcc, 0, v67, vcc
	v_lshlrev_b32_e32 v118, 16, v122
	v_and_b32_e32 v119, 0xffff0000, v122
	v_lshlrev_b32_e32 v122, 16, v124
	v_and_b32_e32 v123, 0xffff0000, v124
	v_lshlrev_b32_e32 v124, 16, v125
	v_and_b32_e32 v125, 0xffff0000, v125
	v_pk_fma_f32 v[62:63], v[62:63], v[138:139], v[120:121]
	global_load_dwordx4 v[72:75], v[64:65], off
	s_nop 0
	global_load_dwordx4 v[68:71], v[68:69], off offset:256
	s_nop 0
	global_load_dwordx4 v[76:79], v[66:67], off offset:2048
	s_nop 0
	global_load_dwordx4 v[64:67], v[64:65], off offset:256
	v_pk_fma_f32 v[60:61], v[60:61], v[136:137], v[118:119]
	v_pk_fma_f32 v[118:119], v[58:59], v[142:143], v[124:125]
	v_pk_fma_f32 v[58:59], v[56:57], v[140:141], v[122:123]
	v_cvt_pk_bf16_f32 v56, v60, v61
	v_cvt_pk_bf16_f32 v57, v62, v63
	s_waitcnt vmcnt(0)
	v_lshlrev_b32_e32 v63, 16, v126
	v_and_b32_e32 v120, 0xffff0000, v126
	v_lshlrev_b32_e32 v121, 16, v127
	v_mul_f32_e32 v63, 0xbfb8aa3b, v63
	v_mul_f32_e32 v120, 0xbfb8aa3b, v120
	v_lshlrev_b32_e32 v123, 16, v128
	v_and_b32_e32 v125, 0xffff0000, v128
	v_exp_f32_e32 v124, v63
	v_exp_f32_e32 v128, v120
	v_mul_f32_e32 v120, 0xbfb8aa3b, v121
	v_and_b32_e32 v122, 0xffff0000, v127
	v_lshlrev_b32_e32 v126, 16, v129
	v_and_b32_e32 v127, 0xffff0000, v129
	v_exp_f32_e32 v129, v120
	v_mul_f32_e32 v122, 0xbfb8aa3b, v122
	v_add_f32_e32 v124, 1.0, v124
	v_add_f32_e32 v121, 1.0, v128
	v_exp_f32_e32 v128, v122
	v_mul_f32_e32 v122, 0xbfb8aa3b, v123
	v_mul_f32_e32 v125, 0xbfb8aa3b, v125
	v_mul_f32_e32 v126, 0xbfb8aa3b, v126
	v_mul_f32_e32 v127, 0xbfb8aa3b, v127
	v_rcp_f32_e32 v120, v124
	v_add_f32_e32 v124, 1.0, v129
	v_exp_f32_e32 v129, v122
	v_exp_f32_e32 v125, v125
	v_exp_f32_e32 v126, v126
	v_exp_f32_e32 v127, v127
	v_rcp_f32_e32 v122, v124
	v_add_f32_e32 v124, 1.0, v129
	v_add_f32_e32 v125, 1.0, v125
	v_add_f32_e32 v126, 1.0, v126
	v_add_f32_e32 v127, 1.0, v127
	v_rcp_f32_e32 v121, v121
	v_add_f32_e32 v123, 1.0, v128
	v_rcp_f32_e32 v124, v124
	v_rcp_f32_e32 v126, v126
	v_rcp_f32_e32 v127, v127
	v_rcp_f32_e32 v125, v125
	v_lshl_add_u64 v[60:61], s[6:7], 0, v[134:135]
	v_rcp_f32_e32 v123, v123
	v_lshl_add_u64 v[60:61], v[60:61], 0, v[188:189]
	v_cvt_pk_bf16_f32 v58, v58, v59
	v_cvt_pk_bf16_f32 v59, v118, v119
	global_store_dwordx4 v[60:61], v[56:59], off
	v_lshlrev_b32_e32 v62, 16, v132
	v_and_b32_e32 v63, 0xffff0000, v132
	v_lshlrev_b32_e32 v56, 16, v130
	v_and_b32_e32 v57, 0xffff0000, v130
	v_lshlrev_b32_e32 v118, 16, v133
	v_and_b32_e32 v119, 0xffff0000, v133
	v_lshlrev_b32_e32 v58, 16, v131
; __device__ __forceinline__ u32x4 pack8(const f32x4 v0, const f32x4 v1) { u32x4 w; w.x = cvt_pk_bf16(v0[0], v0[1]); w.y = cvt_pk_bf16(v0[2], v0[3]); w.z = cvt_pk_bf16(v1[0], v1[1]); w.w = cvt_pk_bf16(v1[2], v1[3]); return w; }
; __device__ __forceinline__ void unpack8(const u32x4 w, f32x4& v0, f32x4& v1) { v0 = (f32x4){bflo(w.x), bfhi(w.x), bflo(w.y), bfhi(w.y)}; v1 = (f32x4){bflo(w.z), bfhi(w.z), bflo(w.w), bfhi(w.w)}; }
; __device__ __forceinline__ f32x4 sig4(const f32x4 v) { return (f32x4){sigmoidf_(v[0]), sigmoidf_(v[1]), sigmoidf_(v[2]), sigmoidf_(v[3])}; }
;     __device__ __forceinline__ void operator()(const AccT& acc, const pg8::Unit& u, int wr, int wc, int fr, int fq) const {
;         const int row0 = u.pm * 256 + wr * 64 + fr, col0 = u.pn * 256 + wc * 32 + 8 * fq;
; #pragma unroll
;         for (int ai = 0; ai < 2; ++ai) { u32x4 gw[4][2], tw[4][2];
; #pragma unroll
;             for (int m = 0; m < 4; ++m)
; #pragma unroll
;                 for (int bj = 0; bj < 2; ++bj) { const int r = row0 + ai * 128 + m * 16; gw[m][bj] = *(const u32x4*)(PROJ + (size_t)r * NPROJ + C_GB + col0 + bj * 128); tw[m][bj] = *(const u32x4*)(T + (size_t)r * D + col0 + bj * 128); }
; #pragma unroll
;             for (int m = 0; m < 4; ++m)
; #pragma unroll
;                 for (int bj = 0; bj < 2; ++bj) { f32x4 g0, g1, t0, t1; unpack8(gw[m][bj], g0, g1); unpack8(tw[m][bj], t0, t1);
;                     *(u32x4*)(O + (size_t)(row0 + ai * 128 + m * 16) * D + col0 + bj * 128) = pack8(t0 + sig4(g0) * acc[ai][bj][m][0], t1 + sig4(g1) * acc[ai][bj][m][1]); } }
;     }
	v_and_b32_e32 v59, 0xffff0000, v131
	v_pk_fma_f32 v[52:53], v[52:53], v[120:121], v[56:57]
	v_pk_fma_f32 v[56:57], v[50:51], v[126:127], v[118:119]
	v_pk_fma_f32 v[50:51], v[48:49], v[124:125], v[62:63]
	v_pk_fma_f32 v[54:55], v[54:55], v[122:123], v[58:59]
	v_cvt_pk_bf16_f32 v48, v52, v53
	v_lshlrev_b32_e32 v53, 16, v108
	v_cvt_pk_bf16_f32 v49, v54, v55
	v_cvt_pk_bf16_f32 v50, v50, v51
	v_cvt_pk_bf16_f32 v51, v56, v57
	v_and_b32_e32 v56, 0xffff0000, v108
	v_lshlrev_b32_e32 v57, 16, v109
	v_mul_f32_e32 v53, 0xbfb8aa3b, v53
	v_mul_f32_e32 v56, 0xbfb8aa3b, v56
	global_store_dwordx4 v[60:61], v[48:51], off offset:256
	v_exp_f32_e32 v60, v53
	v_and_b32_e32 v58, 0xffff0000, v109
	v_lshlrev_b32_e32 v48, 16, v104
	v_and_b32_e32 v49, 0xffff0000, v104
	v_exp_f32_e32 v104, v56
	v_mul_f32_e32 v56, 0xbfb8aa3b, v57
	v_lshlrev_b32_e32 v50, 16, v105
	v_and_b32_e32 v51, 0xffff0000, v105
	v_exp_f32_e32 v105, v56
	v_lshlrev_b32_e32 v59, 16, v110
	v_and_b32_e32 v61, 0xffff0000, v110
	v_lshlrev_b32_e32 v62, 16, v111
	v_and_b32_e32 v63, 0xffff0000, v111
	v_mul_f32_e32 v58, 0xbfb8aa3b, v58
	v_add_f32_e32 v60, 1.0, v60
	v_add_f32_e32 v57, 1.0, v104
	v_exp_f32_e32 v104, v58
	v_mul_f32_e32 v58, 0xbfb8aa3b, v59
	v_mul_f32_e32 v61, 0xbfb8aa3b, v61
	v_mul_f32_e32 v62, 0xbfb8aa3b, v62
	v_mul_f32_e32 v63, 0xbfb8aa3b, v63
	v_rcp_f32_e32 v56, v60
	v_add_f32_e32 v60, 1.0, v105
	v_exp_f32_e32 v105, v58
	v_exp_f32_e32 v61, v61
	v_exp_f32_e32 v62, v62
	v_exp_f32_e32 v63, v63
	v_add_f32_e32 v59, 1.0, v104
	v_rcp_f32_e32 v58, v60
	v_rcp_f32_e32 v59, v59
	v_add_f32_e32 v60, 1.0, v105
	v_add_f32_e32 v61, 1.0, v61
	v_add_f32_e32 v62, 1.0, v62
	v_add_f32_e32 v63, 1.0, v63
	v_rcp_f32_e32 v57, v57
	v_rcp_f32_e32 v60, v60
	v_rcp_f32_e32 v62, v62
	v_rcp_f32_e32 v63, v63
	v_rcp_f32_e32 v61, v61
	v_lshlrev_b32_e32 v52, 16, v106
	v_and_b32_e32 v53, 0xffff0000, v106
	v_lshlrev_b32_e32 v54, 16, v107
	v_and_b32_e32 v55, 0xffff0000, v107
	v_pk_fma_f32 v[46:47], v[46:47], v[58:59], v[50:51]
	v_pk_fma_f32 v[44:45], v[44:45], v[56:57], v[48:49]
	v_pk_fma_f32 v[48:49], v[42:43], v[62:63], v[54:55]
	v_pk_fma_f32 v[42:43], v[40:41], v[60:61], v[52:53]
	v_cvt_pk_bf16_f32 v40, v44, v45
	v_cvt_pk_bf16_f32 v41, v46, v47
	v_lshlrev_b32_e32 v47, 16, v100
	v_and_b32_e32 v50, 0xffff0000, v100
	v_lshlrev_b32_e32 v51, 16, v101
	v_mul_f32_e32 v47, 0xbfb8aa3b, v47
	v_mul_f32_e32 v50, 0xbfb8aa3b, v50
	v_exp_f32_e32 v54, v47
	v_exp_f32_e32 v58, v50
	v_mul_f32_e32 v50, 0xbfb8aa3b, v51
	v_exp_f32_e32 v59, v50
	v_and_b32_e32 v52, 0xffff0000, v101
	v_lshlrev_b32_e32 v53, 16, v102
	v_and_b32_e32 v55, 0xffff0000, v102
	v_lshlrev_b32_e32 v56, 16, v103
	v_and_b32_e32 v57, 0xffff0000, v103
	v_mul_f32_e32 v52, 0xbfb8aa3b, v52
	v_add_f32_e32 v54, 1.0, v54
	v_add_f32_e32 v51, 1.0, v58
	v_exp_f32_e32 v58, v52
	v_mul_f32_e32 v52, 0xbfb8aa3b, v53
	v_mul_f32_e32 v55, 0xbfb8aa3b, v55
	v_mul_f32_e32 v56, 0xbfb8aa3b, v56
	v_mul_f32_e32 v57, 0xbfb8aa3b, v57
	v_rcp_f32_e32 v50, v54
	v_add_f32_e32 v54, 1.0, v59
	v_exp_f32_e32 v59, v52
	v_exp_f32_e32 v55, v55
	v_exp_f32_e32 v56, v56
	v_exp_f32_e32 v57, v57
	v_rcp_f32_e32 v52, v54
	v_add_f32_e32 v54, 1.0, v59
	v_add_f32_e32 v55, 1.0, v55
	v_add_f32_e32 v56, 1.0, v56
	v_add_f32_e32 v57, 1.0, v57
	v_rcp_f32_e32 v51, v51
	v_add_f32_e32 v53, 1.0, v58
	v_rcp_f32_e32 v54, v54
	v_rcp_f32_e32 v56, v56
	v_rcp_f32_e32 v57, v57
	v_rcp_f32_e32 v55, v55
	v_lshl_add_u64 v[44:45], s[6:7], 0, v[116:117]
	v_rcp_f32_e32 v53, v53
	v_lshl_add_u64 v[44:45], v[44:45], 0, v[188:189]
	v_cvt_pk_bf16_f32 v42, v42, v43
	v_cvt_pk_bf16_f32 v43, v48, v49
	global_store_dwordx4 v[44:45], v[40:43], off
	v_lshlrev_b32_e32 v46, 16, v98
	v_and_b32_e32 v47, 0xffff0000, v98
	v_lshlrev_b32_e32 v40, 16, v96
	v_and_b32_e32 v41, 0xffff0000, v96
	v_lshlrev_b32_e32 v48, 16, v99
	v_and_b32_e32 v49, 0xffff0000, v99
	v_lshlrev_b32_e32 v42, 16, v97
	v_and_b32_e32 v43, 0xffff0000, v97
	v_pk_fma_f32 v[36:37], v[36:37], v[50:51], v[40:41]
	v_pk_fma_f32 v[40:41], v[34:35], v[56:57], v[48:49]
	v_pk_fma_f32 v[34:35], v[32:33], v[54:55], v[46:47]
	v_pk_fma_f32 v[38:39], v[38:39], v[52:53], v[42:43]
	v_cvt_pk_bf16_f32 v32, v36, v37
	v_lshlrev_b32_e32 v37, 16, v92
	v_cvt_pk_bf16_f32 v33, v38, v39
	v_cvt_pk_bf16_f32 v34, v34, v35
	v_cvt_pk_bf16_f32 v35, v40, v41
	v_and_b32_e32 v40, 0xffff0000, v92
	v_lshlrev_b32_e32 v41, 16, v93
	v_mul_f32_e32 v37, 0xbfb8aa3b, v37
	v_mul_f32_e32 v40, 0xbfb8aa3b, v40
	global_store_dwordx4 v[44:45], v[32:35], off offset:256
	v_exp_f32_e32 v44, v37
	v_exp_f32_e32 v48, v40
	v_mul_f32_e32 v40, 0xbfb8aa3b, v41
	v_exp_f32_e32 v49, v40
	v_and_b32_e32 v42, 0xffff0000, v93
	v_lshlrev_b32_e32 v43, 16, v94
	v_and_b32_e32 v45, 0xffff0000, v94
	v_lshlrev_b32_e32 v46, 16, v95
	v_and_b32_e32 v47, 0xffff0000, v95
	v_mul_f32_e32 v42, 0xbfb8aa3b, v42
	v_add_f32_e32 v44, 1.0, v44
	v_add_f32_e32 v41, 1.0, v48
	v_exp_f32_e32 v48, v42
	v_mul_f32_e32 v42, 0xbfb8aa3b, v43
	v_mul_f32_e32 v45, 0xbfb8aa3b, v45
	v_mul_f32_e32 v46, 0xbfb8aa3b, v46
	v_mul_f32_e32 v47, 0xbfb8aa3b, v47
	v_rcp_f32_e32 v40, v44
	v_add_f32_e32 v44, 1.0, v49
	v_exp_f32_e32 v49, v42
	v_exp_f32_e32 v45, v45
	v_exp_f32_e32 v46, v46
	v_exp_f32_e32 v47, v47
	v_add_f32_e32 v43, 1.0, v48
	v_rcp_f32_e32 v42, v44
	v_rcp_f32_e32 v43, v43
	v_add_f32_e32 v44, 1.0, v49
	v_add_f32_e32 v45, 1.0, v45
	v_add_f32_e32 v46, 1.0, v46
	v_add_f32_e32 v47, 1.0, v47
	v_rcp_f32_e32 v41, v41
	v_rcp_f32_e32 v44, v44
	v_rcp_f32_e32 v46, v46
	v_rcp_f32_e32 v47, v47
	v_rcp_f32_e32 v45, v45
	v_lshlrev_b32_e32 v34, 16, v89
	v_and_b32_e32 v35, 0xffff0000, v89
	v_lshlrev_b32_e32 v32, 16, v88
	v_and_b32_e32 v33, 0xffff0000, v88
	v_lshlrev_b32_e32 v36, 16, v90
	v_and_b32_e32 v37, 0xffff0000, v90
; __device__ __forceinline__ u32x4 pack8(const f32x4 v0, const f32x4 v1) { u32x4 w; w.x = cvt_pk_bf16(v0[0], v0[1]); w.y = cvt_pk_bf16(v0[2], v0[3]); w.z = cvt_pk_bf16(v1[0], v1[1]); w.w = cvt_pk_bf16(v1[2], v1[3]); return w; }
; __device__ __forceinline__ void unpack8(const u32x4 w, f32x4& v0, f32x4& v1) { v0 = (f32x4){bflo(w.x), bfhi(w.x), bflo(w.y), bfhi(w.y)}; v1 = (f32x4){bflo(w.z), bfhi(w.z), bflo(w.w), bfhi(w.w)}; }
; __device__ __forceinline__ f32x4 sig4(const f32x4 v) { return (f32x4){sigmoidf_(v[0]), sigmoidf_(v[1]), sigmoidf_(v[2]), sigmoidf_(v[3])}; }
;     __device__ __forceinline__ void operator()(const AccT& acc, const pg8::Unit& u, int wr, int wc, int fr, int fq) const {
;         const int row0 = u.pm * 256 + wr * 64 + fr, col0 = u.pn * 256 + wc * 32 + 8 * fq;
; #pragma unroll
;         for (int ai = 0; ai < 2; ++ai) { u32x4 gw[4][2], tw[4][2];
; #pragma unroll
;             for (int m = 0; m < 4; ++m)
; #pragma unroll
;                 for (int bj = 0; bj < 2; ++bj) { const int r = row0 + ai * 128 + m * 16; gw[m][bj] = *(const u32x4*)(PROJ + (size_t)r * NPROJ + C_GB + col0 + bj * 128); tw[m][bj] = *(const u32x4*)(T + (size_t)r * D + col0 + bj * 128); }
; #pragma unroll
;             for (int m = 0; m < 4; ++m)
; #pragma unroll
;                 for (int bj = 0; bj < 2; ++bj) { f32x4 g0, g1, t0, t1; unpack8(gw[m][bj], g0, g1); unpack8(tw[m][bj], t0, t1);
;                     *(u32x4*)(O + (size_t)(row0 + ai * 128 + m * 16) * D + col0 + bj * 128) = pack8(t0 + sig4(g0) * acc[ai][bj][m][0], t1 + sig4(g1) * acc[ai][bj][m][1]); } }
;     }
	v_lshlrev_b32_e32 v38, 16, v91
	v_and_b32_e32 v39, 0xffff0000, v91
	v_pk_fma_f32 v[30:31], v[30:31], v[42:43], v[34:35]
	v_pk_fma_f32 v[28:29], v[28:29], v[40:41], v[32:33]
	v_pk_fma_f32 v[32:33], v[26:27], v[46:47], v[38:39]
	v_pk_fma_f32 v[26:27], v[24:25], v[44:45], v[36:37]
	v_cvt_pk_bf16_f32 v24, v28, v29
	v_cvt_pk_bf16_f32 v25, v30, v31
	v_lshlrev_b32_e32 v31, 16, v84
	v_and_b32_e32 v34, 0xffff0000, v84
	v_lshlrev_b32_e32 v35, 16, v85
	v_mul_f32_e32 v31, 0xbfb8aa3b, v31
	v_mul_f32_e32 v34, 0xbfb8aa3b, v34
	v_exp_f32_e32 v38, v31
	v_exp_f32_e32 v42, v34
	v_mul_f32_e32 v34, 0xbfb8aa3b, v35
	v_exp_f32_e32 v43, v34
	v_and_b32_e32 v36, 0xffff0000, v85
	v_lshlrev_b32_e32 v37, 16, v86
	v_and_b32_e32 v39, 0xffff0000, v86
	v_lshlrev_b32_e32 v40, 16, v87
	v_and_b32_e32 v41, 0xffff0000, v87
	v_mul_f32_e32 v36, 0xbfb8aa3b, v36
	v_add_f32_e32 v38, 1.0, v38
	v_add_f32_e32 v35, 1.0, v42
	v_exp_f32_e32 v42, v36
	v_mul_f32_e32 v36, 0xbfb8aa3b, v37
	v_mul_f32_e32 v39, 0xbfb8aa3b, v39
	v_mul_f32_e32 v40, 0xbfb8aa3b, v40
	v_mul_f32_e32 v41, 0xbfb8aa3b, v41
	v_rcp_f32_e32 v34, v38
	v_add_f32_e32 v38, 1.0, v43
	v_exp_f32_e32 v43, v36
	v_exp_f32_e32 v39, v39
	v_exp_f32_e32 v40, v40
	v_exp_f32_e32 v41, v41
	v_rcp_f32_e32 v36, v38
	v_add_f32_e32 v38, 1.0, v43
	v_add_f32_e32 v39, 1.0, v39
	v_add_f32_e32 v40, 1.0, v40
	v_add_f32_e32 v41, 1.0, v41
	v_rcp_f32_e32 v35, v35
	v_add_f32_e32 v37, 1.0, v42
	v_rcp_f32_e32 v38, v38
	v_rcp_f32_e32 v40, v40
	v_rcp_f32_e32 v41, v41
	v_rcp_f32_e32 v39, v39
	v_lshl_add_u64 v[28:29], s[6:7], 0, v[114:115]
	v_rcp_f32_e32 v37, v37
	v_lshl_add_u64 v[28:29], v[28:29], 0, v[188:189]
	v_cvt_pk_bf16_f32 v26, v26, v27
	v_cvt_pk_bf16_f32 v27, v32, v33
	global_store_dwordx4 v[28:29], v[24:27], off
	v_lshlrev_b32_e32 v30, 16, v82
	v_and_b32_e32 v31, 0xffff0000, v82
	v_lshlrev_b32_e32 v24, 16, v80
	v_and_b32_e32 v25, 0xffff0000, v80
	v_lshlrev_b32_e32 v32, 16, v83
	v_and_b32_e32 v33, 0xffff0000, v83
	v_lshlrev_b32_e32 v26, 16, v81
	v_and_b32_e32 v27, 0xffff0000, v81
	v_pk_fma_f32 v[20:21], v[20:21], v[34:35], v[24:25]
	v_pk_fma_f32 v[24:25], v[18:19], v[40:41], v[32:33]
	v_pk_fma_f32 v[18:19], v[16:17], v[38:39], v[30:31]
	v_pk_fma_f32 v[22:23], v[22:23], v[36:37], v[26:27]
	v_cvt_pk_bf16_f32 v16, v20, v21
	v_lshlrev_b32_e32 v21, 16, v76
	v_cvt_pk_bf16_f32 v17, v22, v23
	v_cvt_pk_bf16_f32 v18, v18, v19
	v_cvt_pk_bf16_f32 v19, v24, v25
	v_and_b32_e32 v24, 0xffff0000, v76
	v_lshlrev_b32_e32 v25, 16, v77
	v_mul_f32_e32 v21, 0xbfb8aa3b, v21
	v_mul_f32_e32 v24, 0xbfb8aa3b, v24
	global_store_dwordx4 v[28:29], v[16:19], off offset:256
	v_exp_f32_e32 v28, v21
	v_exp_f32_e32 v32, v24
	v_mul_f32_e32 v24, 0xbfb8aa3b, v25
	v_exp_f32_e32 v33, v24
	v_and_b32_e32 v26, 0xffff0000, v77
	v_lshlrev_b32_e32 v27, 16, v78
	v_and_b32_e32 v29, 0xffff0000, v78
	v_lshlrev_b32_e32 v30, 16, v79
	v_and_b32_e32 v31, 0xffff0000, v79
	v_mul_f32_e32 v26, 0xbfb8aa3b, v26
	v_add_f32_e32 v28, 1.0, v28
	v_add_f32_e32 v25, 1.0, v32
	v_exp_f32_e32 v32, v26
	v_mul_f32_e32 v26, 0xbfb8aa3b, v27
	v_mul_f32_e32 v29, 0xbfb8aa3b, v29
	v_mul_f32_e32 v30, 0xbfb8aa3b, v30
	v_mul_f32_e32 v31, 0xbfb8aa3b, v31
	v_rcp_f32_e32 v24, v28
	v_add_f32_e32 v28, 1.0, v33
	v_exp_f32_e32 v33, v26
	v_exp_f32_e32 v29, v29
	v_exp_f32_e32 v30, v30
	v_exp_f32_e32 v31, v31
	v_add_f32_e32 v27, 1.0, v32
	v_rcp_f32_e32 v26, v28
	v_rcp_f32_e32 v27, v27
	v_add_f32_e32 v28, 1.0, v33
	v_add_f32_e32 v29, 1.0, v29
	v_add_f32_e32 v30, 1.0, v30
	v_add_f32_e32 v31, 1.0, v31
	v_rcp_f32_e32 v25, v25
	v_rcp_f32_e32 v28, v28
	v_rcp_f32_e32 v30, v30
	v_rcp_f32_e32 v31, v31
	v_rcp_f32_e32 v29, v29
	v_lshlrev_b32_e32 v18, 16, v73
	v_and_b32_e32 v19, 0xffff0000, v73
	v_lshlrev_b32_e32 v16, 16, v72
	v_and_b32_e32 v17, 0xffff0000, v72
	v_lshlrev_b32_e32 v20, 16, v74
	v_and_b32_e32 v21, 0xffff0000, v74
	v_lshlrev_b32_e32 v22, 16, v75
	v_and_b32_e32 v23, 0xffff0000, v75
	v_pk_fma_f32 v[14:15], v[14:15], v[26:27], v[18:19]
	v_pk_fma_f32 v[12:13], v[12:13], v[24:25], v[16:17]
	v_pk_fma_f32 v[16:17], v[10:11], v[30:31], v[22:23]
	v_pk_fma_f32 v[10:11], v[8:9], v[28:29], v[20:21]
	v_cvt_pk_bf16_f32 v8, v12, v13
	v_cvt_pk_bf16_f32 v9, v14, v15
	v_lshlrev_b32_e32 v15, 16, v68
	v_and_b32_e32 v18, 0xffff0000, v68
	v_lshlrev_b32_e32 v19, 16, v69
	v_mul_f32_e32 v15, 0xbfb8aa3b, v15
	v_mul_f32_e32 v18, 0xbfb8aa3b, v18
	v_exp_f32_e32 v22, v15
	v_exp_f32_e32 v26, v18
	v_mul_f32_e32 v18, 0xbfb8aa3b, v19
	v_exp_f32_e32 v27, v18
	v_and_b32_e32 v20, 0xffff0000, v69
	v_lshlrev_b32_e32 v21, 16, v70
	v_and_b32_e32 v23, 0xffff0000, v70
	v_lshlrev_b32_e32 v24, 16, v71
	v_and_b32_e32 v25, 0xffff0000, v71
	v_mul_f32_e32 v20, 0xbfb8aa3b, v20
	v_add_f32_e32 v22, 1.0, v22
	v_add_f32_e32 v19, 1.0, v26
	v_exp_f32_e32 v26, v20
	v_mul_f32_e32 v20, 0xbfb8aa3b, v21
	v_mul_f32_e32 v23, 0xbfb8aa3b, v23
	v_mul_f32_e32 v24, 0xbfb8aa3b, v24
	v_mul_f32_e32 v25, 0xbfb8aa3b, v25
	v_rcp_f32_e32 v18, v22
	v_add_f32_e32 v22, 1.0, v27
	v_exp_f32_e32 v27, v20
	v_exp_f32_e32 v23, v23
	v_exp_f32_e32 v24, v24
	v_exp_f32_e32 v25, v25
	v_rcp_f32_e32 v20, v22
	v_add_f32_e32 v22, 1.0, v27
	v_add_f32_e32 v23, 1.0, v23
	v_add_f32_e32 v24, 1.0, v24
	v_add_f32_e32 v25, 1.0, v25
	v_rcp_f32_e32 v19, v19
	v_add_f32_e32 v21, 1.0, v26
	v_rcp_f32_e32 v22, v22
	v_rcp_f32_e32 v24, v24
	v_rcp_f32_e32 v25, v25
	v_rcp_f32_e32 v23, v23
	v_lshl_add_u64 v[12:13], s[6:7], 0, v[112:113]
	v_rcp_f32_e32 v21, v21
	v_lshl_add_u64 v[12:13], v[12:13], 0, v[188:189]
	v_cvt_pk_bf16_f32 v10, v10, v11
	v_cvt_pk_bf16_f32 v11, v16, v17
	global_store_dwordx4 v[12:13], v[8:11], off
	v_lshlrev_b32_e32 v14, 16, v66
	v_and_b32_e32 v15, 0xffff0000, v66
	v_lshlrev_b32_e32 v8, 16, v64
	v_and_b32_e32 v9, 0xffff0000, v64
	v_lshlrev_b32_e32 v16, 16, v67
	v_and_b32_e32 v17, 0xffff0000, v67
	v_lshlrev_b32_e32 v10, 16, v65
	v_and_b32_e32 v11, 0xffff0000, v65
	v_pk_fma_f32 v[4:5], v[4:5], v[18:19], v[8:9]
	v_pk_fma_f32 v[8:9], v[2:3], v[24:25], v[16:17]
	v_pk_fma_f32 v[2:3], v[0:1], v[22:23], v[14:15]
	s_and_b64 vcc, exec, s[2:3]
	s_mov_b64 s[26:27], s[20:21]
	v_pk_fma_f32 v[6:7], v[6:7], v[20:21], v[10:11]
	v_cvt_pk_bf16_f32 v0, v4, v5
	s_nop 0
	v_cvt_pk_bf16_f32 v1, v6, v7
	v_cvt_pk_bf16_f32 v2, v2, v3
	v_cvt_pk_bf16_f32 v3, v8, v9
	global_store_dwordx4 v[12:13], v[0:3], off offset:256
	s_cbranch_vccz .LBB0_923
	s_waitcnt vmcnt(0)
	s_cmpk_gt_u32 s34, 0xff
	s_cbranch_scc1 .LBB0_934
	s_barrier

; #define PG8_STAGE(bufoff, gbase, voff) do { _Pragma("unroll") for (int _i = 0; _i < 2; ++_i) \
;         __builtin_amdgcn_global_load_lds((const unsigned*)((const char*)(gbase) + (voff)[_i]), (LAS unsigned*)(lds + (bufoff) + ldsw + _i * 8192), 16, 0, 0); } while (0)
; #define PG8_WAIT_V(n) asm volatile("s_waitcnt vmcnt(" #n ")" ::: "memory")
; #define PG8_BAR __builtin_amdgcn_s_barrier()
; template <class Epi>
; __device__ __forceinline__ void gemm_phase(LAS unsigned char* lds, const Gemm g, const StaticOrder& S, const Epi& E) {
;     const int tid = threadIdx.x, wid = __builtin_amdgcn_readfirstlane(tid >> 6), lane = tid & 63, wr = wid >> 2, wc = wid & 3, fr = lane & 15, fq = lane >> 4;
;     const int K = g.K, nt = K / BK;
;     unsigned voffA[2], voffB[2];
; #pragma unroll
;     for (int i = 0; i < 2; ++i) { int R, C; stage_rc(tid * 16 + i * 8192, R, C); const int Rb = Epi::PERM ? ((R & ~31) + perm32(R & 31)) : R;
;         voffA[i] = (unsigned)(R * K + C) * 2u; voffB[i] = (unsigned)(Rb * K + C) * 2u; }
;     const size_t kstep = (size_t)(BK * 2);
;     const size_t hstep = (size_t)HALF * K * 2;
;     const size_t tstep = 2 * hstep;
;     const unsigned ldsw = (unsigned)wid * 1024u;
;     const int aoff = lds_byte(wr * 64 + fr, fq * 8), boff = lds_byte(wc * 32 + fr, fq * 8);
;     ...
;     Unit cur, nxt; int ui = 0;
;     if (!S.next(0, cur)) return;
;     f32x4 acc[2][2][4][2];
; #pragma unroll
;     for (int a = 0; a < 2; ++a)
; #pragma unroll
;         for (int b = 0; b < 2; ++b)
; #pragma unroll
;             for (int m = 0; m < 4; ++m)
; #pragma unroll
;                 for (int n = 0; n < 2; ++n) acc[a][b][m][n] = (f32x4){0.f, 0.f, 0.f, 0.f};
;     bf16x8 At[4][2], B0[2][2], B1[2][2];
;     const char* cA = (const char*)g.A + (size_t)cur.pm * tstep; const char* cB = (const char*)g.Bt + (size_t)cur.pn * tstep;
;     PG8_STAGE(PG8_SB(0, 0), cB, voffB); PG8_STAGE(PG8_SA(0, 0), cA, voffA); PG8_STAGE(PG8_SB(0, 1), cB + hstep, voffB); PG8_STAGE(PG8_SA(0, 1), cA + hstep, voffA);
;     if (wr == 1) PG8_BAR;
;     PG8_WAIT_V(4); PG8_BAR;
;     PG8_STAGE(PG8_SB(1, 0), cB + kstep, voffB); PG8_STAGE(PG8_SA(1, 0), cA + kstep, voffA); PG8_STAGE(PG8_SB(1, 1), cB + hstep + kstep, voffB);
;     PG8_WAIT_V(6); PG8_BAR;
.LBB0_996:
	s_add_u32 s4, s12, 0x1a142000
	s_addc_u32 s5, s13, 0
	s_lshl_b32 s3, s3, 5
	s_mov_b64 s[10:11], 0x80
	s_and_b32 s3, s3, 0x60
	s_add_i32 m0, s40, 0x18000
	v_lshl_add_u64 v[6:7], v[6:7], 0, s[10:11]
	s_ashr_i32 s46, s94, 31
	s_ashr_i32 s47, s96, 31
	s_lshl_b32 s1, s2, 13
	s_lshl_b32 s16, s3, 7
	s_waitcnt vmcnt(4)
	s_barrier
	global_load_lds_dwordx4 v[6:7], off
	v_lshl_add_u64 v[4:5], v[4:5], 0, s[10:11]
	s_add_i32 m0, s40, 0x1a000
	s_add_i32 s48, s40, 0x8000
	s_add_i32 s49, s40, 0xa000
	global_load_lds_dwordx4 v[4:5], off
	v_lshl_add_u64 v[2:3], v[2:3], 0, s[10:11]
	s_mov_b32 m0, s48
	s_add_u32 s18, s30, 0x80080
	global_load_lds_dwordx4 v[2:3], off
	v_lshl_add_u64 v[0:1], v[0:1], 0, s[10:11]
	s_mov_b32 m0, s49
	s_addc_u32 s19, s31, 0
	global_load_lds_dwordx4 v[0:1], off
	s_add_i32 m0, s40, 0x1c000
	s_nop 0
	global_load_lds_dwordx4 v178, s[18:19]
	v_lshl_add_u64 v[0:1], s[18:19], 0, v[182:183]
	s_add_i32 m0, s40, 0x1e000
	s_movk_i32 s18, 0x3c0
	global_load_lds_dwordx4 v[0:1], off
	v_lshlrev_b32_e32 v0, 1, v11
	v_lshlrev_b32_e32 v1, 6, v214
	v_lshlrev_b32_e32 v2, 2, v214
	v_and_b32_e32 v206, 15, v214
	v_and_or_b32 v1, v1, s18, v0
	v_and_b32_e32 v2, 32, v2
	v_lshl_or_b32 v0, v206, 6, v0
	v_bitop3_b32 v208, s16, v1, v2 bitop3:0xf6
	v_lshlrev_b32_e32 v1, 9, v214
	v_bitop3_b32 v0, v0, s1, v2 bitop3:0xde
	v_and_b32_e32 v1, 0x70000, v1
	v_lshlrev_b32_e32 v2, 12, v10
	v_or3_b32 v1, v8, v1, v2
	v_add_u32_e32 v186, v1, v9
	v_lshlrev_b32_e32 v1, 5, v12
	s_waitcnt vmcnt(6)
	v_and_b32_e32 v1, 0xf0000, v1
	v_or3_b32 v1, v8, v1, v2
	s_add_i32 s51, 0, 0x10000
	s_add_i32 s54, 0, 0x14000
	s_mov_b32 s50, s96
	v_lshl_or_b32 v207, s2, 6, v206
	v_or_b32_e32 v209, s3, v11
	v_mov_b32_e32 v187, v185
	v_add_u32_e32 v188, v1, v9
	v_mov_b32_e32 v189, v185
	v_mov_b64_e32 v[190:191], 0x100
	v_mov_b64_e32 v[192:193], 0xff
	v_add_u32_e32 v210, s51, v208
	v_add_u32_e32 v211, 0, v0
	v_add_u32_e32 v212, s54, v208
	s_movk_i32 s55, 0x2080
	s_mov_b32 s16, 0x3f9837f0
	s_movk_i32 s56, 0x1f70
	s_movk_i32 s57, 0x1f60
	s_movk_i32 s58, 0x1f50
	s_movk_i32 s59, 0x1f80
	s_movk_i32 s60, 0x1ff0
	s_movk_i32 s61, 0x1fe0
	s_movk_i32 s62, 0x1fd0
	s_barrier
	s_branch .LBB0_998

; #define PG8_STAGE(bufoff, gbase, voff) do { _Pragma("unroll") for (int _i = 0; _i < 2; ++_i) \
;         __builtin_amdgcn_global_load_lds((const unsigned*)((const char*)(gbase) + (voff)[_i]), (LAS unsigned*)(lds + (bufoff) + ldsw + _i * 8192), 16, 0, 0); } while (0)
; #define PG8_LDA(dst, b, h) do { _Pragma("unroll") for (int m = 0; m < 4; ++m) _Pragma("unroll") for (int k = 0; k < 2; ++k) dst[m][k] = *(const LAS bf16x8*)(lds + PG8_SA(b, h) + aoff + m * 2048 + k * 1024); } while (0)
; #define PG8_LDB(dst, b, h) do { _Pragma("unroll") for (int n = 0; n < 2; ++n) _Pragma("unroll") for (int k = 0; k < 2; ++k) dst[n][k] = *(const LAS bf16x8*)(lds + PG8_SB(b, h) + boff + n * 2048 + k * 1024); } while (0)
; #define PG8_MMA(ai, bj, At, Bt) do { __builtin_amdgcn_s_setprio(1); _Pragma("unroll") for (int m = 0; m < 4; ++m) _Pragma("unroll") for (int n = 0; n < 2; ++n) _Pragma("unroll") for (int k = 0; k < 2; ++k) \
;         acc[ai][bj][m][n] = __builtin_amdgcn_mfma_f32_16x16x32_bf16(Bt[n][k], At[m][k], acc[ai][bj][m][n], 0, 0, 0); __builtin_amdgcn_s_setprio(0); } while (0)
; #define PG8_WAIT_V(n) asm volatile("s_waitcnt vmcnt(" #n ")" ::: "memory")
; #define PG8_WAIT_L(n) asm volatile("s_waitcnt lgkmcnt(" #n ")" ::: "memory")
; #define PG8_BAR __builtin_amdgcn_s_barrier()
; #define PG8_SCHED __builtin_amdgcn_sched_barrier(0)
; template <class Epi>
; __device__ __forceinline__ void gemm_phase(LAS unsigned char* lds, const Gemm g, const StaticOrder& S, const Epi& E) {
;     ...
;             PG8_LDB(B0, 0, 0); PG8_SCHED; PG8_LDA(At, 0, 0); PG8_STAGE(PG8_SA(1, 1), a1 + hstep, voffA);
;             PG8_WAIT_L(8); PG8_BAR; PG8_WAIT_L(0); PG8_MMA(0, 0, At, B0); PG8_BAR; PG8_SCHED;
;             PG8_LDB(B1, 0, 1); PG8_STAGE(PG8_SB(0, 0), b2, voffB);
;             PG8_BAR; PG8_WAIT_L(0); PG8_MMA(0, 1, At, B1); PG8_BAR;
;             PG8_LDA(At, 0, 1); PG8_STAGE(PG8_SA(0, 0), a2, voffA);
;             PG8_BAR; PG8_WAIT_L(0); PG8_MMA(1, 0, At, B0); PG8_BAR; PG8_SCHED;
;             PG8_STAGE(PG8_SB(0, 1), b2 + hstep, voffB);
;             PG8_WAIT_V(6); PG8_BAR; PG8_MMA(1, 1, At, B1); PG8_BAR;
.LBB0_1005:
	ds_read_b128 v[128:131], v210
	ds_read_b128 v[132:135], v210 offset:1024
	ds_read_b128 v[136:139], v210 offset:2048
	ds_read_b128 v[140:143], v210 offset:3072
	s_add_u32 s30, s28, 0xfff80080
	s_addc_u32 s31, s29, -1
	s_cmp_eq_u32 s65, 28
	s_cselect_b32 s35, s1, s31
	s_cselect_b32 s34, s19, s30
	s_cselect_b32 s31, s21, s64
	s_cselect_b32 s30, s27, s63
	s_nop 0
	s_add_i32 m0, s40, 0xc000
	ds_read_b128 v[144:147], v211
	ds_read_b128 v[148:151], v211 offset:1024
	ds_read_b128 v[152:155], v211 offset:2048
	ds_read_b128 v[156:159], v211 offset:3072
	ds_read_b128 v[160:163], v211 offset:4096
	ds_read_b128 v[164:167], v211 offset:5120
	ds_read_b128 v[168:171], v211 offset:6144
	ds_read_b128 v[172:175], v211 offset:7168
	global_load_lds_dwordx4 v186, s[28:29]
	s_nop 0
	s_add_i32 m0, s40, 0xe000
	s_nop 0
	global_load_lds_dwordx4 v188, s[28:29]
	s_waitcnt lgkmcnt(8)
	s_barrier
	s_waitcnt lgkmcnt(0)
	s_waitcnt lgkmcnt(0)
	v_mfma_f32_16x16x32_bf16 v[124:127], v[128:131], v[144:147], v[124:127]
	v_mfma_f32_16x16x32_bf16 v[120:123], v[136:139], v[144:147], v[120:123]
	v_mfma_f32_16x16x32_bf16 v[108:111], v[128:131], v[152:155], v[108:111]
	v_mfma_f32_16x16x32_bf16 v[104:107], v[136:139], v[152:155], v[104:107]
	v_mfma_f32_16x16x32_bf16 v[92:95], v[128:131], v[160:163], v[92:95]
	v_mfma_f32_16x16x32_bf16 v[88:91], v[136:139], v[160:163], v[88:91]
	v_mfma_f32_16x16x32_bf16 v[76:79], v[128:131], v[168:171], v[76:79]
	v_mfma_f32_16x16x32_bf16 v[72:75], v[136:139], v[168:171], v[72:75]
	v_mfma_f32_16x16x32_bf16 v[124:127], v[132:135], v[148:151], v[124:127]
	v_mfma_f32_16x16x32_bf16 v[120:123], v[140:143], v[148:151], v[120:123]
	v_mfma_f32_16x16x32_bf16 v[108:111], v[132:135], v[156:159], v[108:111]
	v_mfma_f32_16x16x32_bf16 v[104:107], v[140:143], v[156:159], v[104:107]
	v_mfma_f32_16x16x32_bf16 v[92:95], v[132:135], v[164:167], v[92:95]
	v_mfma_f32_16x16x32_bf16 v[88:91], v[140:143], v[164:167], v[88:91]
	v_mfma_f32_16x16x32_bf16 v[76:79], v[132:135], v[172:175], v[76:79]
	v_mfma_f32_16x16x32_bf16 v[72:75], v[140:143], v[172:175], v[72:75]
	s_barrier
	s_add_i32 s66, s51, s33
	v_lshl_add_u64 v[220:221], s[30:31], 0, v[178:179]
	s_mov_b32 m0, s66
	ds_read_b128 v[194:197], v212
	ds_read_b128 v[198:201], v212 offset:1024
	ds_read_b128 v[202:205], v212 offset:2048
	ds_read_b128 v[216:219], v212 offset:3072
	global_load_lds_dwordx4 v[220:221], off
	v_lshl_add_u64 v[222:223], s[30:31], 0, v[182:183]
	s_add_i32 m0, s66, 0x2000
	s_nop 0
	global_load_lds_dwordx4 v[222:223], off
	s_barrier
	s_waitcnt lgkmcnt(0)
	s_waitcnt lgkmcnt(0)
	v_mfma_f32_16x16x32_bf16 v[116:119], v[194:197], v[144:147], v[116:119]
	v_mfma_f32_16x16x32_bf16 v[112:115], v[202:205], v[144:147], v[112:115]
	v_mfma_f32_16x16x32_bf16 v[100:103], v[194:197], v[152:155], v[100:103]
	v_mfma_f32_16x16x32_bf16 v[96:99], v[202:205], v[152:155], v[96:99]
	v_mfma_f32_16x16x32_bf16 v[84:87], v[194:197], v[160:163], v[84:87]
	v_mfma_f32_16x16x32_bf16 v[80:83], v[202:205], v[160:163], v[80:83]
	v_mfma_f32_16x16x32_bf16 v[68:71], v[194:197], v[168:171], v[68:71]
	v_mfma_f32_16x16x32_bf16 v[64:67], v[202:205], v[168:171], v[64:67]
	v_mfma_f32_16x16x32_bf16 v[116:119], v[198:201], v[148:151], v[116:119]
	v_mfma_f32_16x16x32_bf16 v[112:115], v[216:219], v[148:151], v[112:115]
	v_mfma_f32_16x16x32_bf16 v[100:103], v[198:201], v[156:159], v[100:103]
	v_mfma_f32_16x16x32_bf16 v[96:99], v[216:219], v[156:159], v[96:99]
	v_mfma_f32_16x16x32_bf16 v[84:87], v[198:201], v[164:167], v[84:87]
	v_mfma_f32_16x16x32_bf16 v[80:83], v[216:219], v[164:167], v[80:83]
	v_mfma_f32_16x16x32_bf16 v[68:71], v[198:201], v[172:175], v[68:71]
	v_mfma_f32_16x16x32_bf16 v[64:67], v[216:219], v[172:175], v[64:67]
	s_mov_b32 m0, s40
	v_lshl_add_u64 v[224:225], s[34:35], 0, v[176:177]
	s_barrier
	ds_read_b128 v[144:147], v211 offset:16384
	ds_read_b128 v[148:151], v211 offset:17408
	ds_read_b128 v[152:155], v211 offset:18432
	ds_read_b128 v[156:159], v211 offset:19456
	ds_read_b128 v[160:163], v211 offset:20480
	ds_read_b128 v[164:167], v211 offset:21504
	ds_read_b128 v[168:171], v211 offset:22528
	ds_read_b128 v[172:175], v211 offset:23552
	global_load_lds_dwordx4 v[224:225], off
	v_lshl_add_u64 v[226:227], s[34:35], 0, v[180:181]
	s_mov_b32 m0, s41
	s_nop 0
	global_load_lds_dwordx4 v[226:227], off
	s_barrier
	s_waitcnt lgkmcnt(0)
	s_waitcnt lgkmcnt(0)
	v_mfma_f32_16x16x32_bf16 v[60:63], v[128:131], v[144:147], v[60:63]
	v_mfma_f32_16x16x32_bf16 v[56:59], v[136:139], v[144:147], v[56:59]
	v_mfma_f32_16x16x32_bf16 v[44:47], v[128:131], v[152:155], v[44:47]
	v_mfma_f32_16x16x32_bf16 v[40:43], v[136:139], v[152:155], v[40:43]
	v_mfma_f32_16x16x32_bf16 v[28:31], v[128:131], v[160:163], v[28:31]
	v_mfma_f32_16x16x32_bf16 v[24:27], v[136:139], v[160:163], v[24:27]
	v_mfma_f32_16x16x32_bf16 v[12:15], v[128:131], v[168:171], v[12:15]
	v_mfma_f32_16x16x32_bf16 v[8:11], v[136:139], v[168:171], v[8:11]
	v_mfma_f32_16x16x32_bf16 v[60:63], v[132:135], v[148:151], v[60:63]
	v_mfma_f32_16x16x32_bf16 v[56:59], v[140:143], v[148:151], v[56:59]
	v_mfma_f32_16x16x32_bf16 v[44:47], v[132:135], v[156:159], v[44:47]
	v_mfma_f32_16x16x32_bf16 v[40:43], v[140:143], v[156:159], v[40:43]
	v_mfma_f32_16x16x32_bf16 v[28:31], v[132:135], v[164:167], v[28:31]
	v_mfma_f32_16x16x32_bf16 v[24:27], v[140:143], v[164:167], v[24:27]
	v_mfma_f32_16x16x32_bf16 v[12:15], v[132:135], v[172:175], v[12:15]
	v_mfma_f32_16x16x32_bf16 v[8:11], v[140:143], v[172:175], v[8:11]
	s_barrier
	s_add_u32 s66, s30, 0x80000
	s_addc_u32 s67, s31, 0
	s_add_i32 s69, s54, s33
	s_nop 0
	s_mov_b32 m0, s69
	s_nop 0
	global_load_lds_dwordx4 v178, s[66:67]
	s_nop 0
	s_add_i32 m0, s69, 0x2000
	s_nop 0
	global_load_lds_dwordx4 v182, s[66:67]
	s_waitcnt vmcnt(6)
	s_barrier
; #define PG8_STAGE(bufoff, gbase, voff) do { _Pragma("unroll") for (int _i = 0; _i < 2; ++_i) \
;         __builtin_amdgcn_global_load_lds((const unsigned*)((const char*)(gbase) + (voff)[_i]), (LAS unsigned*)(lds + (bufoff) + ldsw + _i * 8192), 16, 0, 0); } while (0)
; #define PG8_LDA(dst, b, h) do { _Pragma("unroll") for (int m = 0; m < 4; ++m) _Pragma("unroll") for (int k = 0; k < 2; ++k) dst[m][k] = *(const LAS bf16x8*)(lds + PG8_SA(b, h) + aoff + m * 2048 + k * 1024); } while (0)
; #define PG8_LDB(dst, b, h) do { _Pragma("unroll") for (int n = 0; n < 2; ++n) _Pragma("unroll") for (int k = 0; k < 2; ++k) dst[n][k] = *(const LAS bf16x8*)(lds + PG8_SB(b, h) + boff + n * 2048 + k * 1024); } while (0)
; #define PG8_MMA(ai, bj, At, Bt) do { __builtin_amdgcn_s_setprio(1); _Pragma("unroll") for (int m = 0; m < 4; ++m) _Pragma("unroll") for (int n = 0; n < 2; ++n) _Pragma("unroll") for (int k = 0; k < 2; ++k) \
;         acc[ai][bj][m][n] = __builtin_amdgcn_mfma_f32_16x16x32_bf16(Bt[n][k], At[m][k], acc[ai][bj][m][n], 0, 0, 0); __builtin_amdgcn_s_setprio(0); } while (0)
; #define PG8_WAIT_V(n) asm volatile("s_waitcnt vmcnt(" #n ")" ::: "memory")
; #define PG8_WAIT_L(n) asm volatile("s_waitcnt lgkmcnt(" #n ")" ::: "memory")
; #define PG8_BAR __builtin_amdgcn_s_barrier()
; #define PG8_SCHED __builtin_amdgcn_sched_barrier(0)
; template <class Epi>
; __device__ __forceinline__ void gemm_phase(LAS unsigned char* lds, const Gemm g, const StaticOrder& S, const Epi& E) {
;     ...
;             PG8_WAIT_V(6); PG8_BAR; PG8_MMA(1, 1, At, B1); PG8_BAR;
;             PG8_LDB(B0, 1, 0); PG8_SCHED; PG8_LDA(At, 1, 0); PG8_STAGE(PG8_SA(0, 1), a2 + hstep, voffA);
;             PG8_WAIT_L(8); PG8_BAR; PG8_WAIT_L(0); PG8_MMA(0, 0, At, B0); PG8_BAR; PG8_SCHED;
;             PG8_LDB(B1, 1, 1); PG8_STAGE(PG8_SB(1, 0), b3, voffB);
;             PG8_BAR; PG8_WAIT_L(0); PG8_MMA(0, 1, At, B1); PG8_BAR;
;             PG8_LDA(At, 1, 1); PG8_STAGE(PG8_SA(1, 0), a3, voffA);
;             PG8_BAR; PG8_WAIT_L(0); PG8_MMA(1, 0, At, B0); PG8_BAR; PG8_SCHED;
	v_mfma_f32_16x16x32_bf16 v[52:55], v[194:197], v[144:147], v[52:55]
	v_mfma_f32_16x16x32_bf16 v[48:51], v[202:205], v[144:147], v[48:51]
	v_mfma_f32_16x16x32_bf16 v[36:39], v[194:197], v[152:155], v[36:39]
	v_mfma_f32_16x16x32_bf16 v[32:35], v[202:205], v[152:155], v[32:35]
	v_mfma_f32_16x16x32_bf16 v[20:23], v[194:197], v[160:163], v[20:23]
	v_mfma_f32_16x16x32_bf16 v[16:19], v[202:205], v[160:163], v[16:19]
	v_mfma_f32_16x16x32_bf16 v[4:7], v[194:197], v[168:171], v[4:7]
	v_mfma_f32_16x16x32_bf16 v[0:3], v[202:205], v[168:171], v[0:3]
	v_mfma_f32_16x16x32_bf16 v[52:55], v[198:201], v[148:151], v[52:55]
	v_mfma_f32_16x16x32_bf16 v[48:51], v[216:219], v[148:151], v[48:51]
	v_mfma_f32_16x16x32_bf16 v[36:39], v[198:201], v[156:159], v[36:39]
	v_mfma_f32_16x16x32_bf16 v[32:35], v[216:219], v[156:159], v[32:35]
	v_mfma_f32_16x16x32_bf16 v[20:23], v[198:201], v[164:167], v[20:23]
	v_mfma_f32_16x16x32_bf16 v[16:19], v[216:219], v[164:167], v[16:19]
	v_mfma_f32_16x16x32_bf16 v[4:7], v[198:201], v[172:175], v[4:7]
	v_mfma_f32_16x16x32_bf16 v[0:3], v[216:219], v[172:175], v[0:3]
	s_add_i32 s66, 0, 0x18000
	v_add_u32_e32 v140, s66, v208
	s_barrier
	ds_read_b128 v[128:131], v140
	ds_read_b128 v[132:135], v140 offset:1024
	ds_read_b128 v[136:139], v140 offset:2048
	ds_read_b128 v[140:143], v140 offset:3072
	s_add_u32 s34, s34, 0x80000
	s_addc_u32 s35, s35, 0
	s_mov_b32 m0, s42
	s_nop 0
	ds_read_b128 v[144:147], v211 offset:32768
	ds_read_b128 v[148:151], v211 offset:33792
	ds_read_b128 v[152:155], v211 offset:34816
	ds_read_b128 v[156:159], v211 offset:35840
	ds_read_b128 v[160:163], v211 offset:36864
	ds_read_b128 v[164:167], v211 offset:37888
	ds_read_b128 v[168:171], v211 offset:38912
	ds_read_b128 v[172:175], v211 offset:39936
	global_load_lds_dwordx4 v176, s[34:35]
	s_nop 0
	s_mov_b32 m0, s43
	s_nop 0
	global_load_lds_dwordx4 v180, s[34:35]
	s_waitcnt lgkmcnt(8)
	s_barrier
	s_waitcnt lgkmcnt(0)
	s_waitcnt lgkmcnt(0)
	v_mfma_f32_16x16x32_bf16 v[124:127], v[128:131], v[144:147], v[124:127]
	v_mfma_f32_16x16x32_bf16 v[120:123], v[136:139], v[144:147], v[120:123]
	v_mfma_f32_16x16x32_bf16 v[108:111], v[128:131], v[152:155], v[108:111]
	v_mfma_f32_16x16x32_bf16 v[104:107], v[136:139], v[152:155], v[104:107]
	v_mfma_f32_16x16x32_bf16 v[92:95], v[128:131], v[160:163], v[92:95]
	v_mfma_f32_16x16x32_bf16 v[88:91], v[136:139], v[160:163], v[88:91]
	v_mfma_f32_16x16x32_bf16 v[76:79], v[128:131], v[168:171], v[76:79]
	v_mfma_f32_16x16x32_bf16 v[72:75], v[136:139], v[168:171], v[72:75]
	v_mfma_f32_16x16x32_bf16 v[124:127], v[132:135], v[148:151], v[124:127]
	v_mfma_f32_16x16x32_bf16 v[120:123], v[140:143], v[148:151], v[120:123]
	v_mfma_f32_16x16x32_bf16 v[108:111], v[132:135], v[156:159], v[108:111]
	v_mfma_f32_16x16x32_bf16 v[104:107], v[140:143], v[156:159], v[104:107]
	v_mfma_f32_16x16x32_bf16 v[92:95], v[132:135], v[164:167], v[92:95]
	v_mfma_f32_16x16x32_bf16 v[88:91], v[140:143], v[164:167], v[88:91]
	v_mfma_f32_16x16x32_bf16 v[76:79], v[132:135], v[172:175], v[76:79]
	v_mfma_f32_16x16x32_bf16 v[72:75], v[140:143], v[172:175], v[72:75]
	s_barrier
	s_add_i32 s34, 0, 0x1c000
	s_add_i32 s35, s66, s33
	v_add_u32_e32 v184, s34, v208
	v_lshl_add_u64 v[220:221], v[220:221], 0, s[10:11]
	s_mov_b32 m0, s35
	ds_read_b128 v[194:197], v184
	ds_read_b128 v[198:201], v184 offset:1024
	ds_read_b128 v[202:205], v184 offset:2048
	ds_read_b128 v[216:219], v184 offset:3072
	global_load_lds_dwordx4 v[220:221], off
	v_lshl_add_u64 v[220:221], v[222:223], 0, s[10:11]
	s_add_i32 m0, s35, 0x2000
	s_nop 0
	global_load_lds_dwordx4 v[220:221], off
	s_barrier
	s_waitcnt lgkmcnt(0)
	s_waitcnt lgkmcnt(0)
	v_mfma_f32_16x16x32_bf16 v[116:119], v[194:197], v[144:147], v[116:119]
	v_mfma_f32_16x16x32_bf16 v[112:115], v[202:205], v[144:147], v[112:115]
	v_mfma_f32_16x16x32_bf16 v[100:103], v[194:197], v[152:155], v[100:103]
	v_mfma_f32_16x16x32_bf16 v[96:99], v[202:205], v[152:155], v[96:99]
	v_mfma_f32_16x16x32_bf16 v[84:87], v[194:197], v[160:163], v[84:87]
	v_mfma_f32_16x16x32_bf16 v[80:83], v[202:205], v[160:163], v[80:83]
	v_mfma_f32_16x16x32_bf16 v[68:71], v[194:197], v[168:171], v[68:71]
	v_mfma_f32_16x16x32_bf16 v[64:67], v[202:205], v[168:171], v[64:67]
	v_mfma_f32_16x16x32_bf16 v[116:119], v[198:201], v[148:151], v[116:119]
	v_mfma_f32_16x16x32_bf16 v[112:115], v[216:219], v[148:151], v[112:115]
	v_mfma_f32_16x16x32_bf16 v[100:103], v[198:201], v[156:159], v[100:103]
	v_mfma_f32_16x16x32_bf16 v[96:99], v[216:219], v[156:159], v[96:99]
	v_mfma_f32_16x16x32_bf16 v[84:87], v[198:201], v[164:167], v[84:87]
	v_mfma_f32_16x16x32_bf16 v[80:83], v[216:219], v[164:167], v[80:83]
	v_mfma_f32_16x16x32_bf16 v[68:71], v[198:201], v[172:175], v[68:71]
	v_mfma_f32_16x16x32_bf16 v[64:67], v[216:219], v[172:175], v[64:67]
	s_mov_b32 m0, s48
	v_lshl_add_u64 v[220:221], v[224:225], 0, s[10:11]
	s_barrier
	ds_read_b128 v[144:147], v211 offset:49152
	ds_read_b128 v[148:151], v211 offset:50176
	ds_read_b128 v[152:155], v211 offset:51200
	ds_read_b128 v[156:159], v211 offset:52224
	ds_read_b128 v[160:163], v211 offset:53248
	ds_read_b128 v[164:167], v211 offset:54272
	ds_read_b128 v[168:171], v211 offset:55296
	ds_read_b128 v[172:175], v211 offset:56320
	global_load_lds_dwordx4 v[220:221], off
	v_lshl_add_u64 v[220:221], v[226:227], 0, s[10:11]
	s_mov_b32 m0, s49
	s_nop 0
	global_load_lds_dwordx4 v[220:221], off
	s_barrier
; #define PG8_STAGE(bufoff, gbase, voff) do { _Pragma("unroll") for (int _i = 0; _i < 2; ++_i) \
;         __builtin_amdgcn_global_load_lds((const unsigned*)((const char*)(gbase) + (voff)[_i]), (LAS unsigned*)(lds + (bufoff) + ldsw + _i * 8192), 16, 0, 0); } while (0)
; #define PG8_MMA(ai, bj, At, Bt) do { __builtin_amdgcn_s_setprio(1); _Pragma("unroll") for (int m = 0; m < 4; ++m) _Pragma("unroll") for (int n = 0; n < 2; ++n) _Pragma("unroll") for (int k = 0; k < 2; ++k) \
;         acc[ai][bj][m][n] = __builtin_amdgcn_mfma_f32_16x16x32_bf16(Bt[n][k], At[m][k], acc[ai][bj][m][n], 0, 0, 0); __builtin_amdgcn_s_setprio(0); } while (0)
; #define PG8_WAIT_V(n) asm volatile("s_waitcnt vmcnt(" #n ")" ::: "memory")
; #define PG8_WAIT_L(n) asm volatile("s_waitcnt lgkmcnt(" #n ")" ::: "memory")
; #define PG8_BAR __builtin_amdgcn_s_barrier()
; #define PG8_SCHED __builtin_amdgcn_sched_barrier(0)
; template <class Epi>
; __device__ __forceinline__ void gemm_phase(LAS unsigned char* lds, const Gemm g, const StaticOrder& S, const Epi& E) {
;     ...
;             PG8_BAR; PG8_WAIT_L(0); PG8_MMA(1, 0, At, B0); PG8_BAR; PG8_SCHED;
;             PG8_STAGE(PG8_SB(1, 1), b3 + hstep, voffB);
;             PG8_WAIT_V(6); PG8_BAR; PG8_MMA(1, 1, At, B1); PG8_BAR;
;     __device__ __forceinline__ void operator()(const AccT& acc, const pg8::Unit& u, int wr, int wc, int fr, int fq) const {
;         const int row0 = u.pm * 256 + wr * 64 + fr, col0 = u.pn * 256 + wc * 32 + 8 * fq;
; #pragma unroll
;         for (int ai = 0; ai < 2; ++ai) { f32x4 b0[4][2], b1[4][2];
; #pragma unroll
;             for (int m = 0; m < 4; ++m) { const int r = row0 + ai * 128 + m * 16; const int rc = r < NREAL ? r : NREAL - 1;
; #pragma unroll
;                 for (int bj = 0; bj < 2; ++bj) {
;                     if (mode) unpack8(*(const u32x4*)(X1 + (size_t)rc * D + col0 + bj * 128), b0[m][bj], b1[m][bj]);
;                     else { const float* b2 = (rc < ROW_S ? xp + (size_t)rc * D : xs + (size_t)(rc - ROW_S) * D) + col0 + bj * 128; b0[m][bj] = *(const f32x4*)b2; b1[m][bj] = *(const f32x4*)(b2 + 4); } } }
; #pragma unroll
;             for (int m = 0; m < 4; ++m) { const int r = row0 + ai * 128 + m * 16;
;                 if (r < NREAL) {
	s_waitcnt lgkmcnt(0)
	s_waitcnt lgkmcnt(0)
	v_mfma_f32_16x16x32_bf16 v[60:63], v[128:131], v[144:147], v[60:63]
	v_mfma_f32_16x16x32_bf16 v[56:59], v[136:139], v[144:147], v[56:59]
	v_mfma_f32_16x16x32_bf16 v[44:47], v[128:131], v[152:155], v[44:47]
	v_mfma_f32_16x16x32_bf16 v[40:43], v[136:139], v[152:155], v[40:43]
	v_mfma_f32_16x16x32_bf16 v[28:31], v[128:131], v[160:163], v[28:31]
	v_mfma_f32_16x16x32_bf16 v[24:27], v[136:139], v[160:163], v[24:27]
	v_mfma_f32_16x16x32_bf16 v[12:15], v[128:131], v[168:171], v[12:15]
	v_mfma_f32_16x16x32_bf16 v[8:11], v[136:139], v[168:171], v[8:11]
	v_mfma_f32_16x16x32_bf16 v[60:63], v[132:135], v[148:151], v[60:63]
	v_mfma_f32_16x16x32_bf16 v[56:59], v[140:143], v[148:151], v[56:59]
	v_mfma_f32_16x16x32_bf16 v[44:47], v[132:135], v[156:159], v[44:47]
	v_mfma_f32_16x16x32_bf16 v[40:43], v[140:143], v[156:159], v[40:43]
	v_mfma_f32_16x16x32_bf16 v[28:31], v[132:135], v[164:167], v[28:31]
	v_mfma_f32_16x16x32_bf16 v[24:27], v[140:143], v[164:167], v[24:27]
	v_mfma_f32_16x16x32_bf16 v[12:15], v[132:135], v[172:175], v[12:15]
	v_mfma_f32_16x16x32_bf16 v[8:11], v[140:143], v[172:175], v[8:11]
	s_barrier
	s_add_u32 s30, s30, 0x80080
	s_addc_u32 s31, s31, 0
	s_add_i32 s34, s34, s33
	s_nop 0
	s_mov_b32 m0, s34
	s_nop 0
	global_load_lds_dwordx4 v178, s[30:31]
	v_lshl_add_u64 v[128:129], s[30:31], 0, v[182:183]
	s_add_i32 m0, s34, 0x2000
	s_nop 0
	global_load_lds_dwordx4 v[128:129], off
	s_waitcnt vmcnt(6)
	s_barrier
	v_mfma_f32_16x16x32_bf16 v[52:55], v[194:197], v[144:147], v[52:55]
	v_mfma_f32_16x16x32_bf16 v[48:51], v[202:205], v[144:147], v[48:51]
	v_mfma_f32_16x16x32_bf16 v[36:39], v[194:197], v[152:155], v[36:39]
	v_mfma_f32_16x16x32_bf16 v[32:35], v[202:205], v[152:155], v[32:35]
	v_mfma_f32_16x16x32_bf16 v[20:23], v[194:197], v[160:163], v[20:23]
	v_mfma_f32_16x16x32_bf16 v[16:19], v[202:205], v[160:163], v[16:19]
	v_mfma_f32_16x16x32_bf16 v[4:7], v[194:197], v[168:171], v[4:7]
	v_mfma_f32_16x16x32_bf16 v[0:3], v[202:205], v[168:171], v[0:3]
	v_mfma_f32_16x16x32_bf16 v[52:55], v[198:201], v[148:151], v[52:55]
	v_mfma_f32_16x16x32_bf16 v[48:51], v[216:219], v[148:151], v[48:51]
	v_mfma_f32_16x16x32_bf16 v[36:39], v[198:201], v[156:159], v[36:39]
	v_mfma_f32_16x16x32_bf16 v[32:35], v[216:219], v[156:159], v[32:35]
	v_mfma_f32_16x16x32_bf16 v[20:23], v[198:201], v[164:167], v[20:23]
	v_mfma_f32_16x16x32_bf16 v[16:19], v[216:219], v[164:167], v[16:19]
	v_mfma_f32_16x16x32_bf16 v[4:7], v[198:201], v[172:175], v[4:7]
	v_mfma_f32_16x16x32_bf16 v[0:3], v[216:219], v[172:175], v[0:3]
	s_add_i32 s65, s65, 2
	s_add_u32 s28, s28, 0x100
	s_addc_u32 s29, s29, 0
	s_add_u32 s63, s63, 0x100
	s_addc_u32 s64, s64, 0
	s_cmp_gt_u32 s65, 29
	s_barrier
	s_cbranch_scc0 .LBB0_1005
	v_lshl_add_u32 v196, s26, 8, v207
	v_or_b32_e32 v204, 16, v196
	v_min_i32_e32 v128, 0x207f, v204
	v_ashrrev_i32_e32 v129, 31, v128
	v_add_u32_e32 v184, 0xffffe000, v128
	v_lshl_or_b32 v194, s0, 8, v209
	v_lshlrev_b64 v[130:131], 13, v[184:185]
	v_lshlrev_b64 v[128:129], 13, v[128:129]
	v_ashrrev_i32_e32 v195, 31, v194
	v_lshl_add_u64 v[130:131], s[38:39], 0, v[130:131]
	v_lshl_add_u64 v[128:129], s[36:37], 0, v[128:129]
	v_cmp_gt_i32_e32 vcc, s44, v204
	v_lshlrev_b64 v[198:199], 2, v[194:195]
	v_or_b32_e32 v202, 32, v196
	v_cndmask_b32_e32 v129, v131, v129, vcc
	v_cndmask_b32_e32 v128, v130, v128, vcc
	v_lshl_add_u64 v[128:129], v[128:129], 0, v[198:199]
	global_load_dwordx4 v[168:171], v[128:129], off offset:16
	global_load_dwordx4 v[172:175], v[128:129], off
	global_load_dwordx4 v[160:163], v[128:129], off offset:528
	global_load_dwordx4 v[164:167], v[128:129], off offset:512
	v_min_i32_e32 v128, 0x207f, v202
	v_ashrrev_i32_e32 v129, 31, v128
	v_add_u32_e32 v184, 0xffffe000, v128
	v_lshlrev_b64 v[130:131], 13, v[184:185]
	v_lshlrev_b64 v[128:129], 13, v[128:129]
	v_lshl_add_u64 v[130:131], s[38:39], 0, v[130:131]
	v_lshl_add_u64 v[128:129], s[36:37], 0, v[128:129]
	v_cmp_gt_i32_e32 vcc, s44, v202
	v_or_b32_e32 v200, 48, v196
	v_cmp_gt_i32_e64 s[0:1], s55, v196
	v_cndmask_b32_e32 v129, v131, v129, vcc
	v_cndmask_b32_e32 v128, v130, v128, vcc
	v_lshl_add_u64 v[128:129], v[128:129], 0, v[198:199]
	global_load_dwordx4 v[152:155], v[128:129], off offset:16
	global_load_dwordx4 v[156:159], v[128:129], off
	global_load_dwordx4 v[144:147], v[128:129], off offset:528
	global_load_dwordx4 v[148:151], v[128:129], off offset:512
	v_min_i32_e32 v128, 0x207f, v200
	v_ashrrev_i32_e32 v129, 31, v128
	v_add_u32_e32 v184, 0xffffe000, v128
	v_lshlrev_b64 v[130:131], 13, v[184:185]
	v_lshlrev_b64 v[128:129], 13, v[128:129]
	v_lshl_add_u64 v[130:131], s[38:39], 0, v[130:131]
	v_lshl_add_u64 v[128:129], s[36:37], 0, v[128:129]
	v_cmp_gt_i32_e32 vcc, s44, v200
	s_nop 1
	v_cndmask_b32_e32 v129, v131, v129, vcc
	v_cndmask_b32_e32 v128, v130, v128, vcc
	v_lshl_add_u64 v[132:133], v[128:129], 0, v[198:199]
	global_load_dwordx4 v[136:139], v[132:133], off offset:16
	global_load_dwordx4 v[140:143], v[132:133], off
	global_load_dwordx4 v[128:131], v[132:133], off offset:528
	s_nop 0
	global_load_dwordx4 v[132:135], v[132:133], off offset:512
	v_cmp_gt_i32_e32 vcc, s44, v196
	s_and_saveexec_b64 s[26:27], s[0:1]
	s_cbranch_execnz .LBB0_1015
	s_or_b64 exec, exec, s[26:27]
	v_cmp_gt_i32_e64 s[0:1], s55, v204
	s_and_saveexec_b64 s[26:27], s[0:1]
	s_cbranch_execnz .LBB0_1016

; #define PG8_STAGE(bufoff, gbase, voff) do { _Pragma("unroll") for (int _i = 0; _i < 2; ++_i) \
;         __builtin_amdgcn_global_load_lds((const unsigned*)((const char*)(gbase) + (voff)[_i]), (LAS unsigned*)(lds + (bufoff) + ldsw + _i * 8192), 16, 0, 0); } while (0)
; #define PG8_WAIT_V(n) asm volatile("s_waitcnt vmcnt(" #n ")" ::: "memory")
; #define PG8_BAR __builtin_amdgcn_s_barrier()
; template <class Epi>
; __device__ __forceinline__ void gemm_phase(LAS unsigned char* lds, const Gemm g, const StaticOrder& S, const Epi& E) {
;     const int tid = threadIdx.x, wid = __builtin_amdgcn_readfirstlane(tid >> 6), lane = tid & 63, wr = wid >> 2, wc = wid & 3, fr = lane & 15, fq = lane >> 4;
;     const int K = g.K, nt = K / BK;
;     unsigned voffA[2], voffB[2];
; #pragma unroll
;     for (int i = 0; i < 2; ++i) { int R, C; stage_rc(tid * 16 + i * 8192, R, C); const int Rb = Epi::PERM ? ((R & ~31) + perm32(R & 31)) : R;
;         voffA[i] = (unsigned)(R * K + C) * 2u; voffB[i] = (unsigned)(Rb * K + C) * 2u; }
;     const size_t kstep = (size_t)(BK * 2);
;     const size_t hstep = (size_t)HALF * K * 2;
;     const size_t tstep = 2 * hstep;
;     const unsigned ldsw = (unsigned)wid * 1024u;
;     const int aoff = lds_byte(wr * 64 + fr, fq * 8), boff = lds_byte(wc * 32 + fr, fq * 8);
;     ...
;     Unit cur, nxt; int ui = 0;
;     if (!S.next(0, cur)) return;
;     f32x4 acc[2][2][4][2];
; #pragma unroll
;     for (int a = 0; a < 2; ++a)
; #pragma unroll
;         for (int b = 0; b < 2; ++b)
; #pragma unroll
;             for (int m = 0; m < 4; ++m)
; #pragma unroll
;                 for (int n = 0; n < 2; ++n) acc[a][b][m][n] = (f32x4){0.f, 0.f, 0.f, 0.f};
;     bf16x8 At[4][2], B0[2][2], B1[2][2];
;     const char* cA = (const char*)g.A + (size_t)cur.pm * tstep; const char* cB = (const char*)g.Bt + (size_t)cur.pn * tstep;
;     PG8_STAGE(PG8_SB(0, 0), cB, voffB); PG8_STAGE(PG8_SA(0, 0), cA, voffA); PG8_STAGE(PG8_SB(0, 1), cB + hstep, voffB); PG8_STAGE(PG8_SA(0, 1), cA + hstep, voffA);
;     if (wr == 1) PG8_BAR;
;     PG8_WAIT_V(4); PG8_BAR;
;     PG8_STAGE(PG8_SB(1, 0), cB + kstep, voffB); PG8_STAGE(PG8_SA(1, 0), cA + kstep, voffA); PG8_STAGE(PG8_SB(1, 1), cB + hstep + kstep, voffB);
;     PG8_WAIT_V(6); PG8_BAR;
.LBB0_1142:
	s_add_u32 s0, s12, 0x4542000
	s_addc_u32 s1, s13, 0
	s_lshl_b32 s4, s4, 5
	s_and_b32 s11, s4, 0x60
	s_mov_b64 s[4:5], 0x80
	s_add_i32 m0, s21, 0x18000
	v_lshl_add_u64 v[6:7], v[6:7], 0, s[4:5]
	s_ashr_i32 s35, s94, 31
	s_ashr_i32 s36, s96, 31
	s_lshl_b32 s10, s3, 13
	s_lshl_b32 s16, s11, 7
	s_waitcnt vmcnt(4)
	s_barrier
	global_load_lds_dwordx4 v[6:7], off
	v_lshl_add_u64 v[4:5], v[4:5], 0, s[4:5]
	s_add_i32 m0, s21, 0x1a000
	s_add_i32 s37, s21, 0x8000
	s_add_i32 s38, s21, 0xa000
	global_load_lds_dwordx4 v[4:5], off
	v_lshl_add_u64 v[2:3], v[2:3], 0, s[4:5]
	s_mov_b32 m0, s37
	s_add_u32 s8, s24, 0x80080
	global_load_lds_dwordx4 v[2:3], off
	v_lshl_add_u64 v[0:1], v[0:1], 0, s[4:5]
	s_mov_b32 m0, s38
	s_addc_u32 s9, s25, 0
	global_load_lds_dwordx4 v[0:1], off
	s_add_i32 m0, s21, 0x1c000
	s_nop 0
	global_load_lds_dwordx4 v130, s[8:9]
	v_lshl_add_u64 v[0:1], s[8:9], 0, v[134:135]
	s_add_i32 m0, s21, 0x1e000
	s_sext_i32_i16 s43, s2
	global_load_lds_dwordx4 v[0:1], off
	v_lshlrev_b32_e32 v0, 1, v11
	v_lshlrev_b32_e32 v1, 6, v214
	s_movk_i32 s2, 0x3c0
	v_lshlrev_b32_e32 v2, 2, v214
	v_and_or_b32 v1, v1, s2, v0
	v_and_b32_e32 v2, 32, v2
	v_bitop3_b32 v148, s16, v1, v2 bitop3:0xf6
	v_lshlrev_b32_e32 v1, 9, v214
	v_and_b32_e32 v1, 0x70000, v1
	v_lshlrev_b32_e32 v2, 12, v10
	v_or3_b32 v1, v8, v1, v2
	v_lshlrev_b32_e32 v3, 2, v146
	v_add_u32_e32 v136, v1, v9
	v_lshlrev_b32_e32 v1, 5, v12
	v_lshl_or_b32 v0, v146, 6, v0
	v_and_b32_e32 v3, 32, v3
	s_waitcnt vmcnt(6)
	v_and_b32_e32 v1, 0xf0000, v1
	v_bitop3_b32 v0, v0, s10, v3 bitop3:0xde
	v_or3_b32 v1, v8, v1, v2
	s_add_i32 s40, 0, 0x10000
	s_add_i32 s41, 0, 0x14000
	s_mov_b32 s39, s96
	v_lshl_or_b32 v147, s3, 6, v146
	v_or_b32_e32 v149, s11, v11
	v_mov_b32_e32 v137, v131
	v_add_u32_e32 v138, v1, v9
	v_mov_b32_e32 v139, v131
	v_mov_b64_e32 v[140:141], 0x5ac
	v_mov_b64_e32 v[142:143], 0x5ab
	v_add_u32_e32 v150, s40, v148
	v_add_u32_e32 v151, 0, v0
	v_add_u32_e32 v153, s41, v148
	s_movk_i32 s42, 0x2c00
	s_barrier
	s_waitcnt vmcnt(0)

; #define PG8_STAGE(bufoff, gbase, voff) do { _Pragma("unroll") for (int _i = 0; _i < 2; ++_i) \
;         __builtin_amdgcn_global_load_lds((const unsigned*)((const char*)(gbase) + (voff)[_i]), (LAS unsigned*)(lds + (bufoff) + ldsw + _i * 8192), 16, 0, 0); } while (0)
; #define PG8_LDA(dst, b, h) do { _Pragma("unroll") for (int m = 0; m < 4; ++m) _Pragma("unroll") for (int k = 0; k < 2; ++k) dst[m][k] = *(const LAS bf16x8*)(lds + PG8_SA(b, h) + aoff + m * 2048 + k * 1024); } while (0)
; #define PG8_LDB(dst, b, h) do { _Pragma("unroll") for (int n = 0; n < 2; ++n) _Pragma("unroll") for (int k = 0; k < 2; ++k) dst[n][k] = *(const LAS bf16x8*)(lds + PG8_SB(b, h) + boff + n * 2048 + k * 1024); } while (0)
; #define PG8_MMA(ai, bj, At, Bt) do { __builtin_amdgcn_s_setprio(1); _Pragma("unroll") for (int m = 0; m < 4; ++m) _Pragma("unroll") for (int n = 0; n < 2; ++n) _Pragma("unroll") for (int k = 0; k < 2; ++k) \
;         acc[ai][bj][m][n] = __builtin_amdgcn_mfma_f32_16x16x32_bf16(Bt[n][k], At[m][k], acc[ai][bj][m][n], 0, 0, 0); __builtin_amdgcn_s_setprio(0); } while (0)
; #define PG8_WAIT_V(n) asm volatile("s_waitcnt vmcnt(" #n ")" ::: "memory")
; #define PG8_WAIT_L(n) asm volatile("s_waitcnt lgkmcnt(" #n ")" ::: "memory")
; #define PG8_BAR __builtin_amdgcn_s_barrier()
; #define PG8_SCHED __builtin_amdgcn_sched_barrier(0)
; template <class Epi>
; __device__ __forceinline__ void gemm_phase(LAS unsigned char* lds, const Gemm g, const StaticOrder& S, const Epi& E) {
;     ...
;             PG8_LDB(B0, 0, 0); PG8_SCHED; PG8_LDA(At, 0, 0); PG8_STAGE(PG8_SA(1, 1), a1 + hstep, voffA);
;             PG8_WAIT_L(8); PG8_BAR; PG8_WAIT_L(0); PG8_MMA(0, 0, At, B0); PG8_BAR; PG8_SCHED;
;             PG8_LDB(B1, 0, 1); PG8_STAGE(PG8_SB(0, 0), b2, voffB);
;             PG8_BAR; PG8_WAIT_L(0); PG8_MMA(0, 1, At, B1); PG8_BAR;
;             PG8_LDA(At, 0, 1); PG8_STAGE(PG8_SA(0, 0), a2, voffA);
;             PG8_BAR; PG8_WAIT_L(0); PG8_MMA(1, 0, At, B0); PG8_BAR; PG8_SCHED;
;             PG8_STAGE(PG8_SB(0, 1), b2 + hstep, voffB);
;             PG8_WAIT_V(6); PG8_BAR; PG8_MMA(1, 1, At, B1); PG8_BAR;
.LBB0_1150:
	ds_read_b128 v[154:157], v150
	ds_read_b128 v[158:161], v150 offset:1024
	ds_read_b128 v[162:165], v150 offset:2048
	ds_read_b128 v[166:169], v150 offset:3072
	s_add_u32 s24, s22, 0xfff80080
	s_addc_u32 s25, s23, -1
	s_cmp_eq_u32 s48, 28
	s_cselect_b32 s27, s11, s25
	s_cselect_b32 s26, s44, s24
	s_cselect_b32 s25, s9, s47
	s_cselect_b32 s24, s45, s46
	s_nop 0
	s_add_i32 m0, s21, 0xc000
	ds_read_b128 v[170:173], v151
	ds_read_b128 v[174:177], v151 offset:1024
	ds_read_b128 v[178:181], v151 offset:2048
	ds_read_b128 v[182:185], v151 offset:3072
	ds_read_b128 v[186:189], v151 offset:4096
	ds_read_b128 v[190:193], v151 offset:5120
	ds_read_b128 v[194:197], v151 offset:6144
	ds_read_b128 v[198:201], v151 offset:7168
	global_load_lds_dwordx4 v136, s[22:23]
	s_nop 0
	s_add_i32 m0, s21, 0xe000
	s_nop 0
	global_load_lds_dwordx4 v138, s[22:23]
	s_waitcnt lgkmcnt(8)
	s_barrier
	s_waitcnt lgkmcnt(0)
	s_waitcnt lgkmcnt(0)
	v_mfma_f32_16x16x32_bf16 v[124:127], v[154:157], v[170:173], v[124:127]
	v_mfma_f32_16x16x32_bf16 v[120:123], v[162:165], v[170:173], v[120:123]
	v_mfma_f32_16x16x32_bf16 v[108:111], v[154:157], v[178:181], v[108:111]
	v_mfma_f32_16x16x32_bf16 v[104:107], v[162:165], v[178:181], v[104:107]
	v_mfma_f32_16x16x32_bf16 v[92:95], v[154:157], v[186:189], v[92:95]
	v_mfma_f32_16x16x32_bf16 v[88:91], v[162:165], v[186:189], v[88:91]
	v_mfma_f32_16x16x32_bf16 v[76:79], v[154:157], v[194:197], v[76:79]
	v_mfma_f32_16x16x32_bf16 v[72:75], v[162:165], v[194:197], v[72:75]
	v_mfma_f32_16x16x32_bf16 v[124:127], v[158:161], v[174:177], v[124:127]
	v_mfma_f32_16x16x32_bf16 v[120:123], v[166:169], v[174:177], v[120:123]
	v_mfma_f32_16x16x32_bf16 v[108:111], v[158:161], v[182:185], v[108:111]
	v_mfma_f32_16x16x32_bf16 v[104:107], v[166:169], v[182:185], v[104:107]
	v_mfma_f32_16x16x32_bf16 v[92:95], v[158:161], v[190:193], v[92:95]
	v_mfma_f32_16x16x32_bf16 v[88:91], v[166:169], v[190:193], v[88:91]
	v_mfma_f32_16x16x32_bf16 v[76:79], v[158:161], v[198:201], v[76:79]
	v_mfma_f32_16x16x32_bf16 v[72:75], v[166:169], v[198:201], v[72:75]
	s_barrier
	s_add_i32 s49, s40, s29
	v_lshl_add_u64 v[220:221], s[24:25], 0, v[130:131]
	s_mov_b32 m0, s49
	ds_read_b128 v[202:205], v153
	ds_read_b128 v[206:209], v153 offset:1024
	ds_read_b128 v[210:213], v153 offset:2048
	ds_read_b128 v[216:219], v153 offset:3072
	global_load_lds_dwordx4 v[220:221], off
	v_lshl_add_u64 v[222:223], s[24:25], 0, v[134:135]
	s_add_i32 m0, s49, 0x2000
	s_nop 0
	global_load_lds_dwordx4 v[222:223], off
	s_barrier
	s_waitcnt lgkmcnt(0)
	s_waitcnt lgkmcnt(0)
	v_mfma_f32_16x16x32_bf16 v[116:119], v[202:205], v[170:173], v[116:119]
	v_mfma_f32_16x16x32_bf16 v[112:115], v[210:213], v[170:173], v[112:115]
	v_mfma_f32_16x16x32_bf16 v[100:103], v[202:205], v[178:181], v[100:103]
	v_mfma_f32_16x16x32_bf16 v[96:99], v[210:213], v[178:181], v[96:99]
	v_mfma_f32_16x16x32_bf16 v[84:87], v[202:205], v[186:189], v[84:87]
	v_mfma_f32_16x16x32_bf16 v[80:83], v[210:213], v[186:189], v[80:83]
	v_mfma_f32_16x16x32_bf16 v[68:71], v[202:205], v[194:197], v[68:71]
	v_mfma_f32_16x16x32_bf16 v[64:67], v[210:213], v[194:197], v[64:67]
	v_mfma_f32_16x16x32_bf16 v[116:119], v[206:209], v[174:177], v[116:119]
	v_mfma_f32_16x16x32_bf16 v[112:115], v[216:219], v[174:177], v[112:115]
	v_mfma_f32_16x16x32_bf16 v[100:103], v[206:209], v[182:185], v[100:103]
	v_mfma_f32_16x16x32_bf16 v[96:99], v[216:219], v[182:185], v[96:99]
	v_mfma_f32_16x16x32_bf16 v[84:87], v[206:209], v[190:193], v[84:87]
	v_mfma_f32_16x16x32_bf16 v[80:83], v[216:219], v[190:193], v[80:83]
	v_mfma_f32_16x16x32_bf16 v[68:71], v[206:209], v[198:201], v[68:71]
	v_mfma_f32_16x16x32_bf16 v[64:67], v[216:219], v[198:201], v[64:67]
	s_mov_b32 m0, s21
	v_lshl_add_u64 v[224:225], s[26:27], 0, v[128:129]
	s_barrier
	ds_read_b128 v[170:173], v151 offset:16384
	ds_read_b128 v[174:177], v151 offset:17408
	ds_read_b128 v[178:181], v151 offset:18432
	ds_read_b128 v[182:185], v151 offset:19456
	ds_read_b128 v[186:189], v151 offset:20480
	ds_read_b128 v[190:193], v151 offset:21504
	ds_read_b128 v[194:197], v151 offset:22528
	ds_read_b128 v[198:201], v151 offset:23552
	global_load_lds_dwordx4 v[224:225], off
	v_lshl_add_u64 v[226:227], s[26:27], 0, v[132:133]
	s_mov_b32 m0, s30
	s_nop 0
	global_load_lds_dwordx4 v[226:227], off
	s_barrier
	s_waitcnt lgkmcnt(0)
	s_waitcnt lgkmcnt(0)
	v_mfma_f32_16x16x32_bf16 v[60:63], v[154:157], v[170:173], v[60:63]
	v_mfma_f32_16x16x32_bf16 v[56:59], v[162:165], v[170:173], v[56:59]
	v_mfma_f32_16x16x32_bf16 v[44:47], v[154:157], v[178:181], v[44:47]
	v_mfma_f32_16x16x32_bf16 v[40:43], v[162:165], v[178:181], v[40:43]
	v_mfma_f32_16x16x32_bf16 v[28:31], v[154:157], v[186:189], v[28:31]
	v_mfma_f32_16x16x32_bf16 v[24:27], v[162:165], v[186:189], v[24:27]
	v_mfma_f32_16x16x32_bf16 v[12:15], v[154:157], v[194:197], v[12:15]
	v_mfma_f32_16x16x32_bf16 v[8:11], v[162:165], v[194:197], v[8:11]
	v_mfma_f32_16x16x32_bf16 v[60:63], v[158:161], v[174:177], v[60:63]
	v_mfma_f32_16x16x32_bf16 v[56:59], v[166:169], v[174:177], v[56:59]
	v_mfma_f32_16x16x32_bf16 v[44:47], v[158:161], v[182:185], v[44:47]
	v_mfma_f32_16x16x32_bf16 v[40:43], v[166:169], v[182:185], v[40:43]
	v_mfma_f32_16x16x32_bf16 v[28:31], v[158:161], v[190:193], v[28:31]
	v_mfma_f32_16x16x32_bf16 v[24:27], v[166:169], v[190:193], v[24:27]
	v_mfma_f32_16x16x32_bf16 v[12:15], v[158:161], v[198:201], v[12:15]
	v_mfma_f32_16x16x32_bf16 v[8:11], v[166:169], v[198:201], v[8:11]
	s_barrier
	s_add_u32 s50, s24, 0x80000
	s_addc_u32 s51, s25, 0
	s_add_i32 s49, s41, s29
	s_nop 0
	s_mov_b32 m0, s49
	s_nop 0
	global_load_lds_dwordx4 v130, s[50:51]
	s_nop 0
	s_add_i32 m0, s49, 0x2000
	s_nop 0
	global_load_lds_dwordx4 v134, s[50:51]
	s_waitcnt vmcnt(6)
	s_barrier
; #define PG8_STAGE(bufoff, gbase, voff) do { _Pragma("unroll") for (int _i = 0; _i < 2; ++_i) \
;         __builtin_amdgcn_global_load_lds((const unsigned*)((const char*)(gbase) + (voff)[_i]), (LAS unsigned*)(lds + (bufoff) + ldsw + _i * 8192), 16, 0, 0); } while (0)
; #define PG8_LDA(dst, b, h) do { _Pragma("unroll") for (int m = 0; m < 4; ++m) _Pragma("unroll") for (int k = 0; k < 2; ++k) dst[m][k] = *(const LAS bf16x8*)(lds + PG8_SA(b, h) + aoff + m * 2048 + k * 1024); } while (0)
; #define PG8_LDB(dst, b, h) do { _Pragma("unroll") for (int n = 0; n < 2; ++n) _Pragma("unroll") for (int k = 0; k < 2; ++k) dst[n][k] = *(const LAS bf16x8*)(lds + PG8_SB(b, h) + boff + n * 2048 + k * 1024); } while (0)
; #define PG8_MMA(ai, bj, At, Bt) do { __builtin_amdgcn_s_setprio(1); _Pragma("unroll") for (int m = 0; m < 4; ++m) _Pragma("unroll") for (int n = 0; n < 2; ++n) _Pragma("unroll") for (int k = 0; k < 2; ++k) \
;         acc[ai][bj][m][n] = __builtin_amdgcn_mfma_f32_16x16x32_bf16(Bt[n][k], At[m][k], acc[ai][bj][m][n], 0, 0, 0); __builtin_amdgcn_s_setprio(0); } while (0)
; #define PG8_WAIT_V(n) asm volatile("s_waitcnt vmcnt(" #n ")" ::: "memory")
; #define PG8_WAIT_L(n) asm volatile("s_waitcnt lgkmcnt(" #n ")" ::: "memory")
; #define PG8_BAR __builtin_amdgcn_s_barrier()
; #define PG8_SCHED __builtin_amdgcn_sched_barrier(0)
; template <class Epi>
; __device__ __forceinline__ void gemm_phase(LAS unsigned char* lds, const Gemm g, const StaticOrder& S, const Epi& E) {
;     ...
;             PG8_WAIT_V(6); PG8_BAR; PG8_MMA(1, 1, At, B1); PG8_BAR;
;             PG8_LDB(B0, 1, 0); PG8_SCHED; PG8_LDA(At, 1, 0); PG8_STAGE(PG8_SA(0, 1), a2 + hstep, voffA);
;             PG8_WAIT_L(8); PG8_BAR; PG8_WAIT_L(0); PG8_MMA(0, 0, At, B0); PG8_BAR; PG8_SCHED;
;             PG8_LDB(B1, 1, 1); PG8_STAGE(PG8_SB(1, 0), b3, voffB);
;             PG8_BAR; PG8_WAIT_L(0); PG8_MMA(0, 1, At, B1); PG8_BAR;
;             PG8_LDA(At, 1, 1); PG8_STAGE(PG8_SA(1, 0), a3, voffA);
;             PG8_BAR; PG8_WAIT_L(0); PG8_MMA(1, 0, At, B0); PG8_BAR; PG8_SCHED;
	v_mfma_f32_16x16x32_bf16 v[52:55], v[202:205], v[170:173], v[52:55]
	v_mfma_f32_16x16x32_bf16 v[48:51], v[210:213], v[170:173], v[48:51]
	v_mfma_f32_16x16x32_bf16 v[36:39], v[202:205], v[178:181], v[36:39]
	v_mfma_f32_16x16x32_bf16 v[32:35], v[210:213], v[178:181], v[32:35]
	v_mfma_f32_16x16x32_bf16 v[20:23], v[202:205], v[186:189], v[20:23]
	v_mfma_f32_16x16x32_bf16 v[16:19], v[210:213], v[186:189], v[16:19]
	v_mfma_f32_16x16x32_bf16 v[4:7], v[202:205], v[194:197], v[4:7]
	v_mfma_f32_16x16x32_bf16 v[0:3], v[210:213], v[194:197], v[0:3]
	v_mfma_f32_16x16x32_bf16 v[52:55], v[206:209], v[174:177], v[52:55]
	v_mfma_f32_16x16x32_bf16 v[48:51], v[216:219], v[174:177], v[48:51]
	v_mfma_f32_16x16x32_bf16 v[36:39], v[206:209], v[182:185], v[36:39]
	v_mfma_f32_16x16x32_bf16 v[32:35], v[216:219], v[182:185], v[32:35]
	v_mfma_f32_16x16x32_bf16 v[20:23], v[206:209], v[190:193], v[20:23]
	v_mfma_f32_16x16x32_bf16 v[16:19], v[216:219], v[190:193], v[16:19]
	v_mfma_f32_16x16x32_bf16 v[4:7], v[206:209], v[198:201], v[4:7]
	v_mfma_f32_16x16x32_bf16 v[0:3], v[216:219], v[198:201], v[0:3]
	s_add_i32 s49, 0, 0x18000
	v_add_u32_e32 v166, s49, v148
	s_barrier
	ds_read_b128 v[154:157], v166
	ds_read_b128 v[158:161], v166 offset:1024
	ds_read_b128 v[162:165], v166 offset:2048
	ds_read_b128 v[166:169], v166 offset:3072
	s_add_u32 s26, s26, 0x80000
	s_addc_u32 s27, s27, 0
	s_mov_b32 m0, s31
	s_nop 0
	ds_read_b128 v[170:173], v151 offset:32768
	ds_read_b128 v[174:177], v151 offset:33792
	ds_read_b128 v[178:181], v151 offset:34816
	ds_read_b128 v[182:185], v151 offset:35840
	ds_read_b128 v[186:189], v151 offset:36864
	ds_read_b128 v[190:193], v151 offset:37888
	ds_read_b128 v[194:197], v151 offset:38912
	ds_read_b128 v[198:201], v151 offset:39936
	global_load_lds_dwordx4 v128, s[26:27]
	s_nop 0
	s_mov_b32 m0, s33
	s_nop 0
	global_load_lds_dwordx4 v132, s[26:27]
	s_waitcnt lgkmcnt(8)
	s_barrier
	s_waitcnt lgkmcnt(0)
	s_waitcnt lgkmcnt(0)
	v_mfma_f32_16x16x32_bf16 v[124:127], v[154:157], v[170:173], v[124:127]
	v_mfma_f32_16x16x32_bf16 v[120:123], v[162:165], v[170:173], v[120:123]
	v_mfma_f32_16x16x32_bf16 v[108:111], v[154:157], v[178:181], v[108:111]
	v_mfma_f32_16x16x32_bf16 v[104:107], v[162:165], v[178:181], v[104:107]
	v_mfma_f32_16x16x32_bf16 v[92:95], v[154:157], v[186:189], v[92:95]
	v_mfma_f32_16x16x32_bf16 v[88:91], v[162:165], v[186:189], v[88:91]
	v_mfma_f32_16x16x32_bf16 v[76:79], v[154:157], v[194:197], v[76:79]
	v_mfma_f32_16x16x32_bf16 v[72:75], v[162:165], v[194:197], v[72:75]
	v_mfma_f32_16x16x32_bf16 v[124:127], v[158:161], v[174:177], v[124:127]
	v_mfma_f32_16x16x32_bf16 v[120:123], v[166:169], v[174:177], v[120:123]
	v_mfma_f32_16x16x32_bf16 v[108:111], v[158:161], v[182:185], v[108:111]
	v_mfma_f32_16x16x32_bf16 v[104:107], v[166:169], v[182:185], v[104:107]
	v_mfma_f32_16x16x32_bf16 v[92:95], v[158:161], v[190:193], v[92:95]
	v_mfma_f32_16x16x32_bf16 v[88:91], v[166:169], v[190:193], v[88:91]
	v_mfma_f32_16x16x32_bf16 v[76:79], v[158:161], v[198:201], v[76:79]
	v_mfma_f32_16x16x32_bf16 v[72:75], v[166:169], v[198:201], v[72:75]
	s_barrier
	s_add_i32 s26, 0, 0x1c000
	s_add_i32 s27, s49, s29
	v_add_u32_e32 v216, s26, v148
	v_lshl_add_u64 v[220:221], v[220:221], 0, s[4:5]
	s_mov_b32 m0, s27
	ds_read_b128 v[202:205], v216
	ds_read_b128 v[206:209], v216 offset:1024
	ds_read_b128 v[210:213], v216 offset:2048
	ds_read_b128 v[216:219], v216 offset:3072
	global_load_lds_dwordx4 v[220:221], off
	v_lshl_add_u64 v[220:221], v[222:223], 0, s[4:5]
	s_add_i32 m0, s27, 0x2000
	s_nop 0
	global_load_lds_dwordx4 v[220:221], off
	s_barrier
	s_waitcnt lgkmcnt(0)
	s_waitcnt lgkmcnt(0)
	v_mfma_f32_16x16x32_bf16 v[116:119], v[202:205], v[170:173], v[116:119]
	v_mfma_f32_16x16x32_bf16 v[112:115], v[210:213], v[170:173], v[112:115]
	v_mfma_f32_16x16x32_bf16 v[100:103], v[202:205], v[178:181], v[100:103]
	v_mfma_f32_16x16x32_bf16 v[96:99], v[210:213], v[178:181], v[96:99]
	v_mfma_f32_16x16x32_bf16 v[84:87], v[202:205], v[186:189], v[84:87]
	v_mfma_f32_16x16x32_bf16 v[80:83], v[210:213], v[186:189], v[80:83]
	v_mfma_f32_16x16x32_bf16 v[68:71], v[202:205], v[194:197], v[68:71]
	v_mfma_f32_16x16x32_bf16 v[64:67], v[210:213], v[194:197], v[64:67]
	v_mfma_f32_16x16x32_bf16 v[116:119], v[206:209], v[174:177], v[116:119]
	v_mfma_f32_16x16x32_bf16 v[112:115], v[216:219], v[174:177], v[112:115]
	v_mfma_f32_16x16x32_bf16 v[100:103], v[206:209], v[182:185], v[100:103]
	v_mfma_f32_16x16x32_bf16 v[96:99], v[216:219], v[182:185], v[96:99]
	v_mfma_f32_16x16x32_bf16 v[84:87], v[206:209], v[190:193], v[84:87]
	v_mfma_f32_16x16x32_bf16 v[80:83], v[216:219], v[190:193], v[80:83]
	v_mfma_f32_16x16x32_bf16 v[68:71], v[206:209], v[198:201], v[68:71]
	v_mfma_f32_16x16x32_bf16 v[64:67], v[216:219], v[198:201], v[64:67]
	s_mov_b32 m0, s37
	v_lshl_add_u64 v[220:221], v[224:225], 0, s[4:5]
	s_barrier
	ds_read_b128 v[170:173], v151 offset:49152
	ds_read_b128 v[174:177], v151 offset:50176
	ds_read_b128 v[178:181], v151 offset:51200
	ds_read_b128 v[182:185], v151 offset:52224
	ds_read_b128 v[186:189], v151 offset:53248
	ds_read_b128 v[190:193], v151 offset:54272
	ds_read_b128 v[194:197], v151 offset:55296
	ds_read_b128 v[198:201], v151 offset:56320
	global_load_lds_dwordx4 v[220:221], off
	v_lshl_add_u64 v[220:221], v[226:227], 0, s[4:5]
	s_mov_b32 m0, s38
	s_nop 0
	global_load_lds_dwordx4 v[220:221], off
	s_barrier
; #define PG8_STAGE(bufoff, gbase, voff) do { _Pragma("unroll") for (int _i = 0; _i < 2; ++_i) \
;         __builtin_amdgcn_global_load_lds((const unsigned*)((const char*)(gbase) + (voff)[_i]), (LAS unsigned*)(lds + (bufoff) + ldsw + _i * 8192), 16, 0, 0); } while (0)
; #define PG8_MMA(ai, bj, At, Bt) do { __builtin_amdgcn_s_setprio(1); _Pragma("unroll") for (int m = 0; m < 4; ++m) _Pragma("unroll") for (int n = 0; n < 2; ++n) _Pragma("unroll") for (int k = 0; k < 2; ++k) \
;         acc[ai][bj][m][n] = __builtin_amdgcn_mfma_f32_16x16x32_bf16(Bt[n][k], At[m][k], acc[ai][bj][m][n], 0, 0, 0); __builtin_amdgcn_s_setprio(0); } while (0)
; #define PG8_WAIT_V(n) asm volatile("s_waitcnt vmcnt(" #n ")" ::: "memory")
; #define PG8_WAIT_L(n) asm volatile("s_waitcnt lgkmcnt(" #n ")" ::: "memory")
; #define PG8_BAR __builtin_amdgcn_s_barrier()
; #define PG8_SCHED __builtin_amdgcn_sched_barrier(0)
; __device__ __forceinline__ u32x4 pack8(const f32x4 v0, const f32x4 v1) { u32x4 w; w.x = cvt_pk_bf16(v0[0], v0[1]); w.y = cvt_pk_bf16(v0[2], v0[3]); w.z = cvt_pk_bf16(v1[0], v1[1]); w.w = cvt_pk_bf16(v1[2], v1[3]); return w; }
; __device__ __forceinline__ f32x4 sig4(const f32x4 v) { return (f32x4){sigmoidf_(v[0]), sigmoidf_(v[1]), sigmoidf_(v[2]), sigmoidf_(v[3])}; }
; template <class Epi>
; __device__ __forceinline__ void gemm_phase(LAS unsigned char* lds, const Gemm g, const StaticOrder& S, const Epi& E) {
;     ...
;             PG8_BAR; PG8_WAIT_L(0); PG8_MMA(1, 0, At, B0); PG8_BAR; PG8_SCHED;
;             PG8_STAGE(PG8_SB(1, 1), b3 + hstep, voffB);
;             PG8_WAIT_V(6); PG8_BAR; PG8_MMA(1, 1, At, B1); PG8_BAR;
;     __device__ __forceinline__ void operator()(const AccT& acc, const pg8::Unit& u, int wr, int wc, int fr, int fq) const {
;         const int row0 = u.pm * 256 + wr * 64 + fr, col0 = u.pn * 128 + wc * 32 + 8 * fq;
; #pragma unroll
;         for (int ai = 0; ai < 2; ++ai)
; #pragma unroll
;             for (int m = 0; m < 4; ++m) { const int r = row0 + ai * 128 + m * 16;
;                 const f32x4 g0 = acc[ai][0][m][0], g1 = acc[ai][0][m][1];
;                 const f32x4 o0 = g0 * sig4(g0) * acc[ai][1][m][0], o1 = g1 * sig4(g1) * acc[ai][1][m][1];
;                 *(u32x4*)(O + (size_t)r * DFF + col0) = pack8(o0, o1); }
	s_waitcnt lgkmcnt(0)
	s_waitcnt lgkmcnt(0)
	v_mfma_f32_16x16x32_bf16 v[60:63], v[154:157], v[170:173], v[60:63]
	v_mfma_f32_16x16x32_bf16 v[56:59], v[162:165], v[170:173], v[56:59]
	v_mfma_f32_16x16x32_bf16 v[44:47], v[154:157], v[178:181], v[44:47]
	v_mfma_f32_16x16x32_bf16 v[40:43], v[162:165], v[178:181], v[40:43]
	v_mfma_f32_16x16x32_bf16 v[28:31], v[154:157], v[186:189], v[28:31]
	v_mfma_f32_16x16x32_bf16 v[24:27], v[162:165], v[186:189], v[24:27]
	v_mfma_f32_16x16x32_bf16 v[12:15], v[154:157], v[194:197], v[12:15]
	v_mfma_f32_16x16x32_bf16 v[8:11], v[162:165], v[194:197], v[8:11]
	v_mfma_f32_16x16x32_bf16 v[60:63], v[158:161], v[174:177], v[60:63]
	v_mfma_f32_16x16x32_bf16 v[56:59], v[166:169], v[174:177], v[56:59]
	v_mfma_f32_16x16x32_bf16 v[44:47], v[158:161], v[182:185], v[44:47]
	v_mfma_f32_16x16x32_bf16 v[40:43], v[166:169], v[182:185], v[40:43]
	v_mfma_f32_16x16x32_bf16 v[28:31], v[158:161], v[190:193], v[28:31]
	v_mfma_f32_16x16x32_bf16 v[24:27], v[166:169], v[190:193], v[24:27]
	v_mfma_f32_16x16x32_bf16 v[12:15], v[158:161], v[198:201], v[12:15]
	v_mfma_f32_16x16x32_bf16 v[8:11], v[166:169], v[198:201], v[8:11]
	s_barrier
	s_add_u32 s24, s24, 0x80080
	s_addc_u32 s25, s25, 0
	s_add_i32 s26, s26, s29
	s_nop 0
	s_mov_b32 m0, s26
	s_nop 0
	global_load_lds_dwordx4 v130, s[24:25]
	v_lshl_add_u64 v[154:155], s[24:25], 0, v[134:135]
	s_add_i32 m0, s26, 0x2000
	s_nop 0
	global_load_lds_dwordx4 v[154:155], off
	s_waitcnt vmcnt(6)
	s_barrier
	v_mfma_f32_16x16x32_bf16 v[52:55], v[202:205], v[170:173], v[52:55]
	v_mfma_f32_16x16x32_bf16 v[48:51], v[210:213], v[170:173], v[48:51]
	v_mfma_f32_16x16x32_bf16 v[36:39], v[202:205], v[178:181], v[36:39]
	v_mfma_f32_16x16x32_bf16 v[32:35], v[210:213], v[178:181], v[32:35]
	v_mfma_f32_16x16x32_bf16 v[20:23], v[202:205], v[186:189], v[20:23]
	v_mfma_f32_16x16x32_bf16 v[16:19], v[210:213], v[186:189], v[16:19]
	v_mfma_f32_16x16x32_bf16 v[4:7], v[202:205], v[194:197], v[4:7]
	v_mfma_f32_16x16x32_bf16 v[0:3], v[210:213], v[194:197], v[0:3]
	v_mfma_f32_16x16x32_bf16 v[52:55], v[206:209], v[174:177], v[52:55]
	v_mfma_f32_16x16x32_bf16 v[48:51], v[216:219], v[174:177], v[48:51]
	v_mfma_f32_16x16x32_bf16 v[36:39], v[206:209], v[182:185], v[36:39]
	v_mfma_f32_16x16x32_bf16 v[32:35], v[216:219], v[182:185], v[32:35]
	v_mfma_f32_16x16x32_bf16 v[20:23], v[206:209], v[190:193], v[20:23]
	v_mfma_f32_16x16x32_bf16 v[16:19], v[216:219], v[190:193], v[16:19]
	v_mfma_f32_16x16x32_bf16 v[4:7], v[206:209], v[198:201], v[4:7]
	v_mfma_f32_16x16x32_bf16 v[0:3], v[216:219], v[198:201], v[0:3]
	s_add_i32 s48, s48, 2
	s_add_u32 s22, s22, 0x100
	s_addc_u32 s23, s23, 0
	s_add_u32 s46, s46, 0x100
	s_addc_u32 s47, s47, 0
	s_cmp_gt_u32 s48, 29
	s_barrier
	s_cbranch_scc0 .LBB0_1150
	v_mul_f32_e32 v155, 0xbfb8aa3b, v124
	v_exp_f32_e32 v155, v155
	v_mul_f32_e32 v157, 0xbfb8aa3b, v125
	v_exp_f32_e32 v159, v157
	v_lshl_or_b32 v156, s43, 7, v149
	v_add_f32_e32 v155, 1.0, v155
	v_rcp_f32_e32 v158, v155
	v_add_f32_e32 v155, 1.0, v159
	v_mul_f32_e32 v159, 0xbfb8aa3b, v126
	v_exp_f32_e32 v160, v159
	v_mul_f32_e32 v159, 0xbfb8aa3b, v127
	v_exp_f32_e32 v161, v159
	v_rcp_f32_e32 v159, v155
	v_add_f32_e32 v155, 1.0, v160
	v_rcp_f32_e32 v160, v155
	v_add_f32_e32 v155, 1.0, v161
	v_rcp_f32_e32 v161, v155
	v_mul_f32_e32 v155, 0xbfb8aa3b, v120
	v_pk_mul_f32 v[124:125], v[124:125], v[158:159]
	v_exp_f32_e32 v155, v155
	v_mul_f32_e32 v158, 0xbfb8aa3b, v121
	v_exp_f32_e32 v159, v158
	v_pk_mul_f32 v[126:127], v[126:127], v[160:161]
	v_add_f32_e32 v155, 1.0, v155
	v_rcp_f32_e32 v158, v155
	v_add_f32_e32 v155, 1.0, v159
	v_mul_f32_e32 v159, 0xbfb8aa3b, v122
	v_exp_f32_e32 v160, v159
	v_mul_f32_e32 v159, 0xbfb8aa3b, v123
	v_exp_f32_e32 v161, v159
	v_rcp_f32_e32 v159, v155
	v_add_f32_e32 v155, 1.0, v160
	v_rcp_f32_e32 v160, v155
	v_add_f32_e32 v155, 1.0, v161
	v_rcp_f32_e32 v161, v155
	v_pk_mul_f32 v[120:121], v[120:121], v[158:159]
	v_pk_mul_f32 v[118:119], v[126:127], v[118:119]
	v_pk_mul_f32 v[116:117], v[124:125], v[116:117]
	v_pk_mul_f32 v[122:123], v[122:123], v[160:161]
	v_pk_mul_f32 v[112:113], v[120:121], v[112:113]
	v_lshl_add_u32 v154, s20, 8, v147
	v_ashrrev_i32_e32 v157, 31, v156
	v_pk_mul_f32 v[114:115], v[122:123], v[114:115]
	v_cvt_pk_bf16_f32 v116, v116, v117
	v_cvt_pk_bf16_f32 v117, v118, v119
	v_cvt_pk_bf16_f32 v118, v112, v113
	v_mov_b64_e32 v[112:113], s[0:1]
	v_cvt_pk_bf16_f32 v119, v114, v115
	v_mad_i64_i32 v[120:121], s[22:23], v154, s42, v[112:113]
	v_lshlrev_b64 v[114:115], 1, v[156:157]
	v_lshl_add_u64 v[120:121], v[120:121], 0, v[114:115]
	global_store_dwordx4 v[120:121], v[116:119], off
	v_or_b32_e32 v120, 16, v154
	s_and_b64 vcc, exec, s[2:3]
	v_mul_f32_e32 v116, 0xbfb8aa3b, v108
	v_mul_f32_e32 v117, 0xbfb8aa3b, v109
	v_mul_f32_e32 v118, 0xbfb8aa3b, v110
	v_mul_f32_e32 v119, 0xbfb8aa3b, v111
	v_exp_f32_e32 v116, v116
	v_exp_f32_e32 v117, v117
	v_exp_f32_e32 v118, v118
	v_exp_f32_e32 v119, v119
	v_add_f32_e32 v116, 1.0, v116
	v_add_f32_e32 v117, 1.0, v117
	v_add_f32_e32 v118, 1.0, v118
	v_add_f32_e32 v119, 1.0, v119
	v_rcp_f32_e32 v116, v116
	v_rcp_f32_e32 v117, v117
	v_rcp_f32_e32 v118, v118
	v_rcp_f32_e32 v119, v119
	s_mov_b32 s43, s8
	v_pk_mul_f32 v[108:109], v[108:109], v[116:117]
	v_mul_f32_e32 v116, 0xbfb8aa3b, v104
	v_mul_f32_e32 v117, 0xbfb8aa3b, v105
	v_pk_mul_f32 v[110:111], v[110:111], v[118:119]
	v_mul_f32_e32 v118, 0xbfb8aa3b, v106
	v_mul_f32_e32 v119, 0xbfb8aa3b, v107
	v_exp_f32_e32 v116, v116
	v_exp_f32_e32 v117, v117
	v_exp_f32_e32 v118, v118
	v_exp_f32_e32 v119, v119
	v_add_f32_e32 v116, 1.0, v116
	v_add_f32_e32 v117, 1.0, v117
	v_add_f32_e32 v118, 1.0, v118
	v_add_f32_e32 v119, 1.0, v119
; __device__ __forceinline__ u32x4 pack8(const f32x4 v0, const f32x4 v1) { u32x4 w; w.x = cvt_pk_bf16(v0[0], v0[1]); w.y = cvt_pk_bf16(v0[2], v0[3]); w.z = cvt_pk_bf16(v1[0], v1[1]); w.w = cvt_pk_bf16(v1[2], v1[3]); return w; }
; __device__ __forceinline__ f32x4 sig4(const f32x4 v) { return (f32x4){sigmoidf_(v[0]), sigmoidf_(v[1]), sigmoidf_(v[2]), sigmoidf_(v[3])}; }
;     __device__ __forceinline__ void operator()(const AccT& acc, const pg8::Unit& u, int wr, int wc, int fr, int fq) const {
;         const int row0 = u.pm * 256 + wr * 64 + fr, col0 = u.pn * 128 + wc * 32 + 8 * fq;
; #pragma unroll
;         for (int ai = 0; ai < 2; ++ai)
; #pragma unroll
;             for (int m = 0; m < 4; ++m) { const int r = row0 + ai * 128 + m * 16;
;                 const f32x4 g0 = acc[ai][0][m][0], g1 = acc[ai][0][m][1];
;                 const f32x4 o0 = g0 * sig4(g0) * acc[ai][1][m][0], o1 = g1 * sig4(g1) * acc[ai][1][m][1];
;                 *(u32x4*)(O + (size_t)r * DFF + col0) = pack8(o0, o1); }
	v_rcp_f32_e32 v116, v116
	v_rcp_f32_e32 v117, v117
	v_rcp_f32_e32 v118, v118
	v_rcp_f32_e32 v119, v119
	v_pk_mul_f32 v[100:101], v[108:109], v[100:101]
	v_pk_mul_f32 v[104:105], v[104:105], v[116:117]
	v_pk_mul_f32 v[102:103], v[110:111], v[102:103]
	v_pk_mul_f32 v[106:107], v[106:107], v[118:119]
	s_mov_b32 s20, s10
	v_pk_mul_f32 v[106:107], v[106:107], v[98:99]
	v_pk_mul_f32 v[98:99], v[104:105], v[96:97]
	v_cvt_pk_bf16_f32 v96, v100, v101
	v_mad_i64_i32 v[100:101], s[22:23], v120, s42, v[112:113]
	v_cvt_pk_bf16_f32 v97, v102, v103
	v_cvt_pk_bf16_f32 v98, v98, v99
	v_cvt_pk_bf16_f32 v99, v106, v107
	v_lshl_add_u64 v[100:101], v[100:101], 0, v[114:115]
	global_store_dwordx4 v[100:101], v[96:99], off
	v_or_b32_e32 v100, 32, v154
	s_mov_b64 s[24:25], s[18:19]
	v_mul_f32_e32 v96, 0xbfb8aa3b, v92
	v_mul_f32_e32 v97, 0xbfb8aa3b, v93
	v_mul_f32_e32 v98, 0xbfb8aa3b, v94
	v_mul_f32_e32 v99, 0xbfb8aa3b, v95
	v_exp_f32_e32 v96, v96
	v_exp_f32_e32 v97, v97
	v_exp_f32_e32 v98, v98
	v_exp_f32_e32 v99, v99
	v_add_f32_e32 v96, 1.0, v96
	v_add_f32_e32 v97, 1.0, v97
	v_add_f32_e32 v98, 1.0, v98
	v_add_f32_e32 v99, 1.0, v99
	v_rcp_f32_e32 v96, v96
	v_rcp_f32_e32 v97, v97
	v_rcp_f32_e32 v98, v98
	v_rcp_f32_e32 v99, v99
	v_pk_mul_f32 v[92:93], v[92:93], v[96:97]
	v_mul_f32_e32 v96, 0xbfb8aa3b, v88
	v_mul_f32_e32 v97, 0xbfb8aa3b, v89
	v_pk_mul_f32 v[94:95], v[94:95], v[98:99]
	v_mul_f32_e32 v98, 0xbfb8aa3b, v90
	v_mul_f32_e32 v99, 0xbfb8aa3b, v91
	v_exp_f32_e32 v96, v96
	v_exp_f32_e32 v97, v97
	v_exp_f32_e32 v98, v98
	v_exp_f32_e32 v99, v99
	v_add_f32_e32 v96, 1.0, v96
	v_add_f32_e32 v97, 1.0, v97
	v_add_f32_e32 v98, 1.0, v98
	v_add_f32_e32 v99, 1.0, v99
	v_rcp_f32_e32 v96, v96
	v_rcp_f32_e32 v97, v97
	v_rcp_f32_e32 v98, v98
	v_rcp_f32_e32 v99, v99
	v_pk_mul_f32 v[84:85], v[92:93], v[84:85]
	v_pk_mul_f32 v[88:89], v[88:89], v[96:97]
	v_pk_mul_f32 v[86:87], v[94:95], v[86:87]
	v_pk_mul_f32 v[90:91], v[90:91], v[98:99]
	s_nop 0
	v_pk_mul_f32 v[90:91], v[90:91], v[82:83]
	v_pk_mul_f32 v[82:83], v[88:89], v[80:81]
	v_cvt_pk_bf16_f32 v80, v84, v85
	v_mad_i64_i32 v[84:85], s[22:23], v100, s42, v[112:113]
	v_cvt_pk_bf16_f32 v81, v86, v87
	v_cvt_pk_bf16_f32 v82, v82, v83
	v_cvt_pk_bf16_f32 v83, v90, v91
	v_lshl_add_u64 v[84:85], v[84:85], 0, v[114:115]
	global_store_dwordx4 v[84:85], v[80:83], off
	v_or_b32_e32 v84, 48, v154
	s_nop 0
	v_mul_f32_e32 v80, 0xbfb8aa3b, v76
	v_mul_f32_e32 v81, 0xbfb8aa3b, v77
	v_mul_f32_e32 v82, 0xbfb8aa3b, v78
	v_mul_f32_e32 v83, 0xbfb8aa3b, v79
	v_exp_f32_e32 v80, v80
	v_exp_f32_e32 v81, v81
	v_exp_f32_e32 v82, v82
	v_exp_f32_e32 v83, v83
	v_add_f32_e32 v80, 1.0, v80
	v_add_f32_e32 v81, 1.0, v81
	v_add_f32_e32 v82, 1.0, v82
	v_add_f32_e32 v83, 1.0, v83
	v_rcp_f32_e32 v80, v80
	v_rcp_f32_e32 v81, v81
	v_rcp_f32_e32 v82, v82
	v_rcp_f32_e32 v83, v83
	v_pk_mul_f32 v[76:77], v[76:77], v[80:81]
	v_mul_f32_e32 v80, 0xbfb8aa3b, v72
	v_mul_f32_e32 v81, 0xbfb8aa3b, v73
	v_pk_mul_f32 v[78:79], v[78:79], v[82:83]
	v_mul_f32_e32 v82, 0xbfb8aa3b, v74
	v_mul_f32_e32 v83, 0xbfb8aa3b, v75
	v_exp_f32_e32 v80, v80
	v_exp_f32_e32 v81, v81
	v_exp_f32_e32 v82, v82
	v_exp_f32_e32 v83, v83
	v_add_f32_e32 v80, 1.0, v80
	v_add_f32_e32 v81, 1.0, v81
	v_add_f32_e32 v82, 1.0, v82
	v_add_f32_e32 v83, 1.0, v83
	v_rcp_f32_e32 v80, v80
	v_rcp_f32_e32 v81, v81
	v_rcp_f32_e32 v82, v82
	v_rcp_f32_e32 v83, v83
	v_pk_mul_f32 v[68:69], v[76:77], v[68:69]
	v_pk_mul_f32 v[72:73], v[72:73], v[80:81]
	v_pk_mul_f32 v[70:71], v[78:79], v[70:71]
	v_pk_mul_f32 v[74:75], v[74:75], v[82:83]
	s_nop 0
	v_pk_mul_f32 v[74:75], v[74:75], v[66:67]
	v_pk_mul_f32 v[66:67], v[72:73], v[64:65]
	v_cvt_pk_bf16_f32 v64, v68, v69
	v_mad_i64_i32 v[68:69], s[22:23], v84, s42, v[112:113]
	v_cvt_pk_bf16_f32 v65, v70, v71
	v_cvt_pk_bf16_f32 v66, v66, v67
	v_cvt_pk_bf16_f32 v67, v74, v75
	v_lshl_add_u64 v[68:69], v[68:69], 0, v[114:115]
	global_store_dwordx4 v[68:69], v[64:67], off
	v_add_u32_e32 v68, 0x80, v154
	s_nop 0
	v_mul_f32_e32 v64, 0xbfb8aa3b, v60
	v_mul_f32_e32 v65, 0xbfb8aa3b, v61
	v_mul_f32_e32 v66, 0xbfb8aa3b, v62
	v_mul_f32_e32 v67, 0xbfb8aa3b, v63
	v_exp_f32_e32 v64, v64
	v_exp_f32_e32 v65, v65
	v_exp_f32_e32 v66, v66
	v_exp_f32_e32 v67, v67
	v_add_f32_e32 v64, 1.0, v64
	v_add_f32_e32 v65, 1.0, v65
	v_add_f32_e32 v66, 1.0, v66
	v_add_f32_e32 v67, 1.0, v67
	v_rcp_f32_e32 v64, v64
	v_rcp_f32_e32 v65, v65
	v_rcp_f32_e32 v66, v66
	v_rcp_f32_e32 v67, v67
	v_pk_mul_f32 v[60:61], v[60:61], v[64:65]
	v_mul_f32_e32 v64, 0xbfb8aa3b, v56
	v_mul_f32_e32 v65, 0xbfb8aa3b, v57
	v_pk_mul_f32 v[62:63], v[62:63], v[66:67]
	v_mul_f32_e32 v66, 0xbfb8aa3b, v58
	v_mul_f32_e32 v67, 0xbfb8aa3b, v59
	v_exp_f32_e32 v64, v64
	v_exp_f32_e32 v65, v65
	v_exp_f32_e32 v66, v66
	v_exp_f32_e32 v67, v67
	v_add_f32_e32 v64, 1.0, v64
	v_add_f32_e32 v65, 1.0, v65
	v_add_f32_e32 v66, 1.0, v66
	v_add_f32_e32 v67, 1.0, v67
	v_rcp_f32_e32 v64, v64
	v_rcp_f32_e32 v65, v65
	v_rcp_f32_e32 v66, v66
	v_rcp_f32_e32 v67, v67
	v_pk_mul_f32 v[52:53], v[60:61], v[52:53]
	v_pk_mul_f32 v[56:57], v[56:57], v[64:65]
	v_pk_mul_f32 v[54:55], v[62:63], v[54:55]
	v_pk_mul_f32 v[58:59], v[58:59], v[66:67]
	s_nop 0
	v_pk_mul_f32 v[58:59], v[58:59], v[50:51]
; #define PG8_WAIT_V(n) asm volatile("s_waitcnt vmcnt(" #n ")" ::: "memory")
; #define PG8_BAR __builtin_amdgcn_s_barrier()
; __device__ __forceinline__ u32x4 pack8(const f32x4 v0, const f32x4 v1) { u32x4 w; w.x = cvt_pk_bf16(v0[0], v0[1]); w.y = cvt_pk_bf16(v0[2], v0[3]); w.z = cvt_pk_bf16(v1[0], v1[1]); w.w = cvt_pk_bf16(v1[2], v1[3]); return w; }
; __device__ __forceinline__ f32x4 sig4(const f32x4 v) { return (f32x4){sigmoidf_(v[0]), sigmoidf_(v[1]), sigmoidf_(v[2]), sigmoidf_(v[3])}; }
; template <class Epi>
; __device__ __forceinline__ void gemm_phase(LAS unsigned char* lds, const Gemm g, const StaticOrder& S, const Epi& E) {
;     ...
;     PG8_WAIT_V(0);
;     if (wr == 0) PG8_BAR;
;     PG8_BAR;
;     __device__ __forceinline__ void operator()(const AccT& acc, const pg8::Unit& u, int wr, int wc, int fr, int fq) const {
;         const int row0 = u.pm * 256 + wr * 64 + fr, col0 = u.pn * 128 + wc * 32 + 8 * fq;
; #pragma unroll
;         for (int ai = 0; ai < 2; ++ai)
; #pragma unroll
;             for (int m = 0; m < 4; ++m) { const int r = row0 + ai * 128 + m * 16;
;                 const f32x4 g0 = acc[ai][0][m][0], g1 = acc[ai][0][m][1];
;                 const f32x4 o0 = g0 * sig4(g0) * acc[ai][1][m][0], o1 = g1 * sig4(g1) * acc[ai][1][m][1];
;                 *(u32x4*)(O + (size_t)r * DFF + col0) = pack8(o0, o1); }
	v_pk_mul_f32 v[50:51], v[56:57], v[48:49]
	v_cvt_pk_bf16_f32 v48, v52, v53
	v_mad_i64_i32 v[52:53], s[22:23], v68, s42, v[112:113]
	v_cvt_pk_bf16_f32 v49, v54, v55
	v_cvt_pk_bf16_f32 v50, v50, v51
	v_cvt_pk_bf16_f32 v51, v58, v59
	v_lshl_add_u64 v[52:53], v[52:53], 0, v[114:115]
	global_store_dwordx4 v[52:53], v[48:51], off
	v_add_u32_e32 v52, 0x90, v154
	s_nop 0
	v_mul_f32_e32 v48, 0xbfb8aa3b, v44
	v_mul_f32_e32 v49, 0xbfb8aa3b, v45
	v_mul_f32_e32 v50, 0xbfb8aa3b, v46
	v_mul_f32_e32 v51, 0xbfb8aa3b, v47
	v_exp_f32_e32 v48, v48
	v_exp_f32_e32 v49, v49
	v_exp_f32_e32 v50, v50
	v_exp_f32_e32 v51, v51
	v_add_f32_e32 v48, 1.0, v48
	v_add_f32_e32 v49, 1.0, v49
	v_add_f32_e32 v50, 1.0, v50
	v_add_f32_e32 v51, 1.0, v51
	v_rcp_f32_e32 v48, v48
	v_rcp_f32_e32 v49, v49
	v_rcp_f32_e32 v50, v50
	v_rcp_f32_e32 v51, v51
	v_pk_mul_f32 v[44:45], v[44:45], v[48:49]
	v_mul_f32_e32 v48, 0xbfb8aa3b, v40
	v_mul_f32_e32 v49, 0xbfb8aa3b, v41
	v_pk_mul_f32 v[46:47], v[46:47], v[50:51]
	v_mul_f32_e32 v50, 0xbfb8aa3b, v42
	v_mul_f32_e32 v51, 0xbfb8aa3b, v43
	v_exp_f32_e32 v48, v48
	v_exp_f32_e32 v49, v49
	v_exp_f32_e32 v50, v50
	v_exp_f32_e32 v51, v51
	v_add_f32_e32 v48, 1.0, v48
	v_add_f32_e32 v49, 1.0, v49
	v_add_f32_e32 v50, 1.0, v50
	v_add_f32_e32 v51, 1.0, v51
	v_rcp_f32_e32 v48, v48
	v_rcp_f32_e32 v49, v49
	v_rcp_f32_e32 v50, v50
	v_rcp_f32_e32 v51, v51
	v_pk_mul_f32 v[36:37], v[44:45], v[36:37]
	v_pk_mul_f32 v[40:41], v[40:41], v[48:49]
	v_pk_mul_f32 v[38:39], v[46:47], v[38:39]
	v_pk_mul_f32 v[42:43], v[42:43], v[50:51]
	s_nop 0
	v_pk_mul_f32 v[42:43], v[42:43], v[34:35]
	v_pk_mul_f32 v[34:35], v[40:41], v[32:33]
	v_cvt_pk_bf16_f32 v32, v36, v37
	v_mad_i64_i32 v[36:37], s[22:23], v52, s42, v[112:113]
	v_cvt_pk_bf16_f32 v33, v38, v39
	v_cvt_pk_bf16_f32 v34, v34, v35
	v_cvt_pk_bf16_f32 v35, v42, v43
	v_lshl_add_u64 v[36:37], v[36:37], 0, v[114:115]
	global_store_dwordx4 v[36:37], v[32:35], off
	v_add_u32_e32 v36, 0xa0, v154
	s_nop 0
	v_mul_f32_e32 v32, 0xbfb8aa3b, v28
	v_mul_f32_e32 v33, 0xbfb8aa3b, v29
	v_mul_f32_e32 v34, 0xbfb8aa3b, v30
	v_mul_f32_e32 v35, 0xbfb8aa3b, v31
	v_exp_f32_e32 v32, v32
	v_exp_f32_e32 v33, v33
	v_exp_f32_e32 v34, v34
	v_exp_f32_e32 v35, v35
	v_add_f32_e32 v32, 1.0, v32
	v_add_f32_e32 v33, 1.0, v33
	v_add_f32_e32 v34, 1.0, v34
	v_add_f32_e32 v35, 1.0, v35
	v_rcp_f32_e32 v32, v32
	v_rcp_f32_e32 v33, v33
	v_rcp_f32_e32 v34, v34
	v_rcp_f32_e32 v35, v35
	v_pk_mul_f32 v[28:29], v[28:29], v[32:33]
	v_mul_f32_e32 v32, 0xbfb8aa3b, v24
	v_mul_f32_e32 v33, 0xbfb8aa3b, v25
	v_pk_mul_f32 v[30:31], v[30:31], v[34:35]
	v_mul_f32_e32 v34, 0xbfb8aa3b, v26
	v_mul_f32_e32 v35, 0xbfb8aa3b, v27
	v_exp_f32_e32 v32, v32
	v_exp_f32_e32 v33, v33
	v_exp_f32_e32 v34, v34
	v_exp_f32_e32 v35, v35
	v_add_f32_e32 v32, 1.0, v32
	v_add_f32_e32 v33, 1.0, v33
	v_add_f32_e32 v34, 1.0, v34
	v_add_f32_e32 v35, 1.0, v35
	v_rcp_f32_e32 v32, v32
	v_rcp_f32_e32 v33, v33
	v_rcp_f32_e32 v34, v34
	v_rcp_f32_e32 v35, v35
	v_pk_mul_f32 v[20:21], v[28:29], v[20:21]
	v_pk_mul_f32 v[24:25], v[24:25], v[32:33]
	v_pk_mul_f32 v[22:23], v[30:31], v[22:23]
	v_pk_mul_f32 v[26:27], v[26:27], v[34:35]
	s_nop 0
	v_pk_mul_f32 v[26:27], v[26:27], v[18:19]
	v_pk_mul_f32 v[18:19], v[24:25], v[16:17]
	v_cvt_pk_bf16_f32 v16, v20, v21
	v_mad_i64_i32 v[20:21], s[22:23], v36, s42, v[112:113]
	v_cvt_pk_bf16_f32 v17, v22, v23
	v_cvt_pk_bf16_f32 v18, v18, v19
	v_cvt_pk_bf16_f32 v19, v26, v27
	v_lshl_add_u64 v[20:21], v[20:21], 0, v[114:115]
	global_store_dwordx4 v[20:21], v[16:19], off
	v_add_u32_e32 v20, 0xb0, v154
	s_nop 0
	v_mul_f32_e32 v16, 0xbfb8aa3b, v12
	v_mul_f32_e32 v17, 0xbfb8aa3b, v13
	v_mul_f32_e32 v18, 0xbfb8aa3b, v14
	v_mul_f32_e32 v19, 0xbfb8aa3b, v15
	v_exp_f32_e32 v16, v16
	v_exp_f32_e32 v17, v17
	v_exp_f32_e32 v18, v18
	v_exp_f32_e32 v19, v19
	v_add_f32_e32 v16, 1.0, v16
	v_add_f32_e32 v17, 1.0, v17
	v_add_f32_e32 v18, 1.0, v18
	v_add_f32_e32 v19, 1.0, v19
	v_rcp_f32_e32 v16, v16
	v_rcp_f32_e32 v17, v17
	v_rcp_f32_e32 v18, v18
	v_rcp_f32_e32 v19, v19
	v_pk_mul_f32 v[12:13], v[12:13], v[16:17]
	v_mul_f32_e32 v16, 0xbfb8aa3b, v8
	v_mul_f32_e32 v17, 0xbfb8aa3b, v9
	v_pk_mul_f32 v[14:15], v[14:15], v[18:19]
	v_mul_f32_e32 v18, 0xbfb8aa3b, v10
	v_mul_f32_e32 v19, 0xbfb8aa3b, v11
	v_exp_f32_e32 v16, v16
	v_exp_f32_e32 v17, v17
	v_exp_f32_e32 v18, v18
	v_exp_f32_e32 v19, v19
	v_add_f32_e32 v16, 1.0, v16
	v_add_f32_e32 v17, 1.0, v17
	v_add_f32_e32 v18, 1.0, v18
	v_add_f32_e32 v19, 1.0, v19
	v_rcp_f32_e32 v16, v16
	v_rcp_f32_e32 v17, v17
	v_rcp_f32_e32 v18, v18
	v_rcp_f32_e32 v19, v19
	v_pk_mul_f32 v[4:5], v[12:13], v[4:5]
	v_pk_mul_f32 v[8:9], v[8:9], v[16:17]
	v_pk_mul_f32 v[6:7], v[14:15], v[6:7]
	v_pk_mul_f32 v[10:11], v[10:11], v[18:19]
	s_nop 0
	v_pk_mul_f32 v[10:11], v[10:11], v[2:3]
	v_pk_mul_f32 v[2:3], v[8:9], v[0:1]
	v_cvt_pk_bf16_f32 v0, v4, v5
	v_mad_i64_i32 v[4:5], s[22:23], v20, s42, v[112:113]
	v_lshl_add_u64 v[4:5], v[4:5], 0, v[114:115]
	s_mov_b64 s[22:23], s[16:17]
	v_cvt_pk_bf16_f32 v1, v6, v7
	v_cvt_pk_bf16_f32 v2, v2, v3
	v_cvt_pk_bf16_f32 v3, v10, v11
	global_store_dwordx4 v[4:5], v[0:3], off
	s_cbranch_vccz .LBB0_1143
	s_waitcnt vmcnt(0)
	s_cmpk_gt_u32 s28, 0xff
	s_cbranch_scc1 .LBB0_1154
	s_barrier

; #define PG8_STAGE(bufoff, gbase, voff) do { _Pragma("unroll") for (int _i = 0; _i < 2; ++_i) \
;         __builtin_amdgcn_global_load_lds((const unsigned*)((const char*)(gbase) + (voff)[_i]), (LAS unsigned*)(lds + (bufoff) + ldsw + _i * 8192), 16, 0, 0); } while (0)
; #define PG8_WAIT_V(n) asm volatile("s_waitcnt vmcnt(" #n ")" ::: "memory")
; #define PG8_BAR __builtin_amdgcn_s_barrier()
; template <class Epi>
; __device__ __forceinline__ void gemm_phase(LAS unsigned char* lds, const Gemm g, const StaticOrder& S, const Epi& E) {
;     ...
;     for (int i = 0; i < 2; ++i) { int R, C; stage_rc(tid * 16 + i * 8192, R, C); const int Rb = Epi::PERM ? ((R & ~31) + perm32(R & 31)) : R;
;         voffA[i] = (unsigned)(R * K + C) * 2u; voffB[i] = (unsigned)(Rb * K + C) * 2u; }
;     const size_t kstep = (size_t)(BK * 2);
;     const size_t hstep = (size_t)HALF * K * 2;
;     const size_t tstep = 2 * hstep;
;     const unsigned ldsw = (unsigned)wid * 1024u;
;     const int aoff = lds_byte(wr * 64 + fr, fq * 8), boff = lds_byte(wc * 32 + fr, fq * 8);
;     ...
;     const char* cA = (const char*)g.A + (size_t)cur.pm * tstep; const char* cB = (const char*)g.Bt + (size_t)cur.pn * tstep;
;     PG8_STAGE(PG8_SB(0, 0), cB, voffB); PG8_STAGE(PG8_SA(0, 0), cA, voffA); PG8_STAGE(PG8_SB(0, 1), cB + hstep, voffB); PG8_STAGE(PG8_SA(0, 1), cA + hstep, voffA);
;     if (wr == 1) PG8_BAR;
;     PG8_WAIT_V(4); PG8_BAR;
;     PG8_STAGE(PG8_SB(1, 0), cB + kstep, voffB); PG8_STAGE(PG8_SA(1, 0), cA + kstep, voffA); PG8_STAGE(PG8_SB(1, 1), cB + hstep + kstep, voffB);
;     PG8_WAIT_V(6); PG8_BAR;
.LBB0_1325:
	s_add_u32 s6, s12, 0x1a142000
	s_addc_u32 s7, s13, 0
	s_lshl_b32 s1, s1, 5
	s_mov_b64 s[16:17], 0x80
	s_and_b32 s1, s1, 0x60
	s_add_i32 m0, s29, 0x18000
	v_lshl_add_u64 v[6:7], v[6:7], 0, s[16:17]
	s_ashr_i32 s36, s94, 31
	s_ashr_i32 s37, s96, 31
	s_lshl_b32 s4, s0, 13
	s_lshl_b32 s5, s1, 7
	s_waitcnt vmcnt(4)
	s_barrier
	global_load_lds_dwordx4 v[6:7], off
	v_lshl_add_u64 v[4:5], v[4:5], 0, s[16:17]
	s_add_i32 m0, s29, 0x1a000
	s_add_i32 s38, s29, 0x8000
	s_add_i32 s39, s29, 0xa000
	global_load_lds_dwordx4 v[4:5], off
	v_lshl_add_u64 v[2:3], v[2:3], 0, s[16:17]
	s_mov_b32 m0, s38
	s_add_u32 s2, s24, 0x160080
	global_load_lds_dwordx4 v[2:3], off
	v_lshl_add_u64 v[0:1], v[0:1], 0, s[16:17]
	s_mov_b32 m0, s39
	s_addc_u32 s3, s25, 0
	global_load_lds_dwordx4 v[0:1], off
	s_add_i32 m0, s29, 0x1c000
	s_nop 0
	global_load_lds_dwordx4 v156, s[2:3]
	v_lshl_add_u64 v[0:1], s[2:3], 0, v[160:161]
	s_add_i32 m0, s29, 0x1e000
	s_movk_i32 s2, 0x3c0
	global_load_lds_dwordx4 v[0:1], off
	v_lshlrev_b32_e32 v0, 1, v10
	v_lshlrev_b32_e32 v1, 6, v214
	v_lshlrev_b32_e32 v2, 2, v214
	v_and_b32_e32 v153, 15, v214
	v_and_or_b32 v1, v1, s2, v0
	v_and_b32_e32 v2, 32, v2
	v_lshl_or_b32 v0, v153, 6, v0
	v_bitop3_b32 v183, s5, v1, v2 bitop3:0xf6
	s_waitcnt vmcnt(6)
	v_add_u16_e32 v1, v8, v9
	v_bitop3_b32 v0, v0, s4, v2 bitop3:0xde
	v_lshrrev_b16_e32 v1, 1, v1
	s_add_i32 s41, 0, 0x10000
	s_add_i32 s42, 0, 0x14000
	s_mov_b32 s40, s96
	v_lshl_or_b32 v182, s0, 6, v153
	v_or_b32_e32 v184, s1, v10
	v_add_lshl_u32 v162, v11, v1, 1
	v_mov_b32_e32 v163, v157
	v_add_lshl_u32 v164, v12, v1, 1
	v_mov_b32_e32 v165, v157
	v_mov_b64_e32 v[166:167], 0x100
	v_mov_b64_e32 v[168:169], 0xff
	v_add_u32_e32 v185, s41, v183
	v_add_u32_e32 v186, 0, v0
	v_add_u32_e32 v187, s42, v183
	s_movk_i32 s43, 0x2080
	s_mov_b32 s18, 0x3f9837f0
	s_mov_b64 s[20:21], 0x80000
	s_movk_i32 s44, 0x1ff0
	s_movk_i32 s45, 0x1fe0
	s_movk_i32 s46, 0x1fd0
	s_barrier
	s_branch .LBB0_1327

; #define PG8_STAGE(bufoff, gbase, voff) do { _Pragma("unroll") for (int _i = 0; _i < 2; ++_i) \
;         __builtin_amdgcn_global_load_lds((const unsigned*)((const char*)(gbase) + (voff)[_i]), (LAS unsigned*)(lds + (bufoff) + ldsw + _i * 8192), 16, 0, 0); } while (0)
; #define PG8_LDA(dst, b, h) do { _Pragma("unroll") for (int m = 0; m < 4; ++m) _Pragma("unroll") for (int k = 0; k < 2; ++k) dst[m][k] = *(const LAS bf16x8*)(lds + PG8_SA(b, h) + aoff + m * 2048 + k * 1024); } while (0)
; #define PG8_LDB(dst, b, h) do { _Pragma("unroll") for (int n = 0; n < 2; ++n) _Pragma("unroll") for (int k = 0; k < 2; ++k) dst[n][k] = *(const LAS bf16x8*)(lds + PG8_SB(b, h) + boff + n * 2048 + k * 1024); } while (0)
; #define PG8_MMA(ai, bj, At, Bt) do { __builtin_amdgcn_s_setprio(1); _Pragma("unroll") for (int m = 0; m < 4; ++m) _Pragma("unroll") for (int n = 0; n < 2; ++n) _Pragma("unroll") for (int k = 0; k < 2; ++k) \
;         acc[ai][bj][m][n] = __builtin_amdgcn_mfma_f32_16x16x32_bf16(Bt[n][k], At[m][k], acc[ai][bj][m][n], 0, 0, 0); __builtin_amdgcn_s_setprio(0); } while (0)
; #define PG8_WAIT_V(n) asm volatile("s_waitcnt vmcnt(" #n ")" ::: "memory")
; #define PG8_WAIT_L(n) asm volatile("s_waitcnt lgkmcnt(" #n ")" ::: "memory")
; #define PG8_BAR __builtin_amdgcn_s_barrier()
; #define PG8_SCHED __builtin_amdgcn_sched_barrier(0)
; template <class Epi>
; __device__ __forceinline__ void gemm_phase(LAS unsigned char* lds, const Gemm g, const StaticOrder& S, const Epi& E) {
;     ...
;             PG8_LDB(B0, 0, 0); PG8_SCHED; PG8_LDA(At, 0, 0); PG8_STAGE(PG8_SA(1, 1), a1 + hstep, voffA);
;             PG8_WAIT_L(8); PG8_BAR; PG8_WAIT_L(0); PG8_MMA(0, 0, At, B0); PG8_BAR; PG8_SCHED;
;             PG8_LDB(B1, 0, 1); PG8_STAGE(PG8_SB(0, 0), b2, voffB);
;             PG8_BAR; PG8_WAIT_L(0); PG8_MMA(0, 1, At, B1); PG8_BAR;
;             PG8_LDA(At, 0, 1); PG8_STAGE(PG8_SA(0, 0), a2, voffA);
;             PG8_BAR; PG8_WAIT_L(0); PG8_MMA(1, 0, At, B0); PG8_BAR; PG8_SCHED;
;             PG8_STAGE(PG8_SB(0, 1), b2 + hstep, voffB);
;             PG8_WAIT_V(6); PG8_BAR; PG8_MMA(1, 1, At, B1); PG8_BAR;
.LBB0_1338:
	ds_read_b128 v[128:131], v185
	ds_read_b128 v[132:135], v185 offset:1024
	ds_read_b128 v[136:139], v185 offset:2048
	ds_read_b128 v[140:143], v185 offset:3072
	s_add_u32 s24, s22, 0xffea0080
	s_addc_u32 s25, s23, -1
	s_cmpk_eq_i32 s53, 0x54
	s_cselect_b32 s27, s1, s25
	s_cselect_b32 s26, s0, s24
	s_cselect_b32 s25, s5, s52
	s_cselect_b32 s24, s4, s51
	s_nop 0
	s_add_i32 m0, s29, 0xc000
	ds_read_b128 v[144:147], v186
	ds_read_b128 v[148:151], v186 offset:1024
	ds_read_b128 v[170:173], v186 offset:2048
	ds_read_b128 v[174:177], v186 offset:3072
	ds_read_b128 v[178:181], v186 offset:4096
	ds_read_b128 v[188:191], v186 offset:5120
	ds_read_b128 v[192:195], v186 offset:6144
	ds_read_b128 v[196:199], v186 offset:7168
	global_load_lds_dwordx4 v162, s[22:23]
	s_nop 0
	s_add_i32 m0, s29, 0xe000
	s_nop 0
	global_load_lds_dwordx4 v164, s[22:23]
	s_waitcnt lgkmcnt(8)
	s_barrier
	s_waitcnt lgkmcnt(0)
	s_waitcnt lgkmcnt(0)
	v_mfma_f32_16x16x32_bf16 v[124:127], v[128:131], v[144:147], v[124:127]
	v_mfma_f32_16x16x32_bf16 v[120:123], v[136:139], v[144:147], v[120:123]
	v_mfma_f32_16x16x32_bf16 v[108:111], v[128:131], v[170:173], v[108:111]
	v_mfma_f32_16x16x32_bf16 v[104:107], v[136:139], v[170:173], v[104:107]
	v_mfma_f32_16x16x32_bf16 v[92:95], v[128:131], v[178:181], v[92:95]
	v_mfma_f32_16x16x32_bf16 v[88:91], v[136:139], v[178:181], v[88:91]
	v_mfma_f32_16x16x32_bf16 v[76:79], v[128:131], v[192:195], v[76:79]
	v_mfma_f32_16x16x32_bf16 v[72:75], v[136:139], v[192:195], v[72:75]
	v_mfma_f32_16x16x32_bf16 v[124:127], v[132:135], v[148:151], v[124:127]
	v_mfma_f32_16x16x32_bf16 v[120:123], v[140:143], v[148:151], v[120:123]
	v_mfma_f32_16x16x32_bf16 v[108:111], v[132:135], v[174:177], v[108:111]
	v_mfma_f32_16x16x32_bf16 v[104:107], v[140:143], v[174:177], v[104:107]
	v_mfma_f32_16x16x32_bf16 v[92:95], v[132:135], v[188:191], v[92:95]
	v_mfma_f32_16x16x32_bf16 v[88:91], v[140:143], v[188:191], v[88:91]
	v_mfma_f32_16x16x32_bf16 v[76:79], v[132:135], v[196:199], v[76:79]
	v_mfma_f32_16x16x32_bf16 v[72:75], v[140:143], v[196:199], v[72:75]
	s_barrier
	s_add_i32 s54, s41, s28
	v_lshl_add_u64 v[212:213], s[24:25], 0, v[156:157]
	s_mov_b32 m0, s54
	ds_read_b128 v[200:203], v187
	ds_read_b128 v[204:207], v187 offset:1024
	ds_read_b128 v[208:211], v187 offset:2048
	ds_read_b128 v[216:219], v187 offset:3072
	global_load_lds_dwordx4 v[212:213], off
	v_lshl_add_u64 v[220:221], s[24:25], 0, v[160:161]
	s_add_i32 m0, s54, 0x2000
	s_nop 0
	global_load_lds_dwordx4 v[220:221], off
	s_barrier
	s_waitcnt lgkmcnt(0)
	s_waitcnt lgkmcnt(0)
	v_mfma_f32_16x16x32_bf16 v[116:119], v[200:203], v[144:147], v[116:119]
	v_mfma_f32_16x16x32_bf16 v[112:115], v[208:211], v[144:147], v[112:115]
	v_mfma_f32_16x16x32_bf16 v[100:103], v[200:203], v[170:173], v[100:103]
	v_mfma_f32_16x16x32_bf16 v[96:99], v[208:211], v[170:173], v[96:99]
	v_mfma_f32_16x16x32_bf16 v[84:87], v[200:203], v[178:181], v[84:87]
	v_mfma_f32_16x16x32_bf16 v[80:83], v[208:211], v[178:181], v[80:83]
	v_mfma_f32_16x16x32_bf16 v[68:71], v[200:203], v[192:195], v[68:71]
	v_mfma_f32_16x16x32_bf16 v[64:67], v[208:211], v[192:195], v[64:67]
	v_mfma_f32_16x16x32_bf16 v[116:119], v[204:207], v[148:151], v[116:119]
	v_mfma_f32_16x16x32_bf16 v[112:115], v[216:219], v[148:151], v[112:115]
	v_mfma_f32_16x16x32_bf16 v[100:103], v[204:207], v[174:177], v[100:103]
	v_mfma_f32_16x16x32_bf16 v[96:99], v[216:219], v[174:177], v[96:99]
	v_mfma_f32_16x16x32_bf16 v[84:87], v[204:207], v[188:191], v[84:87]
	v_mfma_f32_16x16x32_bf16 v[80:83], v[216:219], v[188:191], v[80:83]
	v_mfma_f32_16x16x32_bf16 v[68:71], v[204:207], v[196:199], v[68:71]
	v_mfma_f32_16x16x32_bf16 v[64:67], v[216:219], v[196:199], v[64:67]
	s_mov_b32 m0, s29
	v_lshl_add_u64 v[222:223], s[26:27], 0, v[154:155]
	s_barrier
	ds_read_b128 v[144:147], v186 offset:16384
	ds_read_b128 v[148:151], v186 offset:17408
	ds_read_b128 v[170:173], v186 offset:18432
	ds_read_b128 v[174:177], v186 offset:19456
	ds_read_b128 v[178:181], v186 offset:20480
	ds_read_b128 v[188:191], v186 offset:21504
	ds_read_b128 v[192:195], v186 offset:22528
	ds_read_b128 v[196:199], v186 offset:23552
	global_load_lds_dwordx4 v[222:223], off
	v_lshl_add_u64 v[224:225], s[26:27], 0, v[158:159]
	s_mov_b32 m0, s30
	s_nop 0
	global_load_lds_dwordx4 v[224:225], off
	s_barrier
	s_waitcnt lgkmcnt(0)
	s_waitcnt lgkmcnt(0)
	v_mfma_f32_16x16x32_bf16 v[60:63], v[128:131], v[144:147], v[60:63]
	v_mfma_f32_16x16x32_bf16 v[56:59], v[136:139], v[144:147], v[56:59]
	v_mfma_f32_16x16x32_bf16 v[44:47], v[128:131], v[170:173], v[44:47]
	v_mfma_f32_16x16x32_bf16 v[40:43], v[136:139], v[170:173], v[40:43]
	v_mfma_f32_16x16x32_bf16 v[28:31], v[128:131], v[178:181], v[28:31]
	v_mfma_f32_16x16x32_bf16 v[24:27], v[136:139], v[178:181], v[24:27]
	v_mfma_f32_16x16x32_bf16 v[12:15], v[128:131], v[192:195], v[12:15]
	v_mfma_f32_16x16x32_bf16 v[8:11], v[136:139], v[192:195], v[8:11]
	v_mfma_f32_16x16x32_bf16 v[60:63], v[132:135], v[148:151], v[60:63]
	v_mfma_f32_16x16x32_bf16 v[56:59], v[140:143], v[148:151], v[56:59]
	v_mfma_f32_16x16x32_bf16 v[44:47], v[132:135], v[174:177], v[44:47]
	v_mfma_f32_16x16x32_bf16 v[40:43], v[140:143], v[174:177], v[40:43]
	v_mfma_f32_16x16x32_bf16 v[28:31], v[132:135], v[188:191], v[28:31]
	v_mfma_f32_16x16x32_bf16 v[24:27], v[140:143], v[188:191], v[24:27]
	v_mfma_f32_16x16x32_bf16 v[12:15], v[132:135], v[196:199], v[12:15]
	v_mfma_f32_16x16x32_bf16 v[8:11], v[140:143], v[196:199], v[8:11]
	s_barrier
	s_add_u32 s54, s24, 0x160000
	s_addc_u32 s55, s25, 0
	s_add_i32 s56, s42, s28
	s_nop 0
	s_mov_b32 m0, s56
	s_nop 0
	global_load_lds_dwordx4 v156, s[54:55]
	s_nop 0
	s_add_i32 m0, s56, 0x2000
	s_nop 0
	global_load_lds_dwordx4 v160, s[54:55]
	s_waitcnt vmcnt(6)
	s_barrier
; #define PG8_STAGE(bufoff, gbase, voff) do { _Pragma("unroll") for (int _i = 0; _i < 2; ++_i) \
;         __builtin_amdgcn_global_load_lds((const unsigned*)((const char*)(gbase) + (voff)[_i]), (LAS unsigned*)(lds + (bufoff) + ldsw + _i * 8192), 16, 0, 0); } while (0)
; #define PG8_LDA(dst, b, h) do { _Pragma("unroll") for (int m = 0; m < 4; ++m) _Pragma("unroll") for (int k = 0; k < 2; ++k) dst[m][k] = *(const LAS bf16x8*)(lds + PG8_SA(b, h) + aoff + m * 2048 + k * 1024); } while (0)
; #define PG8_LDB(dst, b, h) do { _Pragma("unroll") for (int n = 0; n < 2; ++n) _Pragma("unroll") for (int k = 0; k < 2; ++k) dst[n][k] = *(const LAS bf16x8*)(lds + PG8_SB(b, h) + boff + n * 2048 + k * 1024); } while (0)
; #define PG8_MMA(ai, bj, At, Bt) do { __builtin_amdgcn_s_setprio(1); _Pragma("unroll") for (int m = 0; m < 4; ++m) _Pragma("unroll") for (int n = 0; n < 2; ++n) _Pragma("unroll") for (int k = 0; k < 2; ++k) \
;         acc[ai][bj][m][n] = __builtin_amdgcn_mfma_f32_16x16x32_bf16(Bt[n][k], At[m][k], acc[ai][bj][m][n], 0, 0, 0); __builtin_amdgcn_s_setprio(0); } while (0)
; #define PG8_WAIT_V(n) asm volatile("s_waitcnt vmcnt(" #n ")" ::: "memory")
; #define PG8_WAIT_L(n) asm volatile("s_waitcnt lgkmcnt(" #n ")" ::: "memory")
; #define PG8_BAR __builtin_amdgcn_s_barrier()
; #define PG8_SCHED __builtin_amdgcn_sched_barrier(0)
; template <class Epi>
; __device__ __forceinline__ void gemm_phase(LAS unsigned char* lds, const Gemm g, const StaticOrder& S, const Epi& E) {
;     ...
;             PG8_WAIT_V(6); PG8_BAR; PG8_MMA(1, 1, At, B1); PG8_BAR;
;             PG8_LDB(B0, 1, 0); PG8_SCHED; PG8_LDA(At, 1, 0); PG8_STAGE(PG8_SA(0, 1), a2 + hstep, voffA);
;             PG8_WAIT_L(8); PG8_BAR; PG8_WAIT_L(0); PG8_MMA(0, 0, At, B0); PG8_BAR; PG8_SCHED;
;             PG8_LDB(B1, 1, 1); PG8_STAGE(PG8_SB(1, 0), b3, voffB);
;             PG8_BAR; PG8_WAIT_L(0); PG8_MMA(0, 1, At, B1); PG8_BAR;
;             PG8_LDA(At, 1, 1); PG8_STAGE(PG8_SA(1, 0), a3, voffA);
;             PG8_BAR; PG8_WAIT_L(0); PG8_MMA(1, 0, At, B0); PG8_BAR; PG8_SCHED;
	v_mfma_f32_16x16x32_bf16 v[52:55], v[200:203], v[144:147], v[52:55]
	v_mfma_f32_16x16x32_bf16 v[48:51], v[208:211], v[144:147], v[48:51]
	v_mfma_f32_16x16x32_bf16 v[36:39], v[200:203], v[170:173], v[36:39]
	v_mfma_f32_16x16x32_bf16 v[32:35], v[208:211], v[170:173], v[32:35]
	v_mfma_f32_16x16x32_bf16 v[20:23], v[200:203], v[178:181], v[20:23]
	v_mfma_f32_16x16x32_bf16 v[16:19], v[208:211], v[178:181], v[16:19]
	v_mfma_f32_16x16x32_bf16 v[4:7], v[200:203], v[192:195], v[4:7]
	v_mfma_f32_16x16x32_bf16 v[0:3], v[208:211], v[192:195], v[0:3]
	v_mfma_f32_16x16x32_bf16 v[52:55], v[204:207], v[148:151], v[52:55]
	v_mfma_f32_16x16x32_bf16 v[48:51], v[216:219], v[148:151], v[48:51]
	v_mfma_f32_16x16x32_bf16 v[36:39], v[204:207], v[174:177], v[36:39]
	v_mfma_f32_16x16x32_bf16 v[32:35], v[216:219], v[174:177], v[32:35]
	v_mfma_f32_16x16x32_bf16 v[20:23], v[204:207], v[188:191], v[20:23]
	v_mfma_f32_16x16x32_bf16 v[16:19], v[216:219], v[188:191], v[16:19]
	v_mfma_f32_16x16x32_bf16 v[4:7], v[204:207], v[196:199], v[4:7]
	v_mfma_f32_16x16x32_bf16 v[0:3], v[216:219], v[196:199], v[0:3]
	s_add_i32 s54, 0, 0x18000
	v_add_u32_e32 v140, s54, v183
	s_barrier
	ds_read_b128 v[128:131], v140
	ds_read_b128 v[132:135], v140 offset:1024
	ds_read_b128 v[136:139], v140 offset:2048
	ds_read_b128 v[140:143], v140 offset:3072
	s_add_u32 s26, s26, 0x160000
	s_addc_u32 s27, s27, 0
	s_mov_b32 m0, s31
	s_nop 0
	ds_read_b128 v[144:147], v186 offset:32768
	ds_read_b128 v[148:151], v186 offset:33792
	ds_read_b128 v[170:173], v186 offset:34816
	ds_read_b128 v[174:177], v186 offset:35840
	ds_read_b128 v[178:181], v186 offset:36864
	ds_read_b128 v[188:191], v186 offset:37888
	ds_read_b128 v[192:195], v186 offset:38912
	ds_read_b128 v[196:199], v186 offset:39936
	global_load_lds_dwordx4 v154, s[26:27]
	s_nop 0
	s_mov_b32 m0, s33
	s_nop 0
	global_load_lds_dwordx4 v158, s[26:27]
	s_waitcnt lgkmcnt(8)
	s_barrier
	s_waitcnt lgkmcnt(0)
	s_waitcnt lgkmcnt(0)
	v_mfma_f32_16x16x32_bf16 v[124:127], v[128:131], v[144:147], v[124:127]
	v_mfma_f32_16x16x32_bf16 v[120:123], v[136:139], v[144:147], v[120:123]
	v_mfma_f32_16x16x32_bf16 v[108:111], v[128:131], v[170:173], v[108:111]
	v_mfma_f32_16x16x32_bf16 v[104:107], v[136:139], v[170:173], v[104:107]
	v_mfma_f32_16x16x32_bf16 v[92:95], v[128:131], v[178:181], v[92:95]
	v_mfma_f32_16x16x32_bf16 v[88:91], v[136:139], v[178:181], v[88:91]
	v_mfma_f32_16x16x32_bf16 v[76:79], v[128:131], v[192:195], v[76:79]
	v_mfma_f32_16x16x32_bf16 v[72:75], v[136:139], v[192:195], v[72:75]
	v_mfma_f32_16x16x32_bf16 v[124:127], v[132:135], v[148:151], v[124:127]
	v_mfma_f32_16x16x32_bf16 v[120:123], v[140:143], v[148:151], v[120:123]
	v_mfma_f32_16x16x32_bf16 v[108:111], v[132:135], v[174:177], v[108:111]
	v_mfma_f32_16x16x32_bf16 v[104:107], v[140:143], v[174:177], v[104:107]
	v_mfma_f32_16x16x32_bf16 v[92:95], v[132:135], v[188:191], v[92:95]
	v_mfma_f32_16x16x32_bf16 v[88:91], v[140:143], v[188:191], v[88:91]
	v_mfma_f32_16x16x32_bf16 v[76:79], v[132:135], v[196:199], v[76:79]
	v_mfma_f32_16x16x32_bf16 v[72:75], v[140:143], v[196:199], v[72:75]
	s_barrier
	s_add_i32 s26, 0, 0x1c000
	s_add_i32 s27, s54, s28
	v_add_u32_e32 v216, s26, v183
	v_lshl_add_u64 v[212:213], v[212:213], 0, s[16:17]
	s_mov_b32 m0, s27
	ds_read_b128 v[200:203], v216
	ds_read_b128 v[204:207], v216 offset:1024
	ds_read_b128 v[208:211], v216 offset:2048
	ds_read_b128 v[216:219], v216 offset:3072
	global_load_lds_dwordx4 v[212:213], off
	v_lshl_add_u64 v[212:213], v[220:221], 0, s[16:17]
	s_add_i32 m0, s27, 0x2000
	s_nop 0
	global_load_lds_dwordx4 v[212:213], off
	s_barrier
	s_waitcnt lgkmcnt(0)
	s_waitcnt lgkmcnt(0)
	v_mfma_f32_16x16x32_bf16 v[116:119], v[200:203], v[144:147], v[116:119]
	v_mfma_f32_16x16x32_bf16 v[112:115], v[208:211], v[144:147], v[112:115]
	v_mfma_f32_16x16x32_bf16 v[100:103], v[200:203], v[170:173], v[100:103]
	v_mfma_f32_16x16x32_bf16 v[96:99], v[208:211], v[170:173], v[96:99]
	v_mfma_f32_16x16x32_bf16 v[84:87], v[200:203], v[178:181], v[84:87]
	v_mfma_f32_16x16x32_bf16 v[80:83], v[208:211], v[178:181], v[80:83]
	v_mfma_f32_16x16x32_bf16 v[68:71], v[200:203], v[192:195], v[68:71]
	v_mfma_f32_16x16x32_bf16 v[64:67], v[208:211], v[192:195], v[64:67]
	v_mfma_f32_16x16x32_bf16 v[116:119], v[204:207], v[148:151], v[116:119]
	v_mfma_f32_16x16x32_bf16 v[112:115], v[216:219], v[148:151], v[112:115]
	v_mfma_f32_16x16x32_bf16 v[100:103], v[204:207], v[174:177], v[100:103]
	v_mfma_f32_16x16x32_bf16 v[96:99], v[216:219], v[174:177], v[96:99]
	v_mfma_f32_16x16x32_bf16 v[84:87], v[204:207], v[188:191], v[84:87]
	v_mfma_f32_16x16x32_bf16 v[80:83], v[216:219], v[188:191], v[80:83]
	v_mfma_f32_16x16x32_bf16 v[68:71], v[204:207], v[196:199], v[68:71]
	v_mfma_f32_16x16x32_bf16 v[64:67], v[216:219], v[196:199], v[64:67]
	s_mov_b32 m0, s38
	v_lshl_add_u64 v[212:213], v[222:223], 0, s[16:17]
	s_barrier
; #define PG8_STAGE(bufoff, gbase, voff) do { _Pragma("unroll") for (int _i = 0; _i < 2; ++_i) \
;         __builtin_amdgcn_global_load_lds((const unsigned*)((const char*)(gbase) + (voff)[_i]), (LAS unsigned*)(lds + (bufoff) + ldsw + _i * 8192), 16, 0, 0); } while (0)
; #define PG8_MMA(ai, bj, At, Bt) do { __builtin_amdgcn_s_setprio(1); _Pragma("unroll") for (int m = 0; m < 4; ++m) _Pragma("unroll") for (int n = 0; n < 2; ++n) _Pragma("unroll") for (int k = 0; k < 2; ++k) \
;         acc[ai][bj][m][n] = __builtin_amdgcn_mfma_f32_16x16x32_bf16(Bt[n][k], At[m][k], acc[ai][bj][m][n], 0, 0, 0); __builtin_amdgcn_s_setprio(0); } while (0)
; #define PG8_WAIT_V(n) asm volatile("s_waitcnt vmcnt(" #n ")" ::: "memory")
; #define PG8_WAIT_L(n) asm volatile("s_waitcnt lgkmcnt(" #n ")" ::: "memory")
; #define PG8_BAR __builtin_amdgcn_s_barrier()
; #define PG8_SCHED __builtin_amdgcn_sched_barrier(0)
; __device__ __forceinline__ void unpack8(const u32x4 w, f32x4& v0, f32x4& v1) { v0 = (f32x4){bflo(w.x), bfhi(w.x), bflo(w.y), bfhi(w.y)}; v1 = (f32x4){bflo(w.z), bfhi(w.z), bflo(w.w), bfhi(w.w)}; }
; template <class Epi>
; __device__ __forceinline__ void gemm_phase(LAS unsigned char* lds, const Gemm g, const StaticOrder& S, const Epi& E) {
;     ...
;             PG8_BAR; PG8_WAIT_L(0); PG8_MMA(1, 0, At, B0); PG8_BAR; PG8_SCHED;
;             PG8_STAGE(PG8_SB(1, 1), b3 + hstep, voffB);
;             PG8_WAIT_V(6); PG8_BAR; PG8_MMA(1, 1, At, B1); PG8_BAR;
;         }
;     __device__ __forceinline__ void operator()(const AccT& acc, const pg8::Unit& u, int wr, int wc, int fr, int fq) const {
;     ...
;         for (int ai = 0; ai < 2; ++ai) { f32x4 b0[4][2], b1[4][2];
; #pragma unroll
;             for (int m = 0; m < 4; ++m) { const int r = row0 + ai * 128 + m * 16; const int rc = r < NREAL ? r : NREAL - 1;
; #pragma unroll
;                 for (int bj = 0; bj < 2; ++bj) {
;                     if (mode) unpack8(*(const u32x4*)(X1 + (size_t)rc * D + col0 + bj * 128), b0[m][bj], b1[m][bj]);
;                     else { const float* b2 = (rc < ROW_S ? xp + (size_t)rc * D : xs + (size_t)(rc - ROW_S) * D) + col0 + bj * 128; b0[m][bj] = *(const f32x4*)b2; b1[m][bj] = *(const f32x4*)(b2 + 4); } } }
; #pragma unroll
;             for (int m = 0; m < 4; ++m) { const int r = row0 + ai * 128 + m * 16;
;                 if (r < NREAL) {
	ds_read_b128 v[144:147], v186 offset:49152
	ds_read_b128 v[148:151], v186 offset:50176
	ds_read_b128 v[170:173], v186 offset:51200
	ds_read_b128 v[174:177], v186 offset:52224
	ds_read_b128 v[178:181], v186 offset:53248
	ds_read_b128 v[188:191], v186 offset:54272
	ds_read_b128 v[192:195], v186 offset:55296
	ds_read_b128 v[196:199], v186 offset:56320
	global_load_lds_dwordx4 v[212:213], off
	v_lshl_add_u64 v[212:213], v[224:225], 0, s[16:17]
	s_mov_b32 m0, s39
	s_nop 0
	global_load_lds_dwordx4 v[212:213], off
	s_barrier
	s_waitcnt lgkmcnt(0)
	s_waitcnt lgkmcnt(0)
	v_mfma_f32_16x16x32_bf16 v[60:63], v[128:131], v[144:147], v[60:63]
	v_mfma_f32_16x16x32_bf16 v[56:59], v[136:139], v[144:147], v[56:59]
	v_mfma_f32_16x16x32_bf16 v[44:47], v[128:131], v[170:173], v[44:47]
	v_mfma_f32_16x16x32_bf16 v[40:43], v[136:139], v[170:173], v[40:43]
	v_mfma_f32_16x16x32_bf16 v[28:31], v[128:131], v[178:181], v[28:31]
	v_mfma_f32_16x16x32_bf16 v[24:27], v[136:139], v[178:181], v[24:27]
	v_mfma_f32_16x16x32_bf16 v[12:15], v[128:131], v[192:195], v[12:15]
	v_mfma_f32_16x16x32_bf16 v[8:11], v[136:139], v[192:195], v[8:11]
	v_mfma_f32_16x16x32_bf16 v[60:63], v[132:135], v[148:151], v[60:63]
	v_mfma_f32_16x16x32_bf16 v[56:59], v[140:143], v[148:151], v[56:59]
	v_mfma_f32_16x16x32_bf16 v[44:47], v[132:135], v[174:177], v[44:47]
	v_mfma_f32_16x16x32_bf16 v[40:43], v[140:143], v[174:177], v[40:43]
	v_mfma_f32_16x16x32_bf16 v[28:31], v[132:135], v[188:191], v[28:31]
	v_mfma_f32_16x16x32_bf16 v[24:27], v[140:143], v[188:191], v[24:27]
	v_mfma_f32_16x16x32_bf16 v[12:15], v[132:135], v[196:199], v[12:15]
	v_mfma_f32_16x16x32_bf16 v[8:11], v[140:143], v[196:199], v[8:11]
	s_barrier
	s_add_u32 s24, s24, 0x160080
	s_addc_u32 s25, s25, 0
	s_add_i32 s26, s26, s28
	s_nop 0
	s_mov_b32 m0, s26
	s_nop 0
	global_load_lds_dwordx4 v156, s[24:25]
	v_lshl_add_u64 v[128:129], s[24:25], 0, v[160:161]
	s_add_i32 m0, s26, 0x2000
	s_nop 0
	global_load_lds_dwordx4 v[128:129], off
	s_waitcnt vmcnt(6)
	s_barrier
	v_mfma_f32_16x16x32_bf16 v[52:55], v[200:203], v[144:147], v[52:55]
	v_mfma_f32_16x16x32_bf16 v[48:51], v[208:211], v[144:147], v[48:51]
	v_mfma_f32_16x16x32_bf16 v[36:39], v[200:203], v[170:173], v[36:39]
	v_mfma_f32_16x16x32_bf16 v[32:35], v[208:211], v[170:173], v[32:35]
	v_mfma_f32_16x16x32_bf16 v[20:23], v[200:203], v[178:181], v[20:23]
	v_mfma_f32_16x16x32_bf16 v[16:19], v[208:211], v[178:181], v[16:19]
	v_mfma_f32_16x16x32_bf16 v[4:7], v[200:203], v[192:195], v[4:7]
	v_mfma_f32_16x16x32_bf16 v[0:3], v[208:211], v[192:195], v[0:3]
	v_mfma_f32_16x16x32_bf16 v[52:55], v[204:207], v[148:151], v[52:55]
	v_mfma_f32_16x16x32_bf16 v[48:51], v[216:219], v[148:151], v[48:51]
	v_mfma_f32_16x16x32_bf16 v[36:39], v[204:207], v[174:177], v[36:39]
	v_mfma_f32_16x16x32_bf16 v[32:35], v[216:219], v[174:177], v[32:35]
	v_mfma_f32_16x16x32_bf16 v[20:23], v[204:207], v[188:191], v[20:23]
	v_mfma_f32_16x16x32_bf16 v[16:19], v[216:219], v[188:191], v[16:19]
	v_mfma_f32_16x16x32_bf16 v[4:7], v[204:207], v[196:199], v[4:7]
	v_mfma_f32_16x16x32_bf16 v[0:3], v[216:219], v[196:199], v[0:3]
	s_add_i32 s53, s53, 2
	s_add_u32 s22, s22, 0x100
	s_addc_u32 s23, s23, 0
	s_add_u32 s51, s51, 0x100
	s_addc_u32 s52, s52, 0
	s_cmpk_gt_u32 s53, 0x55
	s_barrier
	s_cbranch_scc0 .LBB0_1338
	v_lshl_add_u32 v172, s50, 8, v182
	v_or_b32_e32 v180, 16, v172
	v_lshl_or_b32 v170, s49, 8, v184
	v_min_i32_e32 v128, 0x207f, v180
	v_ashrrev_i32_e32 v171, 31, v170
	v_ashrrev_i32_e32 v129, 31, v128
	v_lshl_add_u64 v[174:175], v[170:171], 1, s[12:13]
	v_lshlrev_b64 v[128:129], 12, v[128:129]
	v_lshl_add_u64 v[128:129], v[174:175], 0, v[128:129]
	v_or_b32_e32 v178, 32, v172
	global_load_dwordx4 v[148:151], v[128:129], off
	global_load_dwordx4 v[144:147], v[128:129], off offset:256
	v_min_i32_e32 v128, 0x207f, v178
	v_ashrrev_i32_e32 v129, 31, v128
	v_lshlrev_b64 v[128:129], 12, v[128:129]
	v_lshl_add_u64 v[128:129], v[174:175], 0, v[128:129]
	v_or_b32_e32 v176, 48, v172
	global_load_dwordx4 v[140:143], v[128:129], off
	global_load_dwordx4 v[136:139], v[128:129], off offset:256
	v_min_i32_e32 v128, 0x207f, v176
	v_ashrrev_i32_e32 v129, 31, v128
	v_lshlrev_b64 v[128:129], 12, v[128:129]
	v_lshl_add_u64 v[128:129], v[174:175], 0, v[128:129]
	global_load_dwordx4 v[132:135], v[128:129], off
	s_nop 0
	global_load_dwordx4 v[128:131], v[128:129], off offset:256
	v_cmp_gt_i32_e32 vcc, s43, v172
	v_ashrrev_i32_e32 v173, 31, v172
	s_and_saveexec_b64 s[22:23], vcc
	s_cbranch_execnz .LBB0_1348
	s_or_b64 exec, exec, s[22:23]
	v_cmp_gt_i32_e32 vcc, s43, v180
	s_and_saveexec_b64 s[22:23], vcc
	s_cbranch_execnz .LBB0_1349
